# hand-written PEER gather (sorted, 8-slot ring, coalesced fp6 table layout), nt encode loads, GEMM loop reads-before-DMA
# speedup vs baseline: 1.0362x; 1.0362x over previous
; DEV int ltid() { int t = threadIdx.x; asm volatile("" : "+v"(t)); return t; }
; template <class AF, class EPI>
; DEV void gemm_tile256(AF aptr, const u16* Bt, int ldb, int K, EPI epi, char* smem) {
;   const int tid = ltid(), wid = tid >> 6, lane = tid & 63, wr = wid >> 1, wc = wid & 1, fr = lane & 15, fq = lane >> 4;
;   f32x4 acc[8][4];
; #pragma unroll
;   for (int m = 0; m < 8; ++m)
; #pragma unroll
;     for (int n = 0; n < 4; ++n) acc[m][n] = f32x4{0.f, 0.f, 0.f, 0.f};
;   const int nk = K / 32;
;   auto stage = [&](int kt, int buf) {
;     char* SA = smem + buf * 24576;
;     char* SB = SA + 16384;
; #pragma unroll
;     for (int i = 0; i < 4; ++i) {
;       int bo = tid * 16 + i * 4096, r = bo >> 6, c = (bo & 63) >> 1;
;       __builtin_amdgcn_global_load_lds((const unsigned*)aptr(r, kt * 32 + c), (__attribute__((address_space(3))) unsigned*)(SA + bo), 16, 0, 0);
;     }
; #pragma unroll
;     for (int i = 0; i < 2; ++i) {
;       int bo = tid * 16 + i * 4096, r = bo >> 6, c = (bo & 63) >> 1;
;       __builtin_amdgcn_global_load_lds((const unsigned*)(Bt + (size_t)r * ldb + kt * 32 + c), (__attribute__((address_space(3))) unsigned*)(SB + bo), 16, 0, 0);
;     }
;   };
;   asm volatile("s_waitcnt vmcnt(0)" ::: "memory");
;   __syncthreads();
;   stage(0, 0);
;   stage(1, 1);
;   const unsigned lbase = (unsigned)(size_t)(const __attribute__((address_space(3))) char*)smem;
;   const unsigned aoff = lbase + (wr * 128 + fr) * 64 + fq * 16, boff = lbase + 16384 + (wc * 64 + fr) * 64 + fq * 16;
; __global__ void __launch_bounds__(256, 2) fwd_megakernel(Params p) {
;     ...
;   for (int jt = (bid >> 3); jt < 8 * 37; jt += (nb >> 3)) {
;     const int pn = jt >> 3, pm = (bid & 7) * 8 + (jt & 7);
;     const u16* A = p.h + (size_t)pm * 256 * 2048;
;     gemm_tile256([&](int r, int k) { return A + (size_t)r * 2048 + k; }, p.Wt_in + (size_t)pn * 128 * 2048, 2048, 2048,
.LBB0_247:
	s_and_b32 s57, s3, 7
	s_lshl_b32 s0, s57, 19
	s_add_i32 s0, s6, s0
	s_lshl_b32 s44, s0, 1
	s_and_b32 s0, s93, 7
	s_or_b32 s56, s0, s4
	v_readlane_b32 s16, v255, 9
	v_mov_b32_e32 v144, v0
	s_ashr_i32 s38, s93, 3
	s_lshl_b32 s0, s56, 20
	v_readlane_b32 s20, v255, 13
	v_readlane_b32 s21, v255, 14
	v_ashrrev_i32_e32 v2, 2, v144
	s_add_u32 s40, s20, s0
	v_lshlrev_b32_e32 v148, 4, v144
	v_ashrrev_i32_e32 v3, 31, v2
	s_addc_u32 s41, s21, 0
	s_ashr_i32 s39, s38, 31
	v_lshlrev_b64 v[2:3], 12, v[2:3]
	v_add_u32_e32 v10, 0x1000, v148
	s_lshl_b64 s[0:1], s[38:39], 19
	v_lshl_add_u64 v[4:5], s[40:41], 0, v[2:3]
	v_and_b32_e32 v134, 48, v148
	v_readfirstlane_b32 s39, v148
	v_ashrrev_i32_e32 v6, 6, v10
	v_add_u32_e32 v14, 0x2000, v148
	v_readlane_b32 s17, v255, 10
	v_readlane_b32 s18, v255, 11
	v_readlane_b32 s19, v255, 12
	v_readlane_b32 s22, v255, 15
	v_readlane_b32 s23, v255, 16
	v_readlane_b32 s24, v255, 17
	v_readlane_b32 s25, v255, 18
	v_readlane_b32 s26, v255, 19
	v_readlane_b32 s27, v255, 20
	v_readlane_b32 s28, v255, 21
	v_readlane_b32 s29, v255, 22
	v_readlane_b32 s30, v255, 23
	v_readlane_b32 s31, v255, 24
	v_lshl_add_u64 v[4:5], v[4:5], 0, v[134:135]
	s_mov_b32 m0, s39
	v_ashrrev_i32_e32 v7, 31, v6
	v_readfirstlane_b32 s39, v10
	v_ashrrev_i32_e32 v10, 6, v14
	v_add_u32_e32 v18, 0x3000, v148
	v_readlane_b32 s16, v254, 4
	s_waitcnt vmcnt(0)
	s_barrier
; template <class AF, class EPI>
; DEV void gemm_tile256(AF aptr, const u16* Bt, int ldb, int K, EPI epi, char* smem) {
;     ...
;   f32x4 acc[8][4];
; #pragma unroll
;   for (int m = 0; m < 8; ++m)
; #pragma unroll
;     for (int n = 0; n < 4; ++n) acc[m][n] = f32x4{0.f, 0.f, 0.f, 0.f};
;   const int nk = K / 32;
;   auto stage = [&](int kt, int buf) {
;     char* SA = smem + buf * 24576;
;     char* SB = SA + 16384;
; #pragma unroll
;     for (int i = 0; i < 4; ++i) {
;       int bo = tid * 16 + i * 4096, r = bo >> 6, c = (bo & 63) >> 1;
;       __builtin_amdgcn_global_load_lds((const unsigned*)aptr(r, kt * 32 + c), (__attribute__((address_space(3))) unsigned*)(SA + bo), 16, 0, 0);
;     }
; #pragma unroll
;     for (int i = 0; i < 2; ++i) {
;       int bo = tid * 16 + i * 4096, r = bo >> 6, c = (bo & 63) >> 1;
;       __builtin_amdgcn_global_load_lds((const unsigned*)(Bt + (size_t)r * ldb + kt * 32 + c), (__attribute__((address_space(3))) unsigned*)(SB + bo), 16, 0, 0);
;     }
;   };
;   asm volatile("s_waitcnt vmcnt(0)" ::: "memory");
;   __syncthreads();
;   stage(0, 0);
;   stage(1, 1);
;   const unsigned lbase = (unsigned)(size_t)(const __attribute__((address_space(3))) char*)smem;
;   const unsigned aoff = lbase + (wr * 128 + fr) * 64 + fq * 16, boff = lbase + 16384 + (wc * 64 + fr) * 64 + fq * 16;
;   int buf = 0;
; #pragma unroll 1
;   for (int t = 0; t < nk; ++t) {
;     if (t + 1 < nk) asm volatile("s_waitcnt vmcnt(6)" ::: "memory");
;     else asm volatile("s_waitcnt vmcnt(0)" ::: "memory");
	global_load_lds_dwordx4 v[4:5], off
	v_lshlrev_b64 v[6:7], 12, v[6:7]
	s_mov_b32 m0, s39
	v_ashrrev_i32_e32 v11, 31, v10
	v_readfirstlane_b32 s39, v14
	v_ashrrev_i32_e32 v14, 6, v18
	v_readlane_b32 s26, v254, 14
	v_lshl_add_u64 v[8:9], s[40:41], 0, v[6:7]
	v_lshlrev_b64 v[10:11], 12, v[10:11]
	v_ashrrev_i32_e32 v15, 31, v14
	v_readlane_b32 s27, v254, 15
	s_add_u32 s42, s26, s0
	v_lshl_add_u64 v[8:9], v[8:9], 0, v[134:135]
	v_lshl_add_u64 v[12:13], s[40:41], 0, v[10:11]
	v_lshlrev_b64 v[14:15], 12, v[14:15]
	s_addc_u32 s43, s27, s1
	global_load_lds_dwordx4 v[8:9], off
	v_lshl_add_u64 v[12:13], v[12:13], 0, v[134:135]
	s_mov_b32 m0, s39
	v_lshl_add_u64 v[16:17], s[40:41], 0, v[14:15]
	v_readfirstlane_b32 s39, v18
	v_add_u32_e32 v20, 0x4000, v148
	global_load_lds_dwordx4 v[12:13], off
	v_lshl_add_u64 v[16:17], v[16:17], 0, v[134:135]
	s_mov_b32 m0, s39
	v_lshl_add_u64 v[18:19], s[42:43], 0, v[2:3]
	v_readfirstlane_b32 s39, v20
	v_add_u32_e32 v22, 0x5000, v148
	global_load_lds_dwordx4 v[16:17], off
	v_lshl_add_u64 v[18:19], v[18:19], 0, v[134:135]
	s_mov_b32 m0, s39
	v_lshl_add_u64 v[20:21], s[42:43], 0, v[6:7]
	v_readfirstlane_b32 s39, v22
	v_add_u32_e32 v22, 0x6000, v148
	global_load_lds_dwordx4 v[18:19], off
	v_lshl_add_u64 v[20:21], v[20:21], 0, v[134:135]
	s_mov_b32 m0, s39
	v_readfirstlane_b32 s39, v22
	global_load_lds_dwordx4 v[20:21], off
	v_lshl_add_u64 v[4:5], v[4:5], 0, 64
	s_mov_b32 m0, s39
	s_add_u32 s40, s5, s44
	global_load_lds_dwordx4 v[4:5], off
	v_lshl_add_u64 v[4:5], v[8:9], 0, 64
	v_add_u32_e32 v8, 0x7000, v148
	v_bfe_u32 v147, v144, 4, 2
	v_readfirstlane_b32 s39, v8
	v_add_u32_e32 v8, 0x8000, v148
	s_mov_b32 m0, s39
	v_readfirstlane_b32 s39, v8
	v_add_u32_e32 v8, 0x9000, v148
	global_load_lds_dwordx4 v[4:5], off
	v_lshl_add_u64 v[4:5], v[12:13], 0, 64
	s_mov_b32 m0, s39
	v_readfirstlane_b32 s39, v8
	v_add_u32_e32 v8, 0xa000, v148
	global_load_lds_dwordx4 v[4:5], off
	v_lshl_add_u64 v[4:5], v[16:17], 0, 64
	s_mov_b32 m0, s39
	v_readfirstlane_b32 s39, v8
	v_add_u32_e32 v8, 0xb000, v148
	global_load_lds_dwordx4 v[4:5], off
	v_lshl_add_u64 v[4:5], v[18:19], 0, 64
	s_mov_b32 m0, s39
	v_readfirstlane_b32 s39, v8
	global_load_lds_dwordx4 v[4:5], off
	v_lshl_add_u64 v[4:5], v[20:21], 0, 64
	s_mov_b32 m0, s39
	s_addc_u32 s41, s76, 0
	global_load_lds_dwordx4 v[4:5], off
	v_bfe_u32 v145, v144, 6, 1
	v_ashrrev_i32_e32 v159, 7, v144
	v_and_b32_e32 v146, 15, v144
	v_lshlrev_b32_e32 v8, 4, v147
	s_add_u32 s0, s7, s0
	v_lshlrev_b32_e32 v4, 13, v159
	v_lshlrev_b32_e32 v5, 6, v146
	v_lshl_or_b32 v9, v145, 12, v8
	s_movk_i32 s39, 0x4000
	v_or_b32_e32 v2, v2, v134
	v_or_b32_e32 v6, v6, v134
	v_or_b32_e32 v10, v10, v134
	v_or_b32_e32 v14, v14, v134
	s_addc_u32 s1, s8, s1
	v_or3_b32 v149, v4, v8, v5
	v_or3_b32 v150, v5, v9, s39
	v_lshl_add_u64 v[130:131], s[40:41], 0, v[2:3]
	v_lshl_add_u64 v[132:133], s[40:41], 0, v[6:7]
	v_lshl_add_u64 v[136:137], s[40:41], 0, v[10:11]
	v_lshl_add_u64 v[138:139], s[40:41], 0, v[14:15]
	v_lshl_add_u64 v[140:141], s[0:1], 0, v[6:7]
	v_lshl_add_u64 v[142:143], s[0:1], 0, v[2:3]
	s_mov_b64 s[0:1], 0
	s_mov_b32 s39, 0
	s_mov_b32 s42, 0
	v_mov_b32_e32 v2, 0
	v_mov_b32_e32 v3, v135
	v_mov_b32_e32 v4, v135
	v_mov_b32_e32 v5, v135
	v_mov_b32_e32 v6, 0
	v_mov_b32_e32 v7, v135
	v_mov_b32_e32 v8, v135
	v_mov_b32_e32 v9, v135
	v_mov_b32_e32 v10, 0
	v_mov_b32_e32 v11, v135
	v_mov_b32_e32 v12, v135
	v_mov_b32_e32 v13, v135
	v_mov_b32_e32 v14, 0
	v_mov_b32_e32 v15, v135
	v_mov_b32_e32 v16, v135
	v_mov_b32_e32 v17, v135
	v_mov_b32_e32 v18, 0
	v_mov_b32_e32 v19, v135
	v_mov_b32_e32 v20, v135
	v_mov_b32_e32 v21, v135
	v_mov_b32_e32 v22, 0
	v_mov_b32_e32 v23, v135
	v_mov_b32_e32 v24, v135
	v_mov_b32_e32 v25, v135
	v_mov_b32_e32 v26, 0
	v_mov_b32_e32 v27, v135
	v_mov_b32_e32 v28, v135
	v_mov_b32_e32 v29, v135
	v_mov_b32_e32 v30, 0
	v_mov_b32_e32 v31, v135
	v_mov_b32_e32 v32, v135
	v_mov_b32_e32 v33, v135
	v_mov_b32_e32 v34, 0
	v_mov_b32_e32 v35, v135
	v_mov_b32_e32 v36, v135
	v_mov_b32_e32 v37, v135
	v_mov_b32_e32 v38, 0
	v_mov_b32_e32 v39, v135
	v_mov_b32_e32 v40, v135
	v_mov_b32_e32 v41, v135
	v_mov_b32_e32 v42, 0
	v_mov_b32_e32 v43, v135
	v_mov_b32_e32 v44, v135
	v_mov_b32_e32 v45, v135
	v_mov_b32_e32 v94, 0
	v_mov_b32_e32 v95, v135
	v_mov_b32_e32 v96, v135
	v_mov_b32_e32 v97, v135
	v_mov_b32_e32 v98, 0
	v_mov_b32_e32 v99, v135
	v_mov_b32_e32 v100, v135
	v_mov_b32_e32 v101, v135
	v_mov_b32_e32 v102, 0
	v_mov_b32_e32 v103, v135
	v_mov_b32_e32 v104, v135
	v_mov_b32_e32 v105, v135
	v_mov_b32_e32 v106, 0
	v_mov_b32_e32 v107, v135
	v_mov_b32_e32 v108, v135
	v_mov_b32_e32 v109, v135
	v_mov_b32_e32 v110, 0
	v_mov_b32_e32 v111, v135
	v_mov_b32_e32 v112, v135
	v_mov_b32_e32 v113, v135
	v_mov_b32_e32 v114, 0
	v_mov_b32_e32 v115, v135
	v_mov_b32_e32 v116, v135
	v_mov_b32_e32 v117, v135
	v_mov_b32_e32 v118, 0
	v_mov_b32_e32 v119, v135
	v_mov_b32_e32 v120, v135
	v_mov_b32_e32 v121, v135
	v_mov_b32_e32 v122, 0
	v_mov_b32_e32 v123, v135
	v_mov_b32_e32 v124, v135
	v_mov_b32_e32 v125, v135
	v_mov_b32_e32 v126, 0
	v_mov_b32_e32 v127, v135
	v_mov_b32_e32 v128, v135
	v_mov_b32_e32 v129, v135
	v_mov_b32_e32 v46, 0
	v_mov_b32_e32 v47, v135
	v_mov_b32_e32 v48, v135
	v_mov_b32_e32 v49, v135
	v_mov_b32_e32 v50, 0
	v_mov_b32_e32 v51, v135
	v_mov_b32_e32 v52, v135
	v_mov_b32_e32 v53, v135
	v_mov_b32_e32 v54, 0
	v_mov_b32_e32 v55, v135
	v_mov_b32_e32 v56, v135
	v_mov_b32_e32 v57, v135
	v_mov_b32_e32 v58, 0
	v_mov_b32_e32 v59, v135
	v_mov_b32_e32 v60, v135
	v_mov_b32_e32 v61, v135
	v_mov_b32_e32 v62, 0
	v_mov_b32_e32 v63, v135
	v_mov_b32_e32 v64, v135
	v_mov_b32_e32 v65, v135
	v_mov_b32_e32 v66, 0
	v_mov_b32_e32 v67, v135
	v_mov_b32_e32 v68, v135
	v_mov_b32_e32 v69, v135
	v_mov_b32_e32 v70, 0
	v_mov_b32_e32 v71, v135
	v_mov_b32_e32 v72, v135
	v_mov_b32_e32 v73, v135
	v_mov_b32_e32 v74, 0
	v_mov_b32_e32 v75, v135
	v_mov_b32_e32 v76, v135
	v_mov_b32_e32 v77, v135
	v_mov_b32_e32 v78, 0
	v_mov_b32_e32 v79, v135
	v_mov_b32_e32 v80, v135
	v_mov_b32_e32 v81, v135
	v_mov_b32_e32 v82, 0
	v_mov_b32_e32 v83, v135
	v_mov_b32_e32 v84, v135
	v_mov_b32_e32 v85, v135
	v_mov_b32_e32 v86, 0
	v_mov_b32_e32 v87, v135
	v_mov_b32_e32 v88, v135
	v_mov_b32_e32 v89, v135
	v_mov_b32_e32 v90, 0
	v_mov_b32_e32 v91, v135
	v_mov_b32_e32 v92, v135
	v_mov_b32_e32 v93, v135
	v_readlane_b32 s17, v254, 5
	v_readlane_b32 s18, v254, 6
	v_readlane_b32 s19, v254, 7
	v_readlane_b32 s20, v254, 8
	v_readlane_b32 s21, v254, 9
	v_readlane_b32 s22, v254, 10
	v_readlane_b32 s23, v254, 11
	v_readlane_b32 s24, v254, 12
	v_readlane_b32 s25, v254, 13
	v_readlane_b32 s28, v254, 16
	v_readlane_b32 s29, v254, 17
	v_readlane_b32 s30, v254, 18
	v_readlane_b32 s31, v254, 19
	s_branch .LBB0_249
.LBB0_249:
	s_cmpk_eq_i32 s0, 0xfc0
	s_mov_b64 s[40:41], -1
	s_cbranch_scc1 .LBB0_251
	s_waitcnt vmcnt(6)
	s_mov_b64 s[40:41], 0

; template <class AF, class EPI>
; DEV void gemm_tile256(AF aptr, const u16* Bt, int ldb, int K, EPI epi, char* smem) {
;     ...
;     __builtin_amdgcn_s_barrier();
;     if (t + 2 < nk) { int nb2 = buf + 2; if (nb2 >= 3) nb2 -= 3; stage(t + 2, nb2); }
;     const unsigned sa = aoff + buf * 24576, sb = boff + buf * 24576;
;     u32x4 a0, a1, a2, a3, a4, a5, a6, a7, b0, b1, b2, b3;
;     asm volatile("ds_read_b128 %0, %1" : "=v"(b0) : "v"(sb));
;     asm volatile("ds_read_b128 %0, %1 offset:1024" : "=v"(b1) : "v"(sb));
;     asm volatile("ds_read_b128 %0, %1 offset:2048" : "=v"(b2) : "v"(sb));
;     asm volatile("ds_read_b128 %0, %1 offset:3072" : "=v"(b3) : "v"(sb));
;     asm volatile("ds_read_b128 %0, %1" : "=v"(a0) : "v"(sa));
;     asm volatile("ds_read_b128 %0, %1 offset:1024" : "=v"(a1) : "v"(sa));
;     asm volatile("ds_read_b128 %0, %1 offset:2048" : "=v"(a2) : "v"(sa));
;     asm volatile("ds_read_b128 %0, %1 offset:3072" : "=v"(a3) : "v"(sa));
;     asm volatile("ds_read_b128 %0, %1 offset:4096" : "=v"(a4) : "v"(sa));
;     asm volatile("ds_read_b128 %0, %1 offset:5120" : "=v"(a5) : "v"(sa));
;     asm volatile("ds_read_b128 %0, %1 offset:6144" : "=v"(a6) : "v"(sa));
;     asm volatile("ds_read_b128 %0, %1 offset:7168" : "=v"(a7) : "v"(sa));
;     asm volatile("s_waitcnt lgkmcnt(4)" : "+v"(a0), "+v"(a1), "+v"(a2), "+v"(a3), "+v"(b0), "+v"(b1), "+v"(b2), "+v"(b3));
;     bf16x8 Bv[4];
;     Bv[0] = __builtin_bit_cast(bf16x8, b0); Bv[1] = __builtin_bit_cast(bf16x8, b1); Bv[2] = __builtin_bit_cast(bf16x8, b2); Bv[3] = __builtin_bit_cast(bf16x8, b3);
;     {
;       bf16x8 At[4];
;       At[0] = __builtin_bit_cast(bf16x8, a0); At[1] = __builtin_bit_cast(bf16x8, a1); At[2] = __builtin_bit_cast(bf16x8, a2); At[3] = __builtin_bit_cast(bf16x8, a3);
; #pragma unroll
;       for (int m = 0; m < 4; ++m)
; #pragma unroll
;         for (int n = 0; n < 4; ++n) acc[m][n] = __builtin_amdgcn_mfma_f32_16x16x32_bf16(At[m], Bv[n], acc[m][n], 0, 0, 0);
;     }
;     asm volatile("s_waitcnt lgkmcnt(0)" : "+v"(a4), "+v"(a5), "+v"(a6), "+v"(a7));
;     {
;       bf16x8 At[4];
;       At[0] = __builtin_bit_cast(bf16x8, a4); At[1] = __builtin_bit_cast(bf16x8, a5); At[2] = __builtin_bit_cast(bf16x8, a6); At[3] = __builtin_bit_cast(bf16x8, a7);
; #pragma unroll
;       for (int m = 0; m < 4; ++m)
; #pragma unroll
.LBB0_253:
	s_barrier
	s_mul_i32 s40, s39, 0x6000
	v_add_u32_e32 v134, s40, v149
	v_add_u32_e32 v151, s40, v150
	ds_read_b128 v[152:155], v151
	ds_read_b128 v[160:163], v151 offset:1024
	ds_read_b128 v[164:167], v151 offset:2048
	ds_read_b128 v[168:171], v151 offset:3072
	ds_read_b128 v[172:175], v134
	ds_read_b128 v[176:179], v134 offset:1024
	ds_read_b128 v[180:183], v134 offset:2048
	ds_read_b128 v[184:187], v134 offset:3072
	ds_read_b128 v[188:191], v134 offset:4096
	ds_read_b128 v[192:195], v134 offset:5120
	ds_read_b128 v[196:199], v134 offset:6144
	ds_read_b128 v[200:203], v134 offset:7168
	s_cmp_gt_u32 s42, 61
	s_cbranch_scc1 .Lgnodma_g2
	s_cmp_gt_i32 s39, 0
	s_cselect_b32 s40, -1, 2
	s_add_i32 s40, s40, s39
	s_mulk_i32 s40, 0x6000
	v_add_u32_e32 v252, s40, v148
	v_add_u32_e32 v253, 0x1000, v252
	v_readfirstlane_b32 s40, v252
	v_lshl_add_u64 v[250:251], v[130:131], 0, s[0:1]
	s_mov_b32 m0, s40
	v_readfirstlane_b32 s40, v253
	v_add_u32_e32 v253, 0x2000, v252
	global_load_lds_dwordx4 v[250:251], off
	v_lshl_add_u64 v[250:251], v[132:133], 0, s[0:1]
	s_mov_b32 m0, s40
	v_readfirstlane_b32 s40, v253
	v_add_u32_e32 v253, 0x3000, v252
	global_load_lds_dwordx4 v[250:251], off
	v_lshl_add_u64 v[250:251], v[136:137], 0, s[0:1]
	s_mov_b32 m0, s40
	v_readfirstlane_b32 s40, v253
	v_add_u32_e32 v253, 0x4000, v252
	global_load_lds_dwordx4 v[250:251], off
	v_lshl_add_u64 v[250:251], v[138:139], 0, s[0:1]
	s_mov_b32 m0, s40
	v_readfirstlane_b32 s40, v253
	v_add_u32_e32 v252, 0x5000, v252
	global_load_lds_dwordx4 v[250:251], off
	v_lshl_add_u64 v[250:251], v[142:143], 0, s[0:1]
	s_mov_b32 m0, s40
	v_readfirstlane_b32 s40, v252
	global_load_lds_dwordx4 v[250:251], off
	v_lshl_add_u64 v[250:251], v[140:141], 0, s[0:1]
	s_mov_b32 m0, s40
	s_nop 0
	global_load_lds_dwordx4 v[250:251], off
.Lgnodma_g2:
	s_add_i32 s40, s39, 1
	s_cmp_lg_u32 s39, 2
	s_cselect_b32 s39, s40, 0
	s_add_u32 s0, s0, 64
	s_addc_u32 s1, s1, 0
	s_add_i32 s42, s42, 1
	s_waitcnt lgkmcnt(7)
	v_mfma_f32_16x16x32_bf16 v[126:129], v[172:175], v[152:155], v[126:129]
	v_mfma_f32_16x16x32_bf16 v[122:125], v[172:175], v[160:163], v[122:125]
	v_mfma_f32_16x16x32_bf16 v[118:121], v[172:175], v[164:167], v[118:121]
	v_mfma_f32_16x16x32_bf16 v[114:117], v[172:175], v[168:171], v[114:117]
	s_waitcnt lgkmcnt(6)
	v_mfma_f32_16x16x32_bf16 v[110:113], v[176:179], v[152:155], v[110:113]
	v_mfma_f32_16x16x32_bf16 v[106:109], v[176:179], v[160:163], v[106:109]
	v_mfma_f32_16x16x32_bf16 v[102:105], v[176:179], v[164:167], v[102:105]
	v_mfma_f32_16x16x32_bf16 v[98:101], v[176:179], v[168:171], v[98:101]
	s_waitcnt lgkmcnt(5)
	v_mfma_f32_16x16x32_bf16 v[94:97], v[180:183], v[152:155], v[94:97]
	v_mfma_f32_16x16x32_bf16 v[42:45], v[180:183], v[160:163], v[42:45]
	v_mfma_f32_16x16x32_bf16 v[38:41], v[180:183], v[164:167], v[38:41]
	v_mfma_f32_16x16x32_bf16 v[34:37], v[180:183], v[168:171], v[34:37]
	s_waitcnt lgkmcnt(4)
	v_mfma_f32_16x16x32_bf16 v[30:33], v[184:187], v[152:155], v[30:33]
	v_mfma_f32_16x16x32_bf16 v[26:29], v[184:187], v[160:163], v[26:29]
	v_mfma_f32_16x16x32_bf16 v[22:25], v[184:187], v[164:167], v[22:25]
	v_mfma_f32_16x16x32_bf16 v[18:21], v[184:187], v[168:171], v[18:21]
	s_waitcnt lgkmcnt(3)
	v_mfma_f32_16x16x32_bf16 v[14:17], v[188:191], v[152:155], v[14:17]
	v_mfma_f32_16x16x32_bf16 v[10:13], v[188:191], v[160:163], v[10:13]
	v_mfma_f32_16x16x32_bf16 v[6:9], v[188:191], v[164:167], v[6:9]
	v_mfma_f32_16x16x32_bf16 v[2:5], v[188:191], v[168:171], v[2:5]
	s_waitcnt lgkmcnt(2)
	v_mfma_f32_16x16x32_bf16 v[46:49], v[192:195], v[152:155], v[46:49]
	v_mfma_f32_16x16x32_bf16 v[50:53], v[192:195], v[160:163], v[50:53]
	v_mfma_f32_16x16x32_bf16 v[54:57], v[192:195], v[164:167], v[54:57]
	v_mfma_f32_16x16x32_bf16 v[58:61], v[192:195], v[168:171], v[58:61]
	s_waitcnt lgkmcnt(1)
	v_mfma_f32_16x16x32_bf16 v[62:65], v[196:199], v[152:155], v[62:65]
	v_mfma_f32_16x16x32_bf16 v[66:69], v[196:199], v[160:163], v[66:69]
	v_mfma_f32_16x16x32_bf16 v[70:73], v[196:199], v[164:167], v[70:73]
	v_mfma_f32_16x16x32_bf16 v[74:77], v[196:199], v[168:171], v[74:77]
	s_waitcnt lgkmcnt(0)
	v_mfma_f32_16x16x32_bf16 v[78:81], v[200:203], v[152:155], v[78:81]
	v_mfma_f32_16x16x32_bf16 v[82:85], v[200:203], v[160:163], v[82:85]
	v_mfma_f32_16x16x32_bf16 v[86:89], v[200:203], v[164:167], v[86:89]
	v_mfma_f32_16x16x32_bf16 v[90:93], v[200:203], v[168:171], v[90:93]
	s_cmpk_eq_i32 s0, 0x1000
	s_cbranch_scc0 .LBB0_249

; DEV int ltid() { int t = threadIdx.x; asm volatile("" : "+v"(t)); return t; }
; template <class AF, class EPI>
; DEV void gemm_tile256(AF aptr, const u16* Bt, int ldb, int K, EPI epi, char* smem) {
;   const int tid = ltid(), wid = tid >> 6, lane = tid & 63, wr = wid >> 1, wc = wid & 1, fr = lane & 15, fq = lane >> 4;
;   f32x4 acc[8][4];
; #pragma unroll
;   for (int m = 0; m < 8; ++m)
; #pragma unroll
;     for (int n = 0; n < 4; ++n) acc[m][n] = f32x4{0.f, 0.f, 0.f, 0.f};
;   const int nk = K / 32;
;   auto stage = [&](int kt, int buf) {
;     char* SA = smem + buf * 24576;
;     char* SB = SA + 16384;
; #pragma unroll
;     for (int i = 0; i < 4; ++i) {
;       int bo = tid * 16 + i * 4096, r = bo >> 6, c = (bo & 63) >> 1;
;       __builtin_amdgcn_global_load_lds((const unsigned*)aptr(r, kt * 32 + c), (__attribute__((address_space(3))) unsigned*)(SA + bo), 16, 0, 0);
;     }
; #pragma unroll
;     for (int i = 0; i < 2; ++i) {
;       int bo = tid * 16 + i * 4096, r = bo >> 6, c = (bo & 63) >> 1;
;       __builtin_amdgcn_global_load_lds((const unsigned*)(Bt + (size_t)r * ldb + kt * 32 + c), (__attribute__((address_space(3))) unsigned*)(SB + bo), 16, 0, 0);
;     }
;   };
;   asm volatile("s_waitcnt vmcnt(0)" ::: "memory");
;   __syncthreads();
;   stage(0, 0);
;   stage(1, 1);
;   const unsigned lbase = (unsigned)(size_t)(const __attribute__((address_space(3))) char*)smem;
;   const unsigned aoff = lbase + (wr * 128 + fr) * 64 + fq * 16, boff = lbase + 16384 + (wc * 64 + fr) * 64 + fq * 16;
; __global__ void __launch_bounds__(256, 2) fwd_megakernel(Params p) {
;     ...
;   for (int jt = (bid >> 3); jt < 8 * 16; jt += (nb >> 3)) {
;     const int pn = jt >> 3, pm = (bid & 7) * 8 + (jt & 7), b = pm >> 3;
;     const u16* A = p.y + (size_t)pm * 256 * 2048;
;     const float* gt1 = p.mod + (size_t)b * 12288 + 4096 + pn * 128;
;     gemm_tile256([&](int r, int k) { return A + (size_t)r * 2048 + k; }, p.Wt_out + (size_t)pn * 128 * 2048, 2048, 2048,
.LBB0_1241:
	s_and_b32 s6, s3, 7
	s_lshl_b32 s6, s6, 19
	s_and_b32 s7, s24, 7
	s_add_i32 s25, s16, s6
	s_or_b32 s7, s7, s4
	v_mov_b32_e32 v144, v0
	s_lshl_b32 s28, s25, 1
	s_ashr_i32 s6, s24, 3
	s_lshl_b32 s7, s7, 20
	s_mov_b64 s[26:27], s[54:55]
	s_add_u32 s10, s26, s7
	v_ashrrev_i32_e32 v2, 2, v144
	v_lshlrev_b32_e32 v148, 4, v144
	v_ashrrev_i32_e32 v3, 31, v2
	s_addc_u32 s11, s27, 0
	s_ashr_i32 s7, s6, 31
	v_lshlrev_b64 v[2:3], 12, v[2:3]
	v_add_u32_e32 v10, 0x1000, v148
	s_lshl_b64 s[8:9], s[6:7], 19
	v_lshl_add_u64 v[4:5], s[10:11], 0, v[2:3]
	v_and_b32_e32 v134, 48, v148
	v_readfirstlane_b32 s7, v148
	v_ashrrev_i32_e32 v6, 6, v10
	v_add_u32_e32 v14, 0x2000, v148
	v_lshl_add_u64 v[4:5], v[4:5], 0, v[134:135]
	s_mov_b32 m0, s7
	v_ashrrev_i32_e32 v7, 31, v6
	v_readfirstlane_b32 s7, v10
	v_ashrrev_i32_e32 v10, 6, v14
	v_add_u32_e32 v18, 0x3000, v148
	v_readlane_b32 s36, v254, 4
	s_waitcnt vmcnt(0)
	s_barrier
; template <class AF, class EPI>
; DEV void gemm_tile256(AF aptr, const u16* Bt, int ldb, int K, EPI epi, char* smem) {
;     ...
;   f32x4 acc[8][4];
; #pragma unroll
;   for (int m = 0; m < 8; ++m)
; #pragma unroll
;     for (int n = 0; n < 4; ++n) acc[m][n] = f32x4{0.f, 0.f, 0.f, 0.f};
;   const int nk = K / 32;
;   auto stage = [&](int kt, int buf) {
;     char* SA = smem + buf * 24576;
;     char* SB = SA + 16384;
; #pragma unroll
;     for (int i = 0; i < 4; ++i) {
;       int bo = tid * 16 + i * 4096, r = bo >> 6, c = (bo & 63) >> 1;
;       __builtin_amdgcn_global_load_lds((const unsigned*)aptr(r, kt * 32 + c), (__attribute__((address_space(3))) unsigned*)(SA + bo), 16, 0, 0);
;     }
; #pragma unroll
;     for (int i = 0; i < 2; ++i) {
;       int bo = tid * 16 + i * 4096, r = bo >> 6, c = (bo & 63) >> 1;
;       __builtin_amdgcn_global_load_lds((const unsigned*)(Bt + (size_t)r * ldb + kt * 32 + c), (__attribute__((address_space(3))) unsigned*)(SB + bo), 16, 0, 0);
;     }
;   };
;   asm volatile("s_waitcnt vmcnt(0)" ::: "memory");
;   __syncthreads();
;   stage(0, 0);
;   stage(1, 1);
;   const unsigned lbase = (unsigned)(size_t)(const __attribute__((address_space(3))) char*)smem;
;   const unsigned aoff = lbase + (wr * 128 + fr) * 64 + fq * 16, boff = lbase + 16384 + (wc * 64 + fr) * 64 + fq * 16;
;   int buf = 0;
; #pragma unroll 1
;   for (int t = 0; t < nk; ++t) {
;     if (t + 1 < nk) asm volatile("s_waitcnt vmcnt(6)" ::: "memory");
;     else asm volatile("s_waitcnt vmcnt(0)" ::: "memory");
	global_load_lds_dwordx4 v[4:5], off
	v_lshlrev_b64 v[6:7], 12, v[6:7]
	s_mov_b32 m0, s7
	v_ashrrev_i32_e32 v11, 31, v10
	v_readfirstlane_b32 s7, v14
	v_ashrrev_i32_e32 v14, 6, v18
	v_readlane_b32 s48, v254, 16
	v_lshl_add_u64 v[8:9], s[10:11], 0, v[6:7]
	v_lshlrev_b64 v[10:11], 12, v[10:11]
	v_ashrrev_i32_e32 v15, 31, v14
	v_readlane_b32 s49, v254, 17
	s_add_u32 s26, s48, s8
	v_lshl_add_u64 v[8:9], v[8:9], 0, v[134:135]
	v_lshl_add_u64 v[12:13], s[10:11], 0, v[10:11]
	v_lshlrev_b64 v[14:15], 12, v[14:15]
	s_addc_u32 s27, s49, s9
	global_load_lds_dwordx4 v[8:9], off
	v_lshl_add_u64 v[12:13], v[12:13], 0, v[134:135]
	s_mov_b32 m0, s7
	v_lshl_add_u64 v[16:17], s[10:11], 0, v[14:15]
	v_readfirstlane_b32 s7, v18
	v_add_u32_e32 v20, 0x4000, v148
	global_load_lds_dwordx4 v[12:13], off
	v_lshl_add_u64 v[16:17], v[16:17], 0, v[134:135]
	s_mov_b32 m0, s7
	v_lshl_add_u64 v[18:19], s[26:27], 0, v[2:3]
	v_readfirstlane_b32 s7, v20
	v_add_u32_e32 v22, 0x5000, v148
	global_load_lds_dwordx4 v[16:17], off
	v_lshl_add_u64 v[18:19], v[18:19], 0, v[134:135]
	s_mov_b32 m0, s7
	v_lshl_add_u64 v[20:21], s[26:27], 0, v[6:7]
	v_readfirstlane_b32 s7, v22
	v_add_u32_e32 v22, 0x6000, v148
	global_load_lds_dwordx4 v[18:19], off
	v_lshl_add_u64 v[20:21], v[20:21], 0, v[134:135]
	s_mov_b32 m0, s7
	v_readfirstlane_b32 s7, v22
	global_load_lds_dwordx4 v[20:21], off
	v_lshl_add_u64 v[4:5], v[4:5], 0, 64
	s_mov_b32 m0, s7
	s_add_u32 s10, s14, s28
	global_load_lds_dwordx4 v[4:5], off
	v_lshl_add_u64 v[4:5], v[8:9], 0, 64
	v_add_u32_e32 v8, 0x7000, v148
	v_bfe_u32 v147, v144, 4, 2
	v_readfirstlane_b32 s7, v8
	v_add_u32_e32 v8, 0x8000, v148
	s_mov_b32 m0, s7
	v_readfirstlane_b32 s7, v8
	v_add_u32_e32 v8, 0x9000, v148
	global_load_lds_dwordx4 v[4:5], off
	v_lshl_add_u64 v[4:5], v[12:13], 0, 64
	s_mov_b32 m0, s7
	v_readfirstlane_b32 s7, v8
	v_add_u32_e32 v8, 0xa000, v148
	global_load_lds_dwordx4 v[4:5], off
	v_lshl_add_u64 v[4:5], v[16:17], 0, 64
	s_mov_b32 m0, s7
	v_readfirstlane_b32 s7, v8
	v_add_u32_e32 v8, 0xb000, v148
	global_load_lds_dwordx4 v[4:5], off
	v_lshl_add_u64 v[4:5], v[18:19], 0, 64
	s_mov_b32 m0, s7
	v_readfirstlane_b32 s7, v8
	global_load_lds_dwordx4 v[4:5], off
	v_lshl_add_u64 v[4:5], v[20:21], 0, 64
	s_mov_b32 m0, s7
	s_addc_u32 s11, s15, 0
	global_load_lds_dwordx4 v[4:5], off
	v_bfe_u32 v145, v144, 6, 1
	v_ashrrev_i32_e32 v1, 7, v144
	v_and_b32_e32 v146, 15, v144
	v_lshlrev_b32_e32 v8, 4, v147
	s_add_u32 s8, s17, s8
	v_lshlrev_b32_e32 v4, 13, v1
	v_lshlrev_b32_e32 v5, 6, v146
	v_lshl_or_b32 v9, v145, 12, v8
	v_or_b32_e32 v2, v2, v134
	v_or_b32_e32 v6, v6, v134
	v_or_b32_e32 v10, v10, v134
	v_or_b32_e32 v14, v14, v134
	s_addc_u32 s9, s18, s9
	v_or3_b32 v149, v4, v8, v5
	v_or3_b32 v150, v5, v9, s19
	v_lshl_add_u64 v[130:131], s[10:11], 0, v[2:3]
	v_lshl_add_u64 v[132:133], s[10:11], 0, v[6:7]
	v_lshl_add_u64 v[136:137], s[10:11], 0, v[10:11]
	v_lshl_add_u64 v[138:139], s[10:11], 0, v[14:15]
	v_lshl_add_u64 v[140:141], s[8:9], 0, v[6:7]
	v_lshl_add_u64 v[142:143], s[8:9], 0, v[2:3]
	s_mov_b64 s[8:9], 0
	s_mov_b32 s7, 0
	s_mov_b32 s26, 0
	v_mov_b32_e32 v2, 0
	v_mov_b32_e32 v3, v135
	v_mov_b32_e32 v4, v135
	v_mov_b32_e32 v5, v135
	v_mov_b32_e32 v6, 0
	v_mov_b32_e32 v7, v135
	v_mov_b32_e32 v8, v135
	v_mov_b32_e32 v9, v135
	v_mov_b32_e32 v10, 0
	v_mov_b32_e32 v11, v135
	v_mov_b32_e32 v12, v135
	v_mov_b32_e32 v13, v135
	v_mov_b32_e32 v14, 0
	v_mov_b32_e32 v15, v135
	v_mov_b32_e32 v16, v135
	v_mov_b32_e32 v17, v135
	v_mov_b32_e32 v18, 0
	v_mov_b32_e32 v19, v135
	v_mov_b32_e32 v20, v135
	v_mov_b32_e32 v21, v135
	v_mov_b32_e32 v22, 0
	v_mov_b32_e32 v23, v135
	v_mov_b32_e32 v24, v135
	v_mov_b32_e32 v25, v135
	v_mov_b32_e32 v26, 0
	v_mov_b32_e32 v27, v135
	v_mov_b32_e32 v28, v135
	v_mov_b32_e32 v29, v135
	v_mov_b32_e32 v30, 0
	v_mov_b32_e32 v31, v135
	v_mov_b32_e32 v32, v135
	v_mov_b32_e32 v33, v135
	v_mov_b32_e32 v34, 0
	v_mov_b32_e32 v35, v135
	v_mov_b32_e32 v36, v135
	v_mov_b32_e32 v37, v135
	v_mov_b32_e32 v38, 0
	v_mov_b32_e32 v39, v135
	v_mov_b32_e32 v40, v135
	v_mov_b32_e32 v41, v135
	v_mov_b32_e32 v42, 0
	v_mov_b32_e32 v43, v135
	v_mov_b32_e32 v44, v135
	v_mov_b32_e32 v45, v135
	v_mov_b32_e32 v94, 0
	v_mov_b32_e32 v95, v135
	v_mov_b32_e32 v96, v135
	v_mov_b32_e32 v97, v135
	v_mov_b32_e32 v98, 0
	v_mov_b32_e32 v99, v135
	v_mov_b32_e32 v100, v135
	v_mov_b32_e32 v101, v135
	v_mov_b32_e32 v102, 0
	v_mov_b32_e32 v103, v135
	v_mov_b32_e32 v104, v135
	v_mov_b32_e32 v105, v135
	v_mov_b32_e32 v106, 0
	v_mov_b32_e32 v107, v135
	v_mov_b32_e32 v108, v135
	v_mov_b32_e32 v109, v135
	v_mov_b32_e32 v110, 0
	v_mov_b32_e32 v111, v135
	v_mov_b32_e32 v112, v135
	v_mov_b32_e32 v113, v135
	v_mov_b32_e32 v114, 0
	v_mov_b32_e32 v115, v135
	v_mov_b32_e32 v116, v135
	v_mov_b32_e32 v117, v135
	v_mov_b32_e32 v118, 0
	v_mov_b32_e32 v119, v135
	v_mov_b32_e32 v120, v135
	v_mov_b32_e32 v121, v135
	v_mov_b32_e32 v122, 0
	v_mov_b32_e32 v123, v135
	v_mov_b32_e32 v124, v135
	v_mov_b32_e32 v125, v135
	v_mov_b32_e32 v126, 0
	v_mov_b32_e32 v127, v135
	v_mov_b32_e32 v128, v135
	v_mov_b32_e32 v129, v135
	v_mov_b32_e32 v46, 0
	v_mov_b32_e32 v47, v135
	v_mov_b32_e32 v48, v135
	v_mov_b32_e32 v49, v135
	v_mov_b32_e32 v50, 0
	v_mov_b32_e32 v51, v135
	v_mov_b32_e32 v52, v135
	v_mov_b32_e32 v53, v135
	v_mov_b32_e32 v54, 0
	v_mov_b32_e32 v55, v135
	v_mov_b32_e32 v56, v135
	v_mov_b32_e32 v57, v135
	v_mov_b32_e32 v58, 0
	v_mov_b32_e32 v59, v135
	v_mov_b32_e32 v60, v135
	v_mov_b32_e32 v61, v135
	v_mov_b32_e32 v62, 0
	v_mov_b32_e32 v63, v135
	v_mov_b32_e32 v64, v135
	v_mov_b32_e32 v65, v135
	v_mov_b32_e32 v66, 0
	v_mov_b32_e32 v67, v135
	v_mov_b32_e32 v68, v135
	v_mov_b32_e32 v69, v135
	v_mov_b32_e32 v70, 0
	v_mov_b32_e32 v71, v135
	v_mov_b32_e32 v72, v135
	v_mov_b32_e32 v73, v135
	v_mov_b32_e32 v74, 0
	v_mov_b32_e32 v75, v135
	v_mov_b32_e32 v76, v135
	v_mov_b32_e32 v77, v135
	v_mov_b32_e32 v78, 0
	v_mov_b32_e32 v79, v135
	v_mov_b32_e32 v80, v135
	v_mov_b32_e32 v81, v135
	v_mov_b32_e32 v82, 0
	v_mov_b32_e32 v83, v135
	v_mov_b32_e32 v84, v135
	v_mov_b32_e32 v85, v135
	v_mov_b32_e32 v86, 0
	v_mov_b32_e32 v87, v135
	v_mov_b32_e32 v88, v135
	v_mov_b32_e32 v89, v135
	v_mov_b32_e32 v90, 0
	v_mov_b32_e32 v91, v135
	v_mov_b32_e32 v92, v135
	v_mov_b32_e32 v93, v135
	v_readlane_b32 s37, v254, 5
	v_readlane_b32 s38, v254, 6
	v_readlane_b32 s39, v254, 7
	v_readlane_b32 s40, v254, 8
	v_readlane_b32 s41, v254, 9
	v_readlane_b32 s42, v254, 10
	v_readlane_b32 s43, v254, 11
	v_readlane_b32 s44, v254, 12
	v_readlane_b32 s45, v254, 13
	v_readlane_b32 s46, v254, 14
	v_readlane_b32 s47, v254, 15
	v_readlane_b32 s50, v254, 18
	v_readlane_b32 s51, v254, 19
	s_branch .LBB0_1243
.LBB0_1243:
	s_cmpk_eq_i32 s8, 0xfc0
	s_mov_b64 s[10:11], -1
	s_cbranch_scc1 .LBB0_1245
	s_waitcnt vmcnt(6)
	s_mov_b64 s[10:11], 0

; template <class AF, class EPI>
; DEV void gemm_tile256(AF aptr, const u16* Bt, int ldb, int K, EPI epi, char* smem) {
;     ...
;     __builtin_amdgcn_s_barrier();
;     if (t + 2 < nk) { int nb2 = buf + 2; if (nb2 >= 3) nb2 -= 3; stage(t + 2, nb2); }
;     const unsigned sa = aoff + buf * 24576, sb = boff + buf * 24576;
;     u32x4 a0, a1, a2, a3, a4, a5, a6, a7, b0, b1, b2, b3;
;     asm volatile("ds_read_b128 %0, %1" : "=v"(b0) : "v"(sb));
;     asm volatile("ds_read_b128 %0, %1 offset:1024" : "=v"(b1) : "v"(sb));
;     asm volatile("ds_read_b128 %0, %1 offset:2048" : "=v"(b2) : "v"(sb));
;     asm volatile("ds_read_b128 %0, %1 offset:3072" : "=v"(b3) : "v"(sb));
;     asm volatile("ds_read_b128 %0, %1" : "=v"(a0) : "v"(sa));
;     asm volatile("ds_read_b128 %0, %1 offset:1024" : "=v"(a1) : "v"(sa));
;     asm volatile("ds_read_b128 %0, %1 offset:2048" : "=v"(a2) : "v"(sa));
;     asm volatile("ds_read_b128 %0, %1 offset:3072" : "=v"(a3) : "v"(sa));
;     asm volatile("ds_read_b128 %0, %1 offset:4096" : "=v"(a4) : "v"(sa));
;     asm volatile("ds_read_b128 %0, %1 offset:5120" : "=v"(a5) : "v"(sa));
;     asm volatile("ds_read_b128 %0, %1 offset:6144" : "=v"(a6) : "v"(sa));
;     asm volatile("ds_read_b128 %0, %1 offset:7168" : "=v"(a7) : "v"(sa));
;     asm volatile("s_waitcnt lgkmcnt(4)" : "+v"(a0), "+v"(a1), "+v"(a2), "+v"(a3), "+v"(b0), "+v"(b1), "+v"(b2), "+v"(b3));
;     bf16x8 Bv[4];
;     Bv[0] = __builtin_bit_cast(bf16x8, b0); Bv[1] = __builtin_bit_cast(bf16x8, b1); Bv[2] = __builtin_bit_cast(bf16x8, b2); Bv[3] = __builtin_bit_cast(bf16x8, b3);
;     {
;       bf16x8 At[4];
;       At[0] = __builtin_bit_cast(bf16x8, a0); At[1] = __builtin_bit_cast(bf16x8, a1); At[2] = __builtin_bit_cast(bf16x8, a2); At[3] = __builtin_bit_cast(bf16x8, a3);
; #pragma unroll
;       for (int m = 0; m < 4; ++m)
; #pragma unroll
;         for (int n = 0; n < 4; ++n) acc[m][n] = __builtin_amdgcn_mfma_f32_16x16x32_bf16(At[m], Bv[n], acc[m][n], 0, 0, 0);
;     }
;     asm volatile("s_waitcnt lgkmcnt(0)" : "+v"(a4), "+v"(a5), "+v"(a6), "+v"(a7));
;     {
;       bf16x8 At[4];
;       At[0] = __builtin_bit_cast(bf16x8, a4); At[1] = __builtin_bit_cast(bf16x8, a5); At[2] = __builtin_bit_cast(bf16x8, a6); At[3] = __builtin_bit_cast(bf16x8, a7);
; #pragma unroll
;       for (int m = 0; m < 4; ++m)
; #pragma unroll
.LBB0_1247:
	s_barrier
	s_mul_i32 s10, s7, 0x6000
	v_add_u32_e32 v134, s10, v149
	v_add_u32_e32 v151, s10, v150
	ds_read_b128 v[152:155], v151
	ds_read_b128 v[156:159], v151 offset:1024
	ds_read_b128 v[160:163], v151 offset:2048
	ds_read_b128 v[164:167], v151 offset:3072
	ds_read_b128 v[168:171], v134
	ds_read_b128 v[172:175], v134 offset:1024
	ds_read_b128 v[176:179], v134 offset:2048
	ds_read_b128 v[180:183], v134 offset:3072
	ds_read_b128 v[184:187], v134 offset:4096
	ds_read_b128 v[188:191], v134 offset:5120
	ds_read_b128 v[192:195], v134 offset:6144
	ds_read_b128 v[196:199], v134 offset:7168
	s_cmp_gt_u32 s26, 61
	s_cbranch_scc1 .Lgnodma_g1
	s_cmp_gt_i32 s7, 0
	s_cselect_b32 s10, -1, 2
	s_add_i32 s10, s10, s7
	s_mulk_i32 s10, 0x6000
	v_add_u32_e32 v252, s10, v148
	v_add_u32_e32 v253, 0x1000, v252
	v_readfirstlane_b32 s10, v252
	v_lshl_add_u64 v[250:251], v[130:131], 0, s[8:9]
	s_mov_b32 m0, s10
	v_readfirstlane_b32 s10, v253
	v_add_u32_e32 v253, 0x2000, v252
	global_load_lds_dwordx4 v[250:251], off
	v_lshl_add_u64 v[250:251], v[132:133], 0, s[8:9]
	s_mov_b32 m0, s10
	v_readfirstlane_b32 s10, v253
	v_add_u32_e32 v253, 0x3000, v252
	global_load_lds_dwordx4 v[250:251], off
	v_lshl_add_u64 v[250:251], v[136:137], 0, s[8:9]
	s_mov_b32 m0, s10
	v_readfirstlane_b32 s10, v253
	v_add_u32_e32 v253, 0x4000, v252
	global_load_lds_dwordx4 v[250:251], off
	v_lshl_add_u64 v[250:251], v[138:139], 0, s[8:9]
	s_mov_b32 m0, s10
	v_readfirstlane_b32 s10, v253
	v_add_u32_e32 v252, 0x5000, v252
	global_load_lds_dwordx4 v[250:251], off
	v_lshl_add_u64 v[250:251], v[142:143], 0, s[8:9]
	s_mov_b32 m0, s10
	v_readfirstlane_b32 s10, v252
	global_load_lds_dwordx4 v[250:251], off
	v_lshl_add_u64 v[250:251], v[140:141], 0, s[8:9]
	s_mov_b32 m0, s10
	s_nop 0
	global_load_lds_dwordx4 v[250:251], off
.Lgnodma_g1:
	s_add_i32 s10, s7, 1
	s_cmp_lg_u32 s7, 2
	s_cselect_b32 s7, s10, 0
	s_add_u32 s8, s8, 64
	s_addc_u32 s9, s9, 0
	s_add_i32 s26, s26, 1
	s_waitcnt lgkmcnt(7)
	v_mfma_f32_16x16x32_bf16 v[126:129], v[168:171], v[152:155], v[126:129]
	v_mfma_f32_16x16x32_bf16 v[122:125], v[168:171], v[156:159], v[122:125]
	v_mfma_f32_16x16x32_bf16 v[118:121], v[168:171], v[160:163], v[118:121]
	v_mfma_f32_16x16x32_bf16 v[114:117], v[168:171], v[164:167], v[114:117]
	s_waitcnt lgkmcnt(6)
	v_mfma_f32_16x16x32_bf16 v[110:113], v[172:175], v[152:155], v[110:113]
	v_mfma_f32_16x16x32_bf16 v[106:109], v[172:175], v[156:159], v[106:109]
	v_mfma_f32_16x16x32_bf16 v[102:105], v[172:175], v[160:163], v[102:105]
	v_mfma_f32_16x16x32_bf16 v[98:101], v[172:175], v[164:167], v[98:101]
	s_waitcnt lgkmcnt(5)
	v_mfma_f32_16x16x32_bf16 v[94:97], v[176:179], v[152:155], v[94:97]
	v_mfma_f32_16x16x32_bf16 v[42:45], v[176:179], v[156:159], v[42:45]
	v_mfma_f32_16x16x32_bf16 v[38:41], v[176:179], v[160:163], v[38:41]
	v_mfma_f32_16x16x32_bf16 v[34:37], v[176:179], v[164:167], v[34:37]
	s_waitcnt lgkmcnt(4)
	v_mfma_f32_16x16x32_bf16 v[30:33], v[180:183], v[152:155], v[30:33]
	v_mfma_f32_16x16x32_bf16 v[26:29], v[180:183], v[156:159], v[26:29]
	v_mfma_f32_16x16x32_bf16 v[22:25], v[180:183], v[160:163], v[22:25]
	v_mfma_f32_16x16x32_bf16 v[18:21], v[180:183], v[164:167], v[18:21]
	s_waitcnt lgkmcnt(3)
	v_mfma_f32_16x16x32_bf16 v[14:17], v[184:187], v[152:155], v[14:17]
	v_mfma_f32_16x16x32_bf16 v[10:13], v[184:187], v[156:159], v[10:13]
	v_mfma_f32_16x16x32_bf16 v[6:9], v[184:187], v[160:163], v[6:9]
	v_mfma_f32_16x16x32_bf16 v[2:5], v[184:187], v[164:167], v[2:5]
	s_waitcnt lgkmcnt(2)
	v_mfma_f32_16x16x32_bf16 v[46:49], v[188:191], v[152:155], v[46:49]
	v_mfma_f32_16x16x32_bf16 v[50:53], v[188:191], v[156:159], v[50:53]
	v_mfma_f32_16x16x32_bf16 v[54:57], v[188:191], v[160:163], v[54:57]
	v_mfma_f32_16x16x32_bf16 v[58:61], v[188:191], v[164:167], v[58:61]
	s_waitcnt lgkmcnt(1)
	v_mfma_f32_16x16x32_bf16 v[62:65], v[192:195], v[152:155], v[62:65]
	v_mfma_f32_16x16x32_bf16 v[66:69], v[192:195], v[156:159], v[66:69]
	v_mfma_f32_16x16x32_bf16 v[70:73], v[192:195], v[160:163], v[70:73]
	v_mfma_f32_16x16x32_bf16 v[74:77], v[192:195], v[164:167], v[74:77]
	s_waitcnt lgkmcnt(0)
	v_mfma_f32_16x16x32_bf16 v[78:81], v[196:199], v[152:155], v[78:81]
	v_mfma_f32_16x16x32_bf16 v[82:85], v[196:199], v[156:159], v[82:85]
	v_mfma_f32_16x16x32_bf16 v[86:89], v[196:199], v[160:163], v[86:89]
	v_mfma_f32_16x16x32_bf16 v[90:93], v[196:199], v[164:167], v[90:93]
	s_cmpk_eq_i32 s8, 0x1000
	s_cbranch_scc0 .LBB0_1243

; DEV int ltid() { int t = threadIdx.x; asm volatile("" : "+v"(t)); return t; }
; template <class AF, class EPI>
; DEV void gemm_tile256(AF aptr, const u16* Bt, int ldb, int K, EPI epi, char* smem) {
;   const int tid = ltid(), wid = tid >> 6, lane = tid & 63, wr = wid >> 1, wc = wid & 1, fr = lane & 15, fq = lane >> 4;
;   f32x4 acc[8][4];
; #pragma unroll
;   for (int m = 0; m < 8; ++m)
; #pragma unroll
;     for (int n = 0; n < 4; ++n) acc[m][n] = f32x4{0.f, 0.f, 0.f, 0.f};
;   const int nk = K / 32;
;   auto stage = [&](int kt, int buf) {
;     char* SA = smem + buf * 24576;
;     char* SB = SA + 16384;
; #pragma unroll
;     for (int i = 0; i < 4; ++i) {
;       int bo = tid * 16 + i * 4096, r = bo >> 6, c = (bo & 63) >> 1;
;       __builtin_amdgcn_global_load_lds((const unsigned*)aptr(r, kt * 32 + c), (__attribute__((address_space(3))) unsigned*)(SA + bo), 16, 0, 0);
;     }
; #pragma unroll
;     for (int i = 0; i < 2; ++i) {
;       int bo = tid * 16 + i * 4096, r = bo >> 6, c = (bo & 63) >> 1;
;       __builtin_amdgcn_global_load_lds((const unsigned*)(Bt + (size_t)r * ldb + kt * 32 + c), (__attribute__((address_space(3))) unsigned*)(SB + bo), 16, 0, 0);
;     }
;   };
;   asm volatile("s_waitcnt vmcnt(0)" ::: "memory");
;   __syncthreads();
;   stage(0, 0);
;   stage(1, 1);
;   const unsigned lbase = (unsigned)(size_t)(const __attribute__((address_space(3))) char*)smem;
;   const unsigned aoff = lbase + (wr * 128 + fr) * 64 + fq * 16, boff = lbase + 16384 + (wc * 64 + fr) * 64 + fq * 16;
;   int buf = 0;
; #pragma unroll 1
;   for (int t = 0; t < nk; ++t) {
;     if (t + 1 < nk) asm volatile("s_waitcnt vmcnt(6)" ::: "memory");
;     else asm volatile("s_waitcnt vmcnt(0)" ::: "memory");
; __global__ void __launch_bounds__(256, 2) fwd_megakernel(Params p) {
;     ...
;   for (int jt = (bid >> 3); jt < 8 * 16; jt += (nb >> 3)) {
;     const int pn = jt >> 3, pm = (bid & 7) * 8 + (jt & 7);
;     const u16* A = p.h + (size_t)pm * 256 * 2048;
;     gemm_tile256([&](int r, int k) { return A + (size_t)r * 2048 + k; }, p.Wt_q + (size_t)pn * 128 * 2048, 2048, 2048,
.LBB0_1367:
	s_and_b32 s25, s2, 7
	s_lshl_b32 s0, s25, 19
	s_and_b32 s1, s58, 7
	s_add_i32 s0, s11, s0
	s_or_b32 s1, s1, s3
	v_mov_b32_e32 v144, v0
	s_lshl_b32 s28, s0, 1
	s_ashr_i32 s0, s58, 3
	s_lshl_b32 s1, s1, 20
	s_mov_b64 s[8:9], s[80:81]
	s_add_u32 s8, s8, s1
	v_ashrrev_i32_e32 v2, 2, v144
	v_lshlrev_b32_e32 v148, 4, v144
	v_ashrrev_i32_e32 v3, 31, v2
	s_addc_u32 s9, s9, 0
	s_ashr_i32 s1, s0, 31
	v_lshlrev_b64 v[2:3], 12, v[2:3]
	v_add_u32_e32 v10, 0x1000, v148
	s_lshl_b64 s[6:7], s[0:1], 19
	v_lshl_add_u64 v[4:5], s[8:9], 0, v[2:3]
	v_and_b32_e32 v130, 48, v148
	v_readfirstlane_b32 s1, v148
	v_ashrrev_i32_e32 v6, 6, v10
	v_add_u32_e32 v14, 0x2000, v148
	v_lshl_add_u64 v[4:5], v[4:5], 0, v[130:131]
	s_mov_b32 m0, s1
	v_ashrrev_i32_e32 v7, 31, v6
	v_readfirstlane_b32 s1, v10
	v_ashrrev_i32_e32 v10, 6, v14
	v_add_u32_e32 v18, 0x3000, v148
	s_waitcnt vmcnt(0)
	s_barrier
	global_load_lds_dwordx4 v[4:5], off
	v_lshlrev_b64 v[6:7], 12, v[6:7]
	s_mov_b32 m0, s1
	v_ashrrev_i32_e32 v11, 31, v10
	v_readfirstlane_b32 s1, v14
	v_ashrrev_i32_e32 v14, 6, v18
	v_lshl_add_u64 v[8:9], s[8:9], 0, v[6:7]
	v_lshlrev_b64 v[10:11], 12, v[10:11]
	v_ashrrev_i32_e32 v15, 31, v14
	s_add_u32 s26, s50, s6
	v_lshl_add_u64 v[8:9], v[8:9], 0, v[130:131]
	v_lshl_add_u64 v[12:13], s[8:9], 0, v[10:11]
	v_lshlrev_b64 v[14:15], 12, v[14:15]
	s_addc_u32 s27, s51, s7
	global_load_lds_dwordx4 v[8:9], off
	v_lshl_add_u64 v[12:13], v[12:13], 0, v[130:131]
	s_mov_b32 m0, s1
	v_lshl_add_u64 v[16:17], s[8:9], 0, v[14:15]
	v_readfirstlane_b32 s1, v18
	v_add_u32_e32 v20, 0x4000, v148
	global_load_lds_dwordx4 v[12:13], off
	v_lshl_add_u64 v[16:17], v[16:17], 0, v[130:131]
	s_mov_b32 m0, s1
	v_lshl_add_u64 v[18:19], s[26:27], 0, v[2:3]
	v_readfirstlane_b32 s1, v20
	v_add_u32_e32 v22, 0x5000, v148
	global_load_lds_dwordx4 v[16:17], off
	v_lshl_add_u64 v[18:19], v[18:19], 0, v[130:131]
	s_mov_b32 m0, s1
	v_lshl_add_u64 v[20:21], s[26:27], 0, v[6:7]
	v_readfirstlane_b32 s1, v22
	v_add_u32_e32 v22, 0x6000, v148
	global_load_lds_dwordx4 v[18:19], off
	v_lshl_add_u64 v[20:21], v[20:21], 0, v[130:131]
	s_mov_b32 m0, s1
	v_readfirstlane_b32 s1, v22
	global_load_lds_dwordx4 v[20:21], off
	v_lshl_add_u64 v[4:5], v[4:5], 0, 64
	s_mov_b32 m0, s1
	s_add_u32 s8, s5, s28
	global_load_lds_dwordx4 v[4:5], off
	v_lshl_add_u64 v[4:5], v[8:9], 0, 64
	v_add_u32_e32 v8, 0x7000, v148
	v_bfe_u32 v147, v144, 4, 2
	v_readfirstlane_b32 s1, v8
	v_add_u32_e32 v8, 0x8000, v148
	s_mov_b32 m0, s1
	v_readfirstlane_b32 s1, v8
	v_add_u32_e32 v8, 0x9000, v148
	global_load_lds_dwordx4 v[4:5], off
	v_lshl_add_u64 v[4:5], v[12:13], 0, 64
	s_mov_b32 m0, s1
	v_readfirstlane_b32 s1, v8
	v_add_u32_e32 v8, 0xa000, v148
	global_load_lds_dwordx4 v[4:5], off
	v_lshl_add_u64 v[4:5], v[16:17], 0, 64
	s_mov_b32 m0, s1
	v_readfirstlane_b32 s1, v8
	v_add_u32_e32 v8, 0xb000, v148
	global_load_lds_dwordx4 v[4:5], off
	v_lshl_add_u64 v[4:5], v[18:19], 0, 64
	s_mov_b32 m0, s1
	v_readfirstlane_b32 s1, v8
	global_load_lds_dwordx4 v[4:5], off
	v_lshl_add_u64 v[4:5], v[20:21], 0, 64
	s_mov_b32 m0, s1
	s_addc_u32 s9, s10, 0
	global_load_lds_dwordx4 v[4:5], off
	v_bfe_u32 v145, v144, 6, 1
	v_ashrrev_i32_e32 v1, 7, v144
	v_and_b32_e32 v146, 15, v144
	v_lshlrev_b32_e32 v8, 4, v147
	s_add_u32 s6, s12, s6
	v_lshlrev_b32_e32 v4, 13, v1
	v_lshlrev_b32_e32 v5, 6, v146
	v_lshl_or_b32 v9, v145, 12, v8
	v_or_b32_e32 v2, v2, v130
	v_or_b32_e32 v6, v6, v130
	v_or_b32_e32 v10, v10, v130
	v_or_b32_e32 v14, v14, v130
	s_addc_u32 s7, s13, s7
	v_or3_b32 v149, v4, v8, v5
	v_or3_b32 v150, v5, v9, s15
	v_lshl_add_u64 v[132:133], s[8:9], 0, v[2:3]
	v_lshl_add_u64 v[134:135], s[8:9], 0, v[6:7]
	v_lshl_add_u64 v[136:137], s[8:9], 0, v[10:11]
	v_lshl_add_u64 v[138:139], s[8:9], 0, v[14:15]
	v_lshl_add_u64 v[140:141], s[6:7], 0, v[6:7]
	v_lshl_add_u64 v[142:143], s[6:7], 0, v[2:3]
	s_mov_b64 s[6:7], 0
	s_mov_b32 s1, 0
	s_mov_b32 s26, 0
	v_mov_b32_e32 v2, 0
	v_mov_b32_e32 v3, v131
	v_mov_b32_e32 v4, v131
	v_mov_b32_e32 v5, v131
	v_mov_b32_e32 v6, 0
	v_mov_b32_e32 v7, v131
	v_mov_b32_e32 v8, v131
	v_mov_b32_e32 v9, v131
	v_mov_b32_e32 v10, 0
	v_mov_b32_e32 v11, v131
	v_mov_b32_e32 v12, v131
	v_mov_b32_e32 v13, v131
	v_mov_b32_e32 v14, 0
	v_mov_b32_e32 v15, v131
	v_mov_b32_e32 v16, v131
	v_mov_b32_e32 v17, v131
	v_mov_b32_e32 v18, 0
	v_mov_b32_e32 v19, v131
	v_mov_b32_e32 v20, v131
	v_mov_b32_e32 v21, v131
	v_mov_b32_e32 v22, 0
	v_mov_b32_e32 v23, v131
	v_mov_b32_e32 v24, v131
	v_mov_b32_e32 v25, v131
	v_mov_b32_e32 v26, 0
	v_mov_b32_e32 v27, v131
	v_mov_b32_e32 v28, v131
	v_mov_b32_e32 v29, v131
	v_mov_b32_e32 v30, 0
	v_mov_b32_e32 v31, v131
	v_mov_b32_e32 v32, v131
	v_mov_b32_e32 v33, v131
	v_mov_b32_e32 v34, 0
	v_mov_b32_e32 v35, v131
	v_mov_b32_e32 v36, v131
	v_mov_b32_e32 v37, v131
	v_mov_b32_e32 v38, 0
	v_mov_b32_e32 v39, v131
	v_mov_b32_e32 v40, v131
	v_mov_b32_e32 v41, v131
	v_mov_b32_e32 v42, 0
	v_mov_b32_e32 v43, v131
	v_mov_b32_e32 v44, v131
	v_mov_b32_e32 v45, v131
	v_mov_b32_e32 v94, 0
	v_mov_b32_e32 v95, v131
	v_mov_b32_e32 v96, v131
	v_mov_b32_e32 v97, v131
	v_mov_b32_e32 v98, 0
	v_mov_b32_e32 v99, v131
	v_mov_b32_e32 v100, v131
	v_mov_b32_e32 v101, v131
	v_mov_b32_e32 v102, 0
	v_mov_b32_e32 v103, v131
	v_mov_b32_e32 v104, v131
	v_mov_b32_e32 v105, v131
	v_mov_b32_e32 v106, 0
	v_mov_b32_e32 v107, v131
	v_mov_b32_e32 v108, v131
	v_mov_b32_e32 v109, v131
	v_mov_b32_e32 v110, 0
	v_mov_b32_e32 v111, v131
	v_mov_b32_e32 v112, v131
	v_mov_b32_e32 v113, v131
	v_mov_b32_e32 v114, 0
	v_mov_b32_e32 v115, v131
	v_mov_b32_e32 v116, v131
	v_mov_b32_e32 v117, v131
	v_mov_b32_e32 v118, 0
	v_mov_b32_e32 v119, v131
	v_mov_b32_e32 v120, v131
	v_mov_b32_e32 v121, v131
	v_mov_b32_e32 v122, 0
	v_mov_b32_e32 v123, v131
	v_mov_b32_e32 v124, v131
	v_mov_b32_e32 v125, v131
	v_mov_b32_e32 v126, 0
	v_mov_b32_e32 v127, v131
	v_mov_b32_e32 v128, v131
	v_mov_b32_e32 v129, v131
	v_mov_b32_e32 v46, 0
	v_mov_b32_e32 v47, v131
	v_mov_b32_e32 v48, v131
	v_mov_b32_e32 v49, v131
	v_mov_b32_e32 v50, 0
	v_mov_b32_e32 v51, v131
	v_mov_b32_e32 v52, v131
	v_mov_b32_e32 v53, v131
	v_mov_b32_e32 v54, 0
	v_mov_b32_e32 v55, v131
	v_mov_b32_e32 v56, v131
	v_mov_b32_e32 v57, v131
	v_mov_b32_e32 v58, 0
	v_mov_b32_e32 v59, v131
	v_mov_b32_e32 v60, v131
	v_mov_b32_e32 v61, v131
	v_mov_b32_e32 v62, 0
	v_mov_b32_e32 v63, v131
	v_mov_b32_e32 v64, v131
	v_mov_b32_e32 v65, v131
	v_mov_b32_e32 v66, 0
	v_mov_b32_e32 v67, v131
	v_mov_b32_e32 v68, v131
	v_mov_b32_e32 v69, v131
	v_mov_b32_e32 v70, 0
	v_mov_b32_e32 v71, v131
	v_mov_b32_e32 v72, v131
	v_mov_b32_e32 v73, v131
	v_mov_b32_e32 v74, 0
	v_mov_b32_e32 v75, v131
	v_mov_b32_e32 v76, v131
	v_mov_b32_e32 v77, v131
	v_mov_b32_e32 v78, 0
	v_mov_b32_e32 v79, v131
	v_mov_b32_e32 v80, v131
	v_mov_b32_e32 v81, v131
	v_mov_b32_e32 v82, 0
	v_mov_b32_e32 v83, v131
	v_mov_b32_e32 v84, v131
	v_mov_b32_e32 v85, v131
	v_mov_b32_e32 v86, 0
	v_mov_b32_e32 v87, v131
	v_mov_b32_e32 v88, v131
	v_mov_b32_e32 v89, v131
	v_mov_b32_e32 v90, 0
	v_mov_b32_e32 v91, v131
	v_mov_b32_e32 v92, v131
	v_mov_b32_e32 v93, v131
	s_branch .LBB0_1369
; template <class AF, class EPI>
; DEV void gemm_tile256(AF aptr, const u16* Bt, int ldb, int K, EPI epi, char* smem) {
;     ...
;   for (int t = 0; t < nk; ++t) {
;     if (t + 1 < nk) asm volatile("s_waitcnt vmcnt(6)" ::: "memory");
;     else asm volatile("s_waitcnt vmcnt(0)" ::: "memory");
.LBB0_1369:
	s_cmpk_eq_i32 s6, 0xfc0
	s_mov_b64 s[8:9], -1
	s_cbranch_scc1 .LBB0_1371
	s_waitcnt vmcnt(6)
	s_mov_b64 s[8:9], 0

; template <class AF, class EPI>
; DEV void gemm_tile256(AF aptr, const u16* Bt, int ldb, int K, EPI epi, char* smem) {
;     ...
;     __builtin_amdgcn_s_barrier();
;     if (t + 2 < nk) { int nb2 = buf + 2; if (nb2 >= 3) nb2 -= 3; stage(t + 2, nb2); }
;     const unsigned sa = aoff + buf * 24576, sb = boff + buf * 24576;
;     u32x4 a0, a1, a2, a3, a4, a5, a6, a7, b0, b1, b2, b3;
;     asm volatile("ds_read_b128 %0, %1" : "=v"(b0) : "v"(sb));
;     asm volatile("ds_read_b128 %0, %1 offset:1024" : "=v"(b1) : "v"(sb));
;     asm volatile("ds_read_b128 %0, %1 offset:2048" : "=v"(b2) : "v"(sb));
;     asm volatile("ds_read_b128 %0, %1 offset:3072" : "=v"(b3) : "v"(sb));
;     asm volatile("ds_read_b128 %0, %1" : "=v"(a0) : "v"(sa));
;     asm volatile("ds_read_b128 %0, %1 offset:1024" : "=v"(a1) : "v"(sa));
;     asm volatile("ds_read_b128 %0, %1 offset:2048" : "=v"(a2) : "v"(sa));
;     asm volatile("ds_read_b128 %0, %1 offset:3072" : "=v"(a3) : "v"(sa));
;     asm volatile("ds_read_b128 %0, %1 offset:4096" : "=v"(a4) : "v"(sa));
;     asm volatile("ds_read_b128 %0, %1 offset:5120" : "=v"(a5) : "v"(sa));
;     asm volatile("ds_read_b128 %0, %1 offset:6144" : "=v"(a6) : "v"(sa));
;     asm volatile("ds_read_b128 %0, %1 offset:7168" : "=v"(a7) : "v"(sa));
;     asm volatile("s_waitcnt lgkmcnt(4)" : "+v"(a0), "+v"(a1), "+v"(a2), "+v"(a3), "+v"(b0), "+v"(b1), "+v"(b2), "+v"(b3));
;     bf16x8 Bv[4];
;     Bv[0] = __builtin_bit_cast(bf16x8, b0); Bv[1] = __builtin_bit_cast(bf16x8, b1); Bv[2] = __builtin_bit_cast(bf16x8, b2); Bv[3] = __builtin_bit_cast(bf16x8, b3);
;     {
;       bf16x8 At[4];
;       At[0] = __builtin_bit_cast(bf16x8, a0); At[1] = __builtin_bit_cast(bf16x8, a1); At[2] = __builtin_bit_cast(bf16x8, a2); At[3] = __builtin_bit_cast(bf16x8, a3);
; #pragma unroll
;       for (int m = 0; m < 4; ++m)
; #pragma unroll
;         for (int n = 0; n < 4; ++n) acc[m][n] = __builtin_amdgcn_mfma_f32_16x16x32_bf16(At[m], Bv[n], acc[m][n], 0, 0, 0);
;     }
;     asm volatile("s_waitcnt lgkmcnt(0)" : "+v"(a4), "+v"(a5), "+v"(a6), "+v"(a7));
;     {
;       bf16x8 At[4];
;       At[0] = __builtin_bit_cast(bf16x8, a4); At[1] = __builtin_bit_cast(bf16x8, a5); At[2] = __builtin_bit_cast(bf16x8, a6); At[3] = __builtin_bit_cast(bf16x8, a7);
; #pragma unroll
;       for (int m = 0; m < 4; ++m)
; #pragma unroll
.LBB0_1373:
	s_barrier
	s_mul_i32 s8, s1, 0x6000
	v_add_u32_e32 v130, s8, v149
	v_add_u32_e32 v151, s8, v150
	ds_read_b128 v[152:155], v151
	ds_read_b128 v[156:159], v151 offset:1024
	ds_read_b128 v[160:163], v151 offset:2048
	ds_read_b128 v[164:167], v151 offset:3072
	ds_read_b128 v[168:171], v130
	ds_read_b128 v[172:175], v130 offset:1024
	ds_read_b128 v[176:179], v130 offset:2048
	ds_read_b128 v[180:183], v130 offset:3072
	ds_read_b128 v[184:187], v130 offset:4096
	ds_read_b128 v[188:191], v130 offset:5120
	ds_read_b128 v[192:195], v130 offset:6144
	ds_read_b128 v[196:199], v130 offset:7168
	s_cmp_gt_u32 s26, 61
	s_cbranch_scc1 .Lgnodma_g0
	s_cmp_gt_i32 s1, 0
	s_cselect_b32 s8, -1, 2
	s_add_i32 s8, s8, s1
	s_mulk_i32 s8, 0x6000
	v_add_u32_e32 v252, s8, v148
	v_add_u32_e32 v253, 0x1000, v252
	v_readfirstlane_b32 s8, v252
	v_lshl_add_u64 v[250:251], v[132:133], 0, s[6:7]
	s_mov_b32 m0, s8
	v_readfirstlane_b32 s8, v253
	v_add_u32_e32 v253, 0x2000, v252
	global_load_lds_dwordx4 v[250:251], off
	v_lshl_add_u64 v[250:251], v[134:135], 0, s[6:7]
	s_mov_b32 m0, s8
	v_readfirstlane_b32 s8, v253
	v_add_u32_e32 v253, 0x3000, v252
	global_load_lds_dwordx4 v[250:251], off
	v_lshl_add_u64 v[250:251], v[136:137], 0, s[6:7]
	s_mov_b32 m0, s8
	v_readfirstlane_b32 s8, v253
	v_add_u32_e32 v253, 0x4000, v252
	global_load_lds_dwordx4 v[250:251], off
	v_lshl_add_u64 v[250:251], v[138:139], 0, s[6:7]
	s_mov_b32 m0, s8
	v_readfirstlane_b32 s8, v253
	v_add_u32_e32 v252, 0x5000, v252
	global_load_lds_dwordx4 v[250:251], off
	v_lshl_add_u64 v[250:251], v[142:143], 0, s[6:7]
	s_mov_b32 m0, s8
	v_readfirstlane_b32 s8, v252
	global_load_lds_dwordx4 v[250:251], off
	v_lshl_add_u64 v[250:251], v[140:141], 0, s[6:7]
	s_mov_b32 m0, s8
	s_nop 0
	global_load_lds_dwordx4 v[250:251], off
.Lgnodma_g0:
	s_add_i32 s8, s1, 1
	s_cmp_lg_u32 s1, 2
	s_cselect_b32 s1, s8, 0
	s_add_u32 s6, s6, 64
	s_addc_u32 s7, s7, 0
	s_add_i32 s26, s26, 1
	s_waitcnt lgkmcnt(7)
	v_mfma_f32_16x16x32_bf16 v[126:129], v[168:171], v[152:155], v[126:129]
	v_mfma_f32_16x16x32_bf16 v[122:125], v[168:171], v[156:159], v[122:125]
	v_mfma_f32_16x16x32_bf16 v[118:121], v[168:171], v[160:163], v[118:121]
	v_mfma_f32_16x16x32_bf16 v[114:117], v[168:171], v[164:167], v[114:117]
	s_waitcnt lgkmcnt(6)
	v_mfma_f32_16x16x32_bf16 v[110:113], v[172:175], v[152:155], v[110:113]
	v_mfma_f32_16x16x32_bf16 v[106:109], v[172:175], v[156:159], v[106:109]
	v_mfma_f32_16x16x32_bf16 v[102:105], v[172:175], v[160:163], v[102:105]
	v_mfma_f32_16x16x32_bf16 v[98:101], v[172:175], v[164:167], v[98:101]
	s_waitcnt lgkmcnt(5)
	v_mfma_f32_16x16x32_bf16 v[94:97], v[176:179], v[152:155], v[94:97]
	v_mfma_f32_16x16x32_bf16 v[42:45], v[176:179], v[156:159], v[42:45]
	v_mfma_f32_16x16x32_bf16 v[38:41], v[176:179], v[160:163], v[38:41]
	v_mfma_f32_16x16x32_bf16 v[34:37], v[176:179], v[164:167], v[34:37]
	s_waitcnt lgkmcnt(4)
	v_mfma_f32_16x16x32_bf16 v[30:33], v[180:183], v[152:155], v[30:33]
	v_mfma_f32_16x16x32_bf16 v[26:29], v[180:183], v[156:159], v[26:29]
	v_mfma_f32_16x16x32_bf16 v[22:25], v[180:183], v[160:163], v[22:25]
	v_mfma_f32_16x16x32_bf16 v[18:21], v[180:183], v[164:167], v[18:21]
	s_waitcnt lgkmcnt(3)
	v_mfma_f32_16x16x32_bf16 v[14:17], v[184:187], v[152:155], v[14:17]
	v_mfma_f32_16x16x32_bf16 v[10:13], v[184:187], v[156:159], v[10:13]
	v_mfma_f32_16x16x32_bf16 v[6:9], v[184:187], v[160:163], v[6:9]
	v_mfma_f32_16x16x32_bf16 v[2:5], v[184:187], v[164:167], v[2:5]
	s_waitcnt lgkmcnt(2)
	v_mfma_f32_16x16x32_bf16 v[46:49], v[188:191], v[152:155], v[46:49]
	v_mfma_f32_16x16x32_bf16 v[50:53], v[188:191], v[156:159], v[50:53]
	v_mfma_f32_16x16x32_bf16 v[54:57], v[188:191], v[160:163], v[54:57]
	v_mfma_f32_16x16x32_bf16 v[58:61], v[188:191], v[164:167], v[58:61]
	s_waitcnt lgkmcnt(1)
	v_mfma_f32_16x16x32_bf16 v[62:65], v[192:195], v[152:155], v[62:65]
	v_mfma_f32_16x16x32_bf16 v[66:69], v[192:195], v[156:159], v[66:69]
	v_mfma_f32_16x16x32_bf16 v[70:73], v[192:195], v[160:163], v[70:73]
	v_mfma_f32_16x16x32_bf16 v[74:77], v[192:195], v[164:167], v[74:77]
	s_waitcnt lgkmcnt(0)
	v_mfma_f32_16x16x32_bf16 v[78:81], v[196:199], v[152:155], v[78:81]
	v_mfma_f32_16x16x32_bf16 v[82:85], v[196:199], v[156:159], v[82:85]
	v_mfma_f32_16x16x32_bf16 v[86:89], v[196:199], v[160:163], v[86:89]
	v_mfma_f32_16x16x32_bf16 v[90:93], v[196:199], v[164:167], v[90:93]
	s_cmpk_eq_i32 s6, 0x1000
	s_cbranch_scc0 .LBB0_1369

; __global__ void __launch_bounds__(256, 2) fwd_megakernel(Params p) {
;     ...
;   if (bid < (nb >> 1)) {
;   for (size_t blk = (size_t)bid * 256 + tid; blk < (size_t)16384 * 64; blk += (size_t)nb * 256) {
; #pragma unroll
;     for (int tb = 0; tb < 2; ++tb) {
;       const float* src = (tb ? p.peer_up : p.peer_down) + blk * 32;
;       const float sc = tb ? UP_SCALE : DOWN_SCALE;
;       v16f va, vb;
; #pragma unroll
;       for (int q = 0; q < 4; ++q) {
;         const float4 x = *(const float4*)(src + q * 8), y = *(const float4*)(src + q * 8 + 4);
;         va[q * 4] = x.x * sc; vb[q * 4] = x.y * sc; va[q * 4 + 1] = x.z * sc; vb[q * 4 + 1] = x.w * sc;
;         va[q * 4 + 2] = y.x * sc; vb[q * 4 + 2] = y.y * sc; va[q * 4 + 3] = y.z * sc; vb[q * 4 + 3] = y.w * sc;
;       }
;       const v6u o = __builtin_amdgcn_cvt_scalef32_2xpk16_fp6_f32(va, vb, 1.0f);
;       unsigned char* dst = (tb ? p.up8 : p.down8) + blk * 24;
;       *(u32x2*)dst = u32x2{o[0], o[1]}; *(u32x2*)(dst + 8) = u32x2{o[2], o[3]}; *(u32x2*)(dst + 16) = u32x2{o[4], o[5]};
.LBB0_1436:
	s_or_b64 exec, exec, s[0:1]
	s_ashr_i32 s0, s92, 1
	v_mov_b32_e32 v34, v0
	s_cmp_ge_i32 s94, s0
	s_waitcnt lgkmcnt(0)
	s_barrier
	s_cselect_b64 s[72:73], -1, 0
	s_cmp_lt_i32 s94, s0
	v_ashrrev_i32_e32 v35, 31, v34
	s_cbranch_scc0 .LBB0_1441
	s_mov_b64 exec, -1
	v_lshrrev_b32_e32 v54, 6, v0
	v_and_b32_e32 v55, 63, v0
	v_lshlrev_b32_e32 v52, 13, v54
	v_lshl_or_b32 v52, v55, 4, v52
	v_mul_u32_u24_e32 v53, 0xc00, v54
	v_lshl_or_b32 v53, v55, 4, v53
	v_add_u32_e32 v54, 0x1000, v52
	s_lshl_b32 s10, s94, 8
	s_lshl_b32 s11, s92, 8
	s_lshl_b32 s12, s92, 15
	s_mul_i32 s13, s92, 0x3000
	s_mov_b32 s16, 0x42800000
	s_lshl_b32 s0, s94, 15
	s_add_u32 s2, s40, s0
	s_addc_u32 s3, s41, 0
	s_add_u32 s4, s42, s0
	s_addc_u32 s5, s43, 0
	s_mul_i32 s0, s94, 0x3000
	s_add_u32 s6, s62, s0
	s_addc_u32 s7, s63, 0
	s_cmp_lt_u32 s10, 0x100000
	s_cbranch_scc0 .Lenc_end_a
	global_load_dwordx4 v[64:67], v52, s[2:3] nt
	global_load_dwordx4 v[68:71], v52, s[2:3] offset:1024 nt
	global_load_dwordx4 v[72:75], v52, s[2:3] offset:2048 nt
	global_load_dwordx4 v[76:79], v52, s[2:3] offset:3072 nt
	global_load_dwordx4 v[80:83], v54, s[2:3] nt
	global_load_dwordx4 v[84:87], v54, s[2:3] offset:1024 nt
	global_load_dwordx4 v[88:91], v54, s[2:3] offset:2048 nt
	global_load_dwordx4 v[92:95], v54, s[2:3] offset:3072 nt
	global_load_dwordx4 v[96:99], v52, s[4:5] nt
	global_load_dwordx4 v[100:103], v52, s[4:5] offset:1024 nt
	global_load_dwordx4 v[104:107], v52, s[4:5] offset:2048 nt
	global_load_dwordx4 v[108:111], v52, s[4:5] offset:3072 nt
	global_load_dwordx4 v[112:115], v54, s[4:5] nt
	global_load_dwordx4 v[116:119], v54, s[4:5] offset:1024 nt
	global_load_dwordx4 v[120:123], v54, s[4:5] offset:2048 nt
	global_load_dwordx4 v[124:127], v54, s[4:5] offset:3072 nt
.Lenc_loop_a:
	s_add_u32 s10, s10, s11
	s_cmp_lt_u32 s10, 0x100000
	s_cbranch_scc0 .Lenc_last_a_0
	s_add_u32 s2, s2, s12
	s_addc_u32 s3, s3, 0
	s_add_u32 s4, s4, s12
	s_addc_u32 s5, s5, 0
	global_load_dwordx4 v[128:131], v52, s[2:3] nt
	global_load_dwordx4 v[132:135], v52, s[2:3] offset:1024 nt
	global_load_dwordx4 v[136:139], v52, s[2:3] offset:2048 nt
	global_load_dwordx4 v[140:143], v52, s[2:3] offset:3072 nt
	global_load_dwordx4 v[144:147], v54, s[2:3] nt
	global_load_dwordx4 v[148:151], v54, s[2:3] offset:1024 nt
	global_load_dwordx4 v[152:155], v54, s[2:3] offset:2048 nt
	global_load_dwordx4 v[156:159], v54, s[2:3] offset:3072 nt
	global_load_dwordx4 v[160:163], v52, s[4:5] nt
	global_load_dwordx4 v[164:167], v52, s[4:5] offset:1024 nt
	global_load_dwordx4 v[168:171], v52, s[4:5] offset:2048 nt
	global_load_dwordx4 v[172:175], v52, s[4:5] offset:3072 nt
	global_load_dwordx4 v[176:179], v54, s[4:5] nt
	global_load_dwordx4 v[180:183], v54, s[4:5] offset:1024 nt
	global_load_dwordx4 v[184:187], v54, s[4:5] offset:2048 nt
	global_load_dwordx4 v[188:191], v54, s[4:5] offset:3072 nt
	s_waitcnt vmcnt(16)
	v_mul_f32_e32 v2, s16, v64
	v_mul_f32_e32 v3, s16, v66
	v_mul_f32_e32 v4, s16, v68
	v_mul_f32_e32 v5, s16, v70
	v_mul_f32_e32 v6, s16, v72
	v_mul_f32_e32 v7, s16, v74
	v_mul_f32_e32 v8, s16, v76
	v_mul_f32_e32 v9, s16, v78
	v_mul_f32_e32 v10, s16, v80
	v_mul_f32_e32 v11, s16, v82
	v_mul_f32_e32 v12, s16, v84
	v_mul_f32_e32 v13, s16, v86
	v_mul_f32_e32 v14, s16, v88
	v_mul_f32_e32 v15, s16, v90
	v_mul_f32_e32 v16, s16, v92
	v_mul_f32_e32 v17, s16, v94
	v_mul_f32_e32 v18, s16, v65
	v_mul_f32_e32 v19, s16, v67
	v_mul_f32_e32 v20, s16, v69
	v_mul_f32_e32 v21, s16, v71
	v_mul_f32_e32 v22, s16, v73
	v_mul_f32_e32 v23, s16, v75
	v_mul_f32_e32 v24, s16, v77
	v_mul_f32_e32 v25, s16, v79
	v_mul_f32_e32 v26, s16, v81
	v_mul_f32_e32 v27, s16, v83
	v_mul_f32_e32 v28, s16, v85
	v_mul_f32_e32 v29, s16, v87
	v_mul_f32_e32 v30, s16, v89
	v_mul_f32_e32 v31, s16, v91
	v_mul_f32_e32 v32, s16, v93
	v_mul_f32_e32 v33, s16, v95
	s_nop 0
	v_cvt_scalef32_2xpk16_fp6_f32 v[40:45], v[2:17], v[18:33], 1.0
	v_mul_f32_e32 v2, 4.0, v96
	v_mul_f32_e32 v3, 4.0, v98
	v_mul_f32_e32 v4, 4.0, v100
	v_mul_f32_e32 v5, 4.0, v102
	v_mul_f32_e32 v6, 4.0, v104
	v_mul_f32_e32 v7, 4.0, v106
	v_mul_f32_e32 v8, 4.0, v108
	v_mul_f32_e32 v9, 4.0, v110
	v_mul_f32_e32 v10, 4.0, v112
	v_mul_f32_e32 v11, 4.0, v114
	v_mul_f32_e32 v12, 4.0, v116
	v_mul_f32_e32 v13, 4.0, v118
	v_mul_f32_e32 v14, 4.0, v120
	v_mul_f32_e32 v15, 4.0, v122
	v_mul_f32_e32 v16, 4.0, v124
	v_mul_f32_e32 v17, 4.0, v126
	v_mul_f32_e32 v18, 4.0, v97
	v_mul_f32_e32 v19, 4.0, v99
	v_mul_f32_e32 v20, 4.0, v101
	v_mul_f32_e32 v21, 4.0, v103
	v_mul_f32_e32 v22, 4.0, v105
	v_mul_f32_e32 v23, 4.0, v107
	v_mul_f32_e32 v24, 4.0, v109
	v_mul_f32_e32 v25, 4.0, v111
	v_mul_f32_e32 v26, 4.0, v113
	v_mul_f32_e32 v27, 4.0, v115
	v_mul_f32_e32 v28, 4.0, v117
	v_mul_f32_e32 v29, 4.0, v119
	v_mul_f32_e32 v30, 4.0, v121
	v_mul_f32_e32 v31, 4.0, v123
	v_mul_f32_e32 v32, 4.0, v125
	v_mul_f32_e32 v33, 4.0, v127
	s_nop 0
	v_cvt_scalef32_2xpk16_fp6_f32 v[46:51], v[2:17], v[18:33], 1.0
	global_store_dwordx4 v53, v[40:43], s[6:7]
	global_store_dwordx4 v53, v[48:51], s[6:7] offset:1024
	global_store_dwordx4 v53, v[44:47], s[6:7] offset:2048
	s_add_u32 s6, s6, s13
	s_addc_u32 s7, s7, 0
	s_add_u32 s10, s10, s11
	s_cmp_lt_u32 s10, 0x100000
	s_cbranch_scc0 .Lenc_last_a_1
; __global__ void __launch_bounds__(256, 2) fwd_megakernel(Params p) {
;     ...
;   for (size_t blk = (size_t)bid * 256 + tid; blk < (size_t)16384 * 64; blk += (size_t)nb * 256) {
; #pragma unroll
;     for (int tb = 0; tb < 2; ++tb) {
;       const float* src = (tb ? p.peer_up : p.peer_down) + blk * 32;
;       const float sc = tb ? UP_SCALE : DOWN_SCALE;
;       v16f va, vb;
; #pragma unroll
;       for (int q = 0; q < 4; ++q) {
;         const float4 x = *(const float4*)(src + q * 8), y = *(const float4*)(src + q * 8 + 4);
;         va[q * 4] = x.x * sc; vb[q * 4] = x.y * sc; va[q * 4 + 1] = x.z * sc; vb[q * 4 + 1] = x.w * sc;
;         va[q * 4 + 2] = y.x * sc; vb[q * 4 + 2] = y.y * sc; va[q * 4 + 3] = y.z * sc; vb[q * 4 + 3] = y.w * sc;
;       }
;       const v6u o = __builtin_amdgcn_cvt_scalef32_2xpk16_fp6_f32(va, vb, 1.0f);
;       unsigned char* dst = (tb ? p.up8 : p.down8) + blk * 24;
;       *(u32x2*)dst = u32x2{o[0], o[1]}; *(u32x2*)(dst + 8) = u32x2{o[2], o[3]}; *(u32x2*)(dst + 16) = u32x2{o[4], o[5]};
;     }
	s_add_u32 s2, s2, s12
	s_addc_u32 s3, s3, 0
	s_add_u32 s4, s4, s12
	s_addc_u32 s5, s5, 0
	global_load_dwordx4 v[64:67], v52, s[2:3] nt
	global_load_dwordx4 v[68:71], v52, s[2:3] offset:1024 nt
	global_load_dwordx4 v[72:75], v52, s[2:3] offset:2048 nt
	global_load_dwordx4 v[76:79], v52, s[2:3] offset:3072 nt
	global_load_dwordx4 v[80:83], v54, s[2:3] nt
	global_load_dwordx4 v[84:87], v54, s[2:3] offset:1024 nt
	global_load_dwordx4 v[88:91], v54, s[2:3] offset:2048 nt
	global_load_dwordx4 v[92:95], v54, s[2:3] offset:3072 nt
	global_load_dwordx4 v[96:99], v52, s[4:5] nt
	global_load_dwordx4 v[100:103], v52, s[4:5] offset:1024 nt
	global_load_dwordx4 v[104:107], v52, s[4:5] offset:2048 nt
	global_load_dwordx4 v[108:111], v52, s[4:5] offset:3072 nt
	global_load_dwordx4 v[112:115], v54, s[4:5] nt
	global_load_dwordx4 v[116:119], v54, s[4:5] offset:1024 nt
	global_load_dwordx4 v[120:123], v54, s[4:5] offset:2048 nt
	global_load_dwordx4 v[124:127], v54, s[4:5] offset:3072 nt
	s_waitcnt vmcnt(16)
	v_mul_f32_e32 v2, s16, v128
	v_mul_f32_e32 v3, s16, v130
	v_mul_f32_e32 v4, s16, v132
	v_mul_f32_e32 v5, s16, v134
	v_mul_f32_e32 v6, s16, v136
	v_mul_f32_e32 v7, s16, v138
	v_mul_f32_e32 v8, s16, v140
	v_mul_f32_e32 v9, s16, v142
	v_mul_f32_e32 v10, s16, v144
	v_mul_f32_e32 v11, s16, v146
	v_mul_f32_e32 v12, s16, v148
	v_mul_f32_e32 v13, s16, v150
	v_mul_f32_e32 v14, s16, v152
	v_mul_f32_e32 v15, s16, v154
	v_mul_f32_e32 v16, s16, v156
	v_mul_f32_e32 v17, s16, v158
	v_mul_f32_e32 v18, s16, v129
	v_mul_f32_e32 v19, s16, v131
	v_mul_f32_e32 v20, s16, v133
	v_mul_f32_e32 v21, s16, v135
	v_mul_f32_e32 v22, s16, v137
	v_mul_f32_e32 v23, s16, v139
	v_mul_f32_e32 v24, s16, v141
	v_mul_f32_e32 v25, s16, v143
	v_mul_f32_e32 v26, s16, v145
	v_mul_f32_e32 v27, s16, v147
	v_mul_f32_e32 v28, s16, v149
	v_mul_f32_e32 v29, s16, v151
	v_mul_f32_e32 v30, s16, v153
	v_mul_f32_e32 v31, s16, v155
	v_mul_f32_e32 v32, s16, v157
	v_mul_f32_e32 v33, s16, v159
	s_nop 0
	v_cvt_scalef32_2xpk16_fp6_f32 v[40:45], v[2:17], v[18:33], 1.0
	v_mul_f32_e32 v2, 4.0, v160
	v_mul_f32_e32 v3, 4.0, v162
	v_mul_f32_e32 v4, 4.0, v164
	v_mul_f32_e32 v5, 4.0, v166
	v_mul_f32_e32 v6, 4.0, v168
	v_mul_f32_e32 v7, 4.0, v170
	v_mul_f32_e32 v8, 4.0, v172
	v_mul_f32_e32 v9, 4.0, v174
	v_mul_f32_e32 v10, 4.0, v176
	v_mul_f32_e32 v11, 4.0, v178
	v_mul_f32_e32 v12, 4.0, v180
	v_mul_f32_e32 v13, 4.0, v182
	v_mul_f32_e32 v14, 4.0, v184
	v_mul_f32_e32 v15, 4.0, v186
	v_mul_f32_e32 v16, 4.0, v188
	v_mul_f32_e32 v17, 4.0, v190
	v_mul_f32_e32 v18, 4.0, v161
	v_mul_f32_e32 v19, 4.0, v163
	v_mul_f32_e32 v20, 4.0, v165
	v_mul_f32_e32 v21, 4.0, v167
	v_mul_f32_e32 v22, 4.0, v169
	v_mul_f32_e32 v23, 4.0, v171
	v_mul_f32_e32 v24, 4.0, v173
	v_mul_f32_e32 v25, 4.0, v175
	v_mul_f32_e32 v26, 4.0, v177
	v_mul_f32_e32 v27, 4.0, v179
	v_mul_f32_e32 v28, 4.0, v181
	v_mul_f32_e32 v29, 4.0, v183
	v_mul_f32_e32 v30, 4.0, v185
	v_mul_f32_e32 v31, 4.0, v187
	v_mul_f32_e32 v32, 4.0, v189
	v_mul_f32_e32 v33, 4.0, v191
	s_nop 0
	v_cvt_scalef32_2xpk16_fp6_f32 v[46:51], v[2:17], v[18:33], 1.0
	global_store_dwordx4 v53, v[40:43], s[6:7]
	global_store_dwordx4 v53, v[48:51], s[6:7] offset:1024
	global_store_dwordx4 v53, v[44:47], s[6:7] offset:2048
	s_add_u32 s6, s6, s13
	s_addc_u32 s7, s7, 0
	s_branch .Lenc_loop_a
; DEV void peer_route_item(const Params& p, int item, char* smem) {
;   int tid_ = threadIdx.x;
;   asm volatile("" : "+v"(tid_));
;   const int tid = tid_, lane = tid & 63, w = tid >> 6, lq = lane & 15, g4 = lane >> 4;
;   const int hh = item >> 8, tt = item & 255;
;   const int tokL = w * 16 + lq, tok = tt * 64 + tokL;
;   u16* Ks = (u16*)smem;
;   float* topv = (float*)(smem + 34816);
;   int* topi = (int*)(smem + 34816 + 8192);
;   float* cvs = (float*)(smem + 34816 + 16384);
;   int* candA = (int*)(smem + 34816 + 16384 + 13056);
;   int* candB = candA + 50;
;   const float NEG_INF = -__builtin_inff();
; __global__ void __launch_bounds__(256, 2) fwd_megakernel(Params p) {
;     ...
;       for (int q = 0; q < 4; ++q) {
;         const float4 x = *(const float4*)(src + q * 8), y = *(const float4*)(src + q * 8 + 4);
;         va[q * 4] = x.x * sc; vb[q * 4] = x.y * sc; va[q * 4 + 1] = x.z * sc; vb[q * 4 + 1] = x.w * sc;
;         va[q * 4 + 2] = y.x * sc; vb[q * 4 + 2] = y.y * sc; va[q * 4 + 3] = y.z * sc; vb[q * 4 + 3] = y.w * sc;
;       }
;       const v6u o = __builtin_amdgcn_cvt_scalef32_2xpk16_fp6_f32(va, vb, 1.0f);
;       unsigned char* dst = (tb ? p.up8 : p.down8) + blk * 24;
;       *(u32x2*)dst = u32x2{o[0], o[1]}; *(u32x2*)(dst + 8) = u32x2{o[2], o[3]}; *(u32x2*)(dst + 16) = u32x2{o[4], o[5]};
;     }
.Lenc_last_a_0:
	s_waitcnt vmcnt(0)
	v_mul_f32_e32 v2, s16, v64
	v_mul_f32_e32 v3, s16, v66
	v_mul_f32_e32 v4, s16, v68
	v_mul_f32_e32 v5, s16, v70
	v_mul_f32_e32 v6, s16, v72
	v_mul_f32_e32 v7, s16, v74
	v_mul_f32_e32 v8, s16, v76
	v_mul_f32_e32 v9, s16, v78
	v_mul_f32_e32 v10, s16, v80
	v_mul_f32_e32 v11, s16, v82
	v_mul_f32_e32 v12, s16, v84
	v_mul_f32_e32 v13, s16, v86
	v_mul_f32_e32 v14, s16, v88
	v_mul_f32_e32 v15, s16, v90
	v_mul_f32_e32 v16, s16, v92
	v_mul_f32_e32 v17, s16, v94
	v_mul_f32_e32 v18, s16, v65
	v_mul_f32_e32 v19, s16, v67
	v_mul_f32_e32 v20, s16, v69
	v_mul_f32_e32 v21, s16, v71
	v_mul_f32_e32 v22, s16, v73
	v_mul_f32_e32 v23, s16, v75
	v_mul_f32_e32 v24, s16, v77
	v_mul_f32_e32 v25, s16, v79
	v_mul_f32_e32 v26, s16, v81
	v_mul_f32_e32 v27, s16, v83
	v_mul_f32_e32 v28, s16, v85
	v_mul_f32_e32 v29, s16, v87
	v_mul_f32_e32 v30, s16, v89
	v_mul_f32_e32 v31, s16, v91
	v_mul_f32_e32 v32, s16, v93
	v_mul_f32_e32 v33, s16, v95
	s_nop 0
	v_cvt_scalef32_2xpk16_fp6_f32 v[40:45], v[2:17], v[18:33], 1.0
	v_mul_f32_e32 v2, 4.0, v96
	v_mul_f32_e32 v3, 4.0, v98
	v_mul_f32_e32 v4, 4.0, v100
	v_mul_f32_e32 v5, 4.0, v102
	v_mul_f32_e32 v6, 4.0, v104
	v_mul_f32_e32 v7, 4.0, v106
	v_mul_f32_e32 v8, 4.0, v108
	v_mul_f32_e32 v9, 4.0, v110
	v_mul_f32_e32 v10, 4.0, v112
	v_mul_f32_e32 v11, 4.0, v114
	v_mul_f32_e32 v12, 4.0, v116
	v_mul_f32_e32 v13, 4.0, v118
	v_mul_f32_e32 v14, 4.0, v120
	v_mul_f32_e32 v15, 4.0, v122
	v_mul_f32_e32 v16, 4.0, v124
	v_mul_f32_e32 v17, 4.0, v126
	v_mul_f32_e32 v18, 4.0, v97
	v_mul_f32_e32 v19, 4.0, v99
	v_mul_f32_e32 v20, 4.0, v101
	v_mul_f32_e32 v21, 4.0, v103
	v_mul_f32_e32 v22, 4.0, v105
	v_mul_f32_e32 v23, 4.0, v107
	v_mul_f32_e32 v24, 4.0, v109
	v_mul_f32_e32 v25, 4.0, v111
	v_mul_f32_e32 v26, 4.0, v113
	v_mul_f32_e32 v27, 4.0, v115
	v_mul_f32_e32 v28, 4.0, v117
	v_mul_f32_e32 v29, 4.0, v119
	v_mul_f32_e32 v30, 4.0, v121
	v_mul_f32_e32 v31, 4.0, v123
	v_mul_f32_e32 v32, 4.0, v125
	v_mul_f32_e32 v33, 4.0, v127
	s_nop 0
	v_cvt_scalef32_2xpk16_fp6_f32 v[46:51], v[2:17], v[18:33], 1.0
	global_store_dwordx4 v53, v[40:43], s[6:7]
	global_store_dwordx4 v53, v[48:51], s[6:7] offset:1024
	global_store_dwordx4 v53, v[44:47], s[6:7] offset:2048
	s_branch .Lenc_end_a
.Lenc_last_a_1:
	s_waitcnt vmcnt(0)
	v_mul_f32_e32 v2, s16, v128
	v_mul_f32_e32 v3, s16, v130
	v_mul_f32_e32 v4, s16, v132
	v_mul_f32_e32 v5, s16, v134
	v_mul_f32_e32 v6, s16, v136
	v_mul_f32_e32 v7, s16, v138
	v_mul_f32_e32 v8, s16, v140
	v_mul_f32_e32 v9, s16, v142
	v_mul_f32_e32 v10, s16, v144
	v_mul_f32_e32 v11, s16, v146
	v_mul_f32_e32 v12, s16, v148
	v_mul_f32_e32 v13, s16, v150
	v_mul_f32_e32 v14, s16, v152
	v_mul_f32_e32 v15, s16, v154
	v_mul_f32_e32 v16, s16, v156
	v_mul_f32_e32 v17, s16, v158
	v_mul_f32_e32 v18, s16, v129
	v_mul_f32_e32 v19, s16, v131
	v_mul_f32_e32 v20, s16, v133
	v_mul_f32_e32 v21, s16, v135
	v_mul_f32_e32 v22, s16, v137
	v_mul_f32_e32 v23, s16, v139
	v_mul_f32_e32 v24, s16, v141
	v_mul_f32_e32 v25, s16, v143
	v_mul_f32_e32 v26, s16, v145
	v_mul_f32_e32 v27, s16, v147
	v_mul_f32_e32 v28, s16, v149
	v_mul_f32_e32 v29, s16, v151
	v_mul_f32_e32 v30, s16, v153
	v_mul_f32_e32 v31, s16, v155
	v_mul_f32_e32 v32, s16, v157
	v_mul_f32_e32 v33, s16, v159
	s_nop 0
	v_cvt_scalef32_2xpk16_fp6_f32 v[40:45], v[2:17], v[18:33], 1.0
	v_mul_f32_e32 v2, 4.0, v160
	v_mul_f32_e32 v3, 4.0, v162
	v_mul_f32_e32 v4, 4.0, v164
	v_mul_f32_e32 v5, 4.0, v166
	v_mul_f32_e32 v6, 4.0, v168
	v_mul_f32_e32 v7, 4.0, v170
	v_mul_f32_e32 v8, 4.0, v172
	v_mul_f32_e32 v9, 4.0, v174
	v_mul_f32_e32 v10, 4.0, v176
	v_mul_f32_e32 v11, 4.0, v178
	v_mul_f32_e32 v12, 4.0, v180
	v_mul_f32_e32 v13, 4.0, v182
	v_mul_f32_e32 v14, 4.0, v184
	v_mul_f32_e32 v15, 4.0, v186
	v_mul_f32_e32 v16, 4.0, v188
	v_mul_f32_e32 v17, 4.0, v190
	v_mul_f32_e32 v18, 4.0, v161
	v_mul_f32_e32 v19, 4.0, v163
	v_mul_f32_e32 v20, 4.0, v165
	v_mul_f32_e32 v21, 4.0, v167
	v_mul_f32_e32 v22, 4.0, v169
	v_mul_f32_e32 v23, 4.0, v171
	v_mul_f32_e32 v24, 4.0, v173
	v_mul_f32_e32 v25, 4.0, v175
	v_mul_f32_e32 v26, 4.0, v177
	v_mul_f32_e32 v27, 4.0, v179
	v_mul_f32_e32 v28, 4.0, v181
	v_mul_f32_e32 v29, 4.0, v183
	v_mul_f32_e32 v30, 4.0, v185
	v_mul_f32_e32 v31, 4.0, v187
	v_mul_f32_e32 v32, 4.0, v189
	v_mul_f32_e32 v33, 4.0, v191
	s_nop 0
	v_cvt_scalef32_2xpk16_fp6_f32 v[46:51], v[2:17], v[18:33], 1.0
	global_store_dwordx4 v53, v[40:43], s[6:7]
	global_store_dwordx4 v53, v[48:51], s[6:7] offset:1024
	global_store_dwordx4 v53, v[44:47], s[6:7] offset:2048
.Lenc_end_a:
.LBB0_1441:
	v_readlane_b32 s0, v255, 43
	v_readlane_b32 s1, v255, 44
	s_andn2_b64 vcc, exec, s[0:1]
	s_cbranch_vccnz .LBB0_1510
	v_mbcnt_lo_u32_b32 v1, -1, 0
	v_mbcnt_hi_u32_b32 v32, -1, v1
	v_and_b32_e32 v1, 64, v32
	s_movk_i32 s2, 0x110
	v_mov_b32_e32 v3, 0
	s_movk_i32 s3, 0xf800
	s_mov_b32 s75, 0
	s_movk_i32 s4, 0xff80
	s_movk_i32 s5, 0x7f
	s_movk_i32 s33, 0xcc
	s_movk_i32 s58, 0xffc0
	v_xor_b32_e32 v33, 16, v32
	v_add_u32_e32 v36, 64, v1
	v_xor_b32_e32 v37, 32, v32
	v_bfrev_b32_e32 v38, 1
	s_mov_b32 s59, s94
	s_branch .LBB0_1444

; __global__ void __launch_bounds__(256, 2) fwd_megakernel(Params p) {
;     ...
;   if (bid >= (nb >> 1)) {
;   for (size_t blk = (size_t)bid * 256 + tid; blk < (size_t)16384 * 64; blk += (size_t)nb * 256) {
; #pragma unroll
;     for (int tb = 0; tb < 2; ++tb) {
;       const float* src = (tb ? p.peer_up : p.peer_down) + blk * 32;
;       const float sc = tb ? UP_SCALE : DOWN_SCALE;
;       v16f va, vb;
; #pragma unroll
;       for (int q = 0; q < 4; ++q) {
;         const float4 x = *(const float4*)(src + q * 8), y = *(const float4*)(src + q * 8 + 4);
;         va[q * 4] = x.x * sc; vb[q * 4] = x.y * sc; va[q * 4 + 1] = x.z * sc; vb[q * 4 + 1] = x.w * sc;
;         va[q * 4 + 2] = y.x * sc; vb[q * 4 + 2] = y.y * sc; va[q * 4 + 3] = y.z * sc; vb[q * 4 + 3] = y.w * sc;
;       }
;       const v6u o = __builtin_amdgcn_cvt_scalef32_2xpk16_fp6_f32(va, vb, 1.0f);
;       unsigned char* dst = (tb ? p.up8 : p.down8) + blk * 24;
;       *(u32x2*)dst = u32x2{o[0], o[1]}; *(u32x2*)(dst + 8) = u32x2{o[2], o[3]}; *(u32x2*)(dst + 16) = u32x2{o[4], o[5]};
.LBB0_1510:
	s_and_b64 vcc, exec, s[72:73]
	s_cbranch_vccz .LBB0_1515
	s_mov_b64 exec, -1
	v_lshrrev_b32_e32 v54, 6, v0
	v_and_b32_e32 v55, 63, v0
	v_lshlrev_b32_e32 v52, 13, v54
	v_lshl_or_b32 v52, v55, 4, v52
	v_mul_u32_u24_e32 v53, 0xc00, v54
	v_lshl_or_b32 v53, v55, 4, v53
	v_add_u32_e32 v54, 0x1000, v52
	s_lshl_b32 s10, s94, 8
	s_lshl_b32 s11, s92, 8
	s_lshl_b32 s12, s92, 15
	s_mul_i32 s13, s92, 0x3000
	s_mov_b32 s16, 0x42800000
	s_lshl_b32 s0, s94, 15
	s_add_u32 s2, s40, s0
	s_addc_u32 s3, s41, 0
	s_add_u32 s4, s42, s0
	s_addc_u32 s5, s43, 0
	s_mul_i32 s0, s94, 0x3000
	s_add_u32 s6, s62, s0
	s_addc_u32 s7, s63, 0
	s_cmp_lt_u32 s10, 0x100000
	s_cbranch_scc0 .Lenc_end_b
	global_load_dwordx4 v[64:67], v52, s[2:3] nt
	global_load_dwordx4 v[68:71], v52, s[2:3] offset:1024 nt
	global_load_dwordx4 v[72:75], v52, s[2:3] offset:2048 nt
	global_load_dwordx4 v[76:79], v52, s[2:3] offset:3072 nt
	global_load_dwordx4 v[80:83], v54, s[2:3] nt
	global_load_dwordx4 v[84:87], v54, s[2:3] offset:1024 nt
	global_load_dwordx4 v[88:91], v54, s[2:3] offset:2048 nt
	global_load_dwordx4 v[92:95], v54, s[2:3] offset:3072 nt
	global_load_dwordx4 v[96:99], v52, s[4:5] nt
	global_load_dwordx4 v[100:103], v52, s[4:5] offset:1024 nt
	global_load_dwordx4 v[104:107], v52, s[4:5] offset:2048 nt
	global_load_dwordx4 v[108:111], v52, s[4:5] offset:3072 nt
	global_load_dwordx4 v[112:115], v54, s[4:5] nt
	global_load_dwordx4 v[116:119], v54, s[4:5] offset:1024 nt
	global_load_dwordx4 v[120:123], v54, s[4:5] offset:2048 nt
	global_load_dwordx4 v[124:127], v54, s[4:5] offset:3072 nt

; DEV unsigned xb_add(unsigned* p, unsigned v) { return __hip_atomic_fetch_add(p, v, __ATOMIC_RELAXED, __HIP_MEMORY_SCOPE_AGENT); }
; DEV void xcd_barrier(unsigned* bar, unsigned x, volatile unsigned* st) {
;   asm volatile("s_waitcnt vmcnt(0)" ::: "memory");
;   __syncthreads();
;   if (threadIdx.x == 0) {
;     __builtin_amdgcn_s_waitcnt(0);
;     unsigned nloc = st[0], nx = st[1];
;     if (nloc == 0u) { xcd_barrier_complete(bar, x, nloc, nx); st[0] = nloc; st[1] = nx; }
;     const unsigned old = xb_add(&bar[XB_XSUB(x)], 1u);
.Lenc_end_b:
.LBB0_1515:
	s_waitcnt vmcnt(0)
	s_barrier
	s_mov_b64 s[0:1], exec
	v_readlane_b32 s2, v254, 2
	v_readlane_b32 s3, v254, 3
	s_and_b64 s[2:3], s[0:1], s[2:3]
	s_mov_b64 exec, s[2:3]
	s_cbranch_execz .LBB0_1567
	s_mov_b64 s[2:3], src_shared_base
	v_mov_b32_e32 v2, 0x12100
	v_mov_b32_e32 v3, s3
	s_waitcnt vmcnt(0) expcnt(0) lgkmcnt(0)
	flat_load_dword v4, v[2:3] sc0 sc1
	s_waitcnt vmcnt(0)
	v_mov_b32_e32 v2, 0x12104
	flat_load_dword v2, v[2:3] sc0 sc1
	s_waitcnt vmcnt(0) lgkmcnt(0)
	v_cmp_eq_u32_e32 vcc, 0, v4
	s_and_saveexec_b64 s[2:3], vcc
	s_cbranch_execz .LBB0_1531
	s_add_u32 s4, s70, 0x1000
	s_addc_u32 s5, s71, 0
	s_add_u32 s6, s70, 0x1100
	s_addc_u32 s7, s71, 0
	s_add_u32 s8, s70, 0x1200
	s_addc_u32 s9, s71, 0
	s_add_u32 s10, s70, 0x1300
	s_addc_u32 s11, s71, 0
	s_mov_b32 s18, 1
	v_mov_b32_e32 v17, 0
	s_branch .LBB0_1519

; DEV int ltid() { int t = threadIdx.x; asm volatile("" : "+v"(t)); return t; }
; DEV float bflo(unsigned u) { return __uint_as_float(u << 16); }
; DEV float bfhi(unsigned u) { return __uint_as_float(u & 0xffff0000u); }
; DEV void peer_gather_token(const Params& p, int tok) {
;   const int lane = ltid() & 63, b = tok >> 11;
;   float hx[32], acc[32];
;   {
;     const u16* hr = p.h + (size_t)tok * 2048 + lane * 32;
; #pragma unroll
;     for (int q = 0; q < 4; ++q) {
;       u32x4 v = *(const u32x4*)(hr + q * 8);
; #pragma unroll
;       for (int e = 0; e < 4; ++e) { hx[q * 8 + 2 * e] = bflo(v[e]); hx[q * 8 + 2 * e + 1] = bfhi(v[e]); }
;     }
;   }
; #pragma unroll
;   for (int e = 0; e < 32; ++e) acc[e] = 0.f;
;   const int e0 = p.eidx[(size_t)tok * 128 + lane], e1 = p.eidx[(size_t)tok * 128 + 64 + lane];
;   const int g0 = __builtin_bit_cast(int, p.gw[(size_t)tok * 128 + lane]), g1 = __builtin_bit_cast(int, p.gw[(size_t)tok * 128 + 64 + lane]);
;   u32x2 dn[4][3], up[4][3];
;   auto issue = [&](int k, int slot) {
;     const int e = (k < 64) ? __builtin_amdgcn_readlane(e0, k) : __builtin_amdgcn_readlane(e1, k - 64);
;     const unsigned char* dr = p.down8 + (size_t)e * ROW6 + lane * 24;
;     const unsigned char* ur = p.up8 + (size_t)e * ROW6 + lane * 24;
; #pragma unroll
;     for (int i = 0; i < 3; ++i) { dn[slot][i] = *(const u32x2*)(dr + i * 8); up[slot][i] = *(const u32x2*)(ur + i * 8); }
;   };
;   issue(0, 0); issue(1, 1); issue(2, 2);
.LBB0_1567:
	s_or_b64 exec, exec, s[0:1]
	s_waitcnt lgkmcnt(0)
	s_barrier
	s_mov_b64 exec, -1
	v_lshrrev_b32_e32 v2, 6, v0
	v_and_b32_e32 v3, 63, v0
	s_nop 0
	v_readfirstlane_b32 s38, v2
	s_add_i32 s20, s84, s38
	s_lshl_b32 s21, s92, 2
	s_cmpk_lt_u32 s20, 0x4000
	s_cbranch_scc0 .Lp12_end
	v_lshlrev_b32_e32 v1, 4, v3
	v_lshlrev_b32_e32 v242, 2, v3
	v_lshlrev_b32_e32 v243, 3, v3
	v_lshlrev_b32_e32 v244, 4, v3
	v_add_u32_e32 v245, 0x1000, v244
	v_mov_b32_e32 v212, 0x3c800000
	v_mov_b32_e32 v213, 0x3ba10414
	v_mov_b32_e32 v214, 0xb9c68948
	v_mov_b32_e32 v215, 0x7f800000
	v_mov_b32_e32 v207, 0
	s_mov_b32 s9, 0x378e98ab
	s_mov_b32 s10, 0x3b7cd369
	s_mov_b32 s11, 0xbcc618b2
	s_mov_b32 s12, 0x3dda74e4
	s_mov_b32 s13, 0x3f228afd
	s_mov_b32 s14, 0x3e03c728
	s_mov_b32 s15, 0xbfb8aa3b
	s_mov_b32 s16, 0x42ce8ed0
	s_mov_b32 s17, 0xc2b17218
	s_brev_b32 s18, -2
	s_mov_b32 s43, 1
	s_lshl_b32 s38, s20, 9
	s_add_u32 s58, s66, s38
	s_addc_u32 s59, s67, 0
	global_load_dword v216, v242, s[58:59]
	global_load_dword v217, v242, s[58:59] offset:256
	s_add_u32 s58, s68, s38
	s_addc_u32 s59, s69, 0
	global_load_dword v218, v242, s[58:59]
	global_load_dword v219, v242, s[58:59] offset:256
	s_lshl_b32 s38, s20, 12
	s_add_u32 s58, s80, s38
	s_addc_u32 s59, s81, 0
	global_load_dwordx2 v[220:221], v243, s[58:59]
	global_load_dwordx2 v[222:223], v243, s[58:59] offset:512
	global_load_dwordx2 v[224:225], v243, s[58:59] offset:1024
	global_load_dwordx2 v[226:227], v243, s[58:59] offset:1536
	global_load_dwordx2 v[228:229], v243, s[58:59] offset:2048
	global_load_dwordx2 v[230:231], v243, s[58:59] offset:2560
	global_load_dwordx2 v[232:233], v243, s[58:59] offset:3072
	global_load_dwordx2 v[234:235], v243, s[58:59] offset:3584
	s_waitcnt vmcnt(0) lgkmcnt(0)
	s_mov_b32 s36, 0
	s_mov_b32 s37, 0
	v_and_b32_e32 v236, 63, v0
	v_lshrrev_b32_e32 v241, 6, v0
	v_lshl_or_b32 v237, v216, 7, v236
	v_or_b32_e32 v238, 64, v236
	v_lshl_or_b32 v238, v217, 7, v238
	v_mov_b32_e32 v239, 0
	v_mov_b32_e32 v240, 0
	v_lshlrev_b32_e32 v241, 10, v241
	v_lshl_add_u32 v241, v236, 2, v241
	v_readlane_b32 s46, v237, 0
	v_readlane_b32 s47, v238, 0
	s_nop 1
	v_cmp_lt_u32_e64 s[48:49], s46, v237
	v_cmp_lt_u32_e64 s[50:51], s46, v238
	v_cmp_lt_u32_e64 s[52:53], s47, v237
	v_cmp_lt_u32_e64 s[54:55], s47, v238
	v_readlane_b32 s46, v237, 1
	v_readlane_b32 s47, v238, 1
	v_addc_co_u32_e64 v239, s[56:57], 0, v239, s[48:49]
	v_addc_co_u32_e64 v240, s[56:57], 0, v240, s[50:51]
	v_addc_co_u32_e64 v239, s[56:57], 0, v239, s[52:53]
	v_addc_co_u32_e64 v240, s[56:57], 0, v240, s[54:55]
	v_cmp_lt_u32_e64 s[48:49], s46, v237
	v_cmp_lt_u32_e64 s[50:51], s46, v238
	v_cmp_lt_u32_e64 s[52:53], s47, v237
	v_cmp_lt_u32_e64 s[54:55], s47, v238
	v_readlane_b32 s46, v237, 2
	v_readlane_b32 s47, v238, 2
	v_addc_co_u32_e64 v239, s[56:57], 0, v239, s[48:49]
	v_addc_co_u32_e64 v240, s[56:57], 0, v240, s[50:51]
	v_addc_co_u32_e64 v239, s[56:57], 0, v239, s[52:53]
	v_addc_co_u32_e64 v240, s[56:57], 0, v240, s[54:55]
	v_cmp_lt_u32_e64 s[48:49], s46, v237
	v_cmp_lt_u32_e64 s[50:51], s46, v238
	v_cmp_lt_u32_e64 s[52:53], s47, v237
	v_cmp_lt_u32_e64 s[54:55], s47, v238
	v_readlane_b32 s46, v237, 3
	v_readlane_b32 s47, v238, 3
	v_addc_co_u32_e64 v239, s[56:57], 0, v239, s[48:49]
	v_addc_co_u32_e64 v240, s[56:57], 0, v240, s[50:51]
	v_addc_co_u32_e64 v239, s[56:57], 0, v239, s[52:53]
	v_addc_co_u32_e64 v240, s[56:57], 0, v240, s[54:55]
	v_cmp_lt_u32_e64 s[48:49], s46, v237
	v_cmp_lt_u32_e64 s[50:51], s46, v238
	v_cmp_lt_u32_e64 s[52:53], s47, v237
	v_cmp_lt_u32_e64 s[54:55], s47, v238
	v_readlane_b32 s46, v237, 4
	v_readlane_b32 s47, v238, 4
	v_addc_co_u32_e64 v239, s[56:57], 0, v239, s[48:49]
	v_addc_co_u32_e64 v240, s[56:57], 0, v240, s[50:51]
	v_addc_co_u32_e64 v239, s[56:57], 0, v239, s[52:53]
	v_addc_co_u32_e64 v240, s[56:57], 0, v240, s[54:55]
	v_cmp_lt_u32_e64 s[48:49], s46, v237
	v_cmp_lt_u32_e64 s[50:51], s46, v238
	v_cmp_lt_u32_e64 s[52:53], s47, v237
	v_cmp_lt_u32_e64 s[54:55], s47, v238
	v_readlane_b32 s46, v237, 5
	v_readlane_b32 s47, v238, 5
	v_addc_co_u32_e64 v239, s[56:57], 0, v239, s[48:49]
	v_addc_co_u32_e64 v240, s[56:57], 0, v240, s[50:51]
	v_addc_co_u32_e64 v239, s[56:57], 0, v239, s[52:53]
	v_addc_co_u32_e64 v240, s[56:57], 0, v240, s[54:55]
	v_cmp_lt_u32_e64 s[48:49], s46, v237
	v_cmp_lt_u32_e64 s[50:51], s46, v238
	v_cmp_lt_u32_e64 s[52:53], s47, v237
	v_cmp_lt_u32_e64 s[54:55], s47, v238
	v_readlane_b32 s46, v237, 6
	v_readlane_b32 s47, v238, 6
	v_addc_co_u32_e64 v239, s[56:57], 0, v239, s[48:49]
	v_addc_co_u32_e64 v240, s[56:57], 0, v240, s[50:51]
	v_addc_co_u32_e64 v239, s[56:57], 0, v239, s[52:53]
	v_addc_co_u32_e64 v240, s[56:57], 0, v240, s[54:55]
	v_cmp_lt_u32_e64 s[48:49], s46, v237
	v_cmp_lt_u32_e64 s[50:51], s46, v238
	v_cmp_lt_u32_e64 s[52:53], s47, v237
	v_cmp_lt_u32_e64 s[54:55], s47, v238
	v_readlane_b32 s46, v237, 7
	v_readlane_b32 s47, v238, 7
	v_addc_co_u32_e64 v239, s[56:57], 0, v239, s[48:49]
	v_addc_co_u32_e64 v240, s[56:57], 0, v240, s[50:51]
	v_addc_co_u32_e64 v239, s[56:57], 0, v239, s[52:53]
	v_addc_co_u32_e64 v240, s[56:57], 0, v240, s[54:55]
	v_cmp_lt_u32_e64 s[48:49], s46, v237
	v_cmp_lt_u32_e64 s[50:51], s46, v238
	v_cmp_lt_u32_e64 s[52:53], s47, v237
	v_cmp_lt_u32_e64 s[54:55], s47, v238
	v_readlane_b32 s46, v237, 8
	v_readlane_b32 s47, v238, 8
	v_addc_co_u32_e64 v239, s[56:57], 0, v239, s[48:49]
	v_addc_co_u32_e64 v240, s[56:57], 0, v240, s[50:51]
	v_addc_co_u32_e64 v239, s[56:57], 0, v239, s[52:53]
	v_addc_co_u32_e64 v240, s[56:57], 0, v240, s[54:55]
	v_cmp_lt_u32_e64 s[48:49], s46, v237
	v_cmp_lt_u32_e64 s[50:51], s46, v238
	v_cmp_lt_u32_e64 s[52:53], s47, v237
	v_cmp_lt_u32_e64 s[54:55], s47, v238
; DEV void peer_gather_token(const Params& p, int tok) {
;     ...
;   const int e0 = p.eidx[(size_t)tok * 128 + lane], e1 = p.eidx[(size_t)tok * 128 + 64 + lane];
;   const int g0 = __builtin_bit_cast(int, p.gw[(size_t)tok * 128 + lane]), g1 = __builtin_bit_cast(int, p.gw[(size_t)tok * 128 + 64 + lane]);
;   u32x2 dn[4][3], up[4][3];
;   auto issue = [&](int k, int slot) {
;     const int e = (k < 64) ? __builtin_amdgcn_readlane(e0, k) : __builtin_amdgcn_readlane(e1, k - 64);
;     const unsigned char* dr = p.down8 + (size_t)e * ROW6 + lane * 24;
;     const unsigned char* ur = p.up8 + (size_t)e * ROW6 + lane * 24;
; #pragma unroll
;     for (int i = 0; i < 3; ++i) { dn[slot][i] = *(const u32x2*)(dr + i * 8); up[slot][i] = *(const u32x2*)(ur + i * 8); }
;   };
;   issue(0, 0); issue(1, 1); issue(2, 2);
	v_readlane_b32 s46, v237, 9
	v_readlane_b32 s47, v238, 9
	v_addc_co_u32_e64 v239, s[56:57], 0, v239, s[48:49]
	v_addc_co_u32_e64 v240, s[56:57], 0, v240, s[50:51]
	v_addc_co_u32_e64 v239, s[56:57], 0, v239, s[52:53]
	v_addc_co_u32_e64 v240, s[56:57], 0, v240, s[54:55]
	v_cmp_lt_u32_e64 s[48:49], s46, v237
	v_cmp_lt_u32_e64 s[50:51], s46, v238
	v_cmp_lt_u32_e64 s[52:53], s47, v237
	v_cmp_lt_u32_e64 s[54:55], s47, v238
	v_readlane_b32 s46, v237, 10
	v_readlane_b32 s47, v238, 10
	v_addc_co_u32_e64 v239, s[56:57], 0, v239, s[48:49]
	v_addc_co_u32_e64 v240, s[56:57], 0, v240, s[50:51]
	v_addc_co_u32_e64 v239, s[56:57], 0, v239, s[52:53]
	v_addc_co_u32_e64 v240, s[56:57], 0, v240, s[54:55]
	v_cmp_lt_u32_e64 s[48:49], s46, v237
	v_cmp_lt_u32_e64 s[50:51], s46, v238
	v_cmp_lt_u32_e64 s[52:53], s47, v237
	v_cmp_lt_u32_e64 s[54:55], s47, v238
	v_readlane_b32 s46, v237, 11
	v_readlane_b32 s47, v238, 11
	v_addc_co_u32_e64 v239, s[56:57], 0, v239, s[48:49]
	v_addc_co_u32_e64 v240, s[56:57], 0, v240, s[50:51]
	v_addc_co_u32_e64 v239, s[56:57], 0, v239, s[52:53]
	v_addc_co_u32_e64 v240, s[56:57], 0, v240, s[54:55]
	v_cmp_lt_u32_e64 s[48:49], s46, v237
	v_cmp_lt_u32_e64 s[50:51], s46, v238
	v_cmp_lt_u32_e64 s[52:53], s47, v237
	v_cmp_lt_u32_e64 s[54:55], s47, v238
	v_readlane_b32 s46, v237, 12
	v_readlane_b32 s47, v238, 12
	v_addc_co_u32_e64 v239, s[56:57], 0, v239, s[48:49]
	v_addc_co_u32_e64 v240, s[56:57], 0, v240, s[50:51]
	v_addc_co_u32_e64 v239, s[56:57], 0, v239, s[52:53]
	v_addc_co_u32_e64 v240, s[56:57], 0, v240, s[54:55]
	v_cmp_lt_u32_e64 s[48:49], s46, v237
	v_cmp_lt_u32_e64 s[50:51], s46, v238
	v_cmp_lt_u32_e64 s[52:53], s47, v237
	v_cmp_lt_u32_e64 s[54:55], s47, v238
	v_readlane_b32 s46, v237, 13
	v_readlane_b32 s47, v238, 13
	v_addc_co_u32_e64 v239, s[56:57], 0, v239, s[48:49]
	v_addc_co_u32_e64 v240, s[56:57], 0, v240, s[50:51]
	v_addc_co_u32_e64 v239, s[56:57], 0, v239, s[52:53]
	v_addc_co_u32_e64 v240, s[56:57], 0, v240, s[54:55]
	v_cmp_lt_u32_e64 s[48:49], s46, v237
	v_cmp_lt_u32_e64 s[50:51], s46, v238
	v_cmp_lt_u32_e64 s[52:53], s47, v237
	v_cmp_lt_u32_e64 s[54:55], s47, v238
	v_readlane_b32 s46, v237, 14
	v_readlane_b32 s47, v238, 14
	v_addc_co_u32_e64 v239, s[56:57], 0, v239, s[48:49]
	v_addc_co_u32_e64 v240, s[56:57], 0, v240, s[50:51]
	v_addc_co_u32_e64 v239, s[56:57], 0, v239, s[52:53]
	v_addc_co_u32_e64 v240, s[56:57], 0, v240, s[54:55]
	v_cmp_lt_u32_e64 s[48:49], s46, v237
	v_cmp_lt_u32_e64 s[50:51], s46, v238
	v_cmp_lt_u32_e64 s[52:53], s47, v237
	v_cmp_lt_u32_e64 s[54:55], s47, v238
	v_readlane_b32 s46, v237, 15
	v_readlane_b32 s47, v238, 15
	v_addc_co_u32_e64 v239, s[56:57], 0, v239, s[48:49]
	v_addc_co_u32_e64 v240, s[56:57], 0, v240, s[50:51]
	v_addc_co_u32_e64 v239, s[56:57], 0, v239, s[52:53]
	v_addc_co_u32_e64 v240, s[56:57], 0, v240, s[54:55]
	v_cmp_lt_u32_e64 s[48:49], s46, v237
	v_cmp_lt_u32_e64 s[50:51], s46, v238
	v_cmp_lt_u32_e64 s[52:53], s47, v237
	v_cmp_lt_u32_e64 s[54:55], s47, v238
	v_readlane_b32 s46, v237, 16
	v_readlane_b32 s47, v238, 16
	v_addc_co_u32_e64 v239, s[56:57], 0, v239, s[48:49]
	v_addc_co_u32_e64 v240, s[56:57], 0, v240, s[50:51]
	v_addc_co_u32_e64 v239, s[56:57], 0, v239, s[52:53]
	v_addc_co_u32_e64 v240, s[56:57], 0, v240, s[54:55]
	v_cmp_lt_u32_e64 s[48:49], s46, v237
	v_cmp_lt_u32_e64 s[50:51], s46, v238
	v_cmp_lt_u32_e64 s[52:53], s47, v237
	v_cmp_lt_u32_e64 s[54:55], s47, v238
	v_readlane_b32 s46, v237, 17
	v_readlane_b32 s47, v238, 17
	v_addc_co_u32_e64 v239, s[56:57], 0, v239, s[48:49]
	v_addc_co_u32_e64 v240, s[56:57], 0, v240, s[50:51]
	v_addc_co_u32_e64 v239, s[56:57], 0, v239, s[52:53]
	v_addc_co_u32_e64 v240, s[56:57], 0, v240, s[54:55]
	v_cmp_lt_u32_e64 s[48:49], s46, v237
	v_cmp_lt_u32_e64 s[50:51], s46, v238
	v_cmp_lt_u32_e64 s[52:53], s47, v237
	v_cmp_lt_u32_e64 s[54:55], s47, v238
	v_readlane_b32 s46, v237, 18
	v_readlane_b32 s47, v238, 18
	v_addc_co_u32_e64 v239, s[56:57], 0, v239, s[48:49]
	v_addc_co_u32_e64 v240, s[56:57], 0, v240, s[50:51]
	v_addc_co_u32_e64 v239, s[56:57], 0, v239, s[52:53]
	v_addc_co_u32_e64 v240, s[56:57], 0, v240, s[54:55]
	v_cmp_lt_u32_e64 s[48:49], s46, v237
	v_cmp_lt_u32_e64 s[50:51], s46, v238
	v_cmp_lt_u32_e64 s[52:53], s47, v237
	v_cmp_lt_u32_e64 s[54:55], s47, v238
	v_readlane_b32 s46, v237, 19
	v_readlane_b32 s47, v238, 19
	v_addc_co_u32_e64 v239, s[56:57], 0, v239, s[48:49]
	v_addc_co_u32_e64 v240, s[56:57], 0, v240, s[50:51]
	v_addc_co_u32_e64 v239, s[56:57], 0, v239, s[52:53]
	v_addc_co_u32_e64 v240, s[56:57], 0, v240, s[54:55]
	v_cmp_lt_u32_e64 s[48:49], s46, v237
	v_cmp_lt_u32_e64 s[50:51], s46, v238
	v_cmp_lt_u32_e64 s[52:53], s47, v237
	v_cmp_lt_u32_e64 s[54:55], s47, v238
	v_readlane_b32 s46, v237, 20
	v_readlane_b32 s47, v238, 20
	v_addc_co_u32_e64 v239, s[56:57], 0, v239, s[48:49]
	v_addc_co_u32_e64 v240, s[56:57], 0, v240, s[50:51]
	v_addc_co_u32_e64 v239, s[56:57], 0, v239, s[52:53]
	v_addc_co_u32_e64 v240, s[56:57], 0, v240, s[54:55]
	v_cmp_lt_u32_e64 s[48:49], s46, v237
	v_cmp_lt_u32_e64 s[50:51], s46, v238
	v_cmp_lt_u32_e64 s[52:53], s47, v237
	v_cmp_lt_u32_e64 s[54:55], s47, v238
	v_readlane_b32 s46, v237, 21
	v_readlane_b32 s47, v238, 21
	v_addc_co_u32_e64 v239, s[56:57], 0, v239, s[48:49]
	v_addc_co_u32_e64 v240, s[56:57], 0, v240, s[50:51]
	v_addc_co_u32_e64 v239, s[56:57], 0, v239, s[52:53]
	v_addc_co_u32_e64 v240, s[56:57], 0, v240, s[54:55]
	v_cmp_lt_u32_e64 s[48:49], s46, v237
	v_cmp_lt_u32_e64 s[50:51], s46, v238
	v_cmp_lt_u32_e64 s[52:53], s47, v237
	v_cmp_lt_u32_e64 s[54:55], s47, v238
	v_readlane_b32 s46, v237, 22
	v_readlane_b32 s47, v238, 22
	v_addc_co_u32_e64 v239, s[56:57], 0, v239, s[48:49]
; DEV void peer_gather_token(const Params& p, int tok) {
;     ...
;   const int e0 = p.eidx[(size_t)tok * 128 + lane], e1 = p.eidx[(size_t)tok * 128 + 64 + lane];
;   const int g0 = __builtin_bit_cast(int, p.gw[(size_t)tok * 128 + lane]), g1 = __builtin_bit_cast(int, p.gw[(size_t)tok * 128 + 64 + lane]);
;   u32x2 dn[4][3], up[4][3];
;   auto issue = [&](int k, int slot) {
;     const int e = (k < 64) ? __builtin_amdgcn_readlane(e0, k) : __builtin_amdgcn_readlane(e1, k - 64);
;     const unsigned char* dr = p.down8 + (size_t)e * ROW6 + lane * 24;
;     const unsigned char* ur = p.up8 + (size_t)e * ROW6 + lane * 24;
; #pragma unroll
;     for (int i = 0; i < 3; ++i) { dn[slot][i] = *(const u32x2*)(dr + i * 8); up[slot][i] = *(const u32x2*)(ur + i * 8); }
;   };
;   issue(0, 0); issue(1, 1); issue(2, 2);
	v_addc_co_u32_e64 v240, s[56:57], 0, v240, s[50:51]
	v_addc_co_u32_e64 v239, s[56:57], 0, v239, s[52:53]
	v_addc_co_u32_e64 v240, s[56:57], 0, v240, s[54:55]
	v_cmp_lt_u32_e64 s[48:49], s46, v237
	v_cmp_lt_u32_e64 s[50:51], s46, v238
	v_cmp_lt_u32_e64 s[52:53], s47, v237
	v_cmp_lt_u32_e64 s[54:55], s47, v238
	v_readlane_b32 s46, v237, 23
	v_readlane_b32 s47, v238, 23
	v_addc_co_u32_e64 v239, s[56:57], 0, v239, s[48:49]
	v_addc_co_u32_e64 v240, s[56:57], 0, v240, s[50:51]
	v_addc_co_u32_e64 v239, s[56:57], 0, v239, s[52:53]
	v_addc_co_u32_e64 v240, s[56:57], 0, v240, s[54:55]
	v_cmp_lt_u32_e64 s[48:49], s46, v237
	v_cmp_lt_u32_e64 s[50:51], s46, v238
	v_cmp_lt_u32_e64 s[52:53], s47, v237
	v_cmp_lt_u32_e64 s[54:55], s47, v238
	v_readlane_b32 s46, v237, 24
	v_readlane_b32 s47, v238, 24
	v_addc_co_u32_e64 v239, s[56:57], 0, v239, s[48:49]
	v_addc_co_u32_e64 v240, s[56:57], 0, v240, s[50:51]
	v_addc_co_u32_e64 v239, s[56:57], 0, v239, s[52:53]
	v_addc_co_u32_e64 v240, s[56:57], 0, v240, s[54:55]
	v_cmp_lt_u32_e64 s[48:49], s46, v237
	v_cmp_lt_u32_e64 s[50:51], s46, v238
	v_cmp_lt_u32_e64 s[52:53], s47, v237
	v_cmp_lt_u32_e64 s[54:55], s47, v238
	v_readlane_b32 s46, v237, 25
	v_readlane_b32 s47, v238, 25
	v_addc_co_u32_e64 v239, s[56:57], 0, v239, s[48:49]
	v_addc_co_u32_e64 v240, s[56:57], 0, v240, s[50:51]
	v_addc_co_u32_e64 v239, s[56:57], 0, v239, s[52:53]
	v_addc_co_u32_e64 v240, s[56:57], 0, v240, s[54:55]
	v_cmp_lt_u32_e64 s[48:49], s46, v237
	v_cmp_lt_u32_e64 s[50:51], s46, v238
	v_cmp_lt_u32_e64 s[52:53], s47, v237
	v_cmp_lt_u32_e64 s[54:55], s47, v238
	v_readlane_b32 s46, v237, 26
	v_readlane_b32 s47, v238, 26
	v_addc_co_u32_e64 v239, s[56:57], 0, v239, s[48:49]
	v_addc_co_u32_e64 v240, s[56:57], 0, v240, s[50:51]
	v_addc_co_u32_e64 v239, s[56:57], 0, v239, s[52:53]
	v_addc_co_u32_e64 v240, s[56:57], 0, v240, s[54:55]
	v_cmp_lt_u32_e64 s[48:49], s46, v237
	v_cmp_lt_u32_e64 s[50:51], s46, v238
	v_cmp_lt_u32_e64 s[52:53], s47, v237
	v_cmp_lt_u32_e64 s[54:55], s47, v238
	v_readlane_b32 s46, v237, 27
	v_readlane_b32 s47, v238, 27
	v_addc_co_u32_e64 v239, s[56:57], 0, v239, s[48:49]
	v_addc_co_u32_e64 v240, s[56:57], 0, v240, s[50:51]
	v_addc_co_u32_e64 v239, s[56:57], 0, v239, s[52:53]
	v_addc_co_u32_e64 v240, s[56:57], 0, v240, s[54:55]
	v_cmp_lt_u32_e64 s[48:49], s46, v237
	v_cmp_lt_u32_e64 s[50:51], s46, v238
	v_cmp_lt_u32_e64 s[52:53], s47, v237
	v_cmp_lt_u32_e64 s[54:55], s47, v238
	v_readlane_b32 s46, v237, 28
	v_readlane_b32 s47, v238, 28
	v_addc_co_u32_e64 v239, s[56:57], 0, v239, s[48:49]
	v_addc_co_u32_e64 v240, s[56:57], 0, v240, s[50:51]
	v_addc_co_u32_e64 v239, s[56:57], 0, v239, s[52:53]
	v_addc_co_u32_e64 v240, s[56:57], 0, v240, s[54:55]
	v_cmp_lt_u32_e64 s[48:49], s46, v237
	v_cmp_lt_u32_e64 s[50:51], s46, v238
	v_cmp_lt_u32_e64 s[52:53], s47, v237
	v_cmp_lt_u32_e64 s[54:55], s47, v238
	v_readlane_b32 s46, v237, 29
	v_readlane_b32 s47, v238, 29
	v_addc_co_u32_e64 v239, s[56:57], 0, v239, s[48:49]
	v_addc_co_u32_e64 v240, s[56:57], 0, v240, s[50:51]
	v_addc_co_u32_e64 v239, s[56:57], 0, v239, s[52:53]
	v_addc_co_u32_e64 v240, s[56:57], 0, v240, s[54:55]
	v_cmp_lt_u32_e64 s[48:49], s46, v237
	v_cmp_lt_u32_e64 s[50:51], s46, v238
	v_cmp_lt_u32_e64 s[52:53], s47, v237
	v_cmp_lt_u32_e64 s[54:55], s47, v238
	v_readlane_b32 s46, v237, 30
	v_readlane_b32 s47, v238, 30
	v_addc_co_u32_e64 v239, s[56:57], 0, v239, s[48:49]
	v_addc_co_u32_e64 v240, s[56:57], 0, v240, s[50:51]
	v_addc_co_u32_e64 v239, s[56:57], 0, v239, s[52:53]
	v_addc_co_u32_e64 v240, s[56:57], 0, v240, s[54:55]
	v_cmp_lt_u32_e64 s[48:49], s46, v237
	v_cmp_lt_u32_e64 s[50:51], s46, v238
	v_cmp_lt_u32_e64 s[52:53], s47, v237
	v_cmp_lt_u32_e64 s[54:55], s47, v238
	v_readlane_b32 s46, v237, 31
	v_readlane_b32 s47, v238, 31
	v_addc_co_u32_e64 v239, s[56:57], 0, v239, s[48:49]
	v_addc_co_u32_e64 v240, s[56:57], 0, v240, s[50:51]
	v_addc_co_u32_e64 v239, s[56:57], 0, v239, s[52:53]
	v_addc_co_u32_e64 v240, s[56:57], 0, v240, s[54:55]
	v_cmp_lt_u32_e64 s[48:49], s46, v237
	v_cmp_lt_u32_e64 s[50:51], s46, v238
	v_cmp_lt_u32_e64 s[52:53], s47, v237
	v_cmp_lt_u32_e64 s[54:55], s47, v238
	v_readlane_b32 s46, v237, 32
	v_readlane_b32 s47, v238, 32
	v_addc_co_u32_e64 v239, s[56:57], 0, v239, s[48:49]
	v_addc_co_u32_e64 v240, s[56:57], 0, v240, s[50:51]
	v_addc_co_u32_e64 v239, s[56:57], 0, v239, s[52:53]
	v_addc_co_u32_e64 v240, s[56:57], 0, v240, s[54:55]
	v_cmp_lt_u32_e64 s[48:49], s46, v237
	v_cmp_lt_u32_e64 s[50:51], s46, v238
	v_cmp_lt_u32_e64 s[52:53], s47, v237
	v_cmp_lt_u32_e64 s[54:55], s47, v238
	v_readlane_b32 s46, v237, 33
	v_readlane_b32 s47, v238, 33
	v_addc_co_u32_e64 v239, s[56:57], 0, v239, s[48:49]
	v_addc_co_u32_e64 v240, s[56:57], 0, v240, s[50:51]
	v_addc_co_u32_e64 v239, s[56:57], 0, v239, s[52:53]
	v_addc_co_u32_e64 v240, s[56:57], 0, v240, s[54:55]
	v_cmp_lt_u32_e64 s[48:49], s46, v237
	v_cmp_lt_u32_e64 s[50:51], s46, v238
	v_cmp_lt_u32_e64 s[52:53], s47, v237
	v_cmp_lt_u32_e64 s[54:55], s47, v238
	v_readlane_b32 s46, v237, 34
	v_readlane_b32 s47, v238, 34
	v_addc_co_u32_e64 v239, s[56:57], 0, v239, s[48:49]
	v_addc_co_u32_e64 v240, s[56:57], 0, v240, s[50:51]
	v_addc_co_u32_e64 v239, s[56:57], 0, v239, s[52:53]
	v_addc_co_u32_e64 v240, s[56:57], 0, v240, s[54:55]
	v_cmp_lt_u32_e64 s[48:49], s46, v237
	v_cmp_lt_u32_e64 s[50:51], s46, v238
	v_cmp_lt_u32_e64 s[52:53], s47, v237
	v_cmp_lt_u32_e64 s[54:55], s47, v238
	v_readlane_b32 s46, v237, 35
	v_readlane_b32 s47, v238, 35
	v_addc_co_u32_e64 v239, s[56:57], 0, v239, s[48:49]
	v_addc_co_u32_e64 v240, s[56:57], 0, v240, s[50:51]
	v_addc_co_u32_e64 v239, s[56:57], 0, v239, s[52:53]
; DEV void peer_gather_token(const Params& p, int tok) {
;     ...
;   const int e0 = p.eidx[(size_t)tok * 128 + lane], e1 = p.eidx[(size_t)tok * 128 + 64 + lane];
;   const int g0 = __builtin_bit_cast(int, p.gw[(size_t)tok * 128 + lane]), g1 = __builtin_bit_cast(int, p.gw[(size_t)tok * 128 + 64 + lane]);
;   u32x2 dn[4][3], up[4][3];
;   auto issue = [&](int k, int slot) {
;     const int e = (k < 64) ? __builtin_amdgcn_readlane(e0, k) : __builtin_amdgcn_readlane(e1, k - 64);
;     const unsigned char* dr = p.down8 + (size_t)e * ROW6 + lane * 24;
;     const unsigned char* ur = p.up8 + (size_t)e * ROW6 + lane * 24;
; #pragma unroll
;     for (int i = 0; i < 3; ++i) { dn[slot][i] = *(const u32x2*)(dr + i * 8); up[slot][i] = *(const u32x2*)(ur + i * 8); }
;   };
;   issue(0, 0); issue(1, 1); issue(2, 2);
	v_addc_co_u32_e64 v240, s[56:57], 0, v240, s[54:55]
	v_cmp_lt_u32_e64 s[48:49], s46, v237
	v_cmp_lt_u32_e64 s[50:51], s46, v238
	v_cmp_lt_u32_e64 s[52:53], s47, v237
	v_cmp_lt_u32_e64 s[54:55], s47, v238
	v_readlane_b32 s46, v237, 36
	v_readlane_b32 s47, v238, 36
	v_addc_co_u32_e64 v239, s[56:57], 0, v239, s[48:49]
	v_addc_co_u32_e64 v240, s[56:57], 0, v240, s[50:51]
	v_addc_co_u32_e64 v239, s[56:57], 0, v239, s[52:53]
	v_addc_co_u32_e64 v240, s[56:57], 0, v240, s[54:55]
	v_cmp_lt_u32_e64 s[48:49], s46, v237
	v_cmp_lt_u32_e64 s[50:51], s46, v238
	v_cmp_lt_u32_e64 s[52:53], s47, v237
	v_cmp_lt_u32_e64 s[54:55], s47, v238
	v_readlane_b32 s46, v237, 37
	v_readlane_b32 s47, v238, 37
	v_addc_co_u32_e64 v239, s[56:57], 0, v239, s[48:49]
	v_addc_co_u32_e64 v240, s[56:57], 0, v240, s[50:51]
	v_addc_co_u32_e64 v239, s[56:57], 0, v239, s[52:53]
	v_addc_co_u32_e64 v240, s[56:57], 0, v240, s[54:55]
	v_cmp_lt_u32_e64 s[48:49], s46, v237
	v_cmp_lt_u32_e64 s[50:51], s46, v238
	v_cmp_lt_u32_e64 s[52:53], s47, v237
	v_cmp_lt_u32_e64 s[54:55], s47, v238
	v_readlane_b32 s46, v237, 38
	v_readlane_b32 s47, v238, 38
	v_addc_co_u32_e64 v239, s[56:57], 0, v239, s[48:49]
	v_addc_co_u32_e64 v240, s[56:57], 0, v240, s[50:51]
	v_addc_co_u32_e64 v239, s[56:57], 0, v239, s[52:53]
	v_addc_co_u32_e64 v240, s[56:57], 0, v240, s[54:55]
	v_cmp_lt_u32_e64 s[48:49], s46, v237
	v_cmp_lt_u32_e64 s[50:51], s46, v238
	v_cmp_lt_u32_e64 s[52:53], s47, v237
	v_cmp_lt_u32_e64 s[54:55], s47, v238
	v_readlane_b32 s46, v237, 39
	v_readlane_b32 s47, v238, 39
	v_addc_co_u32_e64 v239, s[56:57], 0, v239, s[48:49]
	v_addc_co_u32_e64 v240, s[56:57], 0, v240, s[50:51]
	v_addc_co_u32_e64 v239, s[56:57], 0, v239, s[52:53]
	v_addc_co_u32_e64 v240, s[56:57], 0, v240, s[54:55]
	v_cmp_lt_u32_e64 s[48:49], s46, v237
	v_cmp_lt_u32_e64 s[50:51], s46, v238
	v_cmp_lt_u32_e64 s[52:53], s47, v237
	v_cmp_lt_u32_e64 s[54:55], s47, v238
	v_readlane_b32 s46, v237, 40
	v_readlane_b32 s47, v238, 40
	v_addc_co_u32_e64 v239, s[56:57], 0, v239, s[48:49]
	v_addc_co_u32_e64 v240, s[56:57], 0, v240, s[50:51]
	v_addc_co_u32_e64 v239, s[56:57], 0, v239, s[52:53]
	v_addc_co_u32_e64 v240, s[56:57], 0, v240, s[54:55]
	v_cmp_lt_u32_e64 s[48:49], s46, v237
	v_cmp_lt_u32_e64 s[50:51], s46, v238
	v_cmp_lt_u32_e64 s[52:53], s47, v237
	v_cmp_lt_u32_e64 s[54:55], s47, v238
	v_readlane_b32 s46, v237, 41
	v_readlane_b32 s47, v238, 41
	v_addc_co_u32_e64 v239, s[56:57], 0, v239, s[48:49]
	v_addc_co_u32_e64 v240, s[56:57], 0, v240, s[50:51]
	v_addc_co_u32_e64 v239, s[56:57], 0, v239, s[52:53]
	v_addc_co_u32_e64 v240, s[56:57], 0, v240, s[54:55]
	v_cmp_lt_u32_e64 s[48:49], s46, v237
	v_cmp_lt_u32_e64 s[50:51], s46, v238
	v_cmp_lt_u32_e64 s[52:53], s47, v237
	v_cmp_lt_u32_e64 s[54:55], s47, v238
	v_readlane_b32 s46, v237, 42
	v_readlane_b32 s47, v238, 42
	v_addc_co_u32_e64 v239, s[56:57], 0, v239, s[48:49]
	v_addc_co_u32_e64 v240, s[56:57], 0, v240, s[50:51]
	v_addc_co_u32_e64 v239, s[56:57], 0, v239, s[52:53]
	v_addc_co_u32_e64 v240, s[56:57], 0, v240, s[54:55]
	v_cmp_lt_u32_e64 s[48:49], s46, v237
	v_cmp_lt_u32_e64 s[50:51], s46, v238
	v_cmp_lt_u32_e64 s[52:53], s47, v237
	v_cmp_lt_u32_e64 s[54:55], s47, v238
	v_readlane_b32 s46, v237, 43
	v_readlane_b32 s47, v238, 43
	v_addc_co_u32_e64 v239, s[56:57], 0, v239, s[48:49]
	v_addc_co_u32_e64 v240, s[56:57], 0, v240, s[50:51]
	v_addc_co_u32_e64 v239, s[56:57], 0, v239, s[52:53]
	v_addc_co_u32_e64 v240, s[56:57], 0, v240, s[54:55]
	v_cmp_lt_u32_e64 s[48:49], s46, v237
	v_cmp_lt_u32_e64 s[50:51], s46, v238
	v_cmp_lt_u32_e64 s[52:53], s47, v237
	v_cmp_lt_u32_e64 s[54:55], s47, v238
	v_readlane_b32 s46, v237, 44
	v_readlane_b32 s47, v238, 44
	v_addc_co_u32_e64 v239, s[56:57], 0, v239, s[48:49]
	v_addc_co_u32_e64 v240, s[56:57], 0, v240, s[50:51]
	v_addc_co_u32_e64 v239, s[56:57], 0, v239, s[52:53]
	v_addc_co_u32_e64 v240, s[56:57], 0, v240, s[54:55]
	v_cmp_lt_u32_e64 s[48:49], s46, v237
	v_cmp_lt_u32_e64 s[50:51], s46, v238
	v_cmp_lt_u32_e64 s[52:53], s47, v237
	v_cmp_lt_u32_e64 s[54:55], s47, v238
	v_readlane_b32 s46, v237, 45
	v_readlane_b32 s47, v238, 45
	v_addc_co_u32_e64 v239, s[56:57], 0, v239, s[48:49]
	v_addc_co_u32_e64 v240, s[56:57], 0, v240, s[50:51]
	v_addc_co_u32_e64 v239, s[56:57], 0, v239, s[52:53]
	v_addc_co_u32_e64 v240, s[56:57], 0, v240, s[54:55]
	v_cmp_lt_u32_e64 s[48:49], s46, v237
	v_cmp_lt_u32_e64 s[50:51], s46, v238
	v_cmp_lt_u32_e64 s[52:53], s47, v237
	v_cmp_lt_u32_e64 s[54:55], s47, v238
	v_readlane_b32 s46, v237, 46
	v_readlane_b32 s47, v238, 46
	v_addc_co_u32_e64 v239, s[56:57], 0, v239, s[48:49]
	v_addc_co_u32_e64 v240, s[56:57], 0, v240, s[50:51]
	v_addc_co_u32_e64 v239, s[56:57], 0, v239, s[52:53]
	v_addc_co_u32_e64 v240, s[56:57], 0, v240, s[54:55]
	v_cmp_lt_u32_e64 s[48:49], s46, v237
	v_cmp_lt_u32_e64 s[50:51], s46, v238
	v_cmp_lt_u32_e64 s[52:53], s47, v237
	v_cmp_lt_u32_e64 s[54:55], s47, v238
	v_readlane_b32 s46, v237, 47
	v_readlane_b32 s47, v238, 47
	v_addc_co_u32_e64 v239, s[56:57], 0, v239, s[48:49]
	v_addc_co_u32_e64 v240, s[56:57], 0, v240, s[50:51]
	v_addc_co_u32_e64 v239, s[56:57], 0, v239, s[52:53]
	v_addc_co_u32_e64 v240, s[56:57], 0, v240, s[54:55]
	v_cmp_lt_u32_e64 s[48:49], s46, v237
	v_cmp_lt_u32_e64 s[50:51], s46, v238
	v_cmp_lt_u32_e64 s[52:53], s47, v237
	v_cmp_lt_u32_e64 s[54:55], s47, v238
	v_readlane_b32 s46, v237, 48
	v_readlane_b32 s47, v238, 48
	v_addc_co_u32_e64 v239, s[56:57], 0, v239, s[48:49]
	v_addc_co_u32_e64 v240, s[56:57], 0, v240, s[50:51]
	v_addc_co_u32_e64 v239, s[56:57], 0, v239, s[52:53]
	v_addc_co_u32_e64 v240, s[56:57], 0, v240, s[54:55]
	v_cmp_lt_u32_e64 s[48:49], s46, v237
	v_cmp_lt_u32_e64 s[50:51], s46, v238
; DEV void peer_gather_token(const Params& p, int tok) {
;     ...
;   const int e0 = p.eidx[(size_t)tok * 128 + lane], e1 = p.eidx[(size_t)tok * 128 + 64 + lane];
;   const int g0 = __builtin_bit_cast(int, p.gw[(size_t)tok * 128 + lane]), g1 = __builtin_bit_cast(int, p.gw[(size_t)tok * 128 + 64 + lane]);
;   u32x2 dn[4][3], up[4][3];
;   auto issue = [&](int k, int slot) {
;     const int e = (k < 64) ? __builtin_amdgcn_readlane(e0, k) : __builtin_amdgcn_readlane(e1, k - 64);
;     const unsigned char* dr = p.down8 + (size_t)e * ROW6 + lane * 24;
;     const unsigned char* ur = p.up8 + (size_t)e * ROW6 + lane * 24;
; #pragma unroll
;     for (int i = 0; i < 3; ++i) { dn[slot][i] = *(const u32x2*)(dr + i * 8); up[slot][i] = *(const u32x2*)(ur + i * 8); }
;   };
;   issue(0, 0); issue(1, 1); issue(2, 2);
	v_cmp_lt_u32_e64 s[52:53], s47, v237
	v_cmp_lt_u32_e64 s[54:55], s47, v238
	v_readlane_b32 s46, v237, 49
	v_readlane_b32 s47, v238, 49
	v_addc_co_u32_e64 v239, s[56:57], 0, v239, s[48:49]
	v_addc_co_u32_e64 v240, s[56:57], 0, v240, s[50:51]
	v_addc_co_u32_e64 v239, s[56:57], 0, v239, s[52:53]
	v_addc_co_u32_e64 v240, s[56:57], 0, v240, s[54:55]
	v_cmp_lt_u32_e64 s[48:49], s46, v237
	v_cmp_lt_u32_e64 s[50:51], s46, v238
	v_cmp_lt_u32_e64 s[52:53], s47, v237
	v_cmp_lt_u32_e64 s[54:55], s47, v238
	v_readlane_b32 s46, v237, 50
	v_readlane_b32 s47, v238, 50
	v_addc_co_u32_e64 v239, s[56:57], 0, v239, s[48:49]
	v_addc_co_u32_e64 v240, s[56:57], 0, v240, s[50:51]
	v_addc_co_u32_e64 v239, s[56:57], 0, v239, s[52:53]
	v_addc_co_u32_e64 v240, s[56:57], 0, v240, s[54:55]
	v_cmp_lt_u32_e64 s[48:49], s46, v237
	v_cmp_lt_u32_e64 s[50:51], s46, v238
	v_cmp_lt_u32_e64 s[52:53], s47, v237
	v_cmp_lt_u32_e64 s[54:55], s47, v238
	v_readlane_b32 s46, v237, 51
	v_readlane_b32 s47, v238, 51
	v_addc_co_u32_e64 v239, s[56:57], 0, v239, s[48:49]
	v_addc_co_u32_e64 v240, s[56:57], 0, v240, s[50:51]
	v_addc_co_u32_e64 v239, s[56:57], 0, v239, s[52:53]
	v_addc_co_u32_e64 v240, s[56:57], 0, v240, s[54:55]
	v_cmp_lt_u32_e64 s[48:49], s46, v237
	v_cmp_lt_u32_e64 s[50:51], s46, v238
	v_cmp_lt_u32_e64 s[52:53], s47, v237
	v_cmp_lt_u32_e64 s[54:55], s47, v238
	v_readlane_b32 s46, v237, 52
	v_readlane_b32 s47, v238, 52
	v_addc_co_u32_e64 v239, s[56:57], 0, v239, s[48:49]
	v_addc_co_u32_e64 v240, s[56:57], 0, v240, s[50:51]
	v_addc_co_u32_e64 v239, s[56:57], 0, v239, s[52:53]
	v_addc_co_u32_e64 v240, s[56:57], 0, v240, s[54:55]
	v_cmp_lt_u32_e64 s[48:49], s46, v237
	v_cmp_lt_u32_e64 s[50:51], s46, v238
	v_cmp_lt_u32_e64 s[52:53], s47, v237
	v_cmp_lt_u32_e64 s[54:55], s47, v238
	v_readlane_b32 s46, v237, 53
	v_readlane_b32 s47, v238, 53
	v_addc_co_u32_e64 v239, s[56:57], 0, v239, s[48:49]
	v_addc_co_u32_e64 v240, s[56:57], 0, v240, s[50:51]
	v_addc_co_u32_e64 v239, s[56:57], 0, v239, s[52:53]
	v_addc_co_u32_e64 v240, s[56:57], 0, v240, s[54:55]
	v_cmp_lt_u32_e64 s[48:49], s46, v237
	v_cmp_lt_u32_e64 s[50:51], s46, v238
	v_cmp_lt_u32_e64 s[52:53], s47, v237
	v_cmp_lt_u32_e64 s[54:55], s47, v238
	v_readlane_b32 s46, v237, 54
	v_readlane_b32 s47, v238, 54
	v_addc_co_u32_e64 v239, s[56:57], 0, v239, s[48:49]
	v_addc_co_u32_e64 v240, s[56:57], 0, v240, s[50:51]
	v_addc_co_u32_e64 v239, s[56:57], 0, v239, s[52:53]
	v_addc_co_u32_e64 v240, s[56:57], 0, v240, s[54:55]
	v_cmp_lt_u32_e64 s[48:49], s46, v237
	v_cmp_lt_u32_e64 s[50:51], s46, v238
	v_cmp_lt_u32_e64 s[52:53], s47, v237
	v_cmp_lt_u32_e64 s[54:55], s47, v238
	v_readlane_b32 s46, v237, 55
	v_readlane_b32 s47, v238, 55
	v_addc_co_u32_e64 v239, s[56:57], 0, v239, s[48:49]
	v_addc_co_u32_e64 v240, s[56:57], 0, v240, s[50:51]
	v_addc_co_u32_e64 v239, s[56:57], 0, v239, s[52:53]
	v_addc_co_u32_e64 v240, s[56:57], 0, v240, s[54:55]
	v_cmp_lt_u32_e64 s[48:49], s46, v237
	v_cmp_lt_u32_e64 s[50:51], s46, v238
	v_cmp_lt_u32_e64 s[52:53], s47, v237
	v_cmp_lt_u32_e64 s[54:55], s47, v238
	v_readlane_b32 s46, v237, 56
	v_readlane_b32 s47, v238, 56
	v_addc_co_u32_e64 v239, s[56:57], 0, v239, s[48:49]
	v_addc_co_u32_e64 v240, s[56:57], 0, v240, s[50:51]
	v_addc_co_u32_e64 v239, s[56:57], 0, v239, s[52:53]
	v_addc_co_u32_e64 v240, s[56:57], 0, v240, s[54:55]
	v_cmp_lt_u32_e64 s[48:49], s46, v237
	v_cmp_lt_u32_e64 s[50:51], s46, v238
	v_cmp_lt_u32_e64 s[52:53], s47, v237
	v_cmp_lt_u32_e64 s[54:55], s47, v238
	v_readlane_b32 s46, v237, 57
	v_readlane_b32 s47, v238, 57
	v_addc_co_u32_e64 v239, s[56:57], 0, v239, s[48:49]
	v_addc_co_u32_e64 v240, s[56:57], 0, v240, s[50:51]
	v_addc_co_u32_e64 v239, s[56:57], 0, v239, s[52:53]
	v_addc_co_u32_e64 v240, s[56:57], 0, v240, s[54:55]
	v_cmp_lt_u32_e64 s[48:49], s46, v237
	v_cmp_lt_u32_e64 s[50:51], s46, v238
	v_cmp_lt_u32_e64 s[52:53], s47, v237
	v_cmp_lt_u32_e64 s[54:55], s47, v238
	v_readlane_b32 s46, v237, 58
	v_readlane_b32 s47, v238, 58
	v_addc_co_u32_e64 v239, s[56:57], 0, v239, s[48:49]
	v_addc_co_u32_e64 v240, s[56:57], 0, v240, s[50:51]
	v_addc_co_u32_e64 v239, s[56:57], 0, v239, s[52:53]
	v_addc_co_u32_e64 v240, s[56:57], 0, v240, s[54:55]
	v_cmp_lt_u32_e64 s[48:49], s46, v237
	v_cmp_lt_u32_e64 s[50:51], s46, v238
	v_cmp_lt_u32_e64 s[52:53], s47, v237
	v_cmp_lt_u32_e64 s[54:55], s47, v238
	v_readlane_b32 s46, v237, 59
	v_readlane_b32 s47, v238, 59
	v_addc_co_u32_e64 v239, s[56:57], 0, v239, s[48:49]
	v_addc_co_u32_e64 v240, s[56:57], 0, v240, s[50:51]
	v_addc_co_u32_e64 v239, s[56:57], 0, v239, s[52:53]
	v_addc_co_u32_e64 v240, s[56:57], 0, v240, s[54:55]
	v_cmp_lt_u32_e64 s[48:49], s46, v237
	v_cmp_lt_u32_e64 s[50:51], s46, v238
	v_cmp_lt_u32_e64 s[52:53], s47, v237
	v_cmp_lt_u32_e64 s[54:55], s47, v238
	v_readlane_b32 s46, v237, 60
	v_readlane_b32 s47, v238, 60
	v_addc_co_u32_e64 v239, s[56:57], 0, v239, s[48:49]
	v_addc_co_u32_e64 v240, s[56:57], 0, v240, s[50:51]
	v_addc_co_u32_e64 v239, s[56:57], 0, v239, s[52:53]
	v_addc_co_u32_e64 v240, s[56:57], 0, v240, s[54:55]
	v_cmp_lt_u32_e64 s[48:49], s46, v237
	v_cmp_lt_u32_e64 s[50:51], s46, v238
	v_cmp_lt_u32_e64 s[52:53], s47, v237
	v_cmp_lt_u32_e64 s[54:55], s47, v238
	v_readlane_b32 s46, v237, 61
	v_readlane_b32 s47, v238, 61
	v_addc_co_u32_e64 v239, s[56:57], 0, v239, s[48:49]
	v_addc_co_u32_e64 v240, s[56:57], 0, v240, s[50:51]
	v_addc_co_u32_e64 v239, s[56:57], 0, v239, s[52:53]
	v_addc_co_u32_e64 v240, s[56:57], 0, v240, s[54:55]
	v_cmp_lt_u32_e64 s[48:49], s46, v237
	v_cmp_lt_u32_e64 s[50:51], s46, v238
	v_cmp_lt_u32_e64 s[52:53], s47, v237
	v_cmp_lt_u32_e64 s[54:55], s47, v238
	v_readlane_b32 s46, v237, 62
	v_readlane_b32 s47, v238, 62
	v_addc_co_u32_e64 v239, s[56:57], 0, v239, s[48:49]
	v_addc_co_u32_e64 v240, s[56:57], 0, v240, s[50:51]
	v_addc_co_u32_e64 v239, s[56:57], 0, v239, s[52:53]
	v_addc_co_u32_e64 v240, s[56:57], 0, v240, s[54:55]
	v_cmp_lt_u32_e64 s[48:49], s46, v237
	v_cmp_lt_u32_e64 s[50:51], s46, v238
	v_cmp_lt_u32_e64 s[52:53], s47, v237
	v_cmp_lt_u32_e64 s[54:55], s47, v238
	v_readlane_b32 s46, v237, 63
	v_readlane_b32 s47, v238, 63
	v_addc_co_u32_e64 v239, s[56:57], 0, v239, s[48:49]
	v_addc_co_u32_e64 v240, s[56:57], 0, v240, s[50:51]
	v_addc_co_u32_e64 v239, s[56:57], 0, v239, s[52:53]
	v_addc_co_u32_e64 v240, s[56:57], 0, v240, s[54:55]
	v_cmp_lt_u32_e64 s[48:49], s46, v237
	v_cmp_lt_u32_e64 s[50:51], s46, v238
	v_cmp_lt_u32_e64 s[52:53], s47, v237
	v_cmp_lt_u32_e64 s[54:55], s47, v238
	s_nop 1
	v_addc_co_u32_e64 v239, s[56:57], 0, v239, s[48:49]
	v_addc_co_u32_e64 v240, s[56:57], 0, v240, s[50:51]
	v_addc_co_u32_e64 v239, s[56:57], 0, v239, s[52:53]
	v_addc_co_u32_e64 v240, s[56:57], 0, v240, s[54:55]
	v_and_b32_e32 v237, 0xfffffc00, v241
	v_lshl_add_u32 v239, v239, 2, v237
	v_lshl_add_u32 v240, v240, 2, v237
	ds_write_b32 v239, v216
	ds_write_b32 v240, v217
	ds_write_b32 v239, v218 offset:512
	ds_write_b32 v240, v219 offset:512
	s_waitcnt lgkmcnt(0)
; DEV float gelu_exact(float v) { return 0.5f * v * (1.f + erff(v * 0.7071067811865476f)); }
; DEV void peer_gather_token(const Params& p, int tok) {
;     ...
;   for (int k4 = 0; k4 < 128; k4 += 4) {
; #pragma unroll
;     for (int s = 0; s < 4; ++s) {
;       const int k = k4 + s;
;       if (k + 3 < 128) issue(k + 3, (s + 3) & 3);
;       const v6u dq = v6u{dn[s][0][0], dn[s][0][1], dn[s][1][0], dn[s][1][1], dn[s][2][0], dn[s][2][1]};
;       const v32f dv = __builtin_amdgcn_cvt_scalef32_pk32_f32_fp6(dq, 1.0f);
;       float d0 = 0.f, d1 = 0.f, d2 = 0.f, d3 = 0.f;
; #pragma unroll
;       for (int i = 0; i < 8; ++i) { d0 += dv[4 * i] * hx[4 * i]; d1 += dv[4 * i + 1] * hx[4 * i + 1]; d2 += dv[4 * i + 2] * hx[4 * i + 2]; d3 += dv[4 * i + 3] * hx[4 * i + 3]; }
;       const float d = wave_sum_fast((d0 + d1) + (d2 + d3)) * (1.f / DOWN_SCALE);
;       const float gk = __builtin_bit_cast(float, (k < 64) ? __builtin_amdgcn_readlane(g0, k) : __builtin_amdgcn_readlane(g1, k - 64));
;       const float act = gelu_exact(d) * gk * (1.f / UP_SCALE);
;       const v6u uq = v6u{up[s][0][0], up[s][0][1], up[s][1][0], up[s][1][1], up[s][2][0], up[s][2][1]};
	ds_read_b32 v216, v241
	ds_read_b32 v217, v241 offset:256
	ds_read_b32 v218, v241 offset:512
	ds_read_b32 v219, v241 offset:768
	s_waitcnt lgkmcnt(0)
	s_branch .Lp12_switch
.Lp12_token:
.Lp12_main:
	s_cmp_eq_u32 s22, 7
	s_cbranch_scc0 .Lp12_ne7
	v_mov_b32_e32 v198, v195
.Lp12_ne7:
	s_cmp_eq_u32 s22, 8
	s_cbranch_scc0 .Lp12_ne8
	v_mov_b32_e32 v199, v197
.Lp12_ne8:
	s_waitcnt vmcnt(21)
	v_cvt_scalef32_pk32_f32_fp6 v[2:33], v[98:103], 1.0
	v_mul_f32_e32 v200, v2, v34
	v_mul_f32_e32 v201, v3, v35
	v_mul_f32_e32 v202, v4, v36
	v_mul_f32_e32 v203, v5, v37
	v_fmac_f32_e32 v200, v6, v38
	v_fmac_f32_e32 v201, v7, v39
	v_fmac_f32_e32 v202, v8, v40
	v_fmac_f32_e32 v203, v9, v41
	v_fmac_f32_e32 v200, v10, v42
	v_fmac_f32_e32 v201, v11, v43
	v_fmac_f32_e32 v202, v12, v44
	v_fmac_f32_e32 v203, v13, v45
	v_fmac_f32_e32 v200, v14, v46
	v_fmac_f32_e32 v201, v15, v47
	v_fmac_f32_e32 v202, v16, v48
	v_fmac_f32_e32 v203, v17, v49
	v_fmac_f32_e32 v200, v18, v50
	v_fmac_f32_e32 v201, v19, v51
	v_fmac_f32_e32 v202, v20, v52
	v_fmac_f32_e32 v203, v21, v53
	v_fmac_f32_e32 v200, v22, v54
	v_fmac_f32_e32 v201, v23, v55
	v_fmac_f32_e32 v202, v24, v56
	v_fmac_f32_e32 v203, v25, v57
	v_fmac_f32_e32 v200, v26, v58
	v_fmac_f32_e32 v201, v27, v59
	v_fmac_f32_e32 v202, v28, v60
	v_fmac_f32_e32 v203, v29, v61
	v_fmac_f32_e32 v200, v30, v62
	v_fmac_f32_e32 v201, v31, v63
	v_fmac_f32_e32 v202, v32, v64
	v_fmac_f32_e32 v203, v33, v65
	v_add_f32_e32 v200, v201, v200
	v_add_f32_e32 v202, v203, v202
	v_cvt_scalef32_pk32_f32_fp6 v[2:33], v[104:109], 1.0
	v_add_f32_e32 v200, v202, v200
	s_add_i32 s38, s24, 0
	v_readlane_b32 s26, v199, s38
	s_add_i32 s39, s23, 0
	v_readlane_b32 s25, v198, s39
	v_add_f32_dpp v200, v200, v200 quad_perm:[1,0,3,2] row_mask:0xf bank_mask:0xf bound_ctrl:1
	s_nop 1
	v_add_f32_dpp v200, v200, v200 quad_perm:[2,3,0,1] row_mask:0xf bank_mask:0xf bound_ctrl:1
	s_nop 1
	v_add_f32_dpp v200, v200, v200 row_half_mirror row_mask:0xf bank_mask:0xf bound_ctrl:1
	s_nop 1
	v_add_f32_dpp v200, v200, v200 row_mirror row_mask:0xf bank_mask:0xf bound_ctrl:1
	s_nop 1
	v_add_f32_dpp v200, v200, v200 row_bcast:15 row_mask:0xa bank_mask:0xf
	s_nop 1
	v_add_f32_dpp v200, v200, v200 row_bcast:31 row_mask:0xc bank_mask:0xf
	s_nop 0
	v_readlane_b32 s27, v200, 63
	s_mul_i32 s40, s25, 0xc00
	s_add_u32 s28, s62, s40
	s_addc_u32 s29, s63, 0
	global_load_dwordx4 v[98:101], v1, s[28:29]
	global_load_dwordx4 v[102:105], v1, s[28:29] offset:2048
	global_load_dwordx4 v[106:109], v1, s[28:29] offset:1024
	v_mul_f32_e32 v204, s27, v212
	v_mul_f32_e32 v205, 0x3f3504f3, v204
	v_cmp_lt_f32_e64 s[32:33], |v205|, 1.0
	s_and_b64 vcc, exec, s[32:33]
	s_cbranch_vccnz .Lsm_1
	v_fma_f32 v208, |v205|, s9, v214
	v_fma_f32 v208, |v205|, v208, s10
	v_fma_f32 v208, |v205|, v208, s11
	v_fma_f32 v208, |v205|, v208, s12
	v_fma_f32 v208, |v205|, v208, s13
	v_fma_f32 v208, |v205|, v208, s14
	v_fma_f32 v208, |v205|, v208, |v205|
	v_mul_f32_e32 v209, 0xbfb8aa3b, v208
	v_fma_f32 v210, v208, s15, -v209
	v_rndne_f32_e32 v211, v209
	v_fmac_f32_e32 v210, 0xb2a5705f, v208
	v_sub_f32_e32 v209, v209, v211
	v_add_f32_e32 v209, v209, v210
	v_cvt_i32_f32_e32 v210, v211
	v_exp_f32_e32 v209, v209
	v_cmp_nlt_f32_e32 vcc, s16, v208
	v_ldexp_f32 v209, v209, v210
	s_nop 0
	v_cndmask_b32_e32 v209, 0, v209, vcc
	v_cmp_ngt_f32_e32 vcc, s17, v208
	s_nop 1
	v_cndmask_b32_e32 v208, v215, v209, vcc
	v_sub_f32_e32 v210, 1.0, v208
	s_branch .Ljn_1
.Lsm_1:
	v_mul_f32_e32 v208, v205, v205
	v_fmamk_f32 v209, v208, 0xba1345e1, v213
	v_fmaak_f32 v209, v208, v209, 0xbcdac9b8
	v_fmaak_f32 v209, v208, v209, 0x3de703be
	v_fmaak_f32 v209, v208, v209, 0xbec09330
	v_fmaak_f32 v208, v208, v209, 0x3e0375d0
	v_fma_f32 v210, |v205|, v208, |v205|
; DEV float gelu_exact(float v) { return 0.5f * v * (1.f + erff(v * 0.7071067811865476f)); }
; DEV void peer_gather_token(const Params& p, int tok) {
;     ...
;       const float d = wave_sum_fast((d0 + d1) + (d2 + d3)) * (1.f / DOWN_SCALE);
;       const float gk = __builtin_bit_cast(float, (k < 64) ? __builtin_amdgcn_readlane(g0, k) : __builtin_amdgcn_readlane(g1, k - 64));
;       const float act = gelu_exact(d) * gk * (1.f / UP_SCALE);
;       const v6u uq = v6u{up[s][0][0], up[s][0][1], up[s][1][0], up[s][1][1], up[s][2][0], up[s][2][1]};
;       const v32f uv = __builtin_amdgcn_cvt_scalef32_pk32_f32_fp6(uq, 1.0f);
; #pragma unroll
;       for (int i = 0; i < 32; ++i) acc[i] += act * uv[i];
.Ljn_1:
	v_bfi_b32 v209, s18, v210, v205
	v_mul_f32_e32 v208, 0.5, v204
	v_add_f32_e32 v209, 1.0, v209
	v_mul_f32_e32 v208, v208, v209
	v_mul_f32_e32 v208, s26, v208
	v_mul_f32_e32 v206, 0x3e800000, v208
	v_pk_fma_f32 v[66:67], v[2:3], v[206:207], v[66:67] op_sel_hi:[1,0,1]
	v_pk_fma_f32 v[68:69], v[4:5], v[206:207], v[68:69] op_sel_hi:[1,0,1]
	v_pk_fma_f32 v[70:71], v[6:7], v[206:207], v[70:71] op_sel_hi:[1,0,1]
	v_pk_fma_f32 v[72:73], v[8:9], v[206:207], v[72:73] op_sel_hi:[1,0,1]
	v_pk_fma_f32 v[74:75], v[10:11], v[206:207], v[74:75] op_sel_hi:[1,0,1]
	v_pk_fma_f32 v[76:77], v[12:13], v[206:207], v[76:77] op_sel_hi:[1,0,1]
	v_pk_fma_f32 v[78:79], v[14:15], v[206:207], v[78:79] op_sel_hi:[1,0,1]
	v_pk_fma_f32 v[80:81], v[16:17], v[206:207], v[80:81] op_sel_hi:[1,0,1]
	v_pk_fma_f32 v[82:83], v[18:19], v[206:207], v[82:83] op_sel_hi:[1,0,1]
	v_pk_fma_f32 v[84:85], v[20:21], v[206:207], v[84:85] op_sel_hi:[1,0,1]
	v_pk_fma_f32 v[86:87], v[22:23], v[206:207], v[86:87] op_sel_hi:[1,0,1]
	v_pk_fma_f32 v[88:89], v[24:25], v[206:207], v[88:89] op_sel_hi:[1,0,1]
	v_pk_fma_f32 v[90:91], v[26:27], v[206:207], v[90:91] op_sel_hi:[1,0,1]
	v_pk_fma_f32 v[92:93], v[28:29], v[206:207], v[92:93] op_sel_hi:[1,0,1]
	v_pk_fma_f32 v[94:95], v[30:31], v[206:207], v[94:95] op_sel_hi:[1,0,1]
	v_pk_fma_f32 v[96:97], v[32:33], v[206:207], v[96:97] op_sel_hi:[1,0,1]
	s_waitcnt vmcnt(21)
	v_cvt_scalef32_pk32_f32_fp6 v[2:33], v[110:115], 1.0
	v_mul_f32_e32 v200, v2, v34
	v_mul_f32_e32 v201, v3, v35
	v_mul_f32_e32 v202, v4, v36
	v_mul_f32_e32 v203, v5, v37
	v_fmac_f32_e32 v200, v6, v38
	v_fmac_f32_e32 v201, v7, v39
	v_fmac_f32_e32 v202, v8, v40
	v_fmac_f32_e32 v203, v9, v41
	v_fmac_f32_e32 v200, v10, v42
	v_fmac_f32_e32 v201, v11, v43
	v_fmac_f32_e32 v202, v12, v44
	v_fmac_f32_e32 v203, v13, v45
	v_fmac_f32_e32 v200, v14, v46
	v_fmac_f32_e32 v201, v15, v47
	v_fmac_f32_e32 v202, v16, v48
	v_fmac_f32_e32 v203, v17, v49
	v_fmac_f32_e32 v200, v18, v50
	v_fmac_f32_e32 v201, v19, v51
	v_fmac_f32_e32 v202, v20, v52
	v_fmac_f32_e32 v203, v21, v53
	v_fmac_f32_e32 v200, v22, v54
	v_fmac_f32_e32 v201, v23, v55
	v_fmac_f32_e32 v202, v24, v56
	v_fmac_f32_e32 v203, v25, v57
	v_fmac_f32_e32 v200, v26, v58
	v_fmac_f32_e32 v201, v27, v59
	v_fmac_f32_e32 v202, v28, v60
	v_fmac_f32_e32 v203, v29, v61
	v_fmac_f32_e32 v200, v30, v62
	v_fmac_f32_e32 v201, v31, v63
	v_fmac_f32_e32 v202, v32, v64
	v_fmac_f32_e32 v203, v33, v65
	v_add_f32_e32 v200, v201, v200
	v_add_f32_e32 v202, v203, v202
	v_cvt_scalef32_pk32_f32_fp6 v[2:33], v[116:121], 1.0
	v_add_f32_e32 v200, v202, v200
	s_add_i32 s38, s24, 1
	v_readlane_b32 s26, v199, s38
	s_add_i32 s39, s23, 1
	v_readlane_b32 s25, v198, s39
	v_add_f32_dpp v200, v200, v200 quad_perm:[1,0,3,2] row_mask:0xf bank_mask:0xf bound_ctrl:1
	s_nop 1
	v_add_f32_dpp v200, v200, v200 quad_perm:[2,3,0,1] row_mask:0xf bank_mask:0xf bound_ctrl:1
	s_nop 1
	v_add_f32_dpp v200, v200, v200 row_half_mirror row_mask:0xf bank_mask:0xf bound_ctrl:1
	s_nop 1
	v_add_f32_dpp v200, v200, v200 row_mirror row_mask:0xf bank_mask:0xf bound_ctrl:1
	s_nop 1
	v_add_f32_dpp v200, v200, v200 row_bcast:15 row_mask:0xa bank_mask:0xf
	s_nop 1
	v_add_f32_dpp v200, v200, v200 row_bcast:31 row_mask:0xc bank_mask:0xf
	s_nop 0
	v_readlane_b32 s27, v200, 63
	s_mul_i32 s40, s25, 0xc00
	s_add_u32 s28, s62, s40
	s_addc_u32 s29, s63, 0
	global_load_dwordx4 v[110:113], v1, s[28:29]
	global_load_dwordx4 v[114:117], v1, s[28:29] offset:2048
	global_load_dwordx4 v[118:121], v1, s[28:29] offset:1024
	v_mul_f32_e32 v204, s27, v212
	v_mul_f32_e32 v205, 0x3f3504f3, v204
	v_cmp_lt_f32_e64 s[32:33], |v205|, 1.0
	s_and_b64 vcc, exec, s[32:33]
	s_cbranch_vccnz .Lsm_3
	v_fma_f32 v208, |v205|, s9, v214
	v_fma_f32 v208, |v205|, v208, s10
	v_fma_f32 v208, |v205|, v208, s11
	v_fma_f32 v208, |v205|, v208, s12
	v_fma_f32 v208, |v205|, v208, s13
	v_fma_f32 v208, |v205|, v208, s14
	v_fma_f32 v208, |v205|, v208, |v205|
	v_mul_f32_e32 v209, 0xbfb8aa3b, v208
	v_fma_f32 v210, v208, s15, -v209
	v_rndne_f32_e32 v211, v209
	v_fmac_f32_e32 v210, 0xb2a5705f, v208
	v_sub_f32_e32 v209, v209, v211
	v_add_f32_e32 v209, v209, v210
	v_cvt_i32_f32_e32 v210, v211
	v_exp_f32_e32 v209, v209
	v_cmp_nlt_f32_e32 vcc, s16, v208
	v_ldexp_f32 v209, v209, v210
	s_nop 0
	v_cndmask_b32_e32 v209, 0, v209, vcc
	v_cmp_ngt_f32_e32 vcc, s17, v208
	s_nop 1
	v_cndmask_b32_e32 v208, v215, v209, vcc
	v_sub_f32_e32 v210, 1.0, v208
	s_branch .Ljn_3

; DEV float gelu_exact(float v) { return 0.5f * v * (1.f + erff(v * 0.7071067811865476f)); }
; DEV void peer_gather_token(const Params& p, int tok) {
;     ...
;       if (k + 3 < 128) issue(k + 3, (s + 3) & 3);
;       const v6u dq = v6u{dn[s][0][0], dn[s][0][1], dn[s][1][0], dn[s][1][1], dn[s][2][0], dn[s][2][1]};
;       const v32f dv = __builtin_amdgcn_cvt_scalef32_pk32_f32_fp6(dq, 1.0f);
;       float d0 = 0.f, d1 = 0.f, d2 = 0.f, d3 = 0.f;
; #pragma unroll
;       for (int i = 0; i < 8; ++i) { d0 += dv[4 * i] * hx[4 * i]; d1 += dv[4 * i + 1] * hx[4 * i + 1]; d2 += dv[4 * i + 2] * hx[4 * i + 2]; d3 += dv[4 * i + 3] * hx[4 * i + 3]; }
;       const float d = wave_sum_fast((d0 + d1) + (d2 + d3)) * (1.f / DOWN_SCALE);
;       const float gk = __builtin_bit_cast(float, (k < 64) ? __builtin_amdgcn_readlane(g0, k) : __builtin_amdgcn_readlane(g1, k - 64));
;       const float act = gelu_exact(d) * gk * (1.f / UP_SCALE);
;       const v6u uq = v6u{up[s][0][0], up[s][0][1], up[s][1][0], up[s][1][1], up[s][2][0], up[s][2][1]};
;       const v32f uv = __builtin_amdgcn_cvt_scalef32_pk32_f32_fp6(uq, 1.0f);
; #pragma unroll
;       for (int i = 0; i < 32; ++i) acc[i] += act * uv[i];
.Ljn_3:
	v_bfi_b32 v209, s18, v210, v205
	v_mul_f32_e32 v208, 0.5, v204
	v_add_f32_e32 v209, 1.0, v209
	v_mul_f32_e32 v208, v208, v209
	v_mul_f32_e32 v208, s26, v208
	v_mul_f32_e32 v206, 0x3e800000, v208
	v_pk_fma_f32 v[66:67], v[2:3], v[206:207], v[66:67] op_sel_hi:[1,0,1]
	v_pk_fma_f32 v[68:69], v[4:5], v[206:207], v[68:69] op_sel_hi:[1,0,1]
	v_pk_fma_f32 v[70:71], v[6:7], v[206:207], v[70:71] op_sel_hi:[1,0,1]
	v_pk_fma_f32 v[72:73], v[8:9], v[206:207], v[72:73] op_sel_hi:[1,0,1]
	v_pk_fma_f32 v[74:75], v[10:11], v[206:207], v[74:75] op_sel_hi:[1,0,1]
	v_pk_fma_f32 v[76:77], v[12:13], v[206:207], v[76:77] op_sel_hi:[1,0,1]
	v_pk_fma_f32 v[78:79], v[14:15], v[206:207], v[78:79] op_sel_hi:[1,0,1]
	v_pk_fma_f32 v[80:81], v[16:17], v[206:207], v[80:81] op_sel_hi:[1,0,1]
	v_pk_fma_f32 v[82:83], v[18:19], v[206:207], v[82:83] op_sel_hi:[1,0,1]
	v_pk_fma_f32 v[84:85], v[20:21], v[206:207], v[84:85] op_sel_hi:[1,0,1]
	v_pk_fma_f32 v[86:87], v[22:23], v[206:207], v[86:87] op_sel_hi:[1,0,1]
	v_pk_fma_f32 v[88:89], v[24:25], v[206:207], v[88:89] op_sel_hi:[1,0,1]
	v_pk_fma_f32 v[90:91], v[26:27], v[206:207], v[90:91] op_sel_hi:[1,0,1]
	v_pk_fma_f32 v[92:93], v[28:29], v[206:207], v[92:93] op_sel_hi:[1,0,1]
	v_pk_fma_f32 v[94:95], v[30:31], v[206:207], v[94:95] op_sel_hi:[1,0,1]
	v_pk_fma_f32 v[96:97], v[32:33], v[206:207], v[96:97] op_sel_hi:[1,0,1]
	s_waitcnt vmcnt(21)
	v_cvt_scalef32_pk32_f32_fp6 v[2:33], v[122:127], 1.0
	v_mul_f32_e32 v200, v2, v34
	v_mul_f32_e32 v201, v3, v35
	v_mul_f32_e32 v202, v4, v36
	v_mul_f32_e32 v203, v5, v37
	v_fmac_f32_e32 v200, v6, v38
	v_fmac_f32_e32 v201, v7, v39
	v_fmac_f32_e32 v202, v8, v40
	v_fmac_f32_e32 v203, v9, v41
	v_fmac_f32_e32 v200, v10, v42
	v_fmac_f32_e32 v201, v11, v43
	v_fmac_f32_e32 v202, v12, v44
	v_fmac_f32_e32 v203, v13, v45
	v_fmac_f32_e32 v200, v14, v46
	v_fmac_f32_e32 v201, v15, v47
	v_fmac_f32_e32 v202, v16, v48
	v_fmac_f32_e32 v203, v17, v49
	v_fmac_f32_e32 v200, v18, v50
	v_fmac_f32_e32 v201, v19, v51
	v_fmac_f32_e32 v202, v20, v52
	v_fmac_f32_e32 v203, v21, v53
	v_fmac_f32_e32 v200, v22, v54
	v_fmac_f32_e32 v201, v23, v55
	v_fmac_f32_e32 v202, v24, v56
	v_fmac_f32_e32 v203, v25, v57
	v_fmac_f32_e32 v200, v26, v58
	v_fmac_f32_e32 v201, v27, v59
	v_fmac_f32_e32 v202, v28, v60
	v_fmac_f32_e32 v203, v29, v61
	v_fmac_f32_e32 v200, v30, v62
	v_fmac_f32_e32 v201, v31, v63
	v_fmac_f32_e32 v202, v32, v64
	v_fmac_f32_e32 v203, v33, v65
	v_add_f32_e32 v200, v201, v200
	v_add_f32_e32 v202, v203, v202
	v_cvt_scalef32_pk32_f32_fp6 v[2:33], v[128:133], 1.0
	v_add_f32_e32 v200, v202, v200
	s_add_i32 s38, s24, 2
	v_readlane_b32 s26, v199, s38
	s_add_i32 s39, s23, 2
	v_readlane_b32 s25, v198, s39
	v_add_f32_dpp v200, v200, v200 quad_perm:[1,0,3,2] row_mask:0xf bank_mask:0xf bound_ctrl:1
	s_nop 1
	v_add_f32_dpp v200, v200, v200 quad_perm:[2,3,0,1] row_mask:0xf bank_mask:0xf bound_ctrl:1
	s_nop 1
	v_add_f32_dpp v200, v200, v200 row_half_mirror row_mask:0xf bank_mask:0xf bound_ctrl:1
	s_nop 1
	v_add_f32_dpp v200, v200, v200 row_mirror row_mask:0xf bank_mask:0xf bound_ctrl:1
	s_nop 1
	v_add_f32_dpp v200, v200, v200 row_bcast:15 row_mask:0xa bank_mask:0xf
	s_nop 1
	v_add_f32_dpp v200, v200, v200 row_bcast:31 row_mask:0xc bank_mask:0xf
	s_nop 0
	v_readlane_b32 s27, v200, 63
	s_mul_i32 s40, s25, 0xc00
	s_add_u32 s28, s62, s40
	s_addc_u32 s29, s63, 0
	global_load_dwordx4 v[122:125], v1, s[28:29]
	global_load_dwordx4 v[126:129], v1, s[28:29] offset:2048
	global_load_dwordx4 v[130:133], v1, s[28:29] offset:1024
	v_mul_f32_e32 v204, s27, v212
	v_mul_f32_e32 v205, 0x3f3504f3, v204
	v_cmp_lt_f32_e64 s[32:33], |v205|, 1.0
	s_and_b64 vcc, exec, s[32:33]
	s_cbranch_vccnz .Lsm_5
	v_fma_f32 v208, |v205|, s9, v214
	v_fma_f32 v208, |v205|, v208, s10
	v_fma_f32 v208, |v205|, v208, s11
	v_fma_f32 v208, |v205|, v208, s12
	v_fma_f32 v208, |v205|, v208, s13
	v_fma_f32 v208, |v205|, v208, s14
	v_fma_f32 v208, |v205|, v208, |v205|
	v_mul_f32_e32 v209, 0xbfb8aa3b, v208
	v_fma_f32 v210, v208, s15, -v209
	v_rndne_f32_e32 v211, v209
	v_fmac_f32_e32 v210, 0xb2a5705f, v208
	v_sub_f32_e32 v209, v209, v211
	v_add_f32_e32 v209, v209, v210
	v_cvt_i32_f32_e32 v210, v211
	v_exp_f32_e32 v209, v209
	v_cmp_nlt_f32_e32 vcc, s16, v208
	v_ldexp_f32 v209, v209, v210
	s_nop 0
	v_cndmask_b32_e32 v209, 0, v209, vcc
	v_cmp_ngt_f32_e32 vcc, s17, v208
	s_nop 1
	v_cndmask_b32_e32 v208, v215, v209, vcc
	v_sub_f32_e32 v210, 1.0, v208
	s_branch .Ljn_5

; DEV float gelu_exact(float v) { return 0.5f * v * (1.f + erff(v * 0.7071067811865476f)); }
; DEV void peer_gather_token(const Params& p, int tok) {
;     ...
;       if (k + 3 < 128) issue(k + 3, (s + 3) & 3);
;       const v6u dq = v6u{dn[s][0][0], dn[s][0][1], dn[s][1][0], dn[s][1][1], dn[s][2][0], dn[s][2][1]};
;       const v32f dv = __builtin_amdgcn_cvt_scalef32_pk32_f32_fp6(dq, 1.0f);
;       float d0 = 0.f, d1 = 0.f, d2 = 0.f, d3 = 0.f;
; #pragma unroll
;       for (int i = 0; i < 8; ++i) { d0 += dv[4 * i] * hx[4 * i]; d1 += dv[4 * i + 1] * hx[4 * i + 1]; d2 += dv[4 * i + 2] * hx[4 * i + 2]; d3 += dv[4 * i + 3] * hx[4 * i + 3]; }
;       const float d = wave_sum_fast((d0 + d1) + (d2 + d3)) * (1.f / DOWN_SCALE);
;       const float gk = __builtin_bit_cast(float, (k < 64) ? __builtin_amdgcn_readlane(g0, k) : __builtin_amdgcn_readlane(g1, k - 64));
;       const float act = gelu_exact(d) * gk * (1.f / UP_SCALE);
;       const v6u uq = v6u{up[s][0][0], up[s][0][1], up[s][1][0], up[s][1][1], up[s][2][0], up[s][2][1]};
;       const v32f uv = __builtin_amdgcn_cvt_scalef32_pk32_f32_fp6(uq, 1.0f);
; #pragma unroll
;       for (int i = 0; i < 32; ++i) acc[i] += act * uv[i];
.Ljn_5:
	v_bfi_b32 v209, s18, v210, v205
	v_mul_f32_e32 v208, 0.5, v204
	v_add_f32_e32 v209, 1.0, v209
	v_mul_f32_e32 v208, v208, v209
	v_mul_f32_e32 v208, s26, v208
	v_mul_f32_e32 v206, 0x3e800000, v208
	v_pk_fma_f32 v[66:67], v[2:3], v[206:207], v[66:67] op_sel_hi:[1,0,1]
	v_pk_fma_f32 v[68:69], v[4:5], v[206:207], v[68:69] op_sel_hi:[1,0,1]
	v_pk_fma_f32 v[70:71], v[6:7], v[206:207], v[70:71] op_sel_hi:[1,0,1]
	v_pk_fma_f32 v[72:73], v[8:9], v[206:207], v[72:73] op_sel_hi:[1,0,1]
	v_pk_fma_f32 v[74:75], v[10:11], v[206:207], v[74:75] op_sel_hi:[1,0,1]
	v_pk_fma_f32 v[76:77], v[12:13], v[206:207], v[76:77] op_sel_hi:[1,0,1]
	v_pk_fma_f32 v[78:79], v[14:15], v[206:207], v[78:79] op_sel_hi:[1,0,1]
	v_pk_fma_f32 v[80:81], v[16:17], v[206:207], v[80:81] op_sel_hi:[1,0,1]
	v_pk_fma_f32 v[82:83], v[18:19], v[206:207], v[82:83] op_sel_hi:[1,0,1]
	v_pk_fma_f32 v[84:85], v[20:21], v[206:207], v[84:85] op_sel_hi:[1,0,1]
	v_pk_fma_f32 v[86:87], v[22:23], v[206:207], v[86:87] op_sel_hi:[1,0,1]
	v_pk_fma_f32 v[88:89], v[24:25], v[206:207], v[88:89] op_sel_hi:[1,0,1]
	v_pk_fma_f32 v[90:91], v[26:27], v[206:207], v[90:91] op_sel_hi:[1,0,1]
	v_pk_fma_f32 v[92:93], v[28:29], v[206:207], v[92:93] op_sel_hi:[1,0,1]
	v_pk_fma_f32 v[94:95], v[30:31], v[206:207], v[94:95] op_sel_hi:[1,0,1]
	v_pk_fma_f32 v[96:97], v[32:33], v[206:207], v[96:97] op_sel_hi:[1,0,1]
	s_waitcnt vmcnt(21)
	v_cvt_scalef32_pk32_f32_fp6 v[2:33], v[134:139], 1.0
	v_mul_f32_e32 v200, v2, v34
	v_mul_f32_e32 v201, v3, v35
	v_mul_f32_e32 v202, v4, v36
	v_mul_f32_e32 v203, v5, v37
	v_fmac_f32_e32 v200, v6, v38
	v_fmac_f32_e32 v201, v7, v39
	v_fmac_f32_e32 v202, v8, v40
	v_fmac_f32_e32 v203, v9, v41
	v_fmac_f32_e32 v200, v10, v42
	v_fmac_f32_e32 v201, v11, v43
	v_fmac_f32_e32 v202, v12, v44
	v_fmac_f32_e32 v203, v13, v45
	v_fmac_f32_e32 v200, v14, v46
	v_fmac_f32_e32 v201, v15, v47
	v_fmac_f32_e32 v202, v16, v48
	v_fmac_f32_e32 v203, v17, v49
	v_fmac_f32_e32 v200, v18, v50
	v_fmac_f32_e32 v201, v19, v51
	v_fmac_f32_e32 v202, v20, v52
	v_fmac_f32_e32 v203, v21, v53
	v_fmac_f32_e32 v200, v22, v54
	v_fmac_f32_e32 v201, v23, v55
	v_fmac_f32_e32 v202, v24, v56
	v_fmac_f32_e32 v203, v25, v57
	v_fmac_f32_e32 v200, v26, v58
	v_fmac_f32_e32 v201, v27, v59
	v_fmac_f32_e32 v202, v28, v60
	v_fmac_f32_e32 v203, v29, v61
	v_fmac_f32_e32 v200, v30, v62
	v_fmac_f32_e32 v201, v31, v63
	v_fmac_f32_e32 v202, v32, v64
	v_fmac_f32_e32 v203, v33, v65
	v_add_f32_e32 v200, v201, v200
	v_add_f32_e32 v202, v203, v202
	v_cvt_scalef32_pk32_f32_fp6 v[2:33], v[140:145], 1.0
	v_add_f32_e32 v200, v202, v200
	s_add_i32 s38, s24, 3
	v_readlane_b32 s26, v199, s38
	s_add_i32 s39, s23, 3
	v_readlane_b32 s25, v198, s39
	v_add_f32_dpp v200, v200, v200 quad_perm:[1,0,3,2] row_mask:0xf bank_mask:0xf bound_ctrl:1
	s_nop 1
	v_add_f32_dpp v200, v200, v200 quad_perm:[2,3,0,1] row_mask:0xf bank_mask:0xf bound_ctrl:1
	s_nop 1
	v_add_f32_dpp v200, v200, v200 row_half_mirror row_mask:0xf bank_mask:0xf bound_ctrl:1
	s_nop 1
	v_add_f32_dpp v200, v200, v200 row_mirror row_mask:0xf bank_mask:0xf bound_ctrl:1
	s_nop 1
	v_add_f32_dpp v200, v200, v200 row_bcast:15 row_mask:0xa bank_mask:0xf
	s_nop 1
	v_add_f32_dpp v200, v200, v200 row_bcast:31 row_mask:0xc bank_mask:0xf
	s_nop 0
	v_readlane_b32 s27, v200, 63
	s_mul_i32 s40, s25, 0xc00
	s_add_u32 s28, s62, s40
	s_addc_u32 s29, s63, 0
	global_load_dwordx4 v[134:137], v1, s[28:29]
	global_load_dwordx4 v[138:141], v1, s[28:29] offset:2048
	global_load_dwordx4 v[142:145], v1, s[28:29] offset:1024
	v_mul_f32_e32 v204, s27, v212
	v_mul_f32_e32 v205, 0x3f3504f3, v204
	v_cmp_lt_f32_e64 s[32:33], |v205|, 1.0
	s_and_b64 vcc, exec, s[32:33]
	s_cbranch_vccnz .Lsm_7
	v_fma_f32 v208, |v205|, s9, v214
	v_fma_f32 v208, |v205|, v208, s10
	v_fma_f32 v208, |v205|, v208, s11
	v_fma_f32 v208, |v205|, v208, s12
	v_fma_f32 v208, |v205|, v208, s13
	v_fma_f32 v208, |v205|, v208, s14
	v_fma_f32 v208, |v205|, v208, |v205|
	v_mul_f32_e32 v209, 0xbfb8aa3b, v208
	v_fma_f32 v210, v208, s15, -v209
	v_rndne_f32_e32 v211, v209
	v_fmac_f32_e32 v210, 0xb2a5705f, v208
	v_sub_f32_e32 v209, v209, v211
	v_add_f32_e32 v209, v209, v210
	v_cvt_i32_f32_e32 v210, v211
	v_exp_f32_e32 v209, v209
	v_cmp_nlt_f32_e32 vcc, s16, v208
	v_ldexp_f32 v209, v209, v210
	s_nop 0
	v_cndmask_b32_e32 v209, 0, v209, vcc
	v_cmp_ngt_f32_e32 vcc, s17, v208
	s_nop 1
	v_cndmask_b32_e32 v208, v215, v209, vcc
	v_sub_f32_e32 v210, 1.0, v208
	s_branch .Ljn_7

; DEV float gelu_exact(float v) { return 0.5f * v * (1.f + erff(v * 0.7071067811865476f)); }
; DEV void peer_gather_token(const Params& p, int tok) {
;     ...
;   auto issue = [&](int k, int slot) {
;     const int e = (k < 64) ? __builtin_amdgcn_readlane(e0, k) : __builtin_amdgcn_readlane(e1, k - 64);
;     const unsigned char* dr = p.down8 + (size_t)e * ROW6 + lane * 24;
;     const unsigned char* ur = p.up8 + (size_t)e * ROW6 + lane * 24;
; #pragma unroll
;     for (int i = 0; i < 3; ++i) { dn[slot][i] = *(const u32x2*)(dr + i * 8); up[slot][i] = *(const u32x2*)(ur + i * 8); }
;   };
;   issue(0, 0); issue(1, 1); issue(2, 2);
; #pragma unroll 1
;   for (int k4 = 0; k4 < 128; k4 += 4) {
; #pragma unroll
;     for (int s = 0; s < 4; ++s) {
;       const int k = k4 + s;
;       if (k + 3 < 128) issue(k + 3, (s + 3) & 3);
;       const v6u dq = v6u{dn[s][0][0], dn[s][0][1], dn[s][1][0], dn[s][1][1], dn[s][2][0], dn[s][2][1]};
;       const v32f dv = __builtin_amdgcn_cvt_scalef32_pk32_f32_fp6(dq, 1.0f);
;       float d0 = 0.f, d1 = 0.f, d2 = 0.f, d3 = 0.f;
; #pragma unroll
;       for (int i = 0; i < 8; ++i) { d0 += dv[4 * i] * hx[4 * i]; d1 += dv[4 * i + 1] * hx[4 * i + 1]; d2 += dv[4 * i + 2] * hx[4 * i + 2]; d3 += dv[4 * i + 3] * hx[4 * i + 3]; }
;       const float d = wave_sum_fast((d0 + d1) + (d2 + d3)) * (1.f / DOWN_SCALE);
;       const float gk = __builtin_bit_cast(float, (k < 64) ? __builtin_amdgcn_readlane(g0, k) : __builtin_amdgcn_readlane(g1, k - 64));
;       const float act = gelu_exact(d) * gk * (1.f / UP_SCALE);
;       const v6u uq = v6u{up[s][0][0], up[s][0][1], up[s][1][0], up[s][1][1], up[s][2][0], up[s][2][1]};
;       const v32f uv = __builtin_amdgcn_cvt_scalef32_pk32_f32_fp6(uq, 1.0f);
; #pragma unroll
;       for (int i = 0; i < 32; ++i) acc[i] += act * uv[i];
.Ljn_7:
	v_bfi_b32 v209, s18, v210, v205
	v_mul_f32_e32 v208, 0.5, v204
	v_add_f32_e32 v209, 1.0, v209
	v_mul_f32_e32 v208, v208, v209
	v_mul_f32_e32 v208, s26, v208
	v_mul_f32_e32 v206, 0x3e800000, v208
	v_pk_fma_f32 v[66:67], v[2:3], v[206:207], v[66:67] op_sel_hi:[1,0,1]
	v_pk_fma_f32 v[68:69], v[4:5], v[206:207], v[68:69] op_sel_hi:[1,0,1]
	v_pk_fma_f32 v[70:71], v[6:7], v[206:207], v[70:71] op_sel_hi:[1,0,1]
	v_pk_fma_f32 v[72:73], v[8:9], v[206:207], v[72:73] op_sel_hi:[1,0,1]
	v_pk_fma_f32 v[74:75], v[10:11], v[206:207], v[74:75] op_sel_hi:[1,0,1]
	v_pk_fma_f32 v[76:77], v[12:13], v[206:207], v[76:77] op_sel_hi:[1,0,1]
	v_pk_fma_f32 v[78:79], v[14:15], v[206:207], v[78:79] op_sel_hi:[1,0,1]
	v_pk_fma_f32 v[80:81], v[16:17], v[206:207], v[80:81] op_sel_hi:[1,0,1]
	v_pk_fma_f32 v[82:83], v[18:19], v[206:207], v[82:83] op_sel_hi:[1,0,1]
	v_pk_fma_f32 v[84:85], v[20:21], v[206:207], v[84:85] op_sel_hi:[1,0,1]
	v_pk_fma_f32 v[86:87], v[22:23], v[206:207], v[86:87] op_sel_hi:[1,0,1]
	v_pk_fma_f32 v[88:89], v[24:25], v[206:207], v[88:89] op_sel_hi:[1,0,1]
	v_pk_fma_f32 v[90:91], v[26:27], v[206:207], v[90:91] op_sel_hi:[1,0,1]
	v_pk_fma_f32 v[92:93], v[28:29], v[206:207], v[92:93] op_sel_hi:[1,0,1]
	v_pk_fma_f32 v[94:95], v[30:31], v[206:207], v[94:95] op_sel_hi:[1,0,1]
	v_pk_fma_f32 v[96:97], v[32:33], v[206:207], v[96:97] op_sel_hi:[1,0,1]
	s_waitcnt vmcnt(21)
	v_cvt_scalef32_pk32_f32_fp6 v[2:33], v[146:151], 1.0
	v_mul_f32_e32 v200, v2, v34
	v_mul_f32_e32 v201, v3, v35
	v_mul_f32_e32 v202, v4, v36
	v_mul_f32_e32 v203, v5, v37
	v_fmac_f32_e32 v200, v6, v38
	v_fmac_f32_e32 v201, v7, v39
	v_fmac_f32_e32 v202, v8, v40
	v_fmac_f32_e32 v203, v9, v41
	v_fmac_f32_e32 v200, v10, v42
	v_fmac_f32_e32 v201, v11, v43
	v_fmac_f32_e32 v202, v12, v44
	v_fmac_f32_e32 v203, v13, v45
	v_fmac_f32_e32 v200, v14, v46
	v_fmac_f32_e32 v201, v15, v47
	v_fmac_f32_e32 v202, v16, v48
	v_fmac_f32_e32 v203, v17, v49
	v_fmac_f32_e32 v200, v18, v50
	v_fmac_f32_e32 v201, v19, v51
	v_fmac_f32_e32 v202, v20, v52
	v_fmac_f32_e32 v203, v21, v53
	v_fmac_f32_e32 v200, v22, v54
	v_fmac_f32_e32 v201, v23, v55
	v_fmac_f32_e32 v202, v24, v56
	v_fmac_f32_e32 v203, v25, v57
	v_fmac_f32_e32 v200, v26, v58
	v_fmac_f32_e32 v201, v27, v59
	v_fmac_f32_e32 v202, v28, v60
	v_fmac_f32_e32 v203, v29, v61
	v_fmac_f32_e32 v200, v30, v62
	v_fmac_f32_e32 v201, v31, v63
	v_fmac_f32_e32 v202, v32, v64
	v_fmac_f32_e32 v203, v33, v65
	v_add_f32_e32 v200, v201, v200
	v_add_f32_e32 v202, v203, v202
	v_cvt_scalef32_pk32_f32_fp6 v[2:33], v[152:157], 1.0
	v_add_f32_e32 v200, v202, v200
	s_add_i32 s38, s24, 4
	v_readlane_b32 s26, v199, s38
	s_add_i32 s39, s23, 4
	v_readlane_b32 s25, v198, s39
	v_add_f32_dpp v200, v200, v200 quad_perm:[1,0,3,2] row_mask:0xf bank_mask:0xf bound_ctrl:1
	s_nop 1
	v_add_f32_dpp v200, v200, v200 quad_perm:[2,3,0,1] row_mask:0xf bank_mask:0xf bound_ctrl:1
	s_nop 1
	v_add_f32_dpp v200, v200, v200 row_half_mirror row_mask:0xf bank_mask:0xf bound_ctrl:1
	s_nop 1
	v_add_f32_dpp v200, v200, v200 row_mirror row_mask:0xf bank_mask:0xf bound_ctrl:1
	s_nop 1
	v_add_f32_dpp v200, v200, v200 row_bcast:15 row_mask:0xa bank_mask:0xf
	s_nop 1
	v_add_f32_dpp v200, v200, v200 row_bcast:31 row_mask:0xc bank_mask:0xf
	s_nop 0
	v_readlane_b32 s27, v200, 63
	s_mul_i32 s40, s25, 0xc00
	s_add_u32 s28, s62, s40
	s_addc_u32 s29, s63, 0
	global_load_dwordx4 v[146:149], v1, s[28:29]
	global_load_dwordx4 v[150:153], v1, s[28:29] offset:2048
	global_load_dwordx4 v[154:157], v1, s[28:29] offset:1024
	v_mul_f32_e32 v204, s27, v212
	v_mul_f32_e32 v205, 0x3f3504f3, v204
	v_cmp_lt_f32_e64 s[32:33], |v205|, 1.0
	s_and_b64 vcc, exec, s[32:33]
	s_cbranch_vccnz .Lsm_9
	v_fma_f32 v208, |v205|, s9, v214
	v_fma_f32 v208, |v205|, v208, s10
	v_fma_f32 v208, |v205|, v208, s11
	v_fma_f32 v208, |v205|, v208, s12
	v_fma_f32 v208, |v205|, v208, s13
	v_fma_f32 v208, |v205|, v208, s14
	v_fma_f32 v208, |v205|, v208, |v205|
	v_mul_f32_e32 v209, 0xbfb8aa3b, v208
	v_fma_f32 v210, v208, s15, -v209
	v_rndne_f32_e32 v211, v209
	v_fmac_f32_e32 v210, 0xb2a5705f, v208
	v_sub_f32_e32 v209, v209, v211
	v_add_f32_e32 v209, v209, v210
	v_cvt_i32_f32_e32 v210, v211
	v_exp_f32_e32 v209, v209
	v_cmp_nlt_f32_e32 vcc, s16, v208
	v_ldexp_f32 v209, v209, v210
	s_nop 0
	v_cndmask_b32_e32 v209, 0, v209, vcc
	v_cmp_ngt_f32_e32 vcc, s17, v208
	s_nop 1
	v_cndmask_b32_e32 v208, v215, v209, vcc
	v_sub_f32_e32 v210, 1.0, v208
	s_branch .Ljn_9

; DEV float dpp_row_sum(float v) {
;   v += __builtin_bit_cast(float, __builtin_amdgcn_update_dpp(0, __builtin_bit_cast(int, v), 0xB1, 0xF, 0xF, true));
;   v += __builtin_bit_cast(float, __builtin_amdgcn_update_dpp(0, __builtin_bit_cast(int, v), 0x4E, 0xF, 0xF, true));
;   v += __builtin_bit_cast(float, __builtin_amdgcn_update_dpp(0, __builtin_bit_cast(int, v), 0x141, 0xF, 0xF, true));
;   v += __builtin_bit_cast(float, __builtin_amdgcn_update_dpp(0, __builtin_bit_cast(int, v), 0x140, 0xF, 0xF, true));
;   return v;
; }
; DEV float wave_sum_fast(float v) {
;   v = dpp_row_sum(v);
;   int iv = __builtin_bit_cast(int, v);
;   float s0 = __builtin_bit_cast(float, __builtin_amdgcn_readlane(iv, 0));
;   float s1 = __builtin_bit_cast(float, __builtin_amdgcn_readlane(iv, 16));
;   float s2 = __builtin_bit_cast(float, __builtin_amdgcn_readlane(iv, 32));
;   float s3 = __builtin_bit_cast(float, __builtin_amdgcn_readlane(iv, 48));
;   return (s0 + s1) + (s2 + s3);
; }
; DEV void peer_gather_token(const Params& p, int tok) {
;     ...
;       const v6u dq = v6u{dn[s][0][0], dn[s][0][1], dn[s][1][0], dn[s][1][1], dn[s][2][0], dn[s][2][1]};
;       const v32f dv = __builtin_amdgcn_cvt_scalef32_pk32_f32_fp6(dq, 1.0f);
;       float d0 = 0.f, d1 = 0.f, d2 = 0.f, d3 = 0.f;
; #pragma unroll
;       for (int i = 0; i < 8; ++i) { d0 += dv[4 * i] * hx[4 * i]; d1 += dv[4 * i + 1] * hx[4 * i + 1]; d2 += dv[4 * i + 2] * hx[4 * i + 2]; d3 += dv[4 * i + 3] * hx[4 * i + 3]; }
;       const float d = wave_sum_fast((d0 + d1) + (d2 + d3)) * (1.f / DOWN_SCALE);
.Ljn_9:
	v_bfi_b32 v209, s18, v210, v205
	v_mul_f32_e32 v208, 0.5, v204
	v_add_f32_e32 v209, 1.0, v209
	v_mul_f32_e32 v208, v208, v209
	v_mul_f32_e32 v208, s26, v208
	v_mul_f32_e32 v206, 0x3e800000, v208
	v_pk_fma_f32 v[66:67], v[2:3], v[206:207], v[66:67] op_sel_hi:[1,0,1]
	v_pk_fma_f32 v[68:69], v[4:5], v[206:207], v[68:69] op_sel_hi:[1,0,1]
	v_pk_fma_f32 v[70:71], v[6:7], v[206:207], v[70:71] op_sel_hi:[1,0,1]
	v_pk_fma_f32 v[72:73], v[8:9], v[206:207], v[72:73] op_sel_hi:[1,0,1]
	v_pk_fma_f32 v[74:75], v[10:11], v[206:207], v[74:75] op_sel_hi:[1,0,1]
	v_pk_fma_f32 v[76:77], v[12:13], v[206:207], v[76:77] op_sel_hi:[1,0,1]
	v_pk_fma_f32 v[78:79], v[14:15], v[206:207], v[78:79] op_sel_hi:[1,0,1]
	v_pk_fma_f32 v[80:81], v[16:17], v[206:207], v[80:81] op_sel_hi:[1,0,1]
	v_pk_fma_f32 v[82:83], v[18:19], v[206:207], v[82:83] op_sel_hi:[1,0,1]
	v_pk_fma_f32 v[84:85], v[20:21], v[206:207], v[84:85] op_sel_hi:[1,0,1]
	v_pk_fma_f32 v[86:87], v[22:23], v[206:207], v[86:87] op_sel_hi:[1,0,1]
	v_pk_fma_f32 v[88:89], v[24:25], v[206:207], v[88:89] op_sel_hi:[1,0,1]
	v_pk_fma_f32 v[90:91], v[26:27], v[206:207], v[90:91] op_sel_hi:[1,0,1]
	v_pk_fma_f32 v[92:93], v[28:29], v[206:207], v[92:93] op_sel_hi:[1,0,1]
	v_pk_fma_f32 v[94:95], v[30:31], v[206:207], v[94:95] op_sel_hi:[1,0,1]
	v_pk_fma_f32 v[96:97], v[32:33], v[206:207], v[96:97] op_sel_hi:[1,0,1]
	s_waitcnt vmcnt(21)
	v_cvt_scalef32_pk32_f32_fp6 v[2:33], v[158:163], 1.0
	v_mul_f32_e32 v200, v2, v34
	v_mul_f32_e32 v201, v3, v35
	v_mul_f32_e32 v202, v4, v36
	v_mul_f32_e32 v203, v5, v37
	v_fmac_f32_e32 v200, v6, v38
	v_fmac_f32_e32 v201, v7, v39
	v_fmac_f32_e32 v202, v8, v40
	v_fmac_f32_e32 v203, v9, v41
	v_fmac_f32_e32 v200, v10, v42
	v_fmac_f32_e32 v201, v11, v43
	v_fmac_f32_e32 v202, v12, v44
	v_fmac_f32_e32 v203, v13, v45
	v_fmac_f32_e32 v200, v14, v46
	v_fmac_f32_e32 v201, v15, v47
	v_fmac_f32_e32 v202, v16, v48
	v_fmac_f32_e32 v203, v17, v49
	v_fmac_f32_e32 v200, v18, v50
	v_fmac_f32_e32 v201, v19, v51
	v_fmac_f32_e32 v202, v20, v52
	v_fmac_f32_e32 v203, v21, v53
	v_fmac_f32_e32 v200, v22, v54
	v_fmac_f32_e32 v201, v23, v55
	v_fmac_f32_e32 v202, v24, v56
	v_fmac_f32_e32 v203, v25, v57
	v_fmac_f32_e32 v200, v26, v58
	v_fmac_f32_e32 v201, v27, v59
	v_fmac_f32_e32 v202, v28, v60
	v_fmac_f32_e32 v203, v29, v61
	v_fmac_f32_e32 v200, v30, v62
	v_fmac_f32_e32 v201, v31, v63
	v_fmac_f32_e32 v202, v32, v64
	v_fmac_f32_e32 v203, v33, v65
	v_add_f32_e32 v200, v201, v200
	v_add_f32_e32 v202, v203, v202
	v_cvt_scalef32_pk32_f32_fp6 v[2:33], v[164:169], 1.0
	v_add_f32_e32 v200, v202, v200
	s_add_i32 s38, s24, 5
	v_readlane_b32 s26, v199, s38
	s_add_i32 s39, s23, 5
	v_readlane_b32 s25, v198, s39
	v_add_f32_dpp v200, v200, v200 quad_perm:[1,0,3,2] row_mask:0xf bank_mask:0xf bound_ctrl:1
	s_nop 1
	v_add_f32_dpp v200, v200, v200 quad_perm:[2,3,0,1] row_mask:0xf bank_mask:0xf bound_ctrl:1
	s_nop 1
	v_add_f32_dpp v200, v200, v200 row_half_mirror row_mask:0xf bank_mask:0xf bound_ctrl:1
	s_nop 1
	v_add_f32_dpp v200, v200, v200 row_mirror row_mask:0xf bank_mask:0xf bound_ctrl:1
	s_nop 1
	v_add_f32_dpp v200, v200, v200 row_bcast:15 row_mask:0xa bank_mask:0xf
	s_nop 1
	v_add_f32_dpp v200, v200, v200 row_bcast:31 row_mask:0xc bank_mask:0xf
	s_nop 0
	v_readlane_b32 s27, v200, 63
	s_mul_i32 s40, s25, 0xc00
	s_add_u32 s28, s62, s40
	s_addc_u32 s29, s63, 0
	global_load_dwordx4 v[158:161], v1, s[28:29]
	global_load_dwordx4 v[162:165], v1, s[28:29] offset:2048
	global_load_dwordx4 v[166:169], v1, s[28:29] offset:1024
	v_mul_f32_e32 v204, s27, v212
	v_mul_f32_e32 v205, 0x3f3504f3, v204
	v_cmp_lt_f32_e64 s[32:33], |v205|, 1.0
	s_and_b64 vcc, exec, s[32:33]
	s_cbranch_vccnz .Lsm_11
	v_fma_f32 v208, |v205|, s9, v214
	v_fma_f32 v208, |v205|, v208, s10
	v_fma_f32 v208, |v205|, v208, s11
	v_fma_f32 v208, |v205|, v208, s12
	v_fma_f32 v208, |v205|, v208, s13
	v_fma_f32 v208, |v205|, v208, s14
	v_fma_f32 v208, |v205|, v208, |v205|
	v_mul_f32_e32 v209, 0xbfb8aa3b, v208
	v_fma_f32 v210, v208, s15, -v209
	v_rndne_f32_e32 v211, v209
	v_fmac_f32_e32 v210, 0xb2a5705f, v208
	v_sub_f32_e32 v209, v209, v211
	v_add_f32_e32 v209, v209, v210
	v_cvt_i32_f32_e32 v210, v211
	v_exp_f32_e32 v209, v209
	v_cmp_nlt_f32_e32 vcc, s16, v208
	v_ldexp_f32 v209, v209, v210
	s_nop 0
	v_cndmask_b32_e32 v209, 0, v209, vcc
	v_cmp_ngt_f32_e32 vcc, s17, v208
	s_nop 1
	v_cndmask_b32_e32 v208, v215, v209, vcc
	v_sub_f32_e32 v210, 1.0, v208
	s_branch .Ljn_11

; DEV float gelu_exact(float v) { return 0.5f * v * (1.f + erff(v * 0.7071067811865476f)); }
; DEV void peer_gather_token(const Params& p, int tok) {
;     ...
;       const float d = wave_sum_fast((d0 + d1) + (d2 + d3)) * (1.f / DOWN_SCALE);
;       const float gk = __builtin_bit_cast(float, (k < 64) ? __builtin_amdgcn_readlane(g0, k) : __builtin_amdgcn_readlane(g1, k - 64));
;       const float act = gelu_exact(d) * gk * (1.f / UP_SCALE);
;       const v6u uq = v6u{up[s][0][0], up[s][0][1], up[s][1][0], up[s][1][1], up[s][2][0], up[s][2][1]};
;       const v32f uv = __builtin_amdgcn_cvt_scalef32_pk32_f32_fp6(uq, 1.0f);
; #pragma unroll
;       for (int i = 0; i < 32; ++i) acc[i] += act * uv[i];
.Ljn_11:
	v_bfi_b32 v209, s18, v210, v205
	v_mul_f32_e32 v208, 0.5, v204
	v_add_f32_e32 v209, 1.0, v209
	v_mul_f32_e32 v208, v208, v209
	v_mul_f32_e32 v208, s26, v208
	v_mul_f32_e32 v206, 0x3e800000, v208
	v_pk_fma_f32 v[66:67], v[2:3], v[206:207], v[66:67] op_sel_hi:[1,0,1]
	v_pk_fma_f32 v[68:69], v[4:5], v[206:207], v[68:69] op_sel_hi:[1,0,1]
	v_pk_fma_f32 v[70:71], v[6:7], v[206:207], v[70:71] op_sel_hi:[1,0,1]
	v_pk_fma_f32 v[72:73], v[8:9], v[206:207], v[72:73] op_sel_hi:[1,0,1]
	v_pk_fma_f32 v[74:75], v[10:11], v[206:207], v[74:75] op_sel_hi:[1,0,1]
	v_pk_fma_f32 v[76:77], v[12:13], v[206:207], v[76:77] op_sel_hi:[1,0,1]
	v_pk_fma_f32 v[78:79], v[14:15], v[206:207], v[78:79] op_sel_hi:[1,0,1]
	v_pk_fma_f32 v[80:81], v[16:17], v[206:207], v[80:81] op_sel_hi:[1,0,1]
	v_pk_fma_f32 v[82:83], v[18:19], v[206:207], v[82:83] op_sel_hi:[1,0,1]
	v_pk_fma_f32 v[84:85], v[20:21], v[206:207], v[84:85] op_sel_hi:[1,0,1]
	v_pk_fma_f32 v[86:87], v[22:23], v[206:207], v[86:87] op_sel_hi:[1,0,1]
	v_pk_fma_f32 v[88:89], v[24:25], v[206:207], v[88:89] op_sel_hi:[1,0,1]
	v_pk_fma_f32 v[90:91], v[26:27], v[206:207], v[90:91] op_sel_hi:[1,0,1]
	v_pk_fma_f32 v[92:93], v[28:29], v[206:207], v[92:93] op_sel_hi:[1,0,1]
	v_pk_fma_f32 v[94:95], v[30:31], v[206:207], v[94:95] op_sel_hi:[1,0,1]
	v_pk_fma_f32 v[96:97], v[32:33], v[206:207], v[96:97] op_sel_hi:[1,0,1]
	s_waitcnt vmcnt(21)
	v_cvt_scalef32_pk32_f32_fp6 v[2:33], v[170:175], 1.0
	v_mul_f32_e32 v200, v2, v34
	v_mul_f32_e32 v201, v3, v35
	v_mul_f32_e32 v202, v4, v36
	v_mul_f32_e32 v203, v5, v37
	v_fmac_f32_e32 v200, v6, v38
	v_fmac_f32_e32 v201, v7, v39
	v_fmac_f32_e32 v202, v8, v40
	v_fmac_f32_e32 v203, v9, v41
	v_fmac_f32_e32 v200, v10, v42
	v_fmac_f32_e32 v201, v11, v43
	v_fmac_f32_e32 v202, v12, v44
	v_fmac_f32_e32 v203, v13, v45
	v_fmac_f32_e32 v200, v14, v46
	v_fmac_f32_e32 v201, v15, v47
	v_fmac_f32_e32 v202, v16, v48
	v_fmac_f32_e32 v203, v17, v49
	v_fmac_f32_e32 v200, v18, v50
	v_fmac_f32_e32 v201, v19, v51
	v_fmac_f32_e32 v202, v20, v52
	v_fmac_f32_e32 v203, v21, v53
	v_fmac_f32_e32 v200, v22, v54
	v_fmac_f32_e32 v201, v23, v55
	v_fmac_f32_e32 v202, v24, v56
	v_fmac_f32_e32 v203, v25, v57
	v_fmac_f32_e32 v200, v26, v58
	v_fmac_f32_e32 v201, v27, v59
	v_fmac_f32_e32 v202, v28, v60
	v_fmac_f32_e32 v203, v29, v61
	v_fmac_f32_e32 v200, v30, v62
	v_fmac_f32_e32 v201, v31, v63
	v_fmac_f32_e32 v202, v32, v64
	v_fmac_f32_e32 v203, v33, v65
	v_add_f32_e32 v200, v201, v200
	v_add_f32_e32 v202, v203, v202
	v_cvt_scalef32_pk32_f32_fp6 v[2:33], v[176:181], 1.0
	v_add_f32_e32 v200, v202, v200
	s_add_i32 s38, s24, 6
	v_readlane_b32 s26, v199, s38
	s_add_i32 s39, s23, 6
	v_readlane_b32 s25, v198, s39
	v_add_f32_dpp v200, v200, v200 quad_perm:[1,0,3,2] row_mask:0xf bank_mask:0xf bound_ctrl:1
	s_nop 1
	v_add_f32_dpp v200, v200, v200 quad_perm:[2,3,0,1] row_mask:0xf bank_mask:0xf bound_ctrl:1
	s_nop 1
	v_add_f32_dpp v200, v200, v200 row_half_mirror row_mask:0xf bank_mask:0xf bound_ctrl:1
	s_nop 1
	v_add_f32_dpp v200, v200, v200 row_mirror row_mask:0xf bank_mask:0xf bound_ctrl:1
	s_nop 1
	v_add_f32_dpp v200, v200, v200 row_bcast:15 row_mask:0xa bank_mask:0xf
	s_nop 1
	v_add_f32_dpp v200, v200, v200 row_bcast:31 row_mask:0xc bank_mask:0xf
	s_nop 0
	v_readlane_b32 s27, v200, 63
	s_mul_i32 s40, s25, 0xc00
	s_add_u32 s28, s62, s40
	s_addc_u32 s29, s63, 0
	global_load_dwordx4 v[170:173], v1, s[28:29]
	global_load_dwordx4 v[174:177], v1, s[28:29] offset:2048
	global_load_dwordx4 v[178:181], v1, s[28:29] offset:1024
	v_mul_f32_e32 v204, s27, v212
	v_mul_f32_e32 v205, 0x3f3504f3, v204
	v_cmp_lt_f32_e64 s[32:33], |v205|, 1.0
	s_and_b64 vcc, exec, s[32:33]
	s_cbranch_vccnz .Lsm_13
	v_fma_f32 v208, |v205|, s9, v214
	v_fma_f32 v208, |v205|, v208, s10
	v_fma_f32 v208, |v205|, v208, s11
	v_fma_f32 v208, |v205|, v208, s12
	v_fma_f32 v208, |v205|, v208, s13
	v_fma_f32 v208, |v205|, v208, s14
	v_fma_f32 v208, |v205|, v208, |v205|
	v_mul_f32_e32 v209, 0xbfb8aa3b, v208
	v_fma_f32 v210, v208, s15, -v209
	v_rndne_f32_e32 v211, v209
	v_fmac_f32_e32 v210, 0xb2a5705f, v208
	v_sub_f32_e32 v209, v209, v211
	v_add_f32_e32 v209, v209, v210
	v_cvt_i32_f32_e32 v210, v211
	v_exp_f32_e32 v209, v209
	v_cmp_nlt_f32_e32 vcc, s16, v208
	v_ldexp_f32 v209, v209, v210
	s_nop 0
	v_cndmask_b32_e32 v209, 0, v209, vcc
	v_cmp_ngt_f32_e32 vcc, s17, v208
	s_nop 1
	v_cndmask_b32_e32 v208, v215, v209, vcc
	v_sub_f32_e32 v210, 1.0, v208
	s_branch .Ljn_13

; DEV float gelu_exact(float v) { return 0.5f * v * (1.f + erff(v * 0.7071067811865476f)); }
; DEV void peer_gather_token(const Params& p, int tok) {
;     ...
;   auto issue = [&](int k, int slot) {
;     const int e = (k < 64) ? __builtin_amdgcn_readlane(e0, k) : __builtin_amdgcn_readlane(e1, k - 64);
;     const unsigned char* dr = p.down8 + (size_t)e * ROW6 + lane * 24;
;     const unsigned char* ur = p.up8 + (size_t)e * ROW6 + lane * 24;
; #pragma unroll
;     for (int i = 0; i < 3; ++i) { dn[slot][i] = *(const u32x2*)(dr + i * 8); up[slot][i] = *(const u32x2*)(ur + i * 8); }
;   };
;     ...
;       const v6u dq = v6u{dn[s][0][0], dn[s][0][1], dn[s][1][0], dn[s][1][1], dn[s][2][0], dn[s][2][1]};
;       const v32f dv = __builtin_amdgcn_cvt_scalef32_pk32_f32_fp6(dq, 1.0f);
;       float d0 = 0.f, d1 = 0.f, d2 = 0.f, d3 = 0.f;
; #pragma unroll
;       for (int i = 0; i < 8; ++i) { d0 += dv[4 * i] * hx[4 * i]; d1 += dv[4 * i + 1] * hx[4 * i + 1]; d2 += dv[4 * i + 2] * hx[4 * i + 2]; d3 += dv[4 * i + 3] * hx[4 * i + 3]; }
;       const float d = wave_sum_fast((d0 + d1) + (d2 + d3)) * (1.f / DOWN_SCALE);
;       const float gk = __builtin_bit_cast(float, (k < 64) ? __builtin_amdgcn_readlane(g0, k) : __builtin_amdgcn_readlane(g1, k - 64));
;       const float act = gelu_exact(d) * gk * (1.f / UP_SCALE);
;       const v6u uq = v6u{up[s][0][0], up[s][0][1], up[s][1][0], up[s][1][1], up[s][2][0], up[s][2][1]};
;       const v32f uv = __builtin_amdgcn_cvt_scalef32_pk32_f32_fp6(uq, 1.0f);
.Ljn_13:
	v_bfi_b32 v209, s18, v210, v205
	v_mul_f32_e32 v208, 0.5, v204
	v_add_f32_e32 v209, 1.0, v209
	v_mul_f32_e32 v208, v208, v209
	v_mul_f32_e32 v208, s26, v208
	v_mul_f32_e32 v206, 0x3e800000, v208
	v_pk_fma_f32 v[66:67], v[2:3], v[206:207], v[66:67] op_sel_hi:[1,0,1]
	v_pk_fma_f32 v[68:69], v[4:5], v[206:207], v[68:69] op_sel_hi:[1,0,1]
	v_pk_fma_f32 v[70:71], v[6:7], v[206:207], v[70:71] op_sel_hi:[1,0,1]
	v_pk_fma_f32 v[72:73], v[8:9], v[206:207], v[72:73] op_sel_hi:[1,0,1]
	v_pk_fma_f32 v[74:75], v[10:11], v[206:207], v[74:75] op_sel_hi:[1,0,1]
	v_pk_fma_f32 v[76:77], v[12:13], v[206:207], v[76:77] op_sel_hi:[1,0,1]
	v_pk_fma_f32 v[78:79], v[14:15], v[206:207], v[78:79] op_sel_hi:[1,0,1]
	v_pk_fma_f32 v[80:81], v[16:17], v[206:207], v[80:81] op_sel_hi:[1,0,1]
	v_pk_fma_f32 v[82:83], v[18:19], v[206:207], v[82:83] op_sel_hi:[1,0,1]
	v_pk_fma_f32 v[84:85], v[20:21], v[206:207], v[84:85] op_sel_hi:[1,0,1]
	v_pk_fma_f32 v[86:87], v[22:23], v[206:207], v[86:87] op_sel_hi:[1,0,1]
	v_pk_fma_f32 v[88:89], v[24:25], v[206:207], v[88:89] op_sel_hi:[1,0,1]
	v_pk_fma_f32 v[90:91], v[26:27], v[206:207], v[90:91] op_sel_hi:[1,0,1]
	v_pk_fma_f32 v[92:93], v[28:29], v[206:207], v[92:93] op_sel_hi:[1,0,1]
	v_pk_fma_f32 v[94:95], v[30:31], v[206:207], v[94:95] op_sel_hi:[1,0,1]
	v_pk_fma_f32 v[96:97], v[32:33], v[206:207], v[96:97] op_sel_hi:[1,0,1]
	s_waitcnt vmcnt(21)
	v_cvt_scalef32_pk32_f32_fp6 v[2:33], v[182:187], 1.0
	v_mul_f32_e32 v200, v2, v34
	v_mul_f32_e32 v201, v3, v35
	v_mul_f32_e32 v202, v4, v36
	v_mul_f32_e32 v203, v5, v37
	v_fmac_f32_e32 v200, v6, v38
	v_fmac_f32_e32 v201, v7, v39
	v_fmac_f32_e32 v202, v8, v40
	v_fmac_f32_e32 v203, v9, v41
	v_fmac_f32_e32 v200, v10, v42
	v_fmac_f32_e32 v201, v11, v43
	v_fmac_f32_e32 v202, v12, v44
	v_fmac_f32_e32 v203, v13, v45
	v_fmac_f32_e32 v200, v14, v46
	v_fmac_f32_e32 v201, v15, v47
	v_fmac_f32_e32 v202, v16, v48
	v_fmac_f32_e32 v203, v17, v49
	v_fmac_f32_e32 v200, v18, v50
	v_fmac_f32_e32 v201, v19, v51
	v_fmac_f32_e32 v202, v20, v52
	v_fmac_f32_e32 v203, v21, v53
	v_fmac_f32_e32 v200, v22, v54
	v_fmac_f32_e32 v201, v23, v55
	v_fmac_f32_e32 v202, v24, v56
	v_fmac_f32_e32 v203, v25, v57
	v_fmac_f32_e32 v200, v26, v58
	v_fmac_f32_e32 v201, v27, v59
	v_fmac_f32_e32 v202, v28, v60
	v_fmac_f32_e32 v203, v29, v61
	v_fmac_f32_e32 v200, v30, v62
	v_fmac_f32_e32 v201, v31, v63
	v_fmac_f32_e32 v202, v32, v64
	v_fmac_f32_e32 v203, v33, v65
	v_add_f32_e32 v200, v201, v200
	v_add_f32_e32 v202, v203, v202
	v_cvt_scalef32_pk32_f32_fp6 v[2:33], v[188:193], 1.0
	v_add_f32_e32 v200, v202, v200
	s_add_i32 s38, s24, 7
	v_readlane_b32 s26, v199, s38
	s_add_i32 s39, s23, 7
	v_readlane_b32 s25, v198, s39
	v_add_f32_dpp v200, v200, v200 quad_perm:[1,0,3,2] row_mask:0xf bank_mask:0xf bound_ctrl:1
	s_nop 1
	v_add_f32_dpp v200, v200, v200 quad_perm:[2,3,0,1] row_mask:0xf bank_mask:0xf bound_ctrl:1
	s_nop 1
	v_add_f32_dpp v200, v200, v200 row_half_mirror row_mask:0xf bank_mask:0xf bound_ctrl:1
	s_nop 1
	v_add_f32_dpp v200, v200, v200 row_mirror row_mask:0xf bank_mask:0xf bound_ctrl:1
	s_nop 1
	v_add_f32_dpp v200, v200, v200 row_bcast:15 row_mask:0xa bank_mask:0xf
	s_nop 1
	v_add_f32_dpp v200, v200, v200 row_bcast:31 row_mask:0xc bank_mask:0xf
	s_nop 0
	v_readlane_b32 s27, v200, 63
	s_mul_i32 s40, s25, 0xc00
	s_add_u32 s28, s62, s40
	s_addc_u32 s29, s63, 0
	global_load_dwordx4 v[182:185], v1, s[28:29]
	global_load_dwordx4 v[186:189], v1, s[28:29] offset:2048
	global_load_dwordx4 v[190:193], v1, s[28:29] offset:1024
	v_mul_f32_e32 v204, s27, v212
	v_mul_f32_e32 v205, 0x3f3504f3, v204
	v_cmp_lt_f32_e64 s[32:33], |v205|, 1.0
	s_and_b64 vcc, exec, s[32:33]
	s_cbranch_vccnz .Lsm_15
	v_fma_f32 v208, |v205|, s9, v214
	v_fma_f32 v208, |v205|, v208, s10
	v_fma_f32 v208, |v205|, v208, s11
	v_fma_f32 v208, |v205|, v208, s12
	v_fma_f32 v208, |v205|, v208, s13
	v_fma_f32 v208, |v205|, v208, s14
	v_fma_f32 v208, |v205|, v208, |v205|
	v_mul_f32_e32 v209, 0xbfb8aa3b, v208
	v_fma_f32 v210, v208, s15, -v209
	v_rndne_f32_e32 v211, v209
	v_fmac_f32_e32 v210, 0xb2a5705f, v208
	v_sub_f32_e32 v209, v209, v211
	v_add_f32_e32 v209, v209, v210
	v_cvt_i32_f32_e32 v210, v211
	v_exp_f32_e32 v209, v209
	v_cmp_nlt_f32_e32 vcc, s16, v208
	v_ldexp_f32 v209, v209, v210
	s_nop 0
	v_cndmask_b32_e32 v209, 0, v209, vcc
	v_cmp_ngt_f32_e32 vcc, s17, v208
	s_nop 1
	v_cndmask_b32_e32 v208, v215, v209, vcc
	v_sub_f32_e32 v210, 1.0, v208
	s_branch .Ljn_15

; DEV float bflo(unsigned u) { return __uint_as_float(u << 16); }
; DEV float bfhi(unsigned u) { return __uint_as_float(u & 0xffff0000u); }
; DEV float gelu_exact(float v) { return 0.5f * v * (1.f + erff(v * 0.7071067811865476f)); }
; DEV void peer_gather_token(const Params& p, int tok) {
;     ...
;     const u16* hr = p.h + (size_t)tok * 2048 + lane * 32;
; #pragma unroll
;     for (int q = 0; q < 4; ++q) {
;       u32x4 v = *(const u32x4*)(hr + q * 8);
; #pragma unroll
;       for (int e = 0; e < 4; ++e) { hx[q * 8 + 2 * e] = bflo(v[e]); hx[q * 8 + 2 * e + 1] = bfhi(v[e]); }
;     }
;   }
; #pragma unroll
;   for (int e = 0; e < 32; ++e) acc[e] = 0.f;
;   const int e0 = p.eidx[(size_t)tok * 128 + lane], e1 = p.eidx[(size_t)tok * 128 + 64 + lane];
;   const int g0 = __builtin_bit_cast(int, p.gw[(size_t)tok * 128 + lane]), g1 = __builtin_bit_cast(int, p.gw[(size_t)tok * 128 + 64 + lane]);
;     ...
;   for (int k4 = 0; k4 < 128; k4 += 4) {
; #pragma unroll
;     for (int s = 0; s < 4; ++s) {
;       const int k = k4 + s;
;       if (k + 3 < 128) issue(k + 3, (s + 3) & 3);
;       const v6u dq = v6u{dn[s][0][0], dn[s][0][1], dn[s][1][0], dn[s][1][1], dn[s][2][0], dn[s][2][1]};
;       const v32f dv = __builtin_amdgcn_cvt_scalef32_pk32_f32_fp6(dq, 1.0f);
;       float d0 = 0.f, d1 = 0.f, d2 = 0.f, d3 = 0.f;
; #pragma unroll
;       for (int i = 0; i < 8; ++i) { d0 += dv[4 * i] * hx[4 * i]; d1 += dv[4 * i + 1] * hx[4 * i + 1]; d2 += dv[4 * i + 2] * hx[4 * i + 2]; d3 += dv[4 * i + 3] * hx[4 * i + 3]; }
;       const float d = wave_sum_fast((d0 + d1) + (d2 + d3)) * (1.f / DOWN_SCALE);
;       const float gk = __builtin_bit_cast(float, (k < 64) ? __builtin_amdgcn_readlane(g0, k) : __builtin_amdgcn_readlane(g1, k - 64));
;       const float act = gelu_exact(d) * gk * (1.f / UP_SCALE);
;       const v6u uq = v6u{up[s][0][0], up[s][0][1], up[s][1][0], up[s][1][1], up[s][2][0], up[s][2][1]};
;       const v32f uv = __builtin_amdgcn_cvt_scalef32_pk32_f32_fp6(uq, 1.0f);
; #pragma unroll
;       for (int i = 0; i < 32; ++i) acc[i] += act * uv[i];
.Ljn_15:
	v_bfi_b32 v209, s18, v210, v205
	v_mul_f32_e32 v208, 0.5, v204
	v_add_f32_e32 v209, 1.0, v209
	v_mul_f32_e32 v208, v208, v209
	v_mul_f32_e32 v208, s26, v208
	v_mul_f32_e32 v206, 0x3e800000, v208
	v_pk_fma_f32 v[66:67], v[2:3], v[206:207], v[66:67] op_sel_hi:[1,0,1]
	v_pk_fma_f32 v[68:69], v[4:5], v[206:207], v[68:69] op_sel_hi:[1,0,1]
	v_pk_fma_f32 v[70:71], v[6:7], v[206:207], v[70:71] op_sel_hi:[1,0,1]
	v_pk_fma_f32 v[72:73], v[8:9], v[206:207], v[72:73] op_sel_hi:[1,0,1]
	v_pk_fma_f32 v[74:75], v[10:11], v[206:207], v[74:75] op_sel_hi:[1,0,1]
	v_pk_fma_f32 v[76:77], v[12:13], v[206:207], v[76:77] op_sel_hi:[1,0,1]
	v_pk_fma_f32 v[78:79], v[14:15], v[206:207], v[78:79] op_sel_hi:[1,0,1]
	v_pk_fma_f32 v[80:81], v[16:17], v[206:207], v[80:81] op_sel_hi:[1,0,1]
	v_pk_fma_f32 v[82:83], v[18:19], v[206:207], v[82:83] op_sel_hi:[1,0,1]
	v_pk_fma_f32 v[84:85], v[20:21], v[206:207], v[84:85] op_sel_hi:[1,0,1]
	v_pk_fma_f32 v[86:87], v[22:23], v[206:207], v[86:87] op_sel_hi:[1,0,1]
	v_pk_fma_f32 v[88:89], v[24:25], v[206:207], v[88:89] op_sel_hi:[1,0,1]
	v_pk_fma_f32 v[90:91], v[26:27], v[206:207], v[90:91] op_sel_hi:[1,0,1]
	v_pk_fma_f32 v[92:93], v[28:29], v[206:207], v[92:93] op_sel_hi:[1,0,1]
	v_pk_fma_f32 v[94:95], v[30:31], v[206:207], v[94:95] op_sel_hi:[1,0,1]
	v_pk_fma_f32 v[96:97], v[32:33], v[206:207], v[96:97] op_sel_hi:[1,0,1]
	s_add_i32 s22, s22, 1
	s_add_i32 s23, s23, 8
	s_and_b32 s23, s23, 63
	s_add_i32 s24, s24, 8
	s_and_b32 s24, s24, 63
	s_cmp_lt_u32 s22, 14
	s_cbranch_scc1 .Lp12_main
	s_add_i32 s60, s20, s21
	s_cmpk_lt_u32 s60, 0x4000
	s_cselect_b32 s60, s60, s20
	s_lshl_b32 s38, s60, 9
	s_add_u32 s58, s66, s38
	s_addc_u32 s59, s67, 0
	global_load_dword v216, v242, s[58:59]
	global_load_dword v217, v242, s[58:59] offset:256
	s_add_u32 s58, s68, s38
	s_addc_u32 s59, s69, 0
	global_load_dword v218, v242, s[58:59]
	global_load_dword v219, v242, s[58:59] offset:256
	s_lshl_b32 s38, s60, 12
	s_add_u32 s58, s80, s38
	s_addc_u32 s59, s81, 0
	global_load_dwordx2 v[220:221], v243, s[58:59]
	global_load_dwordx2 v[222:223], v243, s[58:59] offset:512
	global_load_dwordx2 v[224:225], v243, s[58:59] offset:1024
	global_load_dwordx2 v[226:227], v243, s[58:59] offset:1536
	global_load_dwordx2 v[228:229], v243, s[58:59] offset:2048
	global_load_dwordx2 v[230:231], v243, s[58:59] offset:2560
	global_load_dwordx2 v[232:233], v243, s[58:59] offset:3072
	global_load_dwordx2 v[234:235], v243, s[58:59] offset:3584
	s_waitcnt vmcnt(29)
	v_cvt_scalef32_pk32_f32_fp6 v[2:33], v[98:103], 1.0
	v_mul_f32_e32 v200, v2, v34
	v_mul_f32_e32 v201, v3, v35
	v_mul_f32_e32 v202, v4, v36
	v_mul_f32_e32 v203, v5, v37
	v_fmac_f32_e32 v200, v6, v38
	v_fmac_f32_e32 v201, v7, v39
	v_fmac_f32_e32 v202, v8, v40
	v_fmac_f32_e32 v203, v9, v41
	v_fmac_f32_e32 v200, v10, v42
	v_fmac_f32_e32 v201, v11, v43
	v_fmac_f32_e32 v202, v12, v44
	v_fmac_f32_e32 v203, v13, v45
	v_fmac_f32_e32 v200, v14, v46
	v_fmac_f32_e32 v201, v15, v47
	v_fmac_f32_e32 v202, v16, v48
	v_fmac_f32_e32 v203, v17, v49
	v_fmac_f32_e32 v200, v18, v50
	v_fmac_f32_e32 v201, v19, v51
	v_fmac_f32_e32 v202, v20, v52
	v_fmac_f32_e32 v203, v21, v53
	v_fmac_f32_e32 v200, v22, v54
	v_fmac_f32_e32 v201, v23, v55
	v_fmac_f32_e32 v202, v24, v56
	v_fmac_f32_e32 v203, v25, v57
	v_fmac_f32_e32 v200, v26, v58
	v_fmac_f32_e32 v201, v27, v59
	v_fmac_f32_e32 v202, v28, v60
	v_fmac_f32_e32 v203, v29, v61
	v_fmac_f32_e32 v200, v30, v62
	v_fmac_f32_e32 v201, v31, v63
	v_fmac_f32_e32 v202, v32, v64
	v_fmac_f32_e32 v203, v33, v65
	v_add_f32_e32 v200, v201, v200
	v_add_f32_e32 v202, v203, v202
	v_cvt_scalef32_pk32_f32_fp6 v[2:33], v[104:109], 1.0
	v_add_f32_e32 v200, v202, v200
	s_add_i32 s38, s24, 0
	v_readlane_b32 s26, v199, s38
	s_add_i32 s39, s23, 0
	v_readlane_b32 s25, v198, s39
	v_add_f32_dpp v200, v200, v200 quad_perm:[1,0,3,2] row_mask:0xf bank_mask:0xf bound_ctrl:1
	s_nop 1
	v_add_f32_dpp v200, v200, v200 quad_perm:[2,3,0,1] row_mask:0xf bank_mask:0xf bound_ctrl:1
	s_nop 1
	v_add_f32_dpp v200, v200, v200 row_half_mirror row_mask:0xf bank_mask:0xf bound_ctrl:1
	s_nop 1
	v_add_f32_dpp v200, v200, v200 row_mirror row_mask:0xf bank_mask:0xf bound_ctrl:1
	s_nop 1
	v_add_f32_dpp v200, v200, v200 row_bcast:15 row_mask:0xa bank_mask:0xf
	s_nop 1
	v_add_f32_dpp v200, v200, v200 row_bcast:31 row_mask:0xc bank_mask:0xf
	s_nop 0
	v_readlane_b32 s27, v200, 63
	s_mul_i32 s40, s25, 0xc00
	s_add_u32 s28, s62, s40
	s_addc_u32 s29, s63, 0
	global_load_dwordx4 v[98:101], v1, s[28:29]
	global_load_dwordx4 v[102:105], v1, s[28:29] offset:2048
	global_load_dwordx4 v[106:109], v1, s[28:29] offset:1024
	v_mul_f32_e32 v204, s27, v212
	v_mul_f32_e32 v205, 0x3f3504f3, v204
	v_cmp_lt_f32_e64 s[32:33], |v205|, 1.0
	s_and_b64 vcc, exec, s[32:33]
	s_cbranch_vccnz .Lsm_17
	v_fma_f32 v208, |v205|, s9, v214
	v_fma_f32 v208, |v205|, v208, s10
	v_fma_f32 v208, |v205|, v208, s11
	v_fma_f32 v208, |v205|, v208, s12
	v_fma_f32 v208, |v205|, v208, s13
	v_fma_f32 v208, |v205|, v208, s14
	v_fma_f32 v208, |v205|, v208, |v205|
	v_mul_f32_e32 v209, 0xbfb8aa3b, v208
	v_fma_f32 v210, v208, s15, -v209
	v_rndne_f32_e32 v211, v209
	v_fmac_f32_e32 v210, 0xb2a5705f, v208
	v_sub_f32_e32 v209, v209, v211
	v_add_f32_e32 v209, v209, v210
	v_cvt_i32_f32_e32 v210, v211
	v_exp_f32_e32 v209, v209
	v_cmp_nlt_f32_e32 vcc, s16, v208
	v_ldexp_f32 v209, v209, v210
	s_nop 0
	v_cndmask_b32_e32 v209, 0, v209, vcc
	v_cmp_ngt_f32_e32 vcc, s17, v208
	s_nop 1
	v_cndmask_b32_e32 v208, v215, v209, vcc
	v_sub_f32_e32 v210, 1.0, v208
	s_branch .Ljn_17

; DEV float gelu_exact(float v) { return 0.5f * v * (1.f + erff(v * 0.7071067811865476f)); }
; DEV void peer_gather_token(const Params& p, int tok) {
;     ...
;   auto issue = [&](int k, int slot) {
;     const int e = (k < 64) ? __builtin_amdgcn_readlane(e0, k) : __builtin_amdgcn_readlane(e1, k - 64);
;     const unsigned char* dr = p.down8 + (size_t)e * ROW6 + lane * 24;
;     const unsigned char* ur = p.up8 + (size_t)e * ROW6 + lane * 24;
; #pragma unroll
;     for (int i = 0; i < 3; ++i) { dn[slot][i] = *(const u32x2*)(dr + i * 8); up[slot][i] = *(const u32x2*)(ur + i * 8); }
;   };
;   issue(0, 0); issue(1, 1); issue(2, 2);
; #pragma unroll 1
;   for (int k4 = 0; k4 < 128; k4 += 4) {
; #pragma unroll
;     for (int s = 0; s < 4; ++s) {
;       const int k = k4 + s;
;       if (k + 3 < 128) issue(k + 3, (s + 3) & 3);
;       const v6u dq = v6u{dn[s][0][0], dn[s][0][1], dn[s][1][0], dn[s][1][1], dn[s][2][0], dn[s][2][1]};
;       const v32f dv = __builtin_amdgcn_cvt_scalef32_pk32_f32_fp6(dq, 1.0f);
;       float d0 = 0.f, d1 = 0.f, d2 = 0.f, d3 = 0.f;
; #pragma unroll
;       for (int i = 0; i < 8; ++i) { d0 += dv[4 * i] * hx[4 * i]; d1 += dv[4 * i + 1] * hx[4 * i + 1]; d2 += dv[4 * i + 2] * hx[4 * i + 2]; d3 += dv[4 * i + 3] * hx[4 * i + 3]; }
;       const float d = wave_sum_fast((d0 + d1) + (d2 + d3)) * (1.f / DOWN_SCALE);
;       const float gk = __builtin_bit_cast(float, (k < 64) ? __builtin_amdgcn_readlane(g0, k) : __builtin_amdgcn_readlane(g1, k - 64));
;       const float act = gelu_exact(d) * gk * (1.f / UP_SCALE);
;       const v6u uq = v6u{up[s][0][0], up[s][0][1], up[s][1][0], up[s][1][1], up[s][2][0], up[s][2][1]};
;       const v32f uv = __builtin_amdgcn_cvt_scalef32_pk32_f32_fp6(uq, 1.0f);
; #pragma unroll
;       for (int i = 0; i < 32; ++i) acc[i] += act * uv[i];
.Ljn_17:
	v_bfi_b32 v209, s18, v210, v205
	v_mul_f32_e32 v208, 0.5, v204
	v_add_f32_e32 v209, 1.0, v209
	v_mul_f32_e32 v208, v208, v209
	v_mul_f32_e32 v208, s26, v208
	v_mul_f32_e32 v206, 0x3e800000, v208
	v_pk_fma_f32 v[66:67], v[2:3], v[206:207], v[66:67] op_sel_hi:[1,0,1]
	v_pk_fma_f32 v[68:69], v[4:5], v[206:207], v[68:69] op_sel_hi:[1,0,1]
	v_pk_fma_f32 v[70:71], v[6:7], v[206:207], v[70:71] op_sel_hi:[1,0,1]
	v_pk_fma_f32 v[72:73], v[8:9], v[206:207], v[72:73] op_sel_hi:[1,0,1]
	v_pk_fma_f32 v[74:75], v[10:11], v[206:207], v[74:75] op_sel_hi:[1,0,1]
	v_pk_fma_f32 v[76:77], v[12:13], v[206:207], v[76:77] op_sel_hi:[1,0,1]
	v_pk_fma_f32 v[78:79], v[14:15], v[206:207], v[78:79] op_sel_hi:[1,0,1]
	v_pk_fma_f32 v[80:81], v[16:17], v[206:207], v[80:81] op_sel_hi:[1,0,1]
	v_pk_fma_f32 v[82:83], v[18:19], v[206:207], v[82:83] op_sel_hi:[1,0,1]
	v_pk_fma_f32 v[84:85], v[20:21], v[206:207], v[84:85] op_sel_hi:[1,0,1]
	v_pk_fma_f32 v[86:87], v[22:23], v[206:207], v[86:87] op_sel_hi:[1,0,1]
	v_pk_fma_f32 v[88:89], v[24:25], v[206:207], v[88:89] op_sel_hi:[1,0,1]
	v_pk_fma_f32 v[90:91], v[26:27], v[206:207], v[90:91] op_sel_hi:[1,0,1]
	v_pk_fma_f32 v[92:93], v[28:29], v[206:207], v[92:93] op_sel_hi:[1,0,1]
	v_pk_fma_f32 v[94:95], v[30:31], v[206:207], v[94:95] op_sel_hi:[1,0,1]
	v_pk_fma_f32 v[96:97], v[32:33], v[206:207], v[96:97] op_sel_hi:[1,0,1]
	s_waitcnt vmcnt(29)
	v_cvt_scalef32_pk32_f32_fp6 v[2:33], v[110:115], 1.0
	v_mul_f32_e32 v200, v2, v34
	v_mul_f32_e32 v201, v3, v35
	v_mul_f32_e32 v202, v4, v36
	v_mul_f32_e32 v203, v5, v37
	v_fmac_f32_e32 v200, v6, v38
	v_fmac_f32_e32 v201, v7, v39
	v_fmac_f32_e32 v202, v8, v40
	v_fmac_f32_e32 v203, v9, v41
	v_fmac_f32_e32 v200, v10, v42
	v_fmac_f32_e32 v201, v11, v43
	v_fmac_f32_e32 v202, v12, v44
	v_fmac_f32_e32 v203, v13, v45
	v_fmac_f32_e32 v200, v14, v46
	v_fmac_f32_e32 v201, v15, v47
	v_fmac_f32_e32 v202, v16, v48
	v_fmac_f32_e32 v203, v17, v49
	v_fmac_f32_e32 v200, v18, v50
	v_fmac_f32_e32 v201, v19, v51
	v_fmac_f32_e32 v202, v20, v52
	v_fmac_f32_e32 v203, v21, v53
	v_fmac_f32_e32 v200, v22, v54
	v_fmac_f32_e32 v201, v23, v55
	v_fmac_f32_e32 v202, v24, v56
	v_fmac_f32_e32 v203, v25, v57
	v_fmac_f32_e32 v200, v26, v58
	v_fmac_f32_e32 v201, v27, v59
	v_fmac_f32_e32 v202, v28, v60
	v_fmac_f32_e32 v203, v29, v61
	v_fmac_f32_e32 v200, v30, v62
	v_fmac_f32_e32 v201, v31, v63
	v_fmac_f32_e32 v202, v32, v64
	v_fmac_f32_e32 v203, v33, v65
	v_add_f32_e32 v200, v201, v200
	v_add_f32_e32 v202, v203, v202
	v_cvt_scalef32_pk32_f32_fp6 v[2:33], v[116:121], 1.0
	v_add_f32_e32 v200, v202, v200
	s_add_i32 s38, s24, 1
	v_readlane_b32 s26, v199, s38
	s_add_i32 s39, s23, 1
	v_readlane_b32 s25, v198, s39
	v_add_f32_dpp v200, v200, v200 quad_perm:[1,0,3,2] row_mask:0xf bank_mask:0xf bound_ctrl:1
	s_nop 1
	v_add_f32_dpp v200, v200, v200 quad_perm:[2,3,0,1] row_mask:0xf bank_mask:0xf bound_ctrl:1
	s_nop 1
	v_add_f32_dpp v200, v200, v200 row_half_mirror row_mask:0xf bank_mask:0xf bound_ctrl:1
	s_nop 1
	v_add_f32_dpp v200, v200, v200 row_mirror row_mask:0xf bank_mask:0xf bound_ctrl:1
	s_nop 1
	v_add_f32_dpp v200, v200, v200 row_bcast:15 row_mask:0xa bank_mask:0xf
	s_nop 1
	v_add_f32_dpp v200, v200, v200 row_bcast:31 row_mask:0xc bank_mask:0xf
	s_nop 0
	v_readlane_b32 s27, v200, 63
	s_mul_i32 s40, s25, 0xc00
	s_add_u32 s28, s62, s40
	s_addc_u32 s29, s63, 0
	global_load_dwordx4 v[110:113], v1, s[28:29]
	global_load_dwordx4 v[114:117], v1, s[28:29] offset:2048
	global_load_dwordx4 v[118:121], v1, s[28:29] offset:1024
	v_mul_f32_e32 v204, s27, v212
	v_mul_f32_e32 v205, 0x3f3504f3, v204
	v_cmp_lt_f32_e64 s[32:33], |v205|, 1.0
	s_and_b64 vcc, exec, s[32:33]
	s_cbranch_vccnz .Lsm_19
	v_fma_f32 v208, |v205|, s9, v214
	v_fma_f32 v208, |v205|, v208, s10
	v_fma_f32 v208, |v205|, v208, s11
	v_fma_f32 v208, |v205|, v208, s12
	v_fma_f32 v208, |v205|, v208, s13
	v_fma_f32 v208, |v205|, v208, s14
	v_fma_f32 v208, |v205|, v208, |v205|
	v_mul_f32_e32 v209, 0xbfb8aa3b, v208
	v_fma_f32 v210, v208, s15, -v209
	v_rndne_f32_e32 v211, v209
	v_fmac_f32_e32 v210, 0xb2a5705f, v208
	v_sub_f32_e32 v209, v209, v211
	v_add_f32_e32 v209, v209, v210
	v_cvt_i32_f32_e32 v210, v211
	v_exp_f32_e32 v209, v209
	v_cmp_nlt_f32_e32 vcc, s16, v208
	v_ldexp_f32 v209, v209, v210
	s_nop 0
	v_cndmask_b32_e32 v209, 0, v209, vcc
	v_cmp_ngt_f32_e32 vcc, s17, v208
	s_nop 1
	v_cndmask_b32_e32 v208, v215, v209, vcc
	v_sub_f32_e32 v210, 1.0, v208
	s_branch .Ljn_19

; DEV float gelu_exact(float v) { return 0.5f * v * (1.f + erff(v * 0.7071067811865476f)); }
; DEV void peer_gather_token(const Params& p, int tok) {
;     ...
;   auto issue = [&](int k, int slot) {
;     const int e = (k < 64) ? __builtin_amdgcn_readlane(e0, k) : __builtin_amdgcn_readlane(e1, k - 64);
;     const unsigned char* dr = p.down8 + (size_t)e * ROW6 + lane * 24;
;     const unsigned char* ur = p.up8 + (size_t)e * ROW6 + lane * 24;
; #pragma unroll
;     for (int i = 0; i < 3; ++i) { dn[slot][i] = *(const u32x2*)(dr + i * 8); up[slot][i] = *(const u32x2*)(ur + i * 8); }
;   };
;   issue(0, 0); issue(1, 1); issue(2, 2);
; #pragma unroll 1
;   for (int k4 = 0; k4 < 128; k4 += 4) {
; #pragma unroll
;     for (int s = 0; s < 4; ++s) {
;       const int k = k4 + s;
;       if (k + 3 < 128) issue(k + 3, (s + 3) & 3);
;       const v6u dq = v6u{dn[s][0][0], dn[s][0][1], dn[s][1][0], dn[s][1][1], dn[s][2][0], dn[s][2][1]};
;       const v32f dv = __builtin_amdgcn_cvt_scalef32_pk32_f32_fp6(dq, 1.0f);
;       float d0 = 0.f, d1 = 0.f, d2 = 0.f, d3 = 0.f;
; #pragma unroll
;       for (int i = 0; i < 8; ++i) { d0 += dv[4 * i] * hx[4 * i]; d1 += dv[4 * i + 1] * hx[4 * i + 1]; d2 += dv[4 * i + 2] * hx[4 * i + 2]; d3 += dv[4 * i + 3] * hx[4 * i + 3]; }
;       const float d = wave_sum_fast((d0 + d1) + (d2 + d3)) * (1.f / DOWN_SCALE);
;       const float gk = __builtin_bit_cast(float, (k < 64) ? __builtin_amdgcn_readlane(g0, k) : __builtin_amdgcn_readlane(g1, k - 64));
;       const float act = gelu_exact(d) * gk * (1.f / UP_SCALE);
;       const v6u uq = v6u{up[s][0][0], up[s][0][1], up[s][1][0], up[s][1][1], up[s][2][0], up[s][2][1]};
;       const v32f uv = __builtin_amdgcn_cvt_scalef32_pk32_f32_fp6(uq, 1.0f);
; #pragma unroll
;       for (int i = 0; i < 32; ++i) acc[i] += act * uv[i];
.Ljn_19:
	v_bfi_b32 v209, s18, v210, v205
	v_mul_f32_e32 v208, 0.5, v204
	v_add_f32_e32 v209, 1.0, v209
	v_mul_f32_e32 v208, v208, v209
	v_mul_f32_e32 v208, s26, v208
	v_mul_f32_e32 v206, 0x3e800000, v208
	v_pk_fma_f32 v[66:67], v[2:3], v[206:207], v[66:67] op_sel_hi:[1,0,1]
	v_pk_fma_f32 v[68:69], v[4:5], v[206:207], v[68:69] op_sel_hi:[1,0,1]
	v_pk_fma_f32 v[70:71], v[6:7], v[206:207], v[70:71] op_sel_hi:[1,0,1]
	v_pk_fma_f32 v[72:73], v[8:9], v[206:207], v[72:73] op_sel_hi:[1,0,1]
	v_pk_fma_f32 v[74:75], v[10:11], v[206:207], v[74:75] op_sel_hi:[1,0,1]
	v_pk_fma_f32 v[76:77], v[12:13], v[206:207], v[76:77] op_sel_hi:[1,0,1]
	v_pk_fma_f32 v[78:79], v[14:15], v[206:207], v[78:79] op_sel_hi:[1,0,1]
	v_pk_fma_f32 v[80:81], v[16:17], v[206:207], v[80:81] op_sel_hi:[1,0,1]
	v_pk_fma_f32 v[82:83], v[18:19], v[206:207], v[82:83] op_sel_hi:[1,0,1]
	v_pk_fma_f32 v[84:85], v[20:21], v[206:207], v[84:85] op_sel_hi:[1,0,1]
	v_pk_fma_f32 v[86:87], v[22:23], v[206:207], v[86:87] op_sel_hi:[1,0,1]
	v_pk_fma_f32 v[88:89], v[24:25], v[206:207], v[88:89] op_sel_hi:[1,0,1]
	v_pk_fma_f32 v[90:91], v[26:27], v[206:207], v[90:91] op_sel_hi:[1,0,1]
	v_pk_fma_f32 v[92:93], v[28:29], v[206:207], v[92:93] op_sel_hi:[1,0,1]
	v_pk_fma_f32 v[94:95], v[30:31], v[206:207], v[94:95] op_sel_hi:[1,0,1]
	v_pk_fma_f32 v[96:97], v[32:33], v[206:207], v[96:97] op_sel_hi:[1,0,1]
	s_waitcnt vmcnt(29)
	v_cvt_scalef32_pk32_f32_fp6 v[2:33], v[122:127], 1.0
	v_mul_f32_e32 v200, v2, v34
	v_mul_f32_e32 v201, v3, v35
	v_mul_f32_e32 v202, v4, v36
	v_mul_f32_e32 v203, v5, v37
	v_fmac_f32_e32 v200, v6, v38
	v_fmac_f32_e32 v201, v7, v39
	v_fmac_f32_e32 v202, v8, v40
	v_fmac_f32_e32 v203, v9, v41
	v_fmac_f32_e32 v200, v10, v42
	v_fmac_f32_e32 v201, v11, v43
	v_fmac_f32_e32 v202, v12, v44
	v_fmac_f32_e32 v203, v13, v45
	v_fmac_f32_e32 v200, v14, v46
	v_fmac_f32_e32 v201, v15, v47
	v_fmac_f32_e32 v202, v16, v48
	v_fmac_f32_e32 v203, v17, v49
	v_fmac_f32_e32 v200, v18, v50
	v_fmac_f32_e32 v201, v19, v51
	v_fmac_f32_e32 v202, v20, v52
	v_fmac_f32_e32 v203, v21, v53
	v_fmac_f32_e32 v200, v22, v54
	v_fmac_f32_e32 v201, v23, v55
	v_fmac_f32_e32 v202, v24, v56
	v_fmac_f32_e32 v203, v25, v57
	v_fmac_f32_e32 v200, v26, v58
	v_fmac_f32_e32 v201, v27, v59
	v_fmac_f32_e32 v202, v28, v60
	v_fmac_f32_e32 v203, v29, v61
	v_fmac_f32_e32 v200, v30, v62
	v_fmac_f32_e32 v201, v31, v63
	v_fmac_f32_e32 v202, v32, v64
	v_fmac_f32_e32 v203, v33, v65
	v_add_f32_e32 v200, v201, v200
	v_add_f32_e32 v202, v203, v202
	v_cvt_scalef32_pk32_f32_fp6 v[2:33], v[128:133], 1.0
	v_add_f32_e32 v200, v202, v200
	s_add_i32 s38, s24, 2
	v_readlane_b32 s26, v199, s38
	s_add_i32 s39, s23, 2
	v_readlane_b32 s25, v198, s39
	v_add_f32_dpp v200, v200, v200 quad_perm:[1,0,3,2] row_mask:0xf bank_mask:0xf bound_ctrl:1
	s_nop 1
	v_add_f32_dpp v200, v200, v200 quad_perm:[2,3,0,1] row_mask:0xf bank_mask:0xf bound_ctrl:1
	s_nop 1
	v_add_f32_dpp v200, v200, v200 row_half_mirror row_mask:0xf bank_mask:0xf bound_ctrl:1
	s_nop 1
	v_add_f32_dpp v200, v200, v200 row_mirror row_mask:0xf bank_mask:0xf bound_ctrl:1
	s_nop 1
	v_add_f32_dpp v200, v200, v200 row_bcast:15 row_mask:0xa bank_mask:0xf
	s_nop 1
	v_add_f32_dpp v200, v200, v200 row_bcast:31 row_mask:0xc bank_mask:0xf
	s_nop 0
	v_readlane_b32 s27, v200, 63
	s_mul_i32 s40, s25, 0xc00
	s_add_u32 s28, s62, s40
	s_addc_u32 s29, s63, 0
	global_load_dwordx4 v[122:125], v1, s[28:29]
	global_load_dwordx4 v[126:129], v1, s[28:29] offset:2048
	global_load_dwordx4 v[130:133], v1, s[28:29] offset:1024
	v_mul_f32_e32 v204, s27, v212
	v_mul_f32_e32 v205, 0x3f3504f3, v204
	v_cmp_lt_f32_e64 s[32:33], |v205|, 1.0
	s_and_b64 vcc, exec, s[32:33]
	s_cbranch_vccnz .Lsm_21
	v_fma_f32 v208, |v205|, s9, v214
	v_fma_f32 v208, |v205|, v208, s10
	v_fma_f32 v208, |v205|, v208, s11
	v_fma_f32 v208, |v205|, v208, s12
	v_fma_f32 v208, |v205|, v208, s13
	v_fma_f32 v208, |v205|, v208, s14
	v_fma_f32 v208, |v205|, v208, |v205|
	v_mul_f32_e32 v209, 0xbfb8aa3b, v208
	v_fma_f32 v210, v208, s15, -v209
	v_rndne_f32_e32 v211, v209
	v_fmac_f32_e32 v210, 0xb2a5705f, v208
	v_sub_f32_e32 v209, v209, v211
	v_add_f32_e32 v209, v209, v210
	v_cvt_i32_f32_e32 v210, v211
	v_exp_f32_e32 v209, v209
	v_cmp_nlt_f32_e32 vcc, s16, v208
	v_ldexp_f32 v209, v209, v210
	s_nop 0
	v_cndmask_b32_e32 v209, 0, v209, vcc
	v_cmp_ngt_f32_e32 vcc, s17, v208
	s_nop 1
	v_cndmask_b32_e32 v208, v215, v209, vcc
	v_sub_f32_e32 v210, 1.0, v208
	s_branch .Ljn_21

; DEV float gelu_exact(float v) { return 0.5f * v * (1.f + erff(v * 0.7071067811865476f)); }
; DEV void peer_gather_token(const Params& p, int tok) {
;     ...
;   auto issue = [&](int k, int slot) {
;     const int e = (k < 64) ? __builtin_amdgcn_readlane(e0, k) : __builtin_amdgcn_readlane(e1, k - 64);
;     const unsigned char* dr = p.down8 + (size_t)e * ROW6 + lane * 24;
;     const unsigned char* ur = p.up8 + (size_t)e * ROW6 + lane * 24;
; #pragma unroll
;     for (int i = 0; i < 3; ++i) { dn[slot][i] = *(const u32x2*)(dr + i * 8); up[slot][i] = *(const u32x2*)(ur + i * 8); }
;   };
;   issue(0, 0); issue(1, 1); issue(2, 2);
; #pragma unroll 1
;   for (int k4 = 0; k4 < 128; k4 += 4) {
; #pragma unroll
;     for (int s = 0; s < 4; ++s) {
;       const int k = k4 + s;
;       if (k + 3 < 128) issue(k + 3, (s + 3) & 3);
;       const v6u dq = v6u{dn[s][0][0], dn[s][0][1], dn[s][1][0], dn[s][1][1], dn[s][2][0], dn[s][2][1]};
;       const v32f dv = __builtin_amdgcn_cvt_scalef32_pk32_f32_fp6(dq, 1.0f);
;       float d0 = 0.f, d1 = 0.f, d2 = 0.f, d3 = 0.f;
; #pragma unroll
;       for (int i = 0; i < 8; ++i) { d0 += dv[4 * i] * hx[4 * i]; d1 += dv[4 * i + 1] * hx[4 * i + 1]; d2 += dv[4 * i + 2] * hx[4 * i + 2]; d3 += dv[4 * i + 3] * hx[4 * i + 3]; }
;       const float d = wave_sum_fast((d0 + d1) + (d2 + d3)) * (1.f / DOWN_SCALE);
;       const float gk = __builtin_bit_cast(float, (k < 64) ? __builtin_amdgcn_readlane(g0, k) : __builtin_amdgcn_readlane(g1, k - 64));
;       const float act = gelu_exact(d) * gk * (1.f / UP_SCALE);
;       const v6u uq = v6u{up[s][0][0], up[s][0][1], up[s][1][0], up[s][1][1], up[s][2][0], up[s][2][1]};
;       const v32f uv = __builtin_amdgcn_cvt_scalef32_pk32_f32_fp6(uq, 1.0f);
; #pragma unroll
;       for (int i = 0; i < 32; ++i) acc[i] += act * uv[i];
.Ljn_21:
	v_bfi_b32 v209, s18, v210, v205
	v_mul_f32_e32 v208, 0.5, v204
	v_add_f32_e32 v209, 1.0, v209
	v_mul_f32_e32 v208, v208, v209
	v_mul_f32_e32 v208, s26, v208
	v_mul_f32_e32 v206, 0x3e800000, v208
	v_pk_fma_f32 v[66:67], v[2:3], v[206:207], v[66:67] op_sel_hi:[1,0,1]
	v_pk_fma_f32 v[68:69], v[4:5], v[206:207], v[68:69] op_sel_hi:[1,0,1]
	v_pk_fma_f32 v[70:71], v[6:7], v[206:207], v[70:71] op_sel_hi:[1,0,1]
	v_pk_fma_f32 v[72:73], v[8:9], v[206:207], v[72:73] op_sel_hi:[1,0,1]
	v_pk_fma_f32 v[74:75], v[10:11], v[206:207], v[74:75] op_sel_hi:[1,0,1]
	v_pk_fma_f32 v[76:77], v[12:13], v[206:207], v[76:77] op_sel_hi:[1,0,1]
	v_pk_fma_f32 v[78:79], v[14:15], v[206:207], v[78:79] op_sel_hi:[1,0,1]
	v_pk_fma_f32 v[80:81], v[16:17], v[206:207], v[80:81] op_sel_hi:[1,0,1]
	v_pk_fma_f32 v[82:83], v[18:19], v[206:207], v[82:83] op_sel_hi:[1,0,1]
	v_pk_fma_f32 v[84:85], v[20:21], v[206:207], v[84:85] op_sel_hi:[1,0,1]
	v_pk_fma_f32 v[86:87], v[22:23], v[206:207], v[86:87] op_sel_hi:[1,0,1]
	v_pk_fma_f32 v[88:89], v[24:25], v[206:207], v[88:89] op_sel_hi:[1,0,1]
	v_pk_fma_f32 v[90:91], v[26:27], v[206:207], v[90:91] op_sel_hi:[1,0,1]
	v_pk_fma_f32 v[92:93], v[28:29], v[206:207], v[92:93] op_sel_hi:[1,0,1]
	v_pk_fma_f32 v[94:95], v[30:31], v[206:207], v[94:95] op_sel_hi:[1,0,1]
	v_pk_fma_f32 v[96:97], v[32:33], v[206:207], v[96:97] op_sel_hi:[1,0,1]
	s_waitcnt vmcnt(29)
	v_cvt_scalef32_pk32_f32_fp6 v[2:33], v[134:139], 1.0
	v_mul_f32_e32 v200, v2, v34
	v_mul_f32_e32 v201, v3, v35
	v_mul_f32_e32 v202, v4, v36
	v_mul_f32_e32 v203, v5, v37
	v_fmac_f32_e32 v200, v6, v38
	v_fmac_f32_e32 v201, v7, v39
	v_fmac_f32_e32 v202, v8, v40
	v_fmac_f32_e32 v203, v9, v41
	v_fmac_f32_e32 v200, v10, v42
	v_fmac_f32_e32 v201, v11, v43
	v_fmac_f32_e32 v202, v12, v44
	v_fmac_f32_e32 v203, v13, v45
	v_fmac_f32_e32 v200, v14, v46
	v_fmac_f32_e32 v201, v15, v47
	v_fmac_f32_e32 v202, v16, v48
	v_fmac_f32_e32 v203, v17, v49
	v_fmac_f32_e32 v200, v18, v50
	v_fmac_f32_e32 v201, v19, v51
	v_fmac_f32_e32 v202, v20, v52
	v_fmac_f32_e32 v203, v21, v53
	v_fmac_f32_e32 v200, v22, v54
	v_fmac_f32_e32 v201, v23, v55
	v_fmac_f32_e32 v202, v24, v56
	v_fmac_f32_e32 v203, v25, v57
	v_fmac_f32_e32 v200, v26, v58
	v_fmac_f32_e32 v201, v27, v59
	v_fmac_f32_e32 v202, v28, v60
	v_fmac_f32_e32 v203, v29, v61
	v_fmac_f32_e32 v200, v30, v62
	v_fmac_f32_e32 v201, v31, v63
	v_fmac_f32_e32 v202, v32, v64
	v_fmac_f32_e32 v203, v33, v65
	v_add_f32_e32 v200, v201, v200
	v_add_f32_e32 v202, v203, v202
	v_cvt_scalef32_pk32_f32_fp6 v[2:33], v[140:145], 1.0
	v_add_f32_e32 v200, v202, v200
	s_add_i32 s38, s24, 3
	v_readlane_b32 s26, v199, s38
	s_add_i32 s39, s23, 3
	v_readlane_b32 s25, v198, s39
	v_add_f32_dpp v200, v200, v200 quad_perm:[1,0,3,2] row_mask:0xf bank_mask:0xf bound_ctrl:1
	s_nop 1
	v_add_f32_dpp v200, v200, v200 quad_perm:[2,3,0,1] row_mask:0xf bank_mask:0xf bound_ctrl:1
	s_nop 1
	v_add_f32_dpp v200, v200, v200 row_half_mirror row_mask:0xf bank_mask:0xf bound_ctrl:1
	s_nop 1
	v_add_f32_dpp v200, v200, v200 row_mirror row_mask:0xf bank_mask:0xf bound_ctrl:1
	s_nop 1
	v_add_f32_dpp v200, v200, v200 row_bcast:15 row_mask:0xa bank_mask:0xf
	s_nop 1
	v_add_f32_dpp v200, v200, v200 row_bcast:31 row_mask:0xc bank_mask:0xf
	s_nop 0
	v_readlane_b32 s27, v200, 63
	s_mul_i32 s40, s25, 0xc00
	s_add_u32 s28, s62, s40
	s_addc_u32 s29, s63, 0
	global_load_dwordx4 v[134:137], v1, s[28:29]
	global_load_dwordx4 v[138:141], v1, s[28:29] offset:2048
	global_load_dwordx4 v[142:145], v1, s[28:29] offset:1024
	v_mul_f32_e32 v204, s27, v212
	v_mul_f32_e32 v205, 0x3f3504f3, v204
	v_cmp_lt_f32_e64 s[32:33], |v205|, 1.0
	s_and_b64 vcc, exec, s[32:33]
	s_cbranch_vccnz .Lsm_23
	v_fma_f32 v208, |v205|, s9, v214
	v_fma_f32 v208, |v205|, v208, s10
	v_fma_f32 v208, |v205|, v208, s11
	v_fma_f32 v208, |v205|, v208, s12
	v_fma_f32 v208, |v205|, v208, s13
	v_fma_f32 v208, |v205|, v208, s14
	v_fma_f32 v208, |v205|, v208, |v205|
	v_mul_f32_e32 v209, 0xbfb8aa3b, v208
	v_fma_f32 v210, v208, s15, -v209
	v_rndne_f32_e32 v211, v209
	v_fmac_f32_e32 v210, 0xb2a5705f, v208
	v_sub_f32_e32 v209, v209, v211
	v_add_f32_e32 v209, v209, v210
	v_cvt_i32_f32_e32 v210, v211
	v_exp_f32_e32 v209, v209
	v_cmp_nlt_f32_e32 vcc, s16, v208
	v_ldexp_f32 v209, v209, v210
	s_nop 0
	v_cndmask_b32_e32 v209, 0, v209, vcc
	v_cmp_ngt_f32_e32 vcc, s17, v208
	s_nop 1
	v_cndmask_b32_e32 v208, v215, v209, vcc
	v_sub_f32_e32 v210, 1.0, v208
	s_branch .Ljn_23

; DEV float gelu_exact(float v) { return 0.5f * v * (1.f + erff(v * 0.7071067811865476f)); }
; DEV void peer_gather_token(const Params& p, int tok) {
;     ...
;   auto issue = [&](int k, int slot) {
;     const int e = (k < 64) ? __builtin_amdgcn_readlane(e0, k) : __builtin_amdgcn_readlane(e1, k - 64);
;     const unsigned char* dr = p.down8 + (size_t)e * ROW6 + lane * 24;
;     const unsigned char* ur = p.up8 + (size_t)e * ROW6 + lane * 24;
; #pragma unroll
;     for (int i = 0; i < 3; ++i) { dn[slot][i] = *(const u32x2*)(dr + i * 8); up[slot][i] = *(const u32x2*)(ur + i * 8); }
;   };
;   issue(0, 0); issue(1, 1); issue(2, 2);
; #pragma unroll 1
;   for (int k4 = 0; k4 < 128; k4 += 4) {
; #pragma unroll
;     for (int s = 0; s < 4; ++s) {
;       const int k = k4 + s;
;       if (k + 3 < 128) issue(k + 3, (s + 3) & 3);
;       const v6u dq = v6u{dn[s][0][0], dn[s][0][1], dn[s][1][0], dn[s][1][1], dn[s][2][0], dn[s][2][1]};
;       const v32f dv = __builtin_amdgcn_cvt_scalef32_pk32_f32_fp6(dq, 1.0f);
;       float d0 = 0.f, d1 = 0.f, d2 = 0.f, d3 = 0.f;
; #pragma unroll
;       for (int i = 0; i < 8; ++i) { d0 += dv[4 * i] * hx[4 * i]; d1 += dv[4 * i + 1] * hx[4 * i + 1]; d2 += dv[4 * i + 2] * hx[4 * i + 2]; d3 += dv[4 * i + 3] * hx[4 * i + 3]; }
;       const float d = wave_sum_fast((d0 + d1) + (d2 + d3)) * (1.f / DOWN_SCALE);
;       const float gk = __builtin_bit_cast(float, (k < 64) ? __builtin_amdgcn_readlane(g0, k) : __builtin_amdgcn_readlane(g1, k - 64));
;       const float act = gelu_exact(d) * gk * (1.f / UP_SCALE);
;       const v6u uq = v6u{up[s][0][0], up[s][0][1], up[s][1][0], up[s][1][1], up[s][2][0], up[s][2][1]};
;       const v32f uv = __builtin_amdgcn_cvt_scalef32_pk32_f32_fp6(uq, 1.0f);
; #pragma unroll
;       for (int i = 0; i < 32; ++i) acc[i] += act * uv[i];
.Ljn_23:
	v_bfi_b32 v209, s18, v210, v205
	v_mul_f32_e32 v208, 0.5, v204
	v_add_f32_e32 v209, 1.0, v209
	v_mul_f32_e32 v208, v208, v209
	v_mul_f32_e32 v208, s26, v208
	v_mul_f32_e32 v206, 0x3e800000, v208
	v_pk_fma_f32 v[66:67], v[2:3], v[206:207], v[66:67] op_sel_hi:[1,0,1]
	v_pk_fma_f32 v[68:69], v[4:5], v[206:207], v[68:69] op_sel_hi:[1,0,1]
	v_pk_fma_f32 v[70:71], v[6:7], v[206:207], v[70:71] op_sel_hi:[1,0,1]
	v_pk_fma_f32 v[72:73], v[8:9], v[206:207], v[72:73] op_sel_hi:[1,0,1]
	v_pk_fma_f32 v[74:75], v[10:11], v[206:207], v[74:75] op_sel_hi:[1,0,1]
	v_pk_fma_f32 v[76:77], v[12:13], v[206:207], v[76:77] op_sel_hi:[1,0,1]
	v_pk_fma_f32 v[78:79], v[14:15], v[206:207], v[78:79] op_sel_hi:[1,0,1]
	v_pk_fma_f32 v[80:81], v[16:17], v[206:207], v[80:81] op_sel_hi:[1,0,1]
	v_pk_fma_f32 v[82:83], v[18:19], v[206:207], v[82:83] op_sel_hi:[1,0,1]
	v_pk_fma_f32 v[84:85], v[20:21], v[206:207], v[84:85] op_sel_hi:[1,0,1]
	v_pk_fma_f32 v[86:87], v[22:23], v[206:207], v[86:87] op_sel_hi:[1,0,1]
	v_pk_fma_f32 v[88:89], v[24:25], v[206:207], v[88:89] op_sel_hi:[1,0,1]
	v_pk_fma_f32 v[90:91], v[26:27], v[206:207], v[90:91] op_sel_hi:[1,0,1]
	v_pk_fma_f32 v[92:93], v[28:29], v[206:207], v[92:93] op_sel_hi:[1,0,1]
	v_pk_fma_f32 v[94:95], v[30:31], v[206:207], v[94:95] op_sel_hi:[1,0,1]
	v_pk_fma_f32 v[96:97], v[32:33], v[206:207], v[96:97] op_sel_hi:[1,0,1]
	s_waitcnt vmcnt(29)
	v_cvt_scalef32_pk32_f32_fp6 v[2:33], v[146:151], 1.0
	v_mul_f32_e32 v200, v2, v34
	v_mul_f32_e32 v201, v3, v35
	v_mul_f32_e32 v202, v4, v36
	v_mul_f32_e32 v203, v5, v37
	v_fmac_f32_e32 v200, v6, v38
	v_fmac_f32_e32 v201, v7, v39
	v_fmac_f32_e32 v202, v8, v40
	v_fmac_f32_e32 v203, v9, v41
	v_fmac_f32_e32 v200, v10, v42
	v_fmac_f32_e32 v201, v11, v43
	v_fmac_f32_e32 v202, v12, v44
	v_fmac_f32_e32 v203, v13, v45
	v_fmac_f32_e32 v200, v14, v46
	v_fmac_f32_e32 v201, v15, v47
	v_fmac_f32_e32 v202, v16, v48
	v_fmac_f32_e32 v203, v17, v49
	v_fmac_f32_e32 v200, v18, v50
	v_fmac_f32_e32 v201, v19, v51
	v_fmac_f32_e32 v202, v20, v52
	v_fmac_f32_e32 v203, v21, v53
	v_fmac_f32_e32 v200, v22, v54
	v_fmac_f32_e32 v201, v23, v55
	v_fmac_f32_e32 v202, v24, v56
	v_fmac_f32_e32 v203, v25, v57
	v_fmac_f32_e32 v200, v26, v58
	v_fmac_f32_e32 v201, v27, v59
	v_fmac_f32_e32 v202, v28, v60
	v_fmac_f32_e32 v203, v29, v61
	v_fmac_f32_e32 v200, v30, v62
	v_fmac_f32_e32 v201, v31, v63
	v_fmac_f32_e32 v202, v32, v64
	v_fmac_f32_e32 v203, v33, v65
	v_add_f32_e32 v200, v201, v200
	v_add_f32_e32 v202, v203, v202
	v_cvt_scalef32_pk32_f32_fp6 v[2:33], v[152:157], 1.0
	v_add_f32_e32 v200, v202, v200
	s_add_i32 s38, s24, 4
	v_readlane_b32 s26, v199, s38
	s_add_i32 s39, s23, 4
	v_readlane_b32 s25, v198, s39
	v_add_f32_dpp v200, v200, v200 quad_perm:[1,0,3,2] row_mask:0xf bank_mask:0xf bound_ctrl:1
	s_nop 1
	v_add_f32_dpp v200, v200, v200 quad_perm:[2,3,0,1] row_mask:0xf bank_mask:0xf bound_ctrl:1
	s_nop 1
	v_add_f32_dpp v200, v200, v200 row_half_mirror row_mask:0xf bank_mask:0xf bound_ctrl:1
	s_nop 1
	v_add_f32_dpp v200, v200, v200 row_mirror row_mask:0xf bank_mask:0xf bound_ctrl:1
	s_nop 1
	v_add_f32_dpp v200, v200, v200 row_bcast:15 row_mask:0xa bank_mask:0xf
	s_nop 1
	v_add_f32_dpp v200, v200, v200 row_bcast:31 row_mask:0xc bank_mask:0xf
	s_nop 0
	v_readlane_b32 s27, v200, 63
	s_mul_i32 s40, s25, 0xc00
	s_add_u32 s28, s62, s40
	s_addc_u32 s29, s63, 0
	global_load_dwordx4 v[146:149], v1, s[28:29]
	global_load_dwordx4 v[150:153], v1, s[28:29] offset:2048
	global_load_dwordx4 v[154:157], v1, s[28:29] offset:1024
	v_mul_f32_e32 v204, s27, v212
	v_mul_f32_e32 v205, 0x3f3504f3, v204
	v_cmp_lt_f32_e64 s[32:33], |v205|, 1.0
	s_and_b64 vcc, exec, s[32:33]
	s_cbranch_vccnz .Lsm_25
	v_fma_f32 v208, |v205|, s9, v214
	v_fma_f32 v208, |v205|, v208, s10
	v_fma_f32 v208, |v205|, v208, s11
	v_fma_f32 v208, |v205|, v208, s12
	v_fma_f32 v208, |v205|, v208, s13
	v_fma_f32 v208, |v205|, v208, s14
	v_fma_f32 v208, |v205|, v208, |v205|
	v_mul_f32_e32 v209, 0xbfb8aa3b, v208
	v_fma_f32 v210, v208, s15, -v209
	v_rndne_f32_e32 v211, v209
	v_fmac_f32_e32 v210, 0xb2a5705f, v208
	v_sub_f32_e32 v209, v209, v211
	v_add_f32_e32 v209, v209, v210
	v_cvt_i32_f32_e32 v210, v211
	v_exp_f32_e32 v209, v209
	v_cmp_nlt_f32_e32 vcc, s16, v208
	v_ldexp_f32 v209, v209, v210
	s_nop 0
	v_cndmask_b32_e32 v209, 0, v209, vcc
	v_cmp_ngt_f32_e32 vcc, s17, v208
	s_nop 1
	v_cndmask_b32_e32 v208, v215, v209, vcc
	v_sub_f32_e32 v210, 1.0, v208
	s_branch .Ljn_25

; DEV float gelu_exact(float v) { return 0.5f * v * (1.f + erff(v * 0.7071067811865476f)); }
; DEV void peer_gather_token(const Params& p, int tok) {
;     ...
;   auto issue = [&](int k, int slot) {
;     const int e = (k < 64) ? __builtin_amdgcn_readlane(e0, k) : __builtin_amdgcn_readlane(e1, k - 64);
;     const unsigned char* dr = p.down8 + (size_t)e * ROW6 + lane * 24;
;     const unsigned char* ur = p.up8 + (size_t)e * ROW6 + lane * 24;
; #pragma unroll
;     for (int i = 0; i < 3; ++i) { dn[slot][i] = *(const u32x2*)(dr + i * 8); up[slot][i] = *(const u32x2*)(ur + i * 8); }
;   };
;   issue(0, 0); issue(1, 1); issue(2, 2);
; #pragma unroll 1
;   for (int k4 = 0; k4 < 128; k4 += 4) {
; #pragma unroll
;     for (int s = 0; s < 4; ++s) {
;       const int k = k4 + s;
;       if (k + 3 < 128) issue(k + 3, (s + 3) & 3);
;       const v6u dq = v6u{dn[s][0][0], dn[s][0][1], dn[s][1][0], dn[s][1][1], dn[s][2][0], dn[s][2][1]};
;       const v32f dv = __builtin_amdgcn_cvt_scalef32_pk32_f32_fp6(dq, 1.0f);
;       float d0 = 0.f, d1 = 0.f, d2 = 0.f, d3 = 0.f;
; #pragma unroll
;       for (int i = 0; i < 8; ++i) { d0 += dv[4 * i] * hx[4 * i]; d1 += dv[4 * i + 1] * hx[4 * i + 1]; d2 += dv[4 * i + 2] * hx[4 * i + 2]; d3 += dv[4 * i + 3] * hx[4 * i + 3]; }
;       const float d = wave_sum_fast((d0 + d1) + (d2 + d3)) * (1.f / DOWN_SCALE);
;       const float gk = __builtin_bit_cast(float, (k < 64) ? __builtin_amdgcn_readlane(g0, k) : __builtin_amdgcn_readlane(g1, k - 64));
;       const float act = gelu_exact(d) * gk * (1.f / UP_SCALE);
;       const v6u uq = v6u{up[s][0][0], up[s][0][1], up[s][1][0], up[s][1][1], up[s][2][0], up[s][2][1]};
;       const v32f uv = __builtin_amdgcn_cvt_scalef32_pk32_f32_fp6(uq, 1.0f);
; #pragma unroll
;       for (int i = 0; i < 32; ++i) acc[i] += act * uv[i];
.Ljn_25:
	v_bfi_b32 v209, s18, v210, v205
	v_mul_f32_e32 v208, 0.5, v204
	v_add_f32_e32 v209, 1.0, v209
	v_mul_f32_e32 v208, v208, v209
	v_mul_f32_e32 v208, s26, v208
	v_mul_f32_e32 v206, 0x3e800000, v208
	v_pk_fma_f32 v[66:67], v[2:3], v[206:207], v[66:67] op_sel_hi:[1,0,1]
	v_pk_fma_f32 v[68:69], v[4:5], v[206:207], v[68:69] op_sel_hi:[1,0,1]
	v_pk_fma_f32 v[70:71], v[6:7], v[206:207], v[70:71] op_sel_hi:[1,0,1]
	v_pk_fma_f32 v[72:73], v[8:9], v[206:207], v[72:73] op_sel_hi:[1,0,1]
	v_pk_fma_f32 v[74:75], v[10:11], v[206:207], v[74:75] op_sel_hi:[1,0,1]
	v_pk_fma_f32 v[76:77], v[12:13], v[206:207], v[76:77] op_sel_hi:[1,0,1]
	v_pk_fma_f32 v[78:79], v[14:15], v[206:207], v[78:79] op_sel_hi:[1,0,1]
	v_pk_fma_f32 v[80:81], v[16:17], v[206:207], v[80:81] op_sel_hi:[1,0,1]
	v_pk_fma_f32 v[82:83], v[18:19], v[206:207], v[82:83] op_sel_hi:[1,0,1]
	v_pk_fma_f32 v[84:85], v[20:21], v[206:207], v[84:85] op_sel_hi:[1,0,1]
	v_pk_fma_f32 v[86:87], v[22:23], v[206:207], v[86:87] op_sel_hi:[1,0,1]
	v_pk_fma_f32 v[88:89], v[24:25], v[206:207], v[88:89] op_sel_hi:[1,0,1]
	v_pk_fma_f32 v[90:91], v[26:27], v[206:207], v[90:91] op_sel_hi:[1,0,1]
	v_pk_fma_f32 v[92:93], v[28:29], v[206:207], v[92:93] op_sel_hi:[1,0,1]
	v_pk_fma_f32 v[94:95], v[30:31], v[206:207], v[94:95] op_sel_hi:[1,0,1]
	v_pk_fma_f32 v[96:97], v[32:33], v[206:207], v[96:97] op_sel_hi:[1,0,1]
	s_waitcnt vmcnt(29)
	v_cvt_scalef32_pk32_f32_fp6 v[2:33], v[158:163], 1.0
	v_mul_f32_e32 v200, v2, v34
	v_mul_f32_e32 v201, v3, v35
	v_mul_f32_e32 v202, v4, v36
	v_mul_f32_e32 v203, v5, v37
	v_fmac_f32_e32 v200, v6, v38
	v_fmac_f32_e32 v201, v7, v39
	v_fmac_f32_e32 v202, v8, v40
	v_fmac_f32_e32 v203, v9, v41
	v_fmac_f32_e32 v200, v10, v42
	v_fmac_f32_e32 v201, v11, v43
	v_fmac_f32_e32 v202, v12, v44
	v_fmac_f32_e32 v203, v13, v45
	v_fmac_f32_e32 v200, v14, v46
	v_fmac_f32_e32 v201, v15, v47
	v_fmac_f32_e32 v202, v16, v48
	v_fmac_f32_e32 v203, v17, v49
	v_fmac_f32_e32 v200, v18, v50
	v_fmac_f32_e32 v201, v19, v51
	v_fmac_f32_e32 v202, v20, v52
	v_fmac_f32_e32 v203, v21, v53
	v_fmac_f32_e32 v200, v22, v54
	v_fmac_f32_e32 v201, v23, v55
	v_fmac_f32_e32 v202, v24, v56
	v_fmac_f32_e32 v203, v25, v57
	v_fmac_f32_e32 v200, v26, v58
	v_fmac_f32_e32 v201, v27, v59
	v_fmac_f32_e32 v202, v28, v60
	v_fmac_f32_e32 v203, v29, v61
	v_fmac_f32_e32 v200, v30, v62
	v_fmac_f32_e32 v201, v31, v63
	v_fmac_f32_e32 v202, v32, v64
	v_fmac_f32_e32 v203, v33, v65
	v_add_f32_e32 v200, v201, v200
	v_add_f32_e32 v202, v203, v202
	v_cvt_scalef32_pk32_f32_fp6 v[2:33], v[164:169], 1.0
	v_add_f32_e32 v200, v202, v200
	s_add_i32 s38, s24, 5
	v_readlane_b32 s26, v199, s38
	s_add_i32 s39, s23, 5
	v_readlane_b32 s25, v198, s39
	v_add_f32_dpp v200, v200, v200 quad_perm:[1,0,3,2] row_mask:0xf bank_mask:0xf bound_ctrl:1
	s_nop 1
	v_add_f32_dpp v200, v200, v200 quad_perm:[2,3,0,1] row_mask:0xf bank_mask:0xf bound_ctrl:1
	s_nop 1
	v_add_f32_dpp v200, v200, v200 row_half_mirror row_mask:0xf bank_mask:0xf bound_ctrl:1
	s_nop 1
	v_add_f32_dpp v200, v200, v200 row_mirror row_mask:0xf bank_mask:0xf bound_ctrl:1
	s_nop 1
	v_add_f32_dpp v200, v200, v200 row_bcast:15 row_mask:0xa bank_mask:0xf
	s_nop 1
	v_add_f32_dpp v200, v200, v200 row_bcast:31 row_mask:0xc bank_mask:0xf
	s_nop 0
	v_readlane_b32 s27, v200, 63
	s_mul_i32 s40, s25, 0xc00
	s_add_u32 s28, s62, s40
	s_addc_u32 s29, s63, 0
	global_load_dwordx4 v[158:161], v1, s[28:29]
	global_load_dwordx4 v[162:165], v1, s[28:29] offset:2048
	global_load_dwordx4 v[166:169], v1, s[28:29] offset:1024
	v_mul_f32_e32 v204, s27, v212
	v_mul_f32_e32 v205, 0x3f3504f3, v204
	v_cmp_lt_f32_e64 s[32:33], |v205|, 1.0
	s_and_b64 vcc, exec, s[32:33]
	s_cbranch_vccnz .Lsm_27
	v_fma_f32 v208, |v205|, s9, v214
	v_fma_f32 v208, |v205|, v208, s10
	v_fma_f32 v208, |v205|, v208, s11
	v_fma_f32 v208, |v205|, v208, s12
	v_fma_f32 v208, |v205|, v208, s13
	v_fma_f32 v208, |v205|, v208, s14
	v_fma_f32 v208, |v205|, v208, |v205|
	v_mul_f32_e32 v209, 0xbfb8aa3b, v208
	v_fma_f32 v210, v208, s15, -v209
	v_rndne_f32_e32 v211, v209
	v_fmac_f32_e32 v210, 0xb2a5705f, v208
	v_sub_f32_e32 v209, v209, v211
	v_add_f32_e32 v209, v209, v210
	v_cvt_i32_f32_e32 v210, v211
	v_exp_f32_e32 v209, v209
	v_cmp_nlt_f32_e32 vcc, s16, v208
	v_ldexp_f32 v209, v209, v210
	s_nop 0
	v_cndmask_b32_e32 v209, 0, v209, vcc
	v_cmp_ngt_f32_e32 vcc, s17, v208
	s_nop 1
	v_cndmask_b32_e32 v208, v215, v209, vcc
	v_sub_f32_e32 v210, 1.0, v208
	s_branch .Ljn_27

; DEV float gelu_exact(float v) { return 0.5f * v * (1.f + erff(v * 0.7071067811865476f)); }
; DEV void peer_gather_token(const Params& p, int tok) {
;     ...
;   auto issue = [&](int k, int slot) {
;     const int e = (k < 64) ? __builtin_amdgcn_readlane(e0, k) : __builtin_amdgcn_readlane(e1, k - 64);
;     const unsigned char* dr = p.down8 + (size_t)e * ROW6 + lane * 24;
;     const unsigned char* ur = p.up8 + (size_t)e * ROW6 + lane * 24;
; #pragma unroll
;     for (int i = 0; i < 3; ++i) { dn[slot][i] = *(const u32x2*)(dr + i * 8); up[slot][i] = *(const u32x2*)(ur + i * 8); }
;   };
;   issue(0, 0); issue(1, 1); issue(2, 2);
; #pragma unroll 1
;   for (int k4 = 0; k4 < 128; k4 += 4) {
; #pragma unroll
;     for (int s = 0; s < 4; ++s) {
;       const int k = k4 + s;
;       if (k + 3 < 128) issue(k + 3, (s + 3) & 3);
;       const v6u dq = v6u{dn[s][0][0], dn[s][0][1], dn[s][1][0], dn[s][1][1], dn[s][2][0], dn[s][2][1]};
;       const v32f dv = __builtin_amdgcn_cvt_scalef32_pk32_f32_fp6(dq, 1.0f);
;       float d0 = 0.f, d1 = 0.f, d2 = 0.f, d3 = 0.f;
; #pragma unroll
;       for (int i = 0; i < 8; ++i) { d0 += dv[4 * i] * hx[4 * i]; d1 += dv[4 * i + 1] * hx[4 * i + 1]; d2 += dv[4 * i + 2] * hx[4 * i + 2]; d3 += dv[4 * i + 3] * hx[4 * i + 3]; }
;       const float d = wave_sum_fast((d0 + d1) + (d2 + d3)) * (1.f / DOWN_SCALE);
;       const float gk = __builtin_bit_cast(float, (k < 64) ? __builtin_amdgcn_readlane(g0, k) : __builtin_amdgcn_readlane(g1, k - 64));
;       const float act = gelu_exact(d) * gk * (1.f / UP_SCALE);
;       const v6u uq = v6u{up[s][0][0], up[s][0][1], up[s][1][0], up[s][1][1], up[s][2][0], up[s][2][1]};
;       const v32f uv = __builtin_amdgcn_cvt_scalef32_pk32_f32_fp6(uq, 1.0f);
; #pragma unroll
;       for (int i = 0; i < 32; ++i) acc[i] += act * uv[i];
.Ljn_27:
	v_bfi_b32 v209, s18, v210, v205
	v_mul_f32_e32 v208, 0.5, v204
	v_add_f32_e32 v209, 1.0, v209
	v_mul_f32_e32 v208, v208, v209
	v_mul_f32_e32 v208, s26, v208
	v_mul_f32_e32 v206, 0x3e800000, v208
	v_pk_fma_f32 v[66:67], v[2:3], v[206:207], v[66:67] op_sel_hi:[1,0,1]
	v_pk_fma_f32 v[68:69], v[4:5], v[206:207], v[68:69] op_sel_hi:[1,0,1]
	v_pk_fma_f32 v[70:71], v[6:7], v[206:207], v[70:71] op_sel_hi:[1,0,1]
	v_pk_fma_f32 v[72:73], v[8:9], v[206:207], v[72:73] op_sel_hi:[1,0,1]
	v_pk_fma_f32 v[74:75], v[10:11], v[206:207], v[74:75] op_sel_hi:[1,0,1]
	v_pk_fma_f32 v[76:77], v[12:13], v[206:207], v[76:77] op_sel_hi:[1,0,1]
	v_pk_fma_f32 v[78:79], v[14:15], v[206:207], v[78:79] op_sel_hi:[1,0,1]
	v_pk_fma_f32 v[80:81], v[16:17], v[206:207], v[80:81] op_sel_hi:[1,0,1]
	v_pk_fma_f32 v[82:83], v[18:19], v[206:207], v[82:83] op_sel_hi:[1,0,1]
	v_pk_fma_f32 v[84:85], v[20:21], v[206:207], v[84:85] op_sel_hi:[1,0,1]
	v_pk_fma_f32 v[86:87], v[22:23], v[206:207], v[86:87] op_sel_hi:[1,0,1]
	v_pk_fma_f32 v[88:89], v[24:25], v[206:207], v[88:89] op_sel_hi:[1,0,1]
	v_pk_fma_f32 v[90:91], v[26:27], v[206:207], v[90:91] op_sel_hi:[1,0,1]
	v_pk_fma_f32 v[92:93], v[28:29], v[206:207], v[92:93] op_sel_hi:[1,0,1]
	v_pk_fma_f32 v[94:95], v[30:31], v[206:207], v[94:95] op_sel_hi:[1,0,1]
	v_pk_fma_f32 v[96:97], v[32:33], v[206:207], v[96:97] op_sel_hi:[1,0,1]
	s_waitcnt vmcnt(29)
	v_cvt_scalef32_pk32_f32_fp6 v[2:33], v[170:175], 1.0
	v_mul_f32_e32 v200, v2, v34
	v_mul_f32_e32 v201, v3, v35
	v_mul_f32_e32 v202, v4, v36
	v_mul_f32_e32 v203, v5, v37
	v_fmac_f32_e32 v200, v6, v38
	v_fmac_f32_e32 v201, v7, v39
	v_fmac_f32_e32 v202, v8, v40
	v_fmac_f32_e32 v203, v9, v41
	v_fmac_f32_e32 v200, v10, v42
	v_fmac_f32_e32 v201, v11, v43
	v_fmac_f32_e32 v202, v12, v44
	v_fmac_f32_e32 v203, v13, v45
	v_fmac_f32_e32 v200, v14, v46
	v_fmac_f32_e32 v201, v15, v47
	v_fmac_f32_e32 v202, v16, v48
	v_fmac_f32_e32 v203, v17, v49
	v_fmac_f32_e32 v200, v18, v50
	v_fmac_f32_e32 v201, v19, v51
	v_fmac_f32_e32 v202, v20, v52
	v_fmac_f32_e32 v203, v21, v53
	v_fmac_f32_e32 v200, v22, v54
	v_fmac_f32_e32 v201, v23, v55
	v_fmac_f32_e32 v202, v24, v56
	v_fmac_f32_e32 v203, v25, v57
	v_fmac_f32_e32 v200, v26, v58
	v_fmac_f32_e32 v201, v27, v59
	v_fmac_f32_e32 v202, v28, v60
	v_fmac_f32_e32 v203, v29, v61
	v_fmac_f32_e32 v200, v30, v62
	v_fmac_f32_e32 v201, v31, v63
	v_fmac_f32_e32 v202, v32, v64
	v_fmac_f32_e32 v203, v33, v65
	v_add_f32_e32 v200, v201, v200
	v_add_f32_e32 v202, v203, v202
	v_cvt_scalef32_pk32_f32_fp6 v[2:33], v[176:181], 1.0
	v_add_f32_e32 v200, v202, v200
	s_add_i32 s38, s24, 6
	v_readlane_b32 s26, v199, s38
	s_add_i32 s39, s23, 6
	v_readlane_b32 s25, v198, s39
	v_add_f32_dpp v200, v200, v200 quad_perm:[1,0,3,2] row_mask:0xf bank_mask:0xf bound_ctrl:1
	s_nop 1
	v_add_f32_dpp v200, v200, v200 quad_perm:[2,3,0,1] row_mask:0xf bank_mask:0xf bound_ctrl:1
	s_nop 1
	v_add_f32_dpp v200, v200, v200 row_half_mirror row_mask:0xf bank_mask:0xf bound_ctrl:1
	s_nop 1
	v_add_f32_dpp v200, v200, v200 row_mirror row_mask:0xf bank_mask:0xf bound_ctrl:1
	s_nop 1
	v_add_f32_dpp v200, v200, v200 row_bcast:15 row_mask:0xa bank_mask:0xf
	s_nop 1
	v_add_f32_dpp v200, v200, v200 row_bcast:31 row_mask:0xc bank_mask:0xf
	s_nop 0
	v_readlane_b32 s27, v200, 63
	s_mul_i32 s40, s25, 0xc00
	s_add_u32 s28, s62, s40
	s_addc_u32 s29, s63, 0
	global_load_dwordx4 v[170:173], v1, s[28:29]
	global_load_dwordx4 v[174:177], v1, s[28:29] offset:2048
	global_load_dwordx4 v[178:181], v1, s[28:29] offset:1024
	v_mul_f32_e32 v204, s27, v212
	v_mul_f32_e32 v205, 0x3f3504f3, v204
	v_cmp_lt_f32_e64 s[32:33], |v205|, 1.0
	s_and_b64 vcc, exec, s[32:33]
	s_cbranch_vccnz .Lsm_29
	v_fma_f32 v208, |v205|, s9, v214
	v_fma_f32 v208, |v205|, v208, s10
	v_fma_f32 v208, |v205|, v208, s11
	v_fma_f32 v208, |v205|, v208, s12
	v_fma_f32 v208, |v205|, v208, s13
	v_fma_f32 v208, |v205|, v208, s14
	v_fma_f32 v208, |v205|, v208, |v205|
	v_mul_f32_e32 v209, 0xbfb8aa3b, v208
	v_fma_f32 v210, v208, s15, -v209
	v_rndne_f32_e32 v211, v209
	v_fmac_f32_e32 v210, 0xb2a5705f, v208
	v_sub_f32_e32 v209, v209, v211
	v_add_f32_e32 v209, v209, v210
	v_cvt_i32_f32_e32 v210, v211
	v_exp_f32_e32 v209, v209
	v_cmp_nlt_f32_e32 vcc, s16, v208
	v_ldexp_f32 v209, v209, v210
	s_nop 0
	v_cndmask_b32_e32 v209, 0, v209, vcc
	v_cmp_ngt_f32_e32 vcc, s17, v208
	s_nop 1
	v_cndmask_b32_e32 v208, v215, v209, vcc
	v_sub_f32_e32 v210, 1.0, v208
	s_branch .Ljn_29

; DEV float gelu_exact(float v) { return 0.5f * v * (1.f + erff(v * 0.7071067811865476f)); }
; DEV void peer_gather_token(const Params& p, int tok) {
;     ...
;   auto issue = [&](int k, int slot) {
;     const int e = (k < 64) ? __builtin_amdgcn_readlane(e0, k) : __builtin_amdgcn_readlane(e1, k - 64);
;     const unsigned char* dr = p.down8 + (size_t)e * ROW6 + lane * 24;
;     const unsigned char* ur = p.up8 + (size_t)e * ROW6 + lane * 24;
; #pragma unroll
;     for (int i = 0; i < 3; ++i) { dn[slot][i] = *(const u32x2*)(dr + i * 8); up[slot][i] = *(const u32x2*)(ur + i * 8); }
;   };
;   issue(0, 0); issue(1, 1); issue(2, 2);
; #pragma unroll 1
;   for (int k4 = 0; k4 < 128; k4 += 4) {
; #pragma unroll
;     for (int s = 0; s < 4; ++s) {
;       const int k = k4 + s;
;       if (k + 3 < 128) issue(k + 3, (s + 3) & 3);
;       const v6u dq = v6u{dn[s][0][0], dn[s][0][1], dn[s][1][0], dn[s][1][1], dn[s][2][0], dn[s][2][1]};
;       const v32f dv = __builtin_amdgcn_cvt_scalef32_pk32_f32_fp6(dq, 1.0f);
;       float d0 = 0.f, d1 = 0.f, d2 = 0.f, d3 = 0.f;
; #pragma unroll
;       for (int i = 0; i < 8; ++i) { d0 += dv[4 * i] * hx[4 * i]; d1 += dv[4 * i + 1] * hx[4 * i + 1]; d2 += dv[4 * i + 2] * hx[4 * i + 2]; d3 += dv[4 * i + 3] * hx[4 * i + 3]; }
;       const float d = wave_sum_fast((d0 + d1) + (d2 + d3)) * (1.f / DOWN_SCALE);
;       const float gk = __builtin_bit_cast(float, (k < 64) ? __builtin_amdgcn_readlane(g0, k) : __builtin_amdgcn_readlane(g1, k - 64));
;       const float act = gelu_exact(d) * gk * (1.f / UP_SCALE);
;       const v6u uq = v6u{up[s][0][0], up[s][0][1], up[s][1][0], up[s][1][1], up[s][2][0], up[s][2][1]};
;       const v32f uv = __builtin_amdgcn_cvt_scalef32_pk32_f32_fp6(uq, 1.0f);
; #pragma unroll
;       for (int i = 0; i < 32; ++i) acc[i] += act * uv[i];
.Ljn_29:
	v_bfi_b32 v209, s18, v210, v205
	v_mul_f32_e32 v208, 0.5, v204
	v_add_f32_e32 v209, 1.0, v209
	v_mul_f32_e32 v208, v208, v209
	v_mul_f32_e32 v208, s26, v208
	v_mul_f32_e32 v206, 0x3e800000, v208
	v_pk_fma_f32 v[66:67], v[2:3], v[206:207], v[66:67] op_sel_hi:[1,0,1]
	v_pk_fma_f32 v[68:69], v[4:5], v[206:207], v[68:69] op_sel_hi:[1,0,1]
	v_pk_fma_f32 v[70:71], v[6:7], v[206:207], v[70:71] op_sel_hi:[1,0,1]
	v_pk_fma_f32 v[72:73], v[8:9], v[206:207], v[72:73] op_sel_hi:[1,0,1]
	v_pk_fma_f32 v[74:75], v[10:11], v[206:207], v[74:75] op_sel_hi:[1,0,1]
	v_pk_fma_f32 v[76:77], v[12:13], v[206:207], v[76:77] op_sel_hi:[1,0,1]
	v_pk_fma_f32 v[78:79], v[14:15], v[206:207], v[78:79] op_sel_hi:[1,0,1]
	v_pk_fma_f32 v[80:81], v[16:17], v[206:207], v[80:81] op_sel_hi:[1,0,1]
	v_pk_fma_f32 v[82:83], v[18:19], v[206:207], v[82:83] op_sel_hi:[1,0,1]
	v_pk_fma_f32 v[84:85], v[20:21], v[206:207], v[84:85] op_sel_hi:[1,0,1]
	v_pk_fma_f32 v[86:87], v[22:23], v[206:207], v[86:87] op_sel_hi:[1,0,1]
	v_pk_fma_f32 v[88:89], v[24:25], v[206:207], v[88:89] op_sel_hi:[1,0,1]
	v_pk_fma_f32 v[90:91], v[26:27], v[206:207], v[90:91] op_sel_hi:[1,0,1]
	v_pk_fma_f32 v[92:93], v[28:29], v[206:207], v[92:93] op_sel_hi:[1,0,1]
	v_pk_fma_f32 v[94:95], v[30:31], v[206:207], v[94:95] op_sel_hi:[1,0,1]
	v_pk_fma_f32 v[96:97], v[32:33], v[206:207], v[96:97] op_sel_hi:[1,0,1]
	s_waitcnt vmcnt(29)
	v_cvt_scalef32_pk32_f32_fp6 v[2:33], v[182:187], 1.0
	v_mul_f32_e32 v200, v2, v34
	v_mul_f32_e32 v201, v3, v35
	v_mul_f32_e32 v202, v4, v36
	v_mul_f32_e32 v203, v5, v37
	v_fmac_f32_e32 v200, v6, v38
	v_fmac_f32_e32 v201, v7, v39
	v_fmac_f32_e32 v202, v8, v40
	v_fmac_f32_e32 v203, v9, v41
	v_fmac_f32_e32 v200, v10, v42
	v_fmac_f32_e32 v201, v11, v43
	v_fmac_f32_e32 v202, v12, v44
	v_fmac_f32_e32 v203, v13, v45
	v_fmac_f32_e32 v200, v14, v46
	v_fmac_f32_e32 v201, v15, v47
	v_fmac_f32_e32 v202, v16, v48
	v_fmac_f32_e32 v203, v17, v49
	v_fmac_f32_e32 v200, v18, v50
	v_fmac_f32_e32 v201, v19, v51
	v_fmac_f32_e32 v202, v20, v52
	v_fmac_f32_e32 v203, v21, v53
	v_fmac_f32_e32 v200, v22, v54
	v_fmac_f32_e32 v201, v23, v55
	v_fmac_f32_e32 v202, v24, v56
	v_fmac_f32_e32 v203, v25, v57
	v_fmac_f32_e32 v200, v26, v58
	v_fmac_f32_e32 v201, v27, v59
	v_fmac_f32_e32 v202, v28, v60
	v_fmac_f32_e32 v203, v29, v61
	v_fmac_f32_e32 v200, v30, v62
	v_fmac_f32_e32 v201, v31, v63
	v_fmac_f32_e32 v202, v32, v64
	v_fmac_f32_e32 v203, v33, v65
	v_add_f32_e32 v200, v201, v200
	v_add_f32_e32 v202, v203, v202
	v_cvt_scalef32_pk32_f32_fp6 v[2:33], v[188:193], 1.0
	v_add_f32_e32 v200, v202, v200
	s_add_i32 s38, s24, 7
	v_readlane_b32 s26, v199, s38
	s_add_i32 s39, s23, 7
	v_readlane_b32 s25, v198, s39
	v_add_f32_dpp v200, v200, v200 quad_perm:[1,0,3,2] row_mask:0xf bank_mask:0xf bound_ctrl:1
	s_nop 1
	v_add_f32_dpp v200, v200, v200 quad_perm:[2,3,0,1] row_mask:0xf bank_mask:0xf bound_ctrl:1
	s_nop 1
	v_add_f32_dpp v200, v200, v200 row_half_mirror row_mask:0xf bank_mask:0xf bound_ctrl:1
	s_nop 1
	v_add_f32_dpp v200, v200, v200 row_mirror row_mask:0xf bank_mask:0xf bound_ctrl:1
	s_nop 1
	v_add_f32_dpp v200, v200, v200 row_bcast:15 row_mask:0xa bank_mask:0xf
	s_nop 1
	v_add_f32_dpp v200, v200, v200 row_bcast:31 row_mask:0xc bank_mask:0xf
	s_nop 0
	v_readlane_b32 s27, v200, 63
	s_mul_i32 s40, s25, 0xc00
	s_add_u32 s28, s62, s40
	s_addc_u32 s29, s63, 0
	global_load_dwordx4 v[182:185], v1, s[28:29]
	global_load_dwordx4 v[186:189], v1, s[28:29] offset:2048
	global_load_dwordx4 v[190:193], v1, s[28:29] offset:1024
	v_mul_f32_e32 v204, s27, v212
	v_mul_f32_e32 v205, 0x3f3504f3, v204
	v_cmp_lt_f32_e64 s[32:33], |v205|, 1.0
	s_and_b64 vcc, exec, s[32:33]
	s_cbranch_vccnz .Lsm_31
	v_fma_f32 v208, |v205|, s9, v214
	v_fma_f32 v208, |v205|, v208, s10
	v_fma_f32 v208, |v205|, v208, s11
	v_fma_f32 v208, |v205|, v208, s12
	v_fma_f32 v208, |v205|, v208, s13
	v_fma_f32 v208, |v205|, v208, s14
	v_fma_f32 v208, |v205|, v208, |v205|
	v_mul_f32_e32 v209, 0xbfb8aa3b, v208
	v_fma_f32 v210, v208, s15, -v209
	v_rndne_f32_e32 v211, v209
	v_fmac_f32_e32 v210, 0xb2a5705f, v208
	v_sub_f32_e32 v209, v209, v211
	v_add_f32_e32 v209, v209, v210
	v_cvt_i32_f32_e32 v210, v211
	v_exp_f32_e32 v209, v209
	v_cmp_nlt_f32_e32 vcc, s16, v208
	v_ldexp_f32 v209, v209, v210
	s_nop 0
	v_cndmask_b32_e32 v209, 0, v209, vcc
	v_cmp_ngt_f32_e32 vcc, s17, v208
	s_nop 1
	v_cndmask_b32_e32 v208, v215, v209, vcc
	v_sub_f32_e32 v210, 1.0, v208
	s_branch .Ljn_31

; DEV void peer_gather_token(const Params& p, int tok) {
;     ...
;   const int e0 = p.eidx[(size_t)tok * 128 + lane], e1 = p.eidx[(size_t)tok * 128 + 64 + lane];
;   const int g0 = __builtin_bit_cast(int, p.gw[(size_t)tok * 128 + lane]), g1 = __builtin_bit_cast(int, p.gw[(size_t)tok * 128 + 64 + lane]);
;   u32x2 dn[4][3], up[4][3];
;   auto issue = [&](int k, int slot) {
;     const int e = (k < 64) ? __builtin_amdgcn_readlane(e0, k) : __builtin_amdgcn_readlane(e1, k - 64);
.Ljn_31:
	v_bfi_b32 v209, s18, v210, v205
	v_mul_f32_e32 v208, 0.5, v204
	v_add_f32_e32 v209, 1.0, v209
	v_mul_f32_e32 v208, v208, v209
	v_mul_f32_e32 v208, s26, v208
	v_mul_f32_e32 v206, 0x3e800000, v208
	v_pk_fma_f32 v[66:67], v[2:3], v[206:207], v[66:67] op_sel_hi:[1,0,1]
	v_pk_fma_f32 v[68:69], v[4:5], v[206:207], v[68:69] op_sel_hi:[1,0,1]
	v_pk_fma_f32 v[70:71], v[6:7], v[206:207], v[70:71] op_sel_hi:[1,0,1]
	v_pk_fma_f32 v[72:73], v[8:9], v[206:207], v[72:73] op_sel_hi:[1,0,1]
	v_pk_fma_f32 v[74:75], v[10:11], v[206:207], v[74:75] op_sel_hi:[1,0,1]
	v_pk_fma_f32 v[76:77], v[12:13], v[206:207], v[76:77] op_sel_hi:[1,0,1]
	v_pk_fma_f32 v[78:79], v[14:15], v[206:207], v[78:79] op_sel_hi:[1,0,1]
	v_pk_fma_f32 v[80:81], v[16:17], v[206:207], v[80:81] op_sel_hi:[1,0,1]
	v_pk_fma_f32 v[82:83], v[18:19], v[206:207], v[82:83] op_sel_hi:[1,0,1]
	v_pk_fma_f32 v[84:85], v[20:21], v[206:207], v[84:85] op_sel_hi:[1,0,1]
	v_pk_fma_f32 v[86:87], v[22:23], v[206:207], v[86:87] op_sel_hi:[1,0,1]
	v_pk_fma_f32 v[88:89], v[24:25], v[206:207], v[88:89] op_sel_hi:[1,0,1]
	v_pk_fma_f32 v[90:91], v[26:27], v[206:207], v[90:91] op_sel_hi:[1,0,1]
	v_pk_fma_f32 v[92:93], v[28:29], v[206:207], v[92:93] op_sel_hi:[1,0,1]
	v_pk_fma_f32 v[94:95], v[30:31], v[206:207], v[94:95] op_sel_hi:[1,0,1]
	v_pk_fma_f32 v[96:97], v[32:33], v[206:207], v[96:97] op_sel_hi:[1,0,1]
	s_add_i32 s24, s24, 8
	s_and_b32 s24, s24, 63
	s_waitcnt vmcnt(21)
	v_and_b32_e32 v236, 63, v0
	v_lshrrev_b32_e32 v241, 6, v0
	v_lshl_or_b32 v237, v216, 7, v236
	v_or_b32_e32 v238, 64, v236
	v_lshl_or_b32 v238, v217, 7, v238
	v_mov_b32_e32 v239, 0
	v_mov_b32_e32 v240, 0
	v_lshlrev_b32_e32 v241, 10, v241
	v_lshl_add_u32 v241, v236, 2, v241
	v_readlane_b32 s46, v237, 0
	v_readlane_b32 s47, v238, 0
	s_nop 1
	v_cmp_lt_u32_e64 s[48:49], s46, v237
	v_cmp_lt_u32_e64 s[50:51], s46, v238
	v_cmp_lt_u32_e64 s[52:53], s47, v237
	v_cmp_lt_u32_e64 s[54:55], s47, v238
	v_readlane_b32 s46, v237, 1
	v_readlane_b32 s47, v238, 1
	v_addc_co_u32_e64 v239, s[56:57], 0, v239, s[48:49]
	v_addc_co_u32_e64 v240, s[56:57], 0, v240, s[50:51]
	v_addc_co_u32_e64 v239, s[56:57], 0, v239, s[52:53]
	v_addc_co_u32_e64 v240, s[56:57], 0, v240, s[54:55]
	v_cmp_lt_u32_e64 s[48:49], s46, v237
	v_cmp_lt_u32_e64 s[50:51], s46, v238
	v_cmp_lt_u32_e64 s[52:53], s47, v237
	v_cmp_lt_u32_e64 s[54:55], s47, v238
	v_readlane_b32 s46, v237, 2
	v_readlane_b32 s47, v238, 2
	v_addc_co_u32_e64 v239, s[56:57], 0, v239, s[48:49]
	v_addc_co_u32_e64 v240, s[56:57], 0, v240, s[50:51]
	v_addc_co_u32_e64 v239, s[56:57], 0, v239, s[52:53]
	v_addc_co_u32_e64 v240, s[56:57], 0, v240, s[54:55]
	v_cmp_lt_u32_e64 s[48:49], s46, v237
	v_cmp_lt_u32_e64 s[50:51], s46, v238
	v_cmp_lt_u32_e64 s[52:53], s47, v237
	v_cmp_lt_u32_e64 s[54:55], s47, v238
	v_readlane_b32 s46, v237, 3
	v_readlane_b32 s47, v238, 3
	v_addc_co_u32_e64 v239, s[56:57], 0, v239, s[48:49]
	v_addc_co_u32_e64 v240, s[56:57], 0, v240, s[50:51]
	v_addc_co_u32_e64 v239, s[56:57], 0, v239, s[52:53]
	v_addc_co_u32_e64 v240, s[56:57], 0, v240, s[54:55]
	v_cmp_lt_u32_e64 s[48:49], s46, v237
	v_cmp_lt_u32_e64 s[50:51], s46, v238
	v_cmp_lt_u32_e64 s[52:53], s47, v237
	v_cmp_lt_u32_e64 s[54:55], s47, v238
	v_readlane_b32 s46, v237, 4
	v_readlane_b32 s47, v238, 4
	v_addc_co_u32_e64 v239, s[56:57], 0, v239, s[48:49]
	v_addc_co_u32_e64 v240, s[56:57], 0, v240, s[50:51]
	v_addc_co_u32_e64 v239, s[56:57], 0, v239, s[52:53]
	v_addc_co_u32_e64 v240, s[56:57], 0, v240, s[54:55]
	v_cmp_lt_u32_e64 s[48:49], s46, v237
	v_cmp_lt_u32_e64 s[50:51], s46, v238
	v_cmp_lt_u32_e64 s[52:53], s47, v237
	v_cmp_lt_u32_e64 s[54:55], s47, v238
	v_readlane_b32 s46, v237, 5
	v_readlane_b32 s47, v238, 5
	v_addc_co_u32_e64 v239, s[56:57], 0, v239, s[48:49]
	v_addc_co_u32_e64 v240, s[56:57], 0, v240, s[50:51]
	v_addc_co_u32_e64 v239, s[56:57], 0, v239, s[52:53]
	v_addc_co_u32_e64 v240, s[56:57], 0, v240, s[54:55]
	v_cmp_lt_u32_e64 s[48:49], s46, v237
	v_cmp_lt_u32_e64 s[50:51], s46, v238
	v_cmp_lt_u32_e64 s[52:53], s47, v237
	v_cmp_lt_u32_e64 s[54:55], s47, v238
	v_readlane_b32 s46, v237, 6
	v_readlane_b32 s47, v238, 6
	v_addc_co_u32_e64 v239, s[56:57], 0, v239, s[48:49]
	v_addc_co_u32_e64 v240, s[56:57], 0, v240, s[50:51]
	v_addc_co_u32_e64 v239, s[56:57], 0, v239, s[52:53]
	v_addc_co_u32_e64 v240, s[56:57], 0, v240, s[54:55]
	v_cmp_lt_u32_e64 s[48:49], s46, v237
	v_cmp_lt_u32_e64 s[50:51], s46, v238
	v_cmp_lt_u32_e64 s[52:53], s47, v237
	v_cmp_lt_u32_e64 s[54:55], s47, v238
	v_readlane_b32 s46, v237, 7
	v_readlane_b32 s47, v238, 7
	v_addc_co_u32_e64 v239, s[56:57], 0, v239, s[48:49]
	v_addc_co_u32_e64 v240, s[56:57], 0, v240, s[50:51]
	v_addc_co_u32_e64 v239, s[56:57], 0, v239, s[52:53]
	v_addc_co_u32_e64 v240, s[56:57], 0, v240, s[54:55]
	v_cmp_lt_u32_e64 s[48:49], s46, v237
	v_cmp_lt_u32_e64 s[50:51], s46, v238
	v_cmp_lt_u32_e64 s[52:53], s47, v237
	v_cmp_lt_u32_e64 s[54:55], s47, v238
	v_readlane_b32 s46, v237, 8
	v_readlane_b32 s47, v238, 8
	v_addc_co_u32_e64 v239, s[56:57], 0, v239, s[48:49]
	v_addc_co_u32_e64 v240, s[56:57], 0, v240, s[50:51]
	v_addc_co_u32_e64 v239, s[56:57], 0, v239, s[52:53]
	v_addc_co_u32_e64 v240, s[56:57], 0, v240, s[54:55]
	v_cmp_lt_u32_e64 s[48:49], s46, v237
	v_cmp_lt_u32_e64 s[50:51], s46, v238
	v_cmp_lt_u32_e64 s[52:53], s47, v237
	v_cmp_lt_u32_e64 s[54:55], s47, v238
	v_readlane_b32 s46, v237, 9
	v_readlane_b32 s47, v238, 9
	v_addc_co_u32_e64 v239, s[56:57], 0, v239, s[48:49]
	v_addc_co_u32_e64 v240, s[56:57], 0, v240, s[50:51]
	v_addc_co_u32_e64 v239, s[56:57], 0, v239, s[52:53]
	v_addc_co_u32_e64 v240, s[56:57], 0, v240, s[54:55]
	v_cmp_lt_u32_e64 s[48:49], s46, v237
	v_cmp_lt_u32_e64 s[50:51], s46, v238
; DEV void peer_gather_token(const Params& p, int tok) {
;     ...
;   const int e0 = p.eidx[(size_t)tok * 128 + lane], e1 = p.eidx[(size_t)tok * 128 + 64 + lane];
;   const int g0 = __builtin_bit_cast(int, p.gw[(size_t)tok * 128 + lane]), g1 = __builtin_bit_cast(int, p.gw[(size_t)tok * 128 + 64 + lane]);
;   u32x2 dn[4][3], up[4][3];
;   auto issue = [&](int k, int slot) {
;     const int e = (k < 64) ? __builtin_amdgcn_readlane(e0, k) : __builtin_amdgcn_readlane(e1, k - 64);
	v_cmp_lt_u32_e64 s[52:53], s47, v237
	v_cmp_lt_u32_e64 s[54:55], s47, v238
	v_readlane_b32 s46, v237, 10
	v_readlane_b32 s47, v238, 10
	v_addc_co_u32_e64 v239, s[56:57], 0, v239, s[48:49]
	v_addc_co_u32_e64 v240, s[56:57], 0, v240, s[50:51]
	v_addc_co_u32_e64 v239, s[56:57], 0, v239, s[52:53]
	v_addc_co_u32_e64 v240, s[56:57], 0, v240, s[54:55]
	v_cmp_lt_u32_e64 s[48:49], s46, v237
	v_cmp_lt_u32_e64 s[50:51], s46, v238
	v_cmp_lt_u32_e64 s[52:53], s47, v237
	v_cmp_lt_u32_e64 s[54:55], s47, v238
	v_readlane_b32 s46, v237, 11
	v_readlane_b32 s47, v238, 11
	v_addc_co_u32_e64 v239, s[56:57], 0, v239, s[48:49]
	v_addc_co_u32_e64 v240, s[56:57], 0, v240, s[50:51]
	v_addc_co_u32_e64 v239, s[56:57], 0, v239, s[52:53]
	v_addc_co_u32_e64 v240, s[56:57], 0, v240, s[54:55]
	v_cmp_lt_u32_e64 s[48:49], s46, v237
	v_cmp_lt_u32_e64 s[50:51], s46, v238
	v_cmp_lt_u32_e64 s[52:53], s47, v237
	v_cmp_lt_u32_e64 s[54:55], s47, v238
	v_readlane_b32 s46, v237, 12
	v_readlane_b32 s47, v238, 12
	v_addc_co_u32_e64 v239, s[56:57], 0, v239, s[48:49]
	v_addc_co_u32_e64 v240, s[56:57], 0, v240, s[50:51]
	v_addc_co_u32_e64 v239, s[56:57], 0, v239, s[52:53]
	v_addc_co_u32_e64 v240, s[56:57], 0, v240, s[54:55]
	v_cmp_lt_u32_e64 s[48:49], s46, v237
	v_cmp_lt_u32_e64 s[50:51], s46, v238
	v_cmp_lt_u32_e64 s[52:53], s47, v237
	v_cmp_lt_u32_e64 s[54:55], s47, v238
	v_readlane_b32 s46, v237, 13
	v_readlane_b32 s47, v238, 13
	v_addc_co_u32_e64 v239, s[56:57], 0, v239, s[48:49]
	v_addc_co_u32_e64 v240, s[56:57], 0, v240, s[50:51]
	v_addc_co_u32_e64 v239, s[56:57], 0, v239, s[52:53]
	v_addc_co_u32_e64 v240, s[56:57], 0, v240, s[54:55]
	v_cmp_lt_u32_e64 s[48:49], s46, v237
	v_cmp_lt_u32_e64 s[50:51], s46, v238
	v_cmp_lt_u32_e64 s[52:53], s47, v237
	v_cmp_lt_u32_e64 s[54:55], s47, v238
	v_readlane_b32 s46, v237, 14
	v_readlane_b32 s47, v238, 14
	v_addc_co_u32_e64 v239, s[56:57], 0, v239, s[48:49]
	v_addc_co_u32_e64 v240, s[56:57], 0, v240, s[50:51]
	v_addc_co_u32_e64 v239, s[56:57], 0, v239, s[52:53]
	v_addc_co_u32_e64 v240, s[56:57], 0, v240, s[54:55]
	v_cmp_lt_u32_e64 s[48:49], s46, v237
	v_cmp_lt_u32_e64 s[50:51], s46, v238
	v_cmp_lt_u32_e64 s[52:53], s47, v237
	v_cmp_lt_u32_e64 s[54:55], s47, v238
	v_readlane_b32 s46, v237, 15
	v_readlane_b32 s47, v238, 15
	v_addc_co_u32_e64 v239, s[56:57], 0, v239, s[48:49]
	v_addc_co_u32_e64 v240, s[56:57], 0, v240, s[50:51]
	v_addc_co_u32_e64 v239, s[56:57], 0, v239, s[52:53]
	v_addc_co_u32_e64 v240, s[56:57], 0, v240, s[54:55]
	v_cmp_lt_u32_e64 s[48:49], s46, v237
	v_cmp_lt_u32_e64 s[50:51], s46, v238
	v_cmp_lt_u32_e64 s[52:53], s47, v237
	v_cmp_lt_u32_e64 s[54:55], s47, v238
	v_readlane_b32 s46, v237, 16
	v_readlane_b32 s47, v238, 16
	v_addc_co_u32_e64 v239, s[56:57], 0, v239, s[48:49]
	v_addc_co_u32_e64 v240, s[56:57], 0, v240, s[50:51]
	v_addc_co_u32_e64 v239, s[56:57], 0, v239, s[52:53]
	v_addc_co_u32_e64 v240, s[56:57], 0, v240, s[54:55]
	v_cmp_lt_u32_e64 s[48:49], s46, v237
	v_cmp_lt_u32_e64 s[50:51], s46, v238
	v_cmp_lt_u32_e64 s[52:53], s47, v237
	v_cmp_lt_u32_e64 s[54:55], s47, v238
	v_readlane_b32 s46, v237, 17
	v_readlane_b32 s47, v238, 17
	v_addc_co_u32_e64 v239, s[56:57], 0, v239, s[48:49]
	v_addc_co_u32_e64 v240, s[56:57], 0, v240, s[50:51]
	v_addc_co_u32_e64 v239, s[56:57], 0, v239, s[52:53]
	v_addc_co_u32_e64 v240, s[56:57], 0, v240, s[54:55]
	v_cmp_lt_u32_e64 s[48:49], s46, v237
	v_cmp_lt_u32_e64 s[50:51], s46, v238
	v_cmp_lt_u32_e64 s[52:53], s47, v237
	v_cmp_lt_u32_e64 s[54:55], s47, v238
	v_readlane_b32 s46, v237, 18
	v_readlane_b32 s47, v238, 18
	v_addc_co_u32_e64 v239, s[56:57], 0, v239, s[48:49]
	v_addc_co_u32_e64 v240, s[56:57], 0, v240, s[50:51]
	v_addc_co_u32_e64 v239, s[56:57], 0, v239, s[52:53]
	v_addc_co_u32_e64 v240, s[56:57], 0, v240, s[54:55]
	v_cmp_lt_u32_e64 s[48:49], s46, v237
	v_cmp_lt_u32_e64 s[50:51], s46, v238
	v_cmp_lt_u32_e64 s[52:53], s47, v237
	v_cmp_lt_u32_e64 s[54:55], s47, v238
	v_readlane_b32 s46, v237, 19
	v_readlane_b32 s47, v238, 19
	v_addc_co_u32_e64 v239, s[56:57], 0, v239, s[48:49]
	v_addc_co_u32_e64 v240, s[56:57], 0, v240, s[50:51]
	v_addc_co_u32_e64 v239, s[56:57], 0, v239, s[52:53]
	v_addc_co_u32_e64 v240, s[56:57], 0, v240, s[54:55]
	v_cmp_lt_u32_e64 s[48:49], s46, v237
	v_cmp_lt_u32_e64 s[50:51], s46, v238
	v_cmp_lt_u32_e64 s[52:53], s47, v237
	v_cmp_lt_u32_e64 s[54:55], s47, v238
	v_readlane_b32 s46, v237, 20
	v_readlane_b32 s47, v238, 20
	v_addc_co_u32_e64 v239, s[56:57], 0, v239, s[48:49]
	v_addc_co_u32_e64 v240, s[56:57], 0, v240, s[50:51]
	v_addc_co_u32_e64 v239, s[56:57], 0, v239, s[52:53]
	v_addc_co_u32_e64 v240, s[56:57], 0, v240, s[54:55]
	v_cmp_lt_u32_e64 s[48:49], s46, v237
	v_cmp_lt_u32_e64 s[50:51], s46, v238
	v_cmp_lt_u32_e64 s[52:53], s47, v237
	v_cmp_lt_u32_e64 s[54:55], s47, v238
	v_readlane_b32 s46, v237, 21
	v_readlane_b32 s47, v238, 21
	v_addc_co_u32_e64 v239, s[56:57], 0, v239, s[48:49]
	v_addc_co_u32_e64 v240, s[56:57], 0, v240, s[50:51]
	v_addc_co_u32_e64 v239, s[56:57], 0, v239, s[52:53]
	v_addc_co_u32_e64 v240, s[56:57], 0, v240, s[54:55]
	v_cmp_lt_u32_e64 s[48:49], s46, v237
	v_cmp_lt_u32_e64 s[50:51], s46, v238
	v_cmp_lt_u32_e64 s[52:53], s47, v237
	v_cmp_lt_u32_e64 s[54:55], s47, v238
	v_readlane_b32 s46, v237, 22
	v_readlane_b32 s47, v238, 22
	v_addc_co_u32_e64 v239, s[56:57], 0, v239, s[48:49]
	v_addc_co_u32_e64 v240, s[56:57], 0, v240, s[50:51]
	v_addc_co_u32_e64 v239, s[56:57], 0, v239, s[52:53]
	v_addc_co_u32_e64 v240, s[56:57], 0, v240, s[54:55]
	v_cmp_lt_u32_e64 s[48:49], s46, v237
	v_cmp_lt_u32_e64 s[50:51], s46, v238
	v_cmp_lt_u32_e64 s[52:53], s47, v237
	v_cmp_lt_u32_e64 s[54:55], s47, v238
	v_readlane_b32 s46, v237, 23
	v_readlane_b32 s47, v238, 23
; DEV void peer_gather_token(const Params& p, int tok) {
;     ...
;   const int e0 = p.eidx[(size_t)tok * 128 + lane], e1 = p.eidx[(size_t)tok * 128 + 64 + lane];
;   const int g0 = __builtin_bit_cast(int, p.gw[(size_t)tok * 128 + lane]), g1 = __builtin_bit_cast(int, p.gw[(size_t)tok * 128 + 64 + lane]);
;   u32x2 dn[4][3], up[4][3];
;   auto issue = [&](int k, int slot) {
;     const int e = (k < 64) ? __builtin_amdgcn_readlane(e0, k) : __builtin_amdgcn_readlane(e1, k - 64);
	v_addc_co_u32_e64 v239, s[56:57], 0, v239, s[48:49]
	v_addc_co_u32_e64 v240, s[56:57], 0, v240, s[50:51]
	v_addc_co_u32_e64 v239, s[56:57], 0, v239, s[52:53]
	v_addc_co_u32_e64 v240, s[56:57], 0, v240, s[54:55]
	v_cmp_lt_u32_e64 s[48:49], s46, v237
	v_cmp_lt_u32_e64 s[50:51], s46, v238
	v_cmp_lt_u32_e64 s[52:53], s47, v237
	v_cmp_lt_u32_e64 s[54:55], s47, v238
	v_readlane_b32 s46, v237, 24
	v_readlane_b32 s47, v238, 24
	v_addc_co_u32_e64 v239, s[56:57], 0, v239, s[48:49]
	v_addc_co_u32_e64 v240, s[56:57], 0, v240, s[50:51]
	v_addc_co_u32_e64 v239, s[56:57], 0, v239, s[52:53]
	v_addc_co_u32_e64 v240, s[56:57], 0, v240, s[54:55]
	v_cmp_lt_u32_e64 s[48:49], s46, v237
	v_cmp_lt_u32_e64 s[50:51], s46, v238
	v_cmp_lt_u32_e64 s[52:53], s47, v237
	v_cmp_lt_u32_e64 s[54:55], s47, v238
	v_readlane_b32 s46, v237, 25
	v_readlane_b32 s47, v238, 25
	v_addc_co_u32_e64 v239, s[56:57], 0, v239, s[48:49]
	v_addc_co_u32_e64 v240, s[56:57], 0, v240, s[50:51]
	v_addc_co_u32_e64 v239, s[56:57], 0, v239, s[52:53]
	v_addc_co_u32_e64 v240, s[56:57], 0, v240, s[54:55]
	v_cmp_lt_u32_e64 s[48:49], s46, v237
	v_cmp_lt_u32_e64 s[50:51], s46, v238
	v_cmp_lt_u32_e64 s[52:53], s47, v237
	v_cmp_lt_u32_e64 s[54:55], s47, v238
	v_readlane_b32 s46, v237, 26
	v_readlane_b32 s47, v238, 26
	v_addc_co_u32_e64 v239, s[56:57], 0, v239, s[48:49]
	v_addc_co_u32_e64 v240, s[56:57], 0, v240, s[50:51]
	v_addc_co_u32_e64 v239, s[56:57], 0, v239, s[52:53]
	v_addc_co_u32_e64 v240, s[56:57], 0, v240, s[54:55]
	v_cmp_lt_u32_e64 s[48:49], s46, v237
	v_cmp_lt_u32_e64 s[50:51], s46, v238
	v_cmp_lt_u32_e64 s[52:53], s47, v237
	v_cmp_lt_u32_e64 s[54:55], s47, v238
	v_readlane_b32 s46, v237, 27
	v_readlane_b32 s47, v238, 27
	v_addc_co_u32_e64 v239, s[56:57], 0, v239, s[48:49]
	v_addc_co_u32_e64 v240, s[56:57], 0, v240, s[50:51]
	v_addc_co_u32_e64 v239, s[56:57], 0, v239, s[52:53]
	v_addc_co_u32_e64 v240, s[56:57], 0, v240, s[54:55]
	v_cmp_lt_u32_e64 s[48:49], s46, v237
	v_cmp_lt_u32_e64 s[50:51], s46, v238
	v_cmp_lt_u32_e64 s[52:53], s47, v237
	v_cmp_lt_u32_e64 s[54:55], s47, v238
	v_readlane_b32 s46, v237, 28
	v_readlane_b32 s47, v238, 28
	v_addc_co_u32_e64 v239, s[56:57], 0, v239, s[48:49]
	v_addc_co_u32_e64 v240, s[56:57], 0, v240, s[50:51]
	v_addc_co_u32_e64 v239, s[56:57], 0, v239, s[52:53]
	v_addc_co_u32_e64 v240, s[56:57], 0, v240, s[54:55]
	v_cmp_lt_u32_e64 s[48:49], s46, v237
	v_cmp_lt_u32_e64 s[50:51], s46, v238
	v_cmp_lt_u32_e64 s[52:53], s47, v237
	v_cmp_lt_u32_e64 s[54:55], s47, v238
	v_readlane_b32 s46, v237, 29
	v_readlane_b32 s47, v238, 29
	v_addc_co_u32_e64 v239, s[56:57], 0, v239, s[48:49]
	v_addc_co_u32_e64 v240, s[56:57], 0, v240, s[50:51]
	v_addc_co_u32_e64 v239, s[56:57], 0, v239, s[52:53]
	v_addc_co_u32_e64 v240, s[56:57], 0, v240, s[54:55]
	v_cmp_lt_u32_e64 s[48:49], s46, v237
	v_cmp_lt_u32_e64 s[50:51], s46, v238
	v_cmp_lt_u32_e64 s[52:53], s47, v237
	v_cmp_lt_u32_e64 s[54:55], s47, v238
	v_readlane_b32 s46, v237, 30
	v_readlane_b32 s47, v238, 30
	v_addc_co_u32_e64 v239, s[56:57], 0, v239, s[48:49]
	v_addc_co_u32_e64 v240, s[56:57], 0, v240, s[50:51]
	v_addc_co_u32_e64 v239, s[56:57], 0, v239, s[52:53]
	v_addc_co_u32_e64 v240, s[56:57], 0, v240, s[54:55]
	v_cmp_lt_u32_e64 s[48:49], s46, v237
	v_cmp_lt_u32_e64 s[50:51], s46, v238
	v_cmp_lt_u32_e64 s[52:53], s47, v237
	v_cmp_lt_u32_e64 s[54:55], s47, v238
	v_readlane_b32 s46, v237, 31
	v_readlane_b32 s47, v238, 31
	v_addc_co_u32_e64 v239, s[56:57], 0, v239, s[48:49]
	v_addc_co_u32_e64 v240, s[56:57], 0, v240, s[50:51]
	v_addc_co_u32_e64 v239, s[56:57], 0, v239, s[52:53]
	v_addc_co_u32_e64 v240, s[56:57], 0, v240, s[54:55]
	v_cmp_lt_u32_e64 s[48:49], s46, v237
	v_cmp_lt_u32_e64 s[50:51], s46, v238
	v_cmp_lt_u32_e64 s[52:53], s47, v237
	v_cmp_lt_u32_e64 s[54:55], s47, v238
	v_readlane_b32 s46, v237, 32
	v_readlane_b32 s47, v238, 32
	v_addc_co_u32_e64 v239, s[56:57], 0, v239, s[48:49]
	v_addc_co_u32_e64 v240, s[56:57], 0, v240, s[50:51]
	v_addc_co_u32_e64 v239, s[56:57], 0, v239, s[52:53]
	v_addc_co_u32_e64 v240, s[56:57], 0, v240, s[54:55]
	v_cmp_lt_u32_e64 s[48:49], s46, v237
	v_cmp_lt_u32_e64 s[50:51], s46, v238
	v_cmp_lt_u32_e64 s[52:53], s47, v237
	v_cmp_lt_u32_e64 s[54:55], s47, v238
	v_readlane_b32 s46, v237, 33
	v_readlane_b32 s47, v238, 33
	v_addc_co_u32_e64 v239, s[56:57], 0, v239, s[48:49]
	v_addc_co_u32_e64 v240, s[56:57], 0, v240, s[50:51]
	v_addc_co_u32_e64 v239, s[56:57], 0, v239, s[52:53]
	v_addc_co_u32_e64 v240, s[56:57], 0, v240, s[54:55]
	v_cmp_lt_u32_e64 s[48:49], s46, v237
	v_cmp_lt_u32_e64 s[50:51], s46, v238
	v_cmp_lt_u32_e64 s[52:53], s47, v237
	v_cmp_lt_u32_e64 s[54:55], s47, v238
	v_readlane_b32 s46, v237, 34
	v_readlane_b32 s47, v238, 34
	v_addc_co_u32_e64 v239, s[56:57], 0, v239, s[48:49]
	v_addc_co_u32_e64 v240, s[56:57], 0, v240, s[50:51]
	v_addc_co_u32_e64 v239, s[56:57], 0, v239, s[52:53]
	v_addc_co_u32_e64 v240, s[56:57], 0, v240, s[54:55]
	v_cmp_lt_u32_e64 s[48:49], s46, v237
	v_cmp_lt_u32_e64 s[50:51], s46, v238
	v_cmp_lt_u32_e64 s[52:53], s47, v237
	v_cmp_lt_u32_e64 s[54:55], s47, v238
	v_readlane_b32 s46, v237, 35
	v_readlane_b32 s47, v238, 35
	v_addc_co_u32_e64 v239, s[56:57], 0, v239, s[48:49]
	v_addc_co_u32_e64 v240, s[56:57], 0, v240, s[50:51]
	v_addc_co_u32_e64 v239, s[56:57], 0, v239, s[52:53]
	v_addc_co_u32_e64 v240, s[56:57], 0, v240, s[54:55]
	v_cmp_lt_u32_e64 s[48:49], s46, v237
	v_cmp_lt_u32_e64 s[50:51], s46, v238
	v_cmp_lt_u32_e64 s[52:53], s47, v237
	v_cmp_lt_u32_e64 s[54:55], s47, v238
	v_readlane_b32 s46, v237, 36
	v_readlane_b32 s47, v238, 36
	v_addc_co_u32_e64 v239, s[56:57], 0, v239, s[48:49]
	v_addc_co_u32_e64 v240, s[56:57], 0, v240, s[50:51]
; DEV void peer_gather_token(const Params& p, int tok) {
;     ...
;   const int e0 = p.eidx[(size_t)tok * 128 + lane], e1 = p.eidx[(size_t)tok * 128 + 64 + lane];
;   const int g0 = __builtin_bit_cast(int, p.gw[(size_t)tok * 128 + lane]), g1 = __builtin_bit_cast(int, p.gw[(size_t)tok * 128 + 64 + lane]);
;   u32x2 dn[4][3], up[4][3];
;   auto issue = [&](int k, int slot) {
;     const int e = (k < 64) ? __builtin_amdgcn_readlane(e0, k) : __builtin_amdgcn_readlane(e1, k - 64);
	v_addc_co_u32_e64 v239, s[56:57], 0, v239, s[52:53]
	v_addc_co_u32_e64 v240, s[56:57], 0, v240, s[54:55]
	v_cmp_lt_u32_e64 s[48:49], s46, v237
	v_cmp_lt_u32_e64 s[50:51], s46, v238
	v_cmp_lt_u32_e64 s[52:53], s47, v237
	v_cmp_lt_u32_e64 s[54:55], s47, v238
	v_readlane_b32 s46, v237, 37
	v_readlane_b32 s47, v238, 37
	v_addc_co_u32_e64 v239, s[56:57], 0, v239, s[48:49]
	v_addc_co_u32_e64 v240, s[56:57], 0, v240, s[50:51]
	v_addc_co_u32_e64 v239, s[56:57], 0, v239, s[52:53]
	v_addc_co_u32_e64 v240, s[56:57], 0, v240, s[54:55]
	v_cmp_lt_u32_e64 s[48:49], s46, v237
	v_cmp_lt_u32_e64 s[50:51], s46, v238
	v_cmp_lt_u32_e64 s[52:53], s47, v237
	v_cmp_lt_u32_e64 s[54:55], s47, v238
	v_readlane_b32 s46, v237, 38
	v_readlane_b32 s47, v238, 38
	v_addc_co_u32_e64 v239, s[56:57], 0, v239, s[48:49]
	v_addc_co_u32_e64 v240, s[56:57], 0, v240, s[50:51]
	v_addc_co_u32_e64 v239, s[56:57], 0, v239, s[52:53]
	v_addc_co_u32_e64 v240, s[56:57], 0, v240, s[54:55]
	v_cmp_lt_u32_e64 s[48:49], s46, v237
	v_cmp_lt_u32_e64 s[50:51], s46, v238
	v_cmp_lt_u32_e64 s[52:53], s47, v237
	v_cmp_lt_u32_e64 s[54:55], s47, v238
	v_readlane_b32 s46, v237, 39
	v_readlane_b32 s47, v238, 39
	v_addc_co_u32_e64 v239, s[56:57], 0, v239, s[48:49]
	v_addc_co_u32_e64 v240, s[56:57], 0, v240, s[50:51]
	v_addc_co_u32_e64 v239, s[56:57], 0, v239, s[52:53]
	v_addc_co_u32_e64 v240, s[56:57], 0, v240, s[54:55]
	v_cmp_lt_u32_e64 s[48:49], s46, v237
	v_cmp_lt_u32_e64 s[50:51], s46, v238
	v_cmp_lt_u32_e64 s[52:53], s47, v237
	v_cmp_lt_u32_e64 s[54:55], s47, v238
	v_readlane_b32 s46, v237, 40
	v_readlane_b32 s47, v238, 40
	v_addc_co_u32_e64 v239, s[56:57], 0, v239, s[48:49]
	v_addc_co_u32_e64 v240, s[56:57], 0, v240, s[50:51]
	v_addc_co_u32_e64 v239, s[56:57], 0, v239, s[52:53]
	v_addc_co_u32_e64 v240, s[56:57], 0, v240, s[54:55]
	v_cmp_lt_u32_e64 s[48:49], s46, v237
	v_cmp_lt_u32_e64 s[50:51], s46, v238
	v_cmp_lt_u32_e64 s[52:53], s47, v237
	v_cmp_lt_u32_e64 s[54:55], s47, v238
	v_readlane_b32 s46, v237, 41
	v_readlane_b32 s47, v238, 41
	v_addc_co_u32_e64 v239, s[56:57], 0, v239, s[48:49]
	v_addc_co_u32_e64 v240, s[56:57], 0, v240, s[50:51]
	v_addc_co_u32_e64 v239, s[56:57], 0, v239, s[52:53]
	v_addc_co_u32_e64 v240, s[56:57], 0, v240, s[54:55]
	v_cmp_lt_u32_e64 s[48:49], s46, v237
	v_cmp_lt_u32_e64 s[50:51], s46, v238
	v_cmp_lt_u32_e64 s[52:53], s47, v237
	v_cmp_lt_u32_e64 s[54:55], s47, v238
	v_readlane_b32 s46, v237, 42
	v_readlane_b32 s47, v238, 42
	v_addc_co_u32_e64 v239, s[56:57], 0, v239, s[48:49]
	v_addc_co_u32_e64 v240, s[56:57], 0, v240, s[50:51]
	v_addc_co_u32_e64 v239, s[56:57], 0, v239, s[52:53]
	v_addc_co_u32_e64 v240, s[56:57], 0, v240, s[54:55]
	v_cmp_lt_u32_e64 s[48:49], s46, v237
	v_cmp_lt_u32_e64 s[50:51], s46, v238
	v_cmp_lt_u32_e64 s[52:53], s47, v237
	v_cmp_lt_u32_e64 s[54:55], s47, v238
	v_readlane_b32 s46, v237, 43
	v_readlane_b32 s47, v238, 43
	v_addc_co_u32_e64 v239, s[56:57], 0, v239, s[48:49]
	v_addc_co_u32_e64 v240, s[56:57], 0, v240, s[50:51]
	v_addc_co_u32_e64 v239, s[56:57], 0, v239, s[52:53]
	v_addc_co_u32_e64 v240, s[56:57], 0, v240, s[54:55]
	v_cmp_lt_u32_e64 s[48:49], s46, v237
	v_cmp_lt_u32_e64 s[50:51], s46, v238
	v_cmp_lt_u32_e64 s[52:53], s47, v237
	v_cmp_lt_u32_e64 s[54:55], s47, v238
	v_readlane_b32 s46, v237, 44
	v_readlane_b32 s47, v238, 44
	v_addc_co_u32_e64 v239, s[56:57], 0, v239, s[48:49]
	v_addc_co_u32_e64 v240, s[56:57], 0, v240, s[50:51]
	v_addc_co_u32_e64 v239, s[56:57], 0, v239, s[52:53]
	v_addc_co_u32_e64 v240, s[56:57], 0, v240, s[54:55]
	v_cmp_lt_u32_e64 s[48:49], s46, v237
	v_cmp_lt_u32_e64 s[50:51], s46, v238
	v_cmp_lt_u32_e64 s[52:53], s47, v237
	v_cmp_lt_u32_e64 s[54:55], s47, v238
	v_readlane_b32 s46, v237, 45
	v_readlane_b32 s47, v238, 45
	v_addc_co_u32_e64 v239, s[56:57], 0, v239, s[48:49]
	v_addc_co_u32_e64 v240, s[56:57], 0, v240, s[50:51]
	v_addc_co_u32_e64 v239, s[56:57], 0, v239, s[52:53]
	v_addc_co_u32_e64 v240, s[56:57], 0, v240, s[54:55]
	v_cmp_lt_u32_e64 s[48:49], s46, v237
	v_cmp_lt_u32_e64 s[50:51], s46, v238
	v_cmp_lt_u32_e64 s[52:53], s47, v237
	v_cmp_lt_u32_e64 s[54:55], s47, v238
	v_readlane_b32 s46, v237, 46
	v_readlane_b32 s47, v238, 46
	v_addc_co_u32_e64 v239, s[56:57], 0, v239, s[48:49]
	v_addc_co_u32_e64 v240, s[56:57], 0, v240, s[50:51]
	v_addc_co_u32_e64 v239, s[56:57], 0, v239, s[52:53]
	v_addc_co_u32_e64 v240, s[56:57], 0, v240, s[54:55]
	v_cmp_lt_u32_e64 s[48:49], s46, v237
	v_cmp_lt_u32_e64 s[50:51], s46, v238
	v_cmp_lt_u32_e64 s[52:53], s47, v237
	v_cmp_lt_u32_e64 s[54:55], s47, v238
	v_readlane_b32 s46, v237, 47
	v_readlane_b32 s47, v238, 47
	v_addc_co_u32_e64 v239, s[56:57], 0, v239, s[48:49]
	v_addc_co_u32_e64 v240, s[56:57], 0, v240, s[50:51]
	v_addc_co_u32_e64 v239, s[56:57], 0, v239, s[52:53]
	v_addc_co_u32_e64 v240, s[56:57], 0, v240, s[54:55]
	v_cmp_lt_u32_e64 s[48:49], s46, v237
	v_cmp_lt_u32_e64 s[50:51], s46, v238
	v_cmp_lt_u32_e64 s[52:53], s47, v237
	v_cmp_lt_u32_e64 s[54:55], s47, v238
	v_readlane_b32 s46, v237, 48
	v_readlane_b32 s47, v238, 48
	v_addc_co_u32_e64 v239, s[56:57], 0, v239, s[48:49]
	v_addc_co_u32_e64 v240, s[56:57], 0, v240, s[50:51]
	v_addc_co_u32_e64 v239, s[56:57], 0, v239, s[52:53]
	v_addc_co_u32_e64 v240, s[56:57], 0, v240, s[54:55]
	v_cmp_lt_u32_e64 s[48:49], s46, v237
	v_cmp_lt_u32_e64 s[50:51], s46, v238
	v_cmp_lt_u32_e64 s[52:53], s47, v237
	v_cmp_lt_u32_e64 s[54:55], s47, v238
	v_readlane_b32 s46, v237, 49
	v_readlane_b32 s47, v238, 49
	v_addc_co_u32_e64 v239, s[56:57], 0, v239, s[48:49]
	v_addc_co_u32_e64 v240, s[56:57], 0, v240, s[50:51]
	v_addc_co_u32_e64 v239, s[56:57], 0, v239, s[52:53]
	v_addc_co_u32_e64 v240, s[56:57], 0, v240, s[54:55]
	v_cmp_lt_u32_e64 s[48:49], s46, v237
; DEV void peer_gather_token(const Params& p, int tok) {
;     ...
;   const int e0 = p.eidx[(size_t)tok * 128 + lane], e1 = p.eidx[(size_t)tok * 128 + 64 + lane];
;   const int g0 = __builtin_bit_cast(int, p.gw[(size_t)tok * 128 + lane]), g1 = __builtin_bit_cast(int, p.gw[(size_t)tok * 128 + 64 + lane]);
;   u32x2 dn[4][3], up[4][3];
;   auto issue = [&](int k, int slot) {
;     const int e = (k < 64) ? __builtin_amdgcn_readlane(e0, k) : __builtin_amdgcn_readlane(e1, k - 64);
	v_cmp_lt_u32_e64 s[50:51], s46, v238
	v_cmp_lt_u32_e64 s[52:53], s47, v237
	v_cmp_lt_u32_e64 s[54:55], s47, v238
	v_readlane_b32 s46, v237, 50
	v_readlane_b32 s47, v238, 50
	v_addc_co_u32_e64 v239, s[56:57], 0, v239, s[48:49]
	v_addc_co_u32_e64 v240, s[56:57], 0, v240, s[50:51]
	v_addc_co_u32_e64 v239, s[56:57], 0, v239, s[52:53]
	v_addc_co_u32_e64 v240, s[56:57], 0, v240, s[54:55]
	v_cmp_lt_u32_e64 s[48:49], s46, v237
	v_cmp_lt_u32_e64 s[50:51], s46, v238
	v_cmp_lt_u32_e64 s[52:53], s47, v237
	v_cmp_lt_u32_e64 s[54:55], s47, v238
	v_readlane_b32 s46, v237, 51
	v_readlane_b32 s47, v238, 51
	v_addc_co_u32_e64 v239, s[56:57], 0, v239, s[48:49]
	v_addc_co_u32_e64 v240, s[56:57], 0, v240, s[50:51]
	v_addc_co_u32_e64 v239, s[56:57], 0, v239, s[52:53]
	v_addc_co_u32_e64 v240, s[56:57], 0, v240, s[54:55]
	v_cmp_lt_u32_e64 s[48:49], s46, v237
	v_cmp_lt_u32_e64 s[50:51], s46, v238
	v_cmp_lt_u32_e64 s[52:53], s47, v237
	v_cmp_lt_u32_e64 s[54:55], s47, v238
	v_readlane_b32 s46, v237, 52
	v_readlane_b32 s47, v238, 52
	v_addc_co_u32_e64 v239, s[56:57], 0, v239, s[48:49]
	v_addc_co_u32_e64 v240, s[56:57], 0, v240, s[50:51]
	v_addc_co_u32_e64 v239, s[56:57], 0, v239, s[52:53]
	v_addc_co_u32_e64 v240, s[56:57], 0, v240, s[54:55]
	v_cmp_lt_u32_e64 s[48:49], s46, v237
	v_cmp_lt_u32_e64 s[50:51], s46, v238
	v_cmp_lt_u32_e64 s[52:53], s47, v237
	v_cmp_lt_u32_e64 s[54:55], s47, v238
	v_readlane_b32 s46, v237, 53
	v_readlane_b32 s47, v238, 53
	v_addc_co_u32_e64 v239, s[56:57], 0, v239, s[48:49]
	v_addc_co_u32_e64 v240, s[56:57], 0, v240, s[50:51]
	v_addc_co_u32_e64 v239, s[56:57], 0, v239, s[52:53]
	v_addc_co_u32_e64 v240, s[56:57], 0, v240, s[54:55]
	v_cmp_lt_u32_e64 s[48:49], s46, v237
	v_cmp_lt_u32_e64 s[50:51], s46, v238
	v_cmp_lt_u32_e64 s[52:53], s47, v237
	v_cmp_lt_u32_e64 s[54:55], s47, v238
	v_readlane_b32 s46, v237, 54
	v_readlane_b32 s47, v238, 54
	v_addc_co_u32_e64 v239, s[56:57], 0, v239, s[48:49]
	v_addc_co_u32_e64 v240, s[56:57], 0, v240, s[50:51]
	v_addc_co_u32_e64 v239, s[56:57], 0, v239, s[52:53]
	v_addc_co_u32_e64 v240, s[56:57], 0, v240, s[54:55]
	v_cmp_lt_u32_e64 s[48:49], s46, v237
	v_cmp_lt_u32_e64 s[50:51], s46, v238
	v_cmp_lt_u32_e64 s[52:53], s47, v237
	v_cmp_lt_u32_e64 s[54:55], s47, v238
	v_readlane_b32 s46, v237, 55
	v_readlane_b32 s47, v238, 55
	v_addc_co_u32_e64 v239, s[56:57], 0, v239, s[48:49]
	v_addc_co_u32_e64 v240, s[56:57], 0, v240, s[50:51]
	v_addc_co_u32_e64 v239, s[56:57], 0, v239, s[52:53]
	v_addc_co_u32_e64 v240, s[56:57], 0, v240, s[54:55]
	v_cmp_lt_u32_e64 s[48:49], s46, v237
	v_cmp_lt_u32_e64 s[50:51], s46, v238
	v_cmp_lt_u32_e64 s[52:53], s47, v237
	v_cmp_lt_u32_e64 s[54:55], s47, v238
	v_readlane_b32 s46, v237, 56
	v_readlane_b32 s47, v238, 56
	v_addc_co_u32_e64 v239, s[56:57], 0, v239, s[48:49]
	v_addc_co_u32_e64 v240, s[56:57], 0, v240, s[50:51]
	v_addc_co_u32_e64 v239, s[56:57], 0, v239, s[52:53]
	v_addc_co_u32_e64 v240, s[56:57], 0, v240, s[54:55]
	v_cmp_lt_u32_e64 s[48:49], s46, v237
	v_cmp_lt_u32_e64 s[50:51], s46, v238
	v_cmp_lt_u32_e64 s[52:53], s47, v237
	v_cmp_lt_u32_e64 s[54:55], s47, v238
	v_readlane_b32 s46, v237, 57
	v_readlane_b32 s47, v238, 57
	v_addc_co_u32_e64 v239, s[56:57], 0, v239, s[48:49]
	v_addc_co_u32_e64 v240, s[56:57], 0, v240, s[50:51]
	v_addc_co_u32_e64 v239, s[56:57], 0, v239, s[52:53]
	v_addc_co_u32_e64 v240, s[56:57], 0, v240, s[54:55]
	v_cmp_lt_u32_e64 s[48:49], s46, v237
	v_cmp_lt_u32_e64 s[50:51], s46, v238
	v_cmp_lt_u32_e64 s[52:53], s47, v237
	v_cmp_lt_u32_e64 s[54:55], s47, v238
	v_readlane_b32 s46, v237, 58
	v_readlane_b32 s47, v238, 58
	v_addc_co_u32_e64 v239, s[56:57], 0, v239, s[48:49]
	v_addc_co_u32_e64 v240, s[56:57], 0, v240, s[50:51]
	v_addc_co_u32_e64 v239, s[56:57], 0, v239, s[52:53]
	v_addc_co_u32_e64 v240, s[56:57], 0, v240, s[54:55]
	v_cmp_lt_u32_e64 s[48:49], s46, v237
	v_cmp_lt_u32_e64 s[50:51], s46, v238
	v_cmp_lt_u32_e64 s[52:53], s47, v237
	v_cmp_lt_u32_e64 s[54:55], s47, v238
	v_readlane_b32 s46, v237, 59
	v_readlane_b32 s47, v238, 59
	v_addc_co_u32_e64 v239, s[56:57], 0, v239, s[48:49]
	v_addc_co_u32_e64 v240, s[56:57], 0, v240, s[50:51]
	v_addc_co_u32_e64 v239, s[56:57], 0, v239, s[52:53]
	v_addc_co_u32_e64 v240, s[56:57], 0, v240, s[54:55]
	v_cmp_lt_u32_e64 s[48:49], s46, v237
	v_cmp_lt_u32_e64 s[50:51], s46, v238
	v_cmp_lt_u32_e64 s[52:53], s47, v237
	v_cmp_lt_u32_e64 s[54:55], s47, v238
	v_readlane_b32 s46, v237, 60
	v_readlane_b32 s47, v238, 60
	v_addc_co_u32_e64 v239, s[56:57], 0, v239, s[48:49]
	v_addc_co_u32_e64 v240, s[56:57], 0, v240, s[50:51]
	v_addc_co_u32_e64 v239, s[56:57], 0, v239, s[52:53]
	v_addc_co_u32_e64 v240, s[56:57], 0, v240, s[54:55]
	v_cmp_lt_u32_e64 s[48:49], s46, v237
	v_cmp_lt_u32_e64 s[50:51], s46, v238
	v_cmp_lt_u32_e64 s[52:53], s47, v237
	v_cmp_lt_u32_e64 s[54:55], s47, v238
	v_readlane_b32 s46, v237, 61
	v_readlane_b32 s47, v238, 61
	v_addc_co_u32_e64 v239, s[56:57], 0, v239, s[48:49]
	v_addc_co_u32_e64 v240, s[56:57], 0, v240, s[50:51]
	v_addc_co_u32_e64 v239, s[56:57], 0, v239, s[52:53]
	v_addc_co_u32_e64 v240, s[56:57], 0, v240, s[54:55]
	v_cmp_lt_u32_e64 s[48:49], s46, v237
	v_cmp_lt_u32_e64 s[50:51], s46, v238
	v_cmp_lt_u32_e64 s[52:53], s47, v237
	v_cmp_lt_u32_e64 s[54:55], s47, v238
	v_readlane_b32 s46, v237, 62
	v_readlane_b32 s47, v238, 62
	v_addc_co_u32_e64 v239, s[56:57], 0, v239, s[48:49]
	v_addc_co_u32_e64 v240, s[56:57], 0, v240, s[50:51]
	v_addc_co_u32_e64 v239, s[56:57], 0, v239, s[52:53]
	v_addc_co_u32_e64 v240, s[56:57], 0, v240, s[54:55]
	v_cmp_lt_u32_e64 s[48:49], s46, v237
	v_cmp_lt_u32_e64 s[50:51], s46, v238
	v_cmp_lt_u32_e64 s[52:53], s47, v237
	v_cmp_lt_u32_e64 s[54:55], s47, v238
	v_readlane_b32 s46, v237, 63
	v_readlane_b32 s47, v238, 63
	v_addc_co_u32_e64 v239, s[56:57], 0, v239, s[48:49]
	v_addc_co_u32_e64 v240, s[56:57], 0, v240, s[50:51]
	v_addc_co_u32_e64 v239, s[56:57], 0, v239, s[52:53]
	v_addc_co_u32_e64 v240, s[56:57], 0, v240, s[54:55]
	v_cmp_lt_u32_e64 s[48:49], s46, v237
	v_cmp_lt_u32_e64 s[50:51], s46, v238
	v_cmp_lt_u32_e64 s[52:53], s47, v237
	v_cmp_lt_u32_e64 s[54:55], s47, v238
	s_nop 1
	v_addc_co_u32_e64 v239, s[56:57], 0, v239, s[48:49]
	v_addc_co_u32_e64 v240, s[56:57], 0, v240, s[50:51]
	v_addc_co_u32_e64 v239, s[56:57], 0, v239, s[52:53]
	v_addc_co_u32_e64 v240, s[56:57], 0, v240, s[54:55]
	v_and_b32_e32 v237, 0xfffffc00, v241
	v_lshl_add_u32 v239, v239, 2, v237
	v_lshl_add_u32 v240, v240, 2, v237
	ds_write_b32 v239, v216
	ds_write_b32 v240, v217
	ds_write_b32 v239, v218 offset:512
	ds_write_b32 v240, v219 offset:512
	s_waitcnt lgkmcnt(0)
; DEV float gelu_exact(float v) { return 0.5f * v * (1.f + erff(v * 0.7071067811865476f)); }
; DEV void peer_gather_token(const Params& p, int tok) {
;     ...
;   const int e0 = p.eidx[(size_t)tok * 128 + lane], e1 = p.eidx[(size_t)tok * 128 + 64 + lane];
;   const int g0 = __builtin_bit_cast(int, p.gw[(size_t)tok * 128 + lane]), g1 = __builtin_bit_cast(int, p.gw[(size_t)tok * 128 + 64 + lane]);
;   u32x2 dn[4][3], up[4][3];
;   auto issue = [&](int k, int slot) {
;     const int e = (k < 64) ? __builtin_amdgcn_readlane(e0, k) : __builtin_amdgcn_readlane(e1, k - 64);
;     const unsigned char* dr = p.down8 + (size_t)e * ROW6 + lane * 24;
;     const unsigned char* ur = p.up8 + (size_t)e * ROW6 + lane * 24;
; #pragma unroll
;     for (int i = 0; i < 3; ++i) { dn[slot][i] = *(const u32x2*)(dr + i * 8); up[slot][i] = *(const u32x2*)(ur + i * 8); }
;   };
;   issue(0, 0); issue(1, 1); issue(2, 2);
; #pragma unroll 1
;   for (int k4 = 0; k4 < 128; k4 += 4) {
; #pragma unroll
;     for (int s = 0; s < 4; ++s) {
;       const int k = k4 + s;
;       if (k + 3 < 128) issue(k + 3, (s + 3) & 3);
;       const v6u dq = v6u{dn[s][0][0], dn[s][0][1], dn[s][1][0], dn[s][1][1], dn[s][2][0], dn[s][2][1]};
;       const v32f dv = __builtin_amdgcn_cvt_scalef32_pk32_f32_fp6(dq, 1.0f);
;       float d0 = 0.f, d1 = 0.f, d2 = 0.f, d3 = 0.f;
; #pragma unroll
;       for (int i = 0; i < 8; ++i) { d0 += dv[4 * i] * hx[4 * i]; d1 += dv[4 * i + 1] * hx[4 * i + 1]; d2 += dv[4 * i + 2] * hx[4 * i + 2]; d3 += dv[4 * i + 3] * hx[4 * i + 3]; }
;       const float d = wave_sum_fast((d0 + d1) + (d2 + d3)) * (1.f / DOWN_SCALE);
;       const float gk = __builtin_bit_cast(float, (k < 64) ? __builtin_amdgcn_readlane(g0, k) : __builtin_amdgcn_readlane(g1, k - 64));
;       const float act = gelu_exact(d) * gk * (1.f / UP_SCALE);
;       const v6u uq = v6u{up[s][0][0], up[s][0][1], up[s][1][0], up[s][1][1], up[s][2][0], up[s][2][1]};
;       const v32f uv = __builtin_amdgcn_cvt_scalef32_pk32_f32_fp6(uq, 1.0f);
; #pragma unroll
;       for (int i = 0; i < 32; ++i) acc[i] += act * uv[i];
	ds_read_b32 v216, v241
	ds_read_b32 v217, v241 offset:256
	ds_read_b32 v218, v241 offset:512
	ds_read_b32 v219, v241 offset:768
	s_waitcnt lgkmcnt(0)
	v_cvt_scalef32_pk32_f32_fp6 v[2:33], v[98:103], 1.0
	v_mul_f32_e32 v200, v2, v34
	v_mul_f32_e32 v201, v3, v35
	v_mul_f32_e32 v202, v4, v36
	v_mul_f32_e32 v203, v5, v37
	v_fmac_f32_e32 v200, v6, v38
	v_fmac_f32_e32 v201, v7, v39
	v_fmac_f32_e32 v202, v8, v40
	v_fmac_f32_e32 v203, v9, v41
	v_fmac_f32_e32 v200, v10, v42
	v_fmac_f32_e32 v201, v11, v43
	v_fmac_f32_e32 v202, v12, v44
	v_fmac_f32_e32 v203, v13, v45
	v_fmac_f32_e32 v200, v14, v46
	v_fmac_f32_e32 v201, v15, v47
	v_fmac_f32_e32 v202, v16, v48
	v_fmac_f32_e32 v203, v17, v49
	v_fmac_f32_e32 v200, v18, v50
	v_fmac_f32_e32 v201, v19, v51
	v_fmac_f32_e32 v202, v20, v52
	v_fmac_f32_e32 v203, v21, v53
	v_fmac_f32_e32 v200, v22, v54
	v_fmac_f32_e32 v201, v23, v55
	v_fmac_f32_e32 v202, v24, v56
	v_fmac_f32_e32 v203, v25, v57
	v_fmac_f32_e32 v200, v26, v58
	v_fmac_f32_e32 v201, v27, v59
	v_fmac_f32_e32 v202, v28, v60
	v_fmac_f32_e32 v203, v29, v61
	v_fmac_f32_e32 v200, v30, v62
	v_fmac_f32_e32 v201, v31, v63
	v_fmac_f32_e32 v202, v32, v64
	v_fmac_f32_e32 v203, v33, v65
	v_add_f32_e32 v200, v201, v200
	v_add_f32_e32 v202, v203, v202
	v_cvt_scalef32_pk32_f32_fp6 v[2:33], v[104:109], 1.0
	v_add_f32_e32 v200, v202, v200
	s_add_i32 s38, s24, 0
	v_readlane_b32 s26, v199, s38
	s_mov_b32 s39, 0
	v_readlane_b32 s25, v216, s39
	v_add_f32_dpp v200, v200, v200 quad_perm:[1,0,3,2] row_mask:0xf bank_mask:0xf bound_ctrl:1
	s_nop 1
	v_add_f32_dpp v200, v200, v200 quad_perm:[2,3,0,1] row_mask:0xf bank_mask:0xf bound_ctrl:1
	s_nop 1
	v_add_f32_dpp v200, v200, v200 row_half_mirror row_mask:0xf bank_mask:0xf bound_ctrl:1
	s_nop 1
	v_add_f32_dpp v200, v200, v200 row_mirror row_mask:0xf bank_mask:0xf bound_ctrl:1
	s_nop 1
	v_add_f32_dpp v200, v200, v200 row_bcast:15 row_mask:0xa bank_mask:0xf
	s_nop 1
	v_add_f32_dpp v200, v200, v200 row_bcast:31 row_mask:0xc bank_mask:0xf
	s_nop 0
	v_readlane_b32 s27, v200, 63
	s_mul_i32 s40, s25, 0xc00
	s_add_u32 s28, s62, s40
	s_addc_u32 s29, s63, 0
	global_load_dwordx4 v[98:101], v1, s[28:29]
	global_load_dwordx4 v[102:105], v1, s[28:29] offset:2048
	global_load_dwordx4 v[106:109], v1, s[28:29] offset:1024
	v_mul_f32_e32 v204, s27, v212
	v_mul_f32_e32 v205, 0x3f3504f3, v204
	v_cmp_lt_f32_e64 s[32:33], |v205|, 1.0
	s_and_b64 vcc, exec, s[32:33]
	s_cbranch_vccnz .Lsm_33
	v_fma_f32 v208, |v205|, s9, v214
	v_fma_f32 v208, |v205|, v208, s10
	v_fma_f32 v208, |v205|, v208, s11
	v_fma_f32 v208, |v205|, v208, s12
	v_fma_f32 v208, |v205|, v208, s13
	v_fma_f32 v208, |v205|, v208, s14
	v_fma_f32 v208, |v205|, v208, |v205|
	v_mul_f32_e32 v209, 0xbfb8aa3b, v208
	v_fma_f32 v210, v208, s15, -v209
	v_rndne_f32_e32 v211, v209
	v_fmac_f32_e32 v210, 0xb2a5705f, v208
	v_sub_f32_e32 v209, v209, v211
	v_add_f32_e32 v209, v209, v210
	v_cvt_i32_f32_e32 v210, v211
	v_exp_f32_e32 v209, v209
	v_cmp_nlt_f32_e32 vcc, s16, v208
	v_ldexp_f32 v209, v209, v210
	s_nop 0
	v_cndmask_b32_e32 v209, 0, v209, vcc
	v_cmp_ngt_f32_e32 vcc, s17, v208
	s_nop 1
	v_cndmask_b32_e32 v208, v215, v209, vcc
	v_sub_f32_e32 v210, 1.0, v208
	s_branch .Ljn_33

; DEV float gelu_exact(float v) { return 0.5f * v * (1.f + erff(v * 0.7071067811865476f)); }
; DEV void peer_gather_token(const Params& p, int tok) {
;     ...
;   auto issue = [&](int k, int slot) {
;     const int e = (k < 64) ? __builtin_amdgcn_readlane(e0, k) : __builtin_amdgcn_readlane(e1, k - 64);
;     const unsigned char* dr = p.down8 + (size_t)e * ROW6 + lane * 24;
;     const unsigned char* ur = p.up8 + (size_t)e * ROW6 + lane * 24;
; #pragma unroll
;     for (int i = 0; i < 3; ++i) { dn[slot][i] = *(const u32x2*)(dr + i * 8); up[slot][i] = *(const u32x2*)(ur + i * 8); }
;   };
;   issue(0, 0); issue(1, 1); issue(2, 2);
; #pragma unroll 1
;   for (int k4 = 0; k4 < 128; k4 += 4) {
; #pragma unroll
;     for (int s = 0; s < 4; ++s) {
;       const int k = k4 + s;
;       if (k + 3 < 128) issue(k + 3, (s + 3) & 3);
;       const v6u dq = v6u{dn[s][0][0], dn[s][0][1], dn[s][1][0], dn[s][1][1], dn[s][2][0], dn[s][2][1]};
;       const v32f dv = __builtin_amdgcn_cvt_scalef32_pk32_f32_fp6(dq, 1.0f);
;       float d0 = 0.f, d1 = 0.f, d2 = 0.f, d3 = 0.f;
; #pragma unroll
;       for (int i = 0; i < 8; ++i) { d0 += dv[4 * i] * hx[4 * i]; d1 += dv[4 * i + 1] * hx[4 * i + 1]; d2 += dv[4 * i + 2] * hx[4 * i + 2]; d3 += dv[4 * i + 3] * hx[4 * i + 3]; }
;       const float d = wave_sum_fast((d0 + d1) + (d2 + d3)) * (1.f / DOWN_SCALE);
;       const float gk = __builtin_bit_cast(float, (k < 64) ? __builtin_amdgcn_readlane(g0, k) : __builtin_amdgcn_readlane(g1, k - 64));
;       const float act = gelu_exact(d) * gk * (1.f / UP_SCALE);
;       const v6u uq = v6u{up[s][0][0], up[s][0][1], up[s][1][0], up[s][1][1], up[s][2][0], up[s][2][1]};
;       const v32f uv = __builtin_amdgcn_cvt_scalef32_pk32_f32_fp6(uq, 1.0f);
; #pragma unroll
;       for (int i = 0; i < 32; ++i) acc[i] += act * uv[i];
.Ljn_33:
	v_bfi_b32 v209, s18, v210, v205
	v_mul_f32_e32 v208, 0.5, v204
	v_add_f32_e32 v209, 1.0, v209
	v_mul_f32_e32 v208, v208, v209
	v_mul_f32_e32 v208, s26, v208
	v_mul_f32_e32 v206, 0x3e800000, v208
	v_pk_fma_f32 v[66:67], v[2:3], v[206:207], v[66:67] op_sel_hi:[1,0,1]
	v_pk_fma_f32 v[68:69], v[4:5], v[206:207], v[68:69] op_sel_hi:[1,0,1]
	v_pk_fma_f32 v[70:71], v[6:7], v[206:207], v[70:71] op_sel_hi:[1,0,1]
	v_pk_fma_f32 v[72:73], v[8:9], v[206:207], v[72:73] op_sel_hi:[1,0,1]
	v_pk_fma_f32 v[74:75], v[10:11], v[206:207], v[74:75] op_sel_hi:[1,0,1]
	v_pk_fma_f32 v[76:77], v[12:13], v[206:207], v[76:77] op_sel_hi:[1,0,1]
	v_pk_fma_f32 v[78:79], v[14:15], v[206:207], v[78:79] op_sel_hi:[1,0,1]
	v_pk_fma_f32 v[80:81], v[16:17], v[206:207], v[80:81] op_sel_hi:[1,0,1]
	v_pk_fma_f32 v[82:83], v[18:19], v[206:207], v[82:83] op_sel_hi:[1,0,1]
	v_pk_fma_f32 v[84:85], v[20:21], v[206:207], v[84:85] op_sel_hi:[1,0,1]
	v_pk_fma_f32 v[86:87], v[22:23], v[206:207], v[86:87] op_sel_hi:[1,0,1]
	v_pk_fma_f32 v[88:89], v[24:25], v[206:207], v[88:89] op_sel_hi:[1,0,1]
	v_pk_fma_f32 v[90:91], v[26:27], v[206:207], v[90:91] op_sel_hi:[1,0,1]
	v_pk_fma_f32 v[92:93], v[28:29], v[206:207], v[92:93] op_sel_hi:[1,0,1]
	v_pk_fma_f32 v[94:95], v[30:31], v[206:207], v[94:95] op_sel_hi:[1,0,1]
	v_pk_fma_f32 v[96:97], v[32:33], v[206:207], v[96:97] op_sel_hi:[1,0,1]
	s_waitcnt vmcnt(21)
	v_cvt_scalef32_pk32_f32_fp6 v[2:33], v[110:115], 1.0
	v_mul_f32_e32 v200, v2, v34
	v_mul_f32_e32 v201, v3, v35
	v_mul_f32_e32 v202, v4, v36
	v_mul_f32_e32 v203, v5, v37
	v_fmac_f32_e32 v200, v6, v38
	v_fmac_f32_e32 v201, v7, v39
	v_fmac_f32_e32 v202, v8, v40
	v_fmac_f32_e32 v203, v9, v41
	v_fmac_f32_e32 v200, v10, v42
	v_fmac_f32_e32 v201, v11, v43
	v_fmac_f32_e32 v202, v12, v44
	v_fmac_f32_e32 v203, v13, v45
	v_fmac_f32_e32 v200, v14, v46
	v_fmac_f32_e32 v201, v15, v47
	v_fmac_f32_e32 v202, v16, v48
	v_fmac_f32_e32 v203, v17, v49
	v_fmac_f32_e32 v200, v18, v50
	v_fmac_f32_e32 v201, v19, v51
	v_fmac_f32_e32 v202, v20, v52
	v_fmac_f32_e32 v203, v21, v53
	v_fmac_f32_e32 v200, v22, v54
	v_fmac_f32_e32 v201, v23, v55
	v_fmac_f32_e32 v202, v24, v56
	v_fmac_f32_e32 v203, v25, v57
	v_fmac_f32_e32 v200, v26, v58
	v_fmac_f32_e32 v201, v27, v59
	v_fmac_f32_e32 v202, v28, v60
	v_fmac_f32_e32 v203, v29, v61
	v_fmac_f32_e32 v200, v30, v62
	v_fmac_f32_e32 v201, v31, v63
	v_fmac_f32_e32 v202, v32, v64
	v_fmac_f32_e32 v203, v33, v65
	v_add_f32_e32 v200, v201, v200
	v_add_f32_e32 v202, v203, v202
	v_cvt_scalef32_pk32_f32_fp6 v[2:33], v[116:121], 1.0
	v_add_f32_e32 v200, v202, v200
	s_add_i32 s38, s24, 1
	v_readlane_b32 s26, v199, s38
	s_mov_b32 s39, 1
	v_readlane_b32 s25, v216, s39
	v_add_f32_dpp v200, v200, v200 quad_perm:[1,0,3,2] row_mask:0xf bank_mask:0xf bound_ctrl:1
	s_nop 1
	v_add_f32_dpp v200, v200, v200 quad_perm:[2,3,0,1] row_mask:0xf bank_mask:0xf bound_ctrl:1
	s_nop 1
	v_add_f32_dpp v200, v200, v200 row_half_mirror row_mask:0xf bank_mask:0xf bound_ctrl:1
	s_nop 1
	v_add_f32_dpp v200, v200, v200 row_mirror row_mask:0xf bank_mask:0xf bound_ctrl:1
	s_nop 1
	v_add_f32_dpp v200, v200, v200 row_bcast:15 row_mask:0xa bank_mask:0xf
	s_nop 1
	v_add_f32_dpp v200, v200, v200 row_bcast:31 row_mask:0xc bank_mask:0xf
	s_nop 0
	v_readlane_b32 s27, v200, 63
	s_mul_i32 s40, s25, 0xc00
	s_add_u32 s28, s62, s40
	s_addc_u32 s29, s63, 0
	global_load_dwordx4 v[110:113], v1, s[28:29]
	global_load_dwordx4 v[114:117], v1, s[28:29] offset:2048
	global_load_dwordx4 v[118:121], v1, s[28:29] offset:1024
	v_mul_f32_e32 v204, s27, v212
	v_mul_f32_e32 v205, 0x3f3504f3, v204
	v_cmp_lt_f32_e64 s[32:33], |v205|, 1.0
	s_and_b64 vcc, exec, s[32:33]
	s_cbranch_vccnz .Lsm_35
	v_fma_f32 v208, |v205|, s9, v214
	v_fma_f32 v208, |v205|, v208, s10
	v_fma_f32 v208, |v205|, v208, s11
	v_fma_f32 v208, |v205|, v208, s12
	v_fma_f32 v208, |v205|, v208, s13
	v_fma_f32 v208, |v205|, v208, s14
	v_fma_f32 v208, |v205|, v208, |v205|
	v_mul_f32_e32 v209, 0xbfb8aa3b, v208
	v_fma_f32 v210, v208, s15, -v209
	v_rndne_f32_e32 v211, v209
	v_fmac_f32_e32 v210, 0xb2a5705f, v208
	v_sub_f32_e32 v209, v209, v211
	v_add_f32_e32 v209, v209, v210
	v_cvt_i32_f32_e32 v210, v211
	v_exp_f32_e32 v209, v209
	v_cmp_nlt_f32_e32 vcc, s16, v208
	v_ldexp_f32 v209, v209, v210
	s_nop 0
	v_cndmask_b32_e32 v209, 0, v209, vcc
	v_cmp_ngt_f32_e32 vcc, s17, v208
	s_nop 1
	v_cndmask_b32_e32 v208, v215, v209, vcc
	v_sub_f32_e32 v210, 1.0, v208
	s_branch .Ljn_35

; DEV float gelu_exact(float v) { return 0.5f * v * (1.f + erff(v * 0.7071067811865476f)); }
; DEV void peer_gather_token(const Params& p, int tok) {
;     ...
;   auto issue = [&](int k, int slot) {
;     const int e = (k < 64) ? __builtin_amdgcn_readlane(e0, k) : __builtin_amdgcn_readlane(e1, k - 64);
;     const unsigned char* dr = p.down8 + (size_t)e * ROW6 + lane * 24;
;     const unsigned char* ur = p.up8 + (size_t)e * ROW6 + lane * 24;
; #pragma unroll
;     for (int i = 0; i < 3; ++i) { dn[slot][i] = *(const u32x2*)(dr + i * 8); up[slot][i] = *(const u32x2*)(ur + i * 8); }
;   };
;   issue(0, 0); issue(1, 1); issue(2, 2);
; #pragma unroll 1
;   for (int k4 = 0; k4 < 128; k4 += 4) {
; #pragma unroll
;     for (int s = 0; s < 4; ++s) {
;       const int k = k4 + s;
;       if (k + 3 < 128) issue(k + 3, (s + 3) & 3);
;       const v6u dq = v6u{dn[s][0][0], dn[s][0][1], dn[s][1][0], dn[s][1][1], dn[s][2][0], dn[s][2][1]};
;       const v32f dv = __builtin_amdgcn_cvt_scalef32_pk32_f32_fp6(dq, 1.0f);
;       float d0 = 0.f, d1 = 0.f, d2 = 0.f, d3 = 0.f;
; #pragma unroll
;       for (int i = 0; i < 8; ++i) { d0 += dv[4 * i] * hx[4 * i]; d1 += dv[4 * i + 1] * hx[4 * i + 1]; d2 += dv[4 * i + 2] * hx[4 * i + 2]; d3 += dv[4 * i + 3] * hx[4 * i + 3]; }
;       const float d = wave_sum_fast((d0 + d1) + (d2 + d3)) * (1.f / DOWN_SCALE);
;       const float gk = __builtin_bit_cast(float, (k < 64) ? __builtin_amdgcn_readlane(g0, k) : __builtin_amdgcn_readlane(g1, k - 64));
;       const float act = gelu_exact(d) * gk * (1.f / UP_SCALE);
;       const v6u uq = v6u{up[s][0][0], up[s][0][1], up[s][1][0], up[s][1][1], up[s][2][0], up[s][2][1]};
;       const v32f uv = __builtin_amdgcn_cvt_scalef32_pk32_f32_fp6(uq, 1.0f);
; #pragma unroll
;       for (int i = 0; i < 32; ++i) acc[i] += act * uv[i];
.Ljn_35:
	v_bfi_b32 v209, s18, v210, v205
	v_mul_f32_e32 v208, 0.5, v204
	v_add_f32_e32 v209, 1.0, v209
	v_mul_f32_e32 v208, v208, v209
	v_mul_f32_e32 v208, s26, v208
	v_mul_f32_e32 v206, 0x3e800000, v208
	v_pk_fma_f32 v[66:67], v[2:3], v[206:207], v[66:67] op_sel_hi:[1,0,1]
	v_pk_fma_f32 v[68:69], v[4:5], v[206:207], v[68:69] op_sel_hi:[1,0,1]
	v_pk_fma_f32 v[70:71], v[6:7], v[206:207], v[70:71] op_sel_hi:[1,0,1]
	v_pk_fma_f32 v[72:73], v[8:9], v[206:207], v[72:73] op_sel_hi:[1,0,1]
	v_pk_fma_f32 v[74:75], v[10:11], v[206:207], v[74:75] op_sel_hi:[1,0,1]
	v_pk_fma_f32 v[76:77], v[12:13], v[206:207], v[76:77] op_sel_hi:[1,0,1]
	v_pk_fma_f32 v[78:79], v[14:15], v[206:207], v[78:79] op_sel_hi:[1,0,1]
	v_pk_fma_f32 v[80:81], v[16:17], v[206:207], v[80:81] op_sel_hi:[1,0,1]
	v_pk_fma_f32 v[82:83], v[18:19], v[206:207], v[82:83] op_sel_hi:[1,0,1]
	v_pk_fma_f32 v[84:85], v[20:21], v[206:207], v[84:85] op_sel_hi:[1,0,1]
	v_pk_fma_f32 v[86:87], v[22:23], v[206:207], v[86:87] op_sel_hi:[1,0,1]
	v_pk_fma_f32 v[88:89], v[24:25], v[206:207], v[88:89] op_sel_hi:[1,0,1]
	v_pk_fma_f32 v[90:91], v[26:27], v[206:207], v[90:91] op_sel_hi:[1,0,1]
	v_pk_fma_f32 v[92:93], v[28:29], v[206:207], v[92:93] op_sel_hi:[1,0,1]
	v_pk_fma_f32 v[94:95], v[30:31], v[206:207], v[94:95] op_sel_hi:[1,0,1]
	v_pk_fma_f32 v[96:97], v[32:33], v[206:207], v[96:97] op_sel_hi:[1,0,1]
	s_waitcnt vmcnt(21)
	v_cvt_scalef32_pk32_f32_fp6 v[2:33], v[122:127], 1.0
	v_mul_f32_e32 v200, v2, v34
	v_mul_f32_e32 v201, v3, v35
	v_mul_f32_e32 v202, v4, v36
	v_mul_f32_e32 v203, v5, v37
	v_fmac_f32_e32 v200, v6, v38
	v_fmac_f32_e32 v201, v7, v39
	v_fmac_f32_e32 v202, v8, v40
	v_fmac_f32_e32 v203, v9, v41
	v_fmac_f32_e32 v200, v10, v42
	v_fmac_f32_e32 v201, v11, v43
	v_fmac_f32_e32 v202, v12, v44
	v_fmac_f32_e32 v203, v13, v45
	v_fmac_f32_e32 v200, v14, v46
	v_fmac_f32_e32 v201, v15, v47
	v_fmac_f32_e32 v202, v16, v48
	v_fmac_f32_e32 v203, v17, v49
	v_fmac_f32_e32 v200, v18, v50
	v_fmac_f32_e32 v201, v19, v51
	v_fmac_f32_e32 v202, v20, v52
	v_fmac_f32_e32 v203, v21, v53
	v_fmac_f32_e32 v200, v22, v54
	v_fmac_f32_e32 v201, v23, v55
	v_fmac_f32_e32 v202, v24, v56
	v_fmac_f32_e32 v203, v25, v57
	v_fmac_f32_e32 v200, v26, v58
	v_fmac_f32_e32 v201, v27, v59
	v_fmac_f32_e32 v202, v28, v60
	v_fmac_f32_e32 v203, v29, v61
	v_fmac_f32_e32 v200, v30, v62
	v_fmac_f32_e32 v201, v31, v63
	v_fmac_f32_e32 v202, v32, v64
	v_fmac_f32_e32 v203, v33, v65
	v_add_f32_e32 v200, v201, v200
	v_add_f32_e32 v202, v203, v202
	v_cvt_scalef32_pk32_f32_fp6 v[2:33], v[128:133], 1.0
	v_add_f32_e32 v200, v202, v200
	s_add_i32 s38, s24, 2
	v_readlane_b32 s26, v199, s38
	s_mov_b32 s39, 2
	v_readlane_b32 s25, v216, s39
	v_add_f32_dpp v200, v200, v200 quad_perm:[1,0,3,2] row_mask:0xf bank_mask:0xf bound_ctrl:1
	s_nop 1
	v_add_f32_dpp v200, v200, v200 quad_perm:[2,3,0,1] row_mask:0xf bank_mask:0xf bound_ctrl:1
	s_nop 1
	v_add_f32_dpp v200, v200, v200 row_half_mirror row_mask:0xf bank_mask:0xf bound_ctrl:1
	s_nop 1
	v_add_f32_dpp v200, v200, v200 row_mirror row_mask:0xf bank_mask:0xf bound_ctrl:1
	s_nop 1
	v_add_f32_dpp v200, v200, v200 row_bcast:15 row_mask:0xa bank_mask:0xf
	s_nop 1
	v_add_f32_dpp v200, v200, v200 row_bcast:31 row_mask:0xc bank_mask:0xf
	s_nop 0
	v_readlane_b32 s27, v200, 63
	s_mul_i32 s40, s25, 0xc00
	s_add_u32 s28, s62, s40
	s_addc_u32 s29, s63, 0
	global_load_dwordx4 v[122:125], v1, s[28:29]
	global_load_dwordx4 v[126:129], v1, s[28:29] offset:2048
	global_load_dwordx4 v[130:133], v1, s[28:29] offset:1024
	v_mul_f32_e32 v204, s27, v212
	v_mul_f32_e32 v205, 0x3f3504f3, v204
	v_cmp_lt_f32_e64 s[32:33], |v205|, 1.0
	s_and_b64 vcc, exec, s[32:33]
	s_cbranch_vccnz .Lsm_37
	v_fma_f32 v208, |v205|, s9, v214
	v_fma_f32 v208, |v205|, v208, s10
	v_fma_f32 v208, |v205|, v208, s11
	v_fma_f32 v208, |v205|, v208, s12
	v_fma_f32 v208, |v205|, v208, s13
	v_fma_f32 v208, |v205|, v208, s14
	v_fma_f32 v208, |v205|, v208, |v205|
	v_mul_f32_e32 v209, 0xbfb8aa3b, v208
	v_fma_f32 v210, v208, s15, -v209
	v_rndne_f32_e32 v211, v209
	v_fmac_f32_e32 v210, 0xb2a5705f, v208
	v_sub_f32_e32 v209, v209, v211
	v_add_f32_e32 v209, v209, v210
	v_cvt_i32_f32_e32 v210, v211
	v_exp_f32_e32 v209, v209
	v_cmp_nlt_f32_e32 vcc, s16, v208
	v_ldexp_f32 v209, v209, v210
	s_nop 0
	v_cndmask_b32_e32 v209, 0, v209, vcc
	v_cmp_ngt_f32_e32 vcc, s17, v208
	s_nop 1
	v_cndmask_b32_e32 v208, v215, v209, vcc
	v_sub_f32_e32 v210, 1.0, v208
	s_branch .Ljn_37

; DEV float gelu_exact(float v) { return 0.5f * v * (1.f + erff(v * 0.7071067811865476f)); }
; DEV void peer_gather_token(const Params& p, int tok) {
;     ...
;   auto issue = [&](int k, int slot) {
;     const int e = (k < 64) ? __builtin_amdgcn_readlane(e0, k) : __builtin_amdgcn_readlane(e1, k - 64);
;     const unsigned char* dr = p.down8 + (size_t)e * ROW6 + lane * 24;
;     const unsigned char* ur = p.up8 + (size_t)e * ROW6 + lane * 24;
; #pragma unroll
;     for (int i = 0; i < 3; ++i) { dn[slot][i] = *(const u32x2*)(dr + i * 8); up[slot][i] = *(const u32x2*)(ur + i * 8); }
;   };
;   issue(0, 0); issue(1, 1); issue(2, 2);
; #pragma unroll 1
;   for (int k4 = 0; k4 < 128; k4 += 4) {
; #pragma unroll
;     for (int s = 0; s < 4; ++s) {
;       const int k = k4 + s;
;       if (k + 3 < 128) issue(k + 3, (s + 3) & 3);
;       const v6u dq = v6u{dn[s][0][0], dn[s][0][1], dn[s][1][0], dn[s][1][1], dn[s][2][0], dn[s][2][1]};
;       const v32f dv = __builtin_amdgcn_cvt_scalef32_pk32_f32_fp6(dq, 1.0f);
;       float d0 = 0.f, d1 = 0.f, d2 = 0.f, d3 = 0.f;
; #pragma unroll
;       for (int i = 0; i < 8; ++i) { d0 += dv[4 * i] * hx[4 * i]; d1 += dv[4 * i + 1] * hx[4 * i + 1]; d2 += dv[4 * i + 2] * hx[4 * i + 2]; d3 += dv[4 * i + 3] * hx[4 * i + 3]; }
;       const float d = wave_sum_fast((d0 + d1) + (d2 + d3)) * (1.f / DOWN_SCALE);
;       const float gk = __builtin_bit_cast(float, (k < 64) ? __builtin_amdgcn_readlane(g0, k) : __builtin_amdgcn_readlane(g1, k - 64));
;       const float act = gelu_exact(d) * gk * (1.f / UP_SCALE);
;       const v6u uq = v6u{up[s][0][0], up[s][0][1], up[s][1][0], up[s][1][1], up[s][2][0], up[s][2][1]};
;       const v32f uv = __builtin_amdgcn_cvt_scalef32_pk32_f32_fp6(uq, 1.0f);
; #pragma unroll
;       for (int i = 0; i < 32; ++i) acc[i] += act * uv[i];
.Ljn_37:
	v_bfi_b32 v209, s18, v210, v205
	v_mul_f32_e32 v208, 0.5, v204
	v_add_f32_e32 v209, 1.0, v209
	v_mul_f32_e32 v208, v208, v209
	v_mul_f32_e32 v208, s26, v208
	v_mul_f32_e32 v206, 0x3e800000, v208
	v_pk_fma_f32 v[66:67], v[2:3], v[206:207], v[66:67] op_sel_hi:[1,0,1]
	v_pk_fma_f32 v[68:69], v[4:5], v[206:207], v[68:69] op_sel_hi:[1,0,1]
	v_pk_fma_f32 v[70:71], v[6:7], v[206:207], v[70:71] op_sel_hi:[1,0,1]
	v_pk_fma_f32 v[72:73], v[8:9], v[206:207], v[72:73] op_sel_hi:[1,0,1]
	v_pk_fma_f32 v[74:75], v[10:11], v[206:207], v[74:75] op_sel_hi:[1,0,1]
	v_pk_fma_f32 v[76:77], v[12:13], v[206:207], v[76:77] op_sel_hi:[1,0,1]
	v_pk_fma_f32 v[78:79], v[14:15], v[206:207], v[78:79] op_sel_hi:[1,0,1]
	v_pk_fma_f32 v[80:81], v[16:17], v[206:207], v[80:81] op_sel_hi:[1,0,1]
	v_pk_fma_f32 v[82:83], v[18:19], v[206:207], v[82:83] op_sel_hi:[1,0,1]
	v_pk_fma_f32 v[84:85], v[20:21], v[206:207], v[84:85] op_sel_hi:[1,0,1]
	v_pk_fma_f32 v[86:87], v[22:23], v[206:207], v[86:87] op_sel_hi:[1,0,1]
	v_pk_fma_f32 v[88:89], v[24:25], v[206:207], v[88:89] op_sel_hi:[1,0,1]
	v_pk_fma_f32 v[90:91], v[26:27], v[206:207], v[90:91] op_sel_hi:[1,0,1]
	v_pk_fma_f32 v[92:93], v[28:29], v[206:207], v[92:93] op_sel_hi:[1,0,1]
	v_pk_fma_f32 v[94:95], v[30:31], v[206:207], v[94:95] op_sel_hi:[1,0,1]
	v_pk_fma_f32 v[96:97], v[32:33], v[206:207], v[96:97] op_sel_hi:[1,0,1]
	s_waitcnt vmcnt(21)
	v_cvt_scalef32_pk32_f32_fp6 v[2:33], v[134:139], 1.0
	v_mul_f32_e32 v200, v2, v34
	v_mul_f32_e32 v201, v3, v35
	v_mul_f32_e32 v202, v4, v36
	v_mul_f32_e32 v203, v5, v37
	v_fmac_f32_e32 v200, v6, v38
	v_fmac_f32_e32 v201, v7, v39
	v_fmac_f32_e32 v202, v8, v40
	v_fmac_f32_e32 v203, v9, v41
	v_fmac_f32_e32 v200, v10, v42
	v_fmac_f32_e32 v201, v11, v43
	v_fmac_f32_e32 v202, v12, v44
	v_fmac_f32_e32 v203, v13, v45
	v_fmac_f32_e32 v200, v14, v46
	v_fmac_f32_e32 v201, v15, v47
	v_fmac_f32_e32 v202, v16, v48
	v_fmac_f32_e32 v203, v17, v49
	v_fmac_f32_e32 v200, v18, v50
	v_fmac_f32_e32 v201, v19, v51
	v_fmac_f32_e32 v202, v20, v52
	v_fmac_f32_e32 v203, v21, v53
	v_fmac_f32_e32 v200, v22, v54
	v_fmac_f32_e32 v201, v23, v55
	v_fmac_f32_e32 v202, v24, v56
	v_fmac_f32_e32 v203, v25, v57
	v_fmac_f32_e32 v200, v26, v58
	v_fmac_f32_e32 v201, v27, v59
	v_fmac_f32_e32 v202, v28, v60
	v_fmac_f32_e32 v203, v29, v61
	v_fmac_f32_e32 v200, v30, v62
	v_fmac_f32_e32 v201, v31, v63
	v_fmac_f32_e32 v202, v32, v64
	v_fmac_f32_e32 v203, v33, v65
	v_add_f32_e32 v200, v201, v200
	v_add_f32_e32 v202, v203, v202
	v_cvt_scalef32_pk32_f32_fp6 v[2:33], v[140:145], 1.0
	v_add_f32_e32 v200, v202, v200
	s_add_i32 s38, s24, 3
	v_readlane_b32 s26, v199, s38
	s_mov_b32 s39, 3
	v_readlane_b32 s25, v216, s39
	v_add_f32_dpp v200, v200, v200 quad_perm:[1,0,3,2] row_mask:0xf bank_mask:0xf bound_ctrl:1
	s_nop 1
	v_add_f32_dpp v200, v200, v200 quad_perm:[2,3,0,1] row_mask:0xf bank_mask:0xf bound_ctrl:1
	s_nop 1
	v_add_f32_dpp v200, v200, v200 row_half_mirror row_mask:0xf bank_mask:0xf bound_ctrl:1
	s_nop 1
	v_add_f32_dpp v200, v200, v200 row_mirror row_mask:0xf bank_mask:0xf bound_ctrl:1
	s_nop 1
	v_add_f32_dpp v200, v200, v200 row_bcast:15 row_mask:0xa bank_mask:0xf
	s_nop 1
	v_add_f32_dpp v200, v200, v200 row_bcast:31 row_mask:0xc bank_mask:0xf
	s_nop 0
	v_readlane_b32 s27, v200, 63
	s_mul_i32 s40, s25, 0xc00
	s_add_u32 s28, s62, s40
	s_addc_u32 s29, s63, 0
	global_load_dwordx4 v[134:137], v1, s[28:29]
	global_load_dwordx4 v[138:141], v1, s[28:29] offset:2048
	global_load_dwordx4 v[142:145], v1, s[28:29] offset:1024
	v_mul_f32_e32 v204, s27, v212
	v_mul_f32_e32 v205, 0x3f3504f3, v204
	v_cmp_lt_f32_e64 s[32:33], |v205|, 1.0
	s_and_b64 vcc, exec, s[32:33]
	s_cbranch_vccnz .Lsm_39
	v_fma_f32 v208, |v205|, s9, v214
	v_fma_f32 v208, |v205|, v208, s10
	v_fma_f32 v208, |v205|, v208, s11
	v_fma_f32 v208, |v205|, v208, s12
	v_fma_f32 v208, |v205|, v208, s13
	v_fma_f32 v208, |v205|, v208, s14
	v_fma_f32 v208, |v205|, v208, |v205|
	v_mul_f32_e32 v209, 0xbfb8aa3b, v208
	v_fma_f32 v210, v208, s15, -v209
	v_rndne_f32_e32 v211, v209
	v_fmac_f32_e32 v210, 0xb2a5705f, v208
	v_sub_f32_e32 v209, v209, v211
	v_add_f32_e32 v209, v209, v210
	v_cvt_i32_f32_e32 v210, v211
	v_exp_f32_e32 v209, v209
	v_cmp_nlt_f32_e32 vcc, s16, v208
	v_ldexp_f32 v209, v209, v210
	s_nop 0
	v_cndmask_b32_e32 v209, 0, v209, vcc
	v_cmp_ngt_f32_e32 vcc, s17, v208
	s_nop 1
	v_cndmask_b32_e32 v208, v215, v209, vcc
	v_sub_f32_e32 v210, 1.0, v208
	s_branch .Ljn_39

; DEV float gelu_exact(float v) { return 0.5f * v * (1.f + erff(v * 0.7071067811865476f)); }
; DEV void peer_gather_token(const Params& p, int tok) {
;     ...
;   auto issue = [&](int k, int slot) {
;     const int e = (k < 64) ? __builtin_amdgcn_readlane(e0, k) : __builtin_amdgcn_readlane(e1, k - 64);
;     const unsigned char* dr = p.down8 + (size_t)e * ROW6 + lane * 24;
;     const unsigned char* ur = p.up8 + (size_t)e * ROW6 + lane * 24;
; #pragma unroll
;     for (int i = 0; i < 3; ++i) { dn[slot][i] = *(const u32x2*)(dr + i * 8); up[slot][i] = *(const u32x2*)(ur + i * 8); }
;   };
;   issue(0, 0); issue(1, 1); issue(2, 2);
; #pragma unroll 1
;   for (int k4 = 0; k4 < 128; k4 += 4) {
; #pragma unroll
;     for (int s = 0; s < 4; ++s) {
;       const int k = k4 + s;
;       if (k + 3 < 128) issue(k + 3, (s + 3) & 3);
;       const v6u dq = v6u{dn[s][0][0], dn[s][0][1], dn[s][1][0], dn[s][1][1], dn[s][2][0], dn[s][2][1]};
;       const v32f dv = __builtin_amdgcn_cvt_scalef32_pk32_f32_fp6(dq, 1.0f);
;       float d0 = 0.f, d1 = 0.f, d2 = 0.f, d3 = 0.f;
; #pragma unroll
;       for (int i = 0; i < 8; ++i) { d0 += dv[4 * i] * hx[4 * i]; d1 += dv[4 * i + 1] * hx[4 * i + 1]; d2 += dv[4 * i + 2] * hx[4 * i + 2]; d3 += dv[4 * i + 3] * hx[4 * i + 3]; }
;       const float d = wave_sum_fast((d0 + d1) + (d2 + d3)) * (1.f / DOWN_SCALE);
;       const float gk = __builtin_bit_cast(float, (k < 64) ? __builtin_amdgcn_readlane(g0, k) : __builtin_amdgcn_readlane(g1, k - 64));
;       const float act = gelu_exact(d) * gk * (1.f / UP_SCALE);
;       const v6u uq = v6u{up[s][0][0], up[s][0][1], up[s][1][0], up[s][1][1], up[s][2][0], up[s][2][1]};
;       const v32f uv = __builtin_amdgcn_cvt_scalef32_pk32_f32_fp6(uq, 1.0f);
; #pragma unroll
;       for (int i = 0; i < 32; ++i) acc[i] += act * uv[i];
.Ljn_39:
	v_bfi_b32 v209, s18, v210, v205
	v_mul_f32_e32 v208, 0.5, v204
	v_add_f32_e32 v209, 1.0, v209
	v_mul_f32_e32 v208, v208, v209
	v_mul_f32_e32 v208, s26, v208
	v_mul_f32_e32 v206, 0x3e800000, v208
	v_pk_fma_f32 v[66:67], v[2:3], v[206:207], v[66:67] op_sel_hi:[1,0,1]
	v_pk_fma_f32 v[68:69], v[4:5], v[206:207], v[68:69] op_sel_hi:[1,0,1]
	v_pk_fma_f32 v[70:71], v[6:7], v[206:207], v[70:71] op_sel_hi:[1,0,1]
	v_pk_fma_f32 v[72:73], v[8:9], v[206:207], v[72:73] op_sel_hi:[1,0,1]
	v_pk_fma_f32 v[74:75], v[10:11], v[206:207], v[74:75] op_sel_hi:[1,0,1]
	v_pk_fma_f32 v[76:77], v[12:13], v[206:207], v[76:77] op_sel_hi:[1,0,1]
	v_pk_fma_f32 v[78:79], v[14:15], v[206:207], v[78:79] op_sel_hi:[1,0,1]
	v_pk_fma_f32 v[80:81], v[16:17], v[206:207], v[80:81] op_sel_hi:[1,0,1]
	v_pk_fma_f32 v[82:83], v[18:19], v[206:207], v[82:83] op_sel_hi:[1,0,1]
	v_pk_fma_f32 v[84:85], v[20:21], v[206:207], v[84:85] op_sel_hi:[1,0,1]
	v_pk_fma_f32 v[86:87], v[22:23], v[206:207], v[86:87] op_sel_hi:[1,0,1]
	v_pk_fma_f32 v[88:89], v[24:25], v[206:207], v[88:89] op_sel_hi:[1,0,1]
	v_pk_fma_f32 v[90:91], v[26:27], v[206:207], v[90:91] op_sel_hi:[1,0,1]
	v_pk_fma_f32 v[92:93], v[28:29], v[206:207], v[92:93] op_sel_hi:[1,0,1]
	v_pk_fma_f32 v[94:95], v[30:31], v[206:207], v[94:95] op_sel_hi:[1,0,1]
	v_pk_fma_f32 v[96:97], v[32:33], v[206:207], v[96:97] op_sel_hi:[1,0,1]
	s_waitcnt vmcnt(21)
	v_cvt_scalef32_pk32_f32_fp6 v[2:33], v[146:151], 1.0
	v_mul_f32_e32 v200, v2, v34
	v_mul_f32_e32 v201, v3, v35
	v_mul_f32_e32 v202, v4, v36
	v_mul_f32_e32 v203, v5, v37
	v_fmac_f32_e32 v200, v6, v38
	v_fmac_f32_e32 v201, v7, v39
	v_fmac_f32_e32 v202, v8, v40
	v_fmac_f32_e32 v203, v9, v41
	v_fmac_f32_e32 v200, v10, v42
	v_fmac_f32_e32 v201, v11, v43
	v_fmac_f32_e32 v202, v12, v44
	v_fmac_f32_e32 v203, v13, v45
	v_fmac_f32_e32 v200, v14, v46
	v_fmac_f32_e32 v201, v15, v47
	v_fmac_f32_e32 v202, v16, v48
	v_fmac_f32_e32 v203, v17, v49
	v_fmac_f32_e32 v200, v18, v50
	v_fmac_f32_e32 v201, v19, v51
	v_fmac_f32_e32 v202, v20, v52
	v_fmac_f32_e32 v203, v21, v53
	v_fmac_f32_e32 v200, v22, v54
	v_fmac_f32_e32 v201, v23, v55
	v_fmac_f32_e32 v202, v24, v56
	v_fmac_f32_e32 v203, v25, v57
	v_fmac_f32_e32 v200, v26, v58
	v_fmac_f32_e32 v201, v27, v59
	v_fmac_f32_e32 v202, v28, v60
	v_fmac_f32_e32 v203, v29, v61
	v_fmac_f32_e32 v200, v30, v62
	v_fmac_f32_e32 v201, v31, v63
	v_fmac_f32_e32 v202, v32, v64
	v_fmac_f32_e32 v203, v33, v65
	v_add_f32_e32 v200, v201, v200
	v_add_f32_e32 v202, v203, v202
	v_cvt_scalef32_pk32_f32_fp6 v[2:33], v[152:157], 1.0
	v_add_f32_e32 v200, v202, v200
	s_add_i32 s38, s24, 4
	v_readlane_b32 s26, v199, s38
	s_mov_b32 s39, 4
	v_readlane_b32 s25, v216, s39
	v_add_f32_dpp v200, v200, v200 quad_perm:[1,0,3,2] row_mask:0xf bank_mask:0xf bound_ctrl:1
	s_nop 1
	v_add_f32_dpp v200, v200, v200 quad_perm:[2,3,0,1] row_mask:0xf bank_mask:0xf bound_ctrl:1
	s_nop 1
	v_add_f32_dpp v200, v200, v200 row_half_mirror row_mask:0xf bank_mask:0xf bound_ctrl:1
	s_nop 1
	v_add_f32_dpp v200, v200, v200 row_mirror row_mask:0xf bank_mask:0xf bound_ctrl:1
	s_nop 1
	v_add_f32_dpp v200, v200, v200 row_bcast:15 row_mask:0xa bank_mask:0xf
	s_nop 1
	v_add_f32_dpp v200, v200, v200 row_bcast:31 row_mask:0xc bank_mask:0xf
	s_nop 0
	v_readlane_b32 s27, v200, 63
	s_mul_i32 s40, s25, 0xc00
	s_add_u32 s28, s62, s40
	s_addc_u32 s29, s63, 0
	global_load_dwordx4 v[146:149], v1, s[28:29]
	global_load_dwordx4 v[150:153], v1, s[28:29] offset:2048
	global_load_dwordx4 v[154:157], v1, s[28:29] offset:1024
	v_mul_f32_e32 v204, s27, v212
	v_mul_f32_e32 v205, 0x3f3504f3, v204
	v_cmp_lt_f32_e64 s[32:33], |v205|, 1.0
	s_and_b64 vcc, exec, s[32:33]
	s_cbranch_vccnz .Lsm_41
	v_fma_f32 v208, |v205|, s9, v214
	v_fma_f32 v208, |v205|, v208, s10
	v_fma_f32 v208, |v205|, v208, s11
	v_fma_f32 v208, |v205|, v208, s12
	v_fma_f32 v208, |v205|, v208, s13
	v_fma_f32 v208, |v205|, v208, s14
	v_fma_f32 v208, |v205|, v208, |v205|
	v_mul_f32_e32 v209, 0xbfb8aa3b, v208
	v_fma_f32 v210, v208, s15, -v209
	v_rndne_f32_e32 v211, v209
	v_fmac_f32_e32 v210, 0xb2a5705f, v208
	v_sub_f32_e32 v209, v209, v211
	v_add_f32_e32 v209, v209, v210
	v_cvt_i32_f32_e32 v210, v211
	v_exp_f32_e32 v209, v209
	v_cmp_nlt_f32_e32 vcc, s16, v208
	v_ldexp_f32 v209, v209, v210
	s_nop 0
	v_cndmask_b32_e32 v209, 0, v209, vcc
	v_cmp_ngt_f32_e32 vcc, s17, v208
	s_nop 1
	v_cndmask_b32_e32 v208, v215, v209, vcc
	v_sub_f32_e32 v210, 1.0, v208
	s_branch .Ljn_41

; DEV float gelu_exact(float v) { return 0.5f * v * (1.f + erff(v * 0.7071067811865476f)); }
; DEV void peer_gather_token(const Params& p, int tok) {
;     ...
;   auto issue = [&](int k, int slot) {
;     const int e = (k < 64) ? __builtin_amdgcn_readlane(e0, k) : __builtin_amdgcn_readlane(e1, k - 64);
;     const unsigned char* dr = p.down8 + (size_t)e * ROW6 + lane * 24;
;     const unsigned char* ur = p.up8 + (size_t)e * ROW6 + lane * 24;
; #pragma unroll
;     for (int i = 0; i < 3; ++i) { dn[slot][i] = *(const u32x2*)(dr + i * 8); up[slot][i] = *(const u32x2*)(ur + i * 8); }
;   };
;   issue(0, 0); issue(1, 1); issue(2, 2);
; #pragma unroll 1
;   for (int k4 = 0; k4 < 128; k4 += 4) {
; #pragma unroll
;     for (int s = 0; s < 4; ++s) {
;       const int k = k4 + s;
;       if (k + 3 < 128) issue(k + 3, (s + 3) & 3);
;       const v6u dq = v6u{dn[s][0][0], dn[s][0][1], dn[s][1][0], dn[s][1][1], dn[s][2][0], dn[s][2][1]};
;       const v32f dv = __builtin_amdgcn_cvt_scalef32_pk32_f32_fp6(dq, 1.0f);
;       float d0 = 0.f, d1 = 0.f, d2 = 0.f, d3 = 0.f;
; #pragma unroll
;       for (int i = 0; i < 8; ++i) { d0 += dv[4 * i] * hx[4 * i]; d1 += dv[4 * i + 1] * hx[4 * i + 1]; d2 += dv[4 * i + 2] * hx[4 * i + 2]; d3 += dv[4 * i + 3] * hx[4 * i + 3]; }
;       const float d = wave_sum_fast((d0 + d1) + (d2 + d3)) * (1.f / DOWN_SCALE);
;       const float gk = __builtin_bit_cast(float, (k < 64) ? __builtin_amdgcn_readlane(g0, k) : __builtin_amdgcn_readlane(g1, k - 64));
;       const float act = gelu_exact(d) * gk * (1.f / UP_SCALE);
;       const v6u uq = v6u{up[s][0][0], up[s][0][1], up[s][1][0], up[s][1][1], up[s][2][0], up[s][2][1]};
;       const v32f uv = __builtin_amdgcn_cvt_scalef32_pk32_f32_fp6(uq, 1.0f);
; #pragma unroll
;       for (int i = 0; i < 32; ++i) acc[i] += act * uv[i];
.Ljn_41:
	v_bfi_b32 v209, s18, v210, v205
	v_mul_f32_e32 v208, 0.5, v204
	v_add_f32_e32 v209, 1.0, v209
	v_mul_f32_e32 v208, v208, v209
	v_mul_f32_e32 v208, s26, v208
	v_mul_f32_e32 v206, 0x3e800000, v208
	v_pk_fma_f32 v[66:67], v[2:3], v[206:207], v[66:67] op_sel_hi:[1,0,1]
	v_pk_fma_f32 v[68:69], v[4:5], v[206:207], v[68:69] op_sel_hi:[1,0,1]
	v_pk_fma_f32 v[70:71], v[6:7], v[206:207], v[70:71] op_sel_hi:[1,0,1]
	v_pk_fma_f32 v[72:73], v[8:9], v[206:207], v[72:73] op_sel_hi:[1,0,1]
	v_pk_fma_f32 v[74:75], v[10:11], v[206:207], v[74:75] op_sel_hi:[1,0,1]
	v_pk_fma_f32 v[76:77], v[12:13], v[206:207], v[76:77] op_sel_hi:[1,0,1]
	v_pk_fma_f32 v[78:79], v[14:15], v[206:207], v[78:79] op_sel_hi:[1,0,1]
	v_pk_fma_f32 v[80:81], v[16:17], v[206:207], v[80:81] op_sel_hi:[1,0,1]
	v_pk_fma_f32 v[82:83], v[18:19], v[206:207], v[82:83] op_sel_hi:[1,0,1]
	v_pk_fma_f32 v[84:85], v[20:21], v[206:207], v[84:85] op_sel_hi:[1,0,1]
	v_pk_fma_f32 v[86:87], v[22:23], v[206:207], v[86:87] op_sel_hi:[1,0,1]
	v_pk_fma_f32 v[88:89], v[24:25], v[206:207], v[88:89] op_sel_hi:[1,0,1]
	v_pk_fma_f32 v[90:91], v[26:27], v[206:207], v[90:91] op_sel_hi:[1,0,1]
	v_pk_fma_f32 v[92:93], v[28:29], v[206:207], v[92:93] op_sel_hi:[1,0,1]
	v_pk_fma_f32 v[94:95], v[30:31], v[206:207], v[94:95] op_sel_hi:[1,0,1]
	v_pk_fma_f32 v[96:97], v[32:33], v[206:207], v[96:97] op_sel_hi:[1,0,1]
	s_waitcnt vmcnt(21)
	v_cvt_scalef32_pk32_f32_fp6 v[2:33], v[158:163], 1.0
	v_mul_f32_e32 v200, v2, v34
	v_mul_f32_e32 v201, v3, v35
	v_mul_f32_e32 v202, v4, v36
	v_mul_f32_e32 v203, v5, v37
	v_fmac_f32_e32 v200, v6, v38
	v_fmac_f32_e32 v201, v7, v39
	v_fmac_f32_e32 v202, v8, v40
	v_fmac_f32_e32 v203, v9, v41
	v_fmac_f32_e32 v200, v10, v42
	v_fmac_f32_e32 v201, v11, v43
	v_fmac_f32_e32 v202, v12, v44
	v_fmac_f32_e32 v203, v13, v45
	v_fmac_f32_e32 v200, v14, v46
	v_fmac_f32_e32 v201, v15, v47
	v_fmac_f32_e32 v202, v16, v48
	v_fmac_f32_e32 v203, v17, v49
	v_fmac_f32_e32 v200, v18, v50
	v_fmac_f32_e32 v201, v19, v51
	v_fmac_f32_e32 v202, v20, v52
	v_fmac_f32_e32 v203, v21, v53
	v_fmac_f32_e32 v200, v22, v54
	v_fmac_f32_e32 v201, v23, v55
	v_fmac_f32_e32 v202, v24, v56
	v_fmac_f32_e32 v203, v25, v57
	v_fmac_f32_e32 v200, v26, v58
	v_fmac_f32_e32 v201, v27, v59
	v_fmac_f32_e32 v202, v28, v60
	v_fmac_f32_e32 v203, v29, v61
	v_fmac_f32_e32 v200, v30, v62
	v_fmac_f32_e32 v201, v31, v63
	v_fmac_f32_e32 v202, v32, v64
	v_fmac_f32_e32 v203, v33, v65
	v_add_f32_e32 v200, v201, v200
	v_add_f32_e32 v202, v203, v202
	v_cvt_scalef32_pk32_f32_fp6 v[2:33], v[164:169], 1.0
	v_add_f32_e32 v200, v202, v200
	s_add_i32 s38, s24, 5
	v_readlane_b32 s26, v199, s38
	s_mov_b32 s39, 5
	v_readlane_b32 s25, v216, s39
	v_add_f32_dpp v200, v200, v200 quad_perm:[1,0,3,2] row_mask:0xf bank_mask:0xf bound_ctrl:1
	s_nop 1
	v_add_f32_dpp v200, v200, v200 quad_perm:[2,3,0,1] row_mask:0xf bank_mask:0xf bound_ctrl:1
	s_nop 1
	v_add_f32_dpp v200, v200, v200 row_half_mirror row_mask:0xf bank_mask:0xf bound_ctrl:1
	s_nop 1
	v_add_f32_dpp v200, v200, v200 row_mirror row_mask:0xf bank_mask:0xf bound_ctrl:1
	s_nop 1
	v_add_f32_dpp v200, v200, v200 row_bcast:15 row_mask:0xa bank_mask:0xf
	s_nop 1
	v_add_f32_dpp v200, v200, v200 row_bcast:31 row_mask:0xc bank_mask:0xf
	s_nop 0
	v_readlane_b32 s27, v200, 63
	s_mul_i32 s40, s25, 0xc00
	s_add_u32 s28, s62, s40
	s_addc_u32 s29, s63, 0
	global_load_dwordx4 v[158:161], v1, s[28:29]
	global_load_dwordx4 v[162:165], v1, s[28:29] offset:2048
	global_load_dwordx4 v[166:169], v1, s[28:29] offset:1024
	v_mul_f32_e32 v204, s27, v212
	v_mul_f32_e32 v205, 0x3f3504f3, v204
	v_cmp_lt_f32_e64 s[32:33], |v205|, 1.0
	s_and_b64 vcc, exec, s[32:33]
	s_cbranch_vccnz .Lsm_43
	v_fma_f32 v208, |v205|, s9, v214
	v_fma_f32 v208, |v205|, v208, s10
	v_fma_f32 v208, |v205|, v208, s11
	v_fma_f32 v208, |v205|, v208, s12
	v_fma_f32 v208, |v205|, v208, s13
	v_fma_f32 v208, |v205|, v208, s14
	v_fma_f32 v208, |v205|, v208, |v205|
	v_mul_f32_e32 v209, 0xbfb8aa3b, v208
	v_fma_f32 v210, v208, s15, -v209
	v_rndne_f32_e32 v211, v209
	v_fmac_f32_e32 v210, 0xb2a5705f, v208
	v_sub_f32_e32 v209, v209, v211
	v_add_f32_e32 v209, v209, v210
	v_cvt_i32_f32_e32 v210, v211
	v_exp_f32_e32 v209, v209
	v_cmp_nlt_f32_e32 vcc, s16, v208
	v_ldexp_f32 v209, v209, v210
	s_nop 0
	v_cndmask_b32_e32 v209, 0, v209, vcc
	v_cmp_ngt_f32_e32 vcc, s17, v208
	s_nop 1
	v_cndmask_b32_e32 v208, v215, v209, vcc
	v_sub_f32_e32 v210, 1.0, v208
	s_branch .Ljn_43

; DEV float gelu_exact(float v) { return 0.5f * v * (1.f + erff(v * 0.7071067811865476f)); }
; DEV void peer_gather_token(const Params& p, int tok) {
;     ...
;   auto issue = [&](int k, int slot) {
;     const int e = (k < 64) ? __builtin_amdgcn_readlane(e0, k) : __builtin_amdgcn_readlane(e1, k - 64);
;     const unsigned char* dr = p.down8 + (size_t)e * ROW6 + lane * 24;
;     const unsigned char* ur = p.up8 + (size_t)e * ROW6 + lane * 24;
; #pragma unroll
;     for (int i = 0; i < 3; ++i) { dn[slot][i] = *(const u32x2*)(dr + i * 8); up[slot][i] = *(const u32x2*)(ur + i * 8); }
;   };
;   issue(0, 0); issue(1, 1); issue(2, 2);
; #pragma unroll 1
;   for (int k4 = 0; k4 < 128; k4 += 4) {
; #pragma unroll
;     for (int s = 0; s < 4; ++s) {
;       const int k = k4 + s;
;       if (k + 3 < 128) issue(k + 3, (s + 3) & 3);
;       const v6u dq = v6u{dn[s][0][0], dn[s][0][1], dn[s][1][0], dn[s][1][1], dn[s][2][0], dn[s][2][1]};
;       const v32f dv = __builtin_amdgcn_cvt_scalef32_pk32_f32_fp6(dq, 1.0f);
;       float d0 = 0.f, d1 = 0.f, d2 = 0.f, d3 = 0.f;
; #pragma unroll
;       for (int i = 0; i < 8; ++i) { d0 += dv[4 * i] * hx[4 * i]; d1 += dv[4 * i + 1] * hx[4 * i + 1]; d2 += dv[4 * i + 2] * hx[4 * i + 2]; d3 += dv[4 * i + 3] * hx[4 * i + 3]; }
;       const float d = wave_sum_fast((d0 + d1) + (d2 + d3)) * (1.f / DOWN_SCALE);
;       const float gk = __builtin_bit_cast(float, (k < 64) ? __builtin_amdgcn_readlane(g0, k) : __builtin_amdgcn_readlane(g1, k - 64));
;       const float act = gelu_exact(d) * gk * (1.f / UP_SCALE);
;       const v6u uq = v6u{up[s][0][0], up[s][0][1], up[s][1][0], up[s][1][1], up[s][2][0], up[s][2][1]};
;       const v32f uv = __builtin_amdgcn_cvt_scalef32_pk32_f32_fp6(uq, 1.0f);
; #pragma unroll
;       for (int i = 0; i < 32; ++i) acc[i] += act * uv[i];
.Ljn_43:
	v_bfi_b32 v209, s18, v210, v205
	v_mul_f32_e32 v208, 0.5, v204
	v_add_f32_e32 v209, 1.0, v209
	v_mul_f32_e32 v208, v208, v209
	v_mul_f32_e32 v208, s26, v208
	v_mul_f32_e32 v206, 0x3e800000, v208
	v_pk_fma_f32 v[66:67], v[2:3], v[206:207], v[66:67] op_sel_hi:[1,0,1]
	v_pk_fma_f32 v[68:69], v[4:5], v[206:207], v[68:69] op_sel_hi:[1,0,1]
	v_pk_fma_f32 v[70:71], v[6:7], v[206:207], v[70:71] op_sel_hi:[1,0,1]
	v_pk_fma_f32 v[72:73], v[8:9], v[206:207], v[72:73] op_sel_hi:[1,0,1]
	v_pk_fma_f32 v[74:75], v[10:11], v[206:207], v[74:75] op_sel_hi:[1,0,1]
	v_pk_fma_f32 v[76:77], v[12:13], v[206:207], v[76:77] op_sel_hi:[1,0,1]
	v_pk_fma_f32 v[78:79], v[14:15], v[206:207], v[78:79] op_sel_hi:[1,0,1]
	v_pk_fma_f32 v[80:81], v[16:17], v[206:207], v[80:81] op_sel_hi:[1,0,1]
	v_pk_fma_f32 v[82:83], v[18:19], v[206:207], v[82:83] op_sel_hi:[1,0,1]
	v_pk_fma_f32 v[84:85], v[20:21], v[206:207], v[84:85] op_sel_hi:[1,0,1]
	v_pk_fma_f32 v[86:87], v[22:23], v[206:207], v[86:87] op_sel_hi:[1,0,1]
	v_pk_fma_f32 v[88:89], v[24:25], v[206:207], v[88:89] op_sel_hi:[1,0,1]
	v_pk_fma_f32 v[90:91], v[26:27], v[206:207], v[90:91] op_sel_hi:[1,0,1]
	v_pk_fma_f32 v[92:93], v[28:29], v[206:207], v[92:93] op_sel_hi:[1,0,1]
	v_pk_fma_f32 v[94:95], v[30:31], v[206:207], v[94:95] op_sel_hi:[1,0,1]
	v_pk_fma_f32 v[96:97], v[32:33], v[206:207], v[96:97] op_sel_hi:[1,0,1]
	s_waitcnt vmcnt(21)
	v_cvt_scalef32_pk32_f32_fp6 v[2:33], v[170:175], 1.0
	v_mul_f32_e32 v200, v2, v34
	v_mul_f32_e32 v201, v3, v35
	v_mul_f32_e32 v202, v4, v36
	v_mul_f32_e32 v203, v5, v37
	v_fmac_f32_e32 v200, v6, v38
	v_fmac_f32_e32 v201, v7, v39
	v_fmac_f32_e32 v202, v8, v40
	v_fmac_f32_e32 v203, v9, v41
	v_fmac_f32_e32 v200, v10, v42
	v_fmac_f32_e32 v201, v11, v43
	v_fmac_f32_e32 v202, v12, v44
	v_fmac_f32_e32 v203, v13, v45
	v_fmac_f32_e32 v200, v14, v46
	v_fmac_f32_e32 v201, v15, v47
	v_fmac_f32_e32 v202, v16, v48
	v_fmac_f32_e32 v203, v17, v49
	v_fmac_f32_e32 v200, v18, v50
	v_fmac_f32_e32 v201, v19, v51
	v_fmac_f32_e32 v202, v20, v52
	v_fmac_f32_e32 v203, v21, v53
	v_fmac_f32_e32 v200, v22, v54
	v_fmac_f32_e32 v201, v23, v55
	v_fmac_f32_e32 v202, v24, v56
	v_fmac_f32_e32 v203, v25, v57
	v_fmac_f32_e32 v200, v26, v58
	v_fmac_f32_e32 v201, v27, v59
	v_fmac_f32_e32 v202, v28, v60
	v_fmac_f32_e32 v203, v29, v61
	v_fmac_f32_e32 v200, v30, v62
	v_fmac_f32_e32 v201, v31, v63
	v_fmac_f32_e32 v202, v32, v64
	v_fmac_f32_e32 v203, v33, v65
	v_add_f32_e32 v200, v201, v200
	v_add_f32_e32 v202, v203, v202
	v_cvt_scalef32_pk32_f32_fp6 v[2:33], v[176:181], 1.0
	v_add_f32_e32 v200, v202, v200
	s_add_i32 s38, s24, 6
	v_readlane_b32 s26, v199, s38
	s_mov_b32 s39, 6
	v_readlane_b32 s25, v216, s39
	v_add_f32_dpp v200, v200, v200 quad_perm:[1,0,3,2] row_mask:0xf bank_mask:0xf bound_ctrl:1
	s_nop 1
	v_add_f32_dpp v200, v200, v200 quad_perm:[2,3,0,1] row_mask:0xf bank_mask:0xf bound_ctrl:1
	s_nop 1
	v_add_f32_dpp v200, v200, v200 row_half_mirror row_mask:0xf bank_mask:0xf bound_ctrl:1
	s_nop 1
	v_add_f32_dpp v200, v200, v200 row_mirror row_mask:0xf bank_mask:0xf bound_ctrl:1
	s_nop 1
	v_add_f32_dpp v200, v200, v200 row_bcast:15 row_mask:0xa bank_mask:0xf
	s_nop 1
	v_add_f32_dpp v200, v200, v200 row_bcast:31 row_mask:0xc bank_mask:0xf
	s_nop 0
	v_readlane_b32 s27, v200, 63
	s_mul_i32 s40, s25, 0xc00
	s_add_u32 s28, s62, s40
	s_addc_u32 s29, s63, 0
	global_load_dwordx4 v[170:173], v1, s[28:29]
	global_load_dwordx4 v[174:177], v1, s[28:29] offset:2048
	global_load_dwordx4 v[178:181], v1, s[28:29] offset:1024
	v_mul_f32_e32 v204, s27, v212
	v_mul_f32_e32 v205, 0x3f3504f3, v204
	v_cmp_lt_f32_e64 s[32:33], |v205|, 1.0
	s_and_b64 vcc, exec, s[32:33]
	s_cbranch_vccnz .Lsm_45
	v_fma_f32 v208, |v205|, s9, v214
	v_fma_f32 v208, |v205|, v208, s10
	v_fma_f32 v208, |v205|, v208, s11
	v_fma_f32 v208, |v205|, v208, s12
	v_fma_f32 v208, |v205|, v208, s13
	v_fma_f32 v208, |v205|, v208, s14
	v_fma_f32 v208, |v205|, v208, |v205|
	v_mul_f32_e32 v209, 0xbfb8aa3b, v208
	v_fma_f32 v210, v208, s15, -v209
	v_rndne_f32_e32 v211, v209
	v_fmac_f32_e32 v210, 0xb2a5705f, v208
	v_sub_f32_e32 v209, v209, v211
	v_add_f32_e32 v209, v209, v210
	v_cvt_i32_f32_e32 v210, v211
	v_exp_f32_e32 v209, v209
	v_cmp_nlt_f32_e32 vcc, s16, v208
	v_ldexp_f32 v209, v209, v210
	s_nop 0
	v_cndmask_b32_e32 v209, 0, v209, vcc
	v_cmp_ngt_f32_e32 vcc, s17, v208
	s_nop 1
	v_cndmask_b32_e32 v208, v215, v209, vcc
	v_sub_f32_e32 v210, 1.0, v208
	s_branch .Ljn_45

; DEV float gelu_exact(float v) { return 0.5f * v * (1.f + erff(v * 0.7071067811865476f)); }
; DEV void peer_gather_token(const Params& p, int tok) {
;     ...
;   auto issue = [&](int k, int slot) {
;     const int e = (k < 64) ? __builtin_amdgcn_readlane(e0, k) : __builtin_amdgcn_readlane(e1, k - 64);
;     const unsigned char* dr = p.down8 + (size_t)e * ROW6 + lane * 24;
;     const unsigned char* ur = p.up8 + (size_t)e * ROW6 + lane * 24;
; #pragma unroll
;     for (int i = 0; i < 3; ++i) { dn[slot][i] = *(const u32x2*)(dr + i * 8); up[slot][i] = *(const u32x2*)(ur + i * 8); }
;   };
;   issue(0, 0); issue(1, 1); issue(2, 2);
; #pragma unroll 1
;   for (int k4 = 0; k4 < 128; k4 += 4) {
; #pragma unroll
;     for (int s = 0; s < 4; ++s) {
;       const int k = k4 + s;
;       if (k + 3 < 128) issue(k + 3, (s + 3) & 3);
;       const v6u dq = v6u{dn[s][0][0], dn[s][0][1], dn[s][1][0], dn[s][1][1], dn[s][2][0], dn[s][2][1]};
;       const v32f dv = __builtin_amdgcn_cvt_scalef32_pk32_f32_fp6(dq, 1.0f);
;       float d0 = 0.f, d1 = 0.f, d2 = 0.f, d3 = 0.f;
; #pragma unroll
;       for (int i = 0; i < 8; ++i) { d0 += dv[4 * i] * hx[4 * i]; d1 += dv[4 * i + 1] * hx[4 * i + 1]; d2 += dv[4 * i + 2] * hx[4 * i + 2]; d3 += dv[4 * i + 3] * hx[4 * i + 3]; }
;       const float d = wave_sum_fast((d0 + d1) + (d2 + d3)) * (1.f / DOWN_SCALE);
;       const float gk = __builtin_bit_cast(float, (k < 64) ? __builtin_amdgcn_readlane(g0, k) : __builtin_amdgcn_readlane(g1, k - 64));
;       const float act = gelu_exact(d) * gk * (1.f / UP_SCALE);
;       const v6u uq = v6u{up[s][0][0], up[s][0][1], up[s][1][0], up[s][1][1], up[s][2][0], up[s][2][1]};
;       const v32f uv = __builtin_amdgcn_cvt_scalef32_pk32_f32_fp6(uq, 1.0f);
; #pragma unroll
;       for (int i = 0; i < 32; ++i) acc[i] += act * uv[i];
.Ljn_45:
	v_bfi_b32 v209, s18, v210, v205
	v_mul_f32_e32 v208, 0.5, v204
	v_add_f32_e32 v209, 1.0, v209
	v_mul_f32_e32 v208, v208, v209
	v_mul_f32_e32 v208, s26, v208
	v_mul_f32_e32 v206, 0x3e800000, v208
	v_pk_fma_f32 v[66:67], v[2:3], v[206:207], v[66:67] op_sel_hi:[1,0,1]
	v_pk_fma_f32 v[68:69], v[4:5], v[206:207], v[68:69] op_sel_hi:[1,0,1]
	v_pk_fma_f32 v[70:71], v[6:7], v[206:207], v[70:71] op_sel_hi:[1,0,1]
	v_pk_fma_f32 v[72:73], v[8:9], v[206:207], v[72:73] op_sel_hi:[1,0,1]
	v_pk_fma_f32 v[74:75], v[10:11], v[206:207], v[74:75] op_sel_hi:[1,0,1]
	v_pk_fma_f32 v[76:77], v[12:13], v[206:207], v[76:77] op_sel_hi:[1,0,1]
	v_pk_fma_f32 v[78:79], v[14:15], v[206:207], v[78:79] op_sel_hi:[1,0,1]
	v_pk_fma_f32 v[80:81], v[16:17], v[206:207], v[80:81] op_sel_hi:[1,0,1]
	v_pk_fma_f32 v[82:83], v[18:19], v[206:207], v[82:83] op_sel_hi:[1,0,1]
	v_pk_fma_f32 v[84:85], v[20:21], v[206:207], v[84:85] op_sel_hi:[1,0,1]
	v_pk_fma_f32 v[86:87], v[22:23], v[206:207], v[86:87] op_sel_hi:[1,0,1]
	v_pk_fma_f32 v[88:89], v[24:25], v[206:207], v[88:89] op_sel_hi:[1,0,1]
	v_pk_fma_f32 v[90:91], v[26:27], v[206:207], v[90:91] op_sel_hi:[1,0,1]
	v_pk_fma_f32 v[92:93], v[28:29], v[206:207], v[92:93] op_sel_hi:[1,0,1]
	v_pk_fma_f32 v[94:95], v[30:31], v[206:207], v[94:95] op_sel_hi:[1,0,1]
	v_pk_fma_f32 v[96:97], v[32:33], v[206:207], v[96:97] op_sel_hi:[1,0,1]
	s_waitcnt vmcnt(21)
	v_cvt_scalef32_pk32_f32_fp6 v[2:33], v[182:187], 1.0
	v_mul_f32_e32 v200, v2, v34
	v_mul_f32_e32 v201, v3, v35
	v_mul_f32_e32 v202, v4, v36
	v_mul_f32_e32 v203, v5, v37
	v_fmac_f32_e32 v200, v6, v38
	v_fmac_f32_e32 v201, v7, v39
	v_fmac_f32_e32 v202, v8, v40
	v_fmac_f32_e32 v203, v9, v41
	v_fmac_f32_e32 v200, v10, v42
	v_fmac_f32_e32 v201, v11, v43
	v_fmac_f32_e32 v202, v12, v44
	v_fmac_f32_e32 v203, v13, v45
	v_fmac_f32_e32 v200, v14, v46
	v_fmac_f32_e32 v201, v15, v47
	v_fmac_f32_e32 v202, v16, v48
	v_fmac_f32_e32 v203, v17, v49
	v_fmac_f32_e32 v200, v18, v50
	v_fmac_f32_e32 v201, v19, v51
	v_fmac_f32_e32 v202, v20, v52
	v_fmac_f32_e32 v203, v21, v53
	v_fmac_f32_e32 v200, v22, v54
	v_fmac_f32_e32 v201, v23, v55
	v_fmac_f32_e32 v202, v24, v56
	v_fmac_f32_e32 v203, v25, v57
	v_fmac_f32_e32 v200, v26, v58
	v_fmac_f32_e32 v201, v27, v59
	v_fmac_f32_e32 v202, v28, v60
	v_fmac_f32_e32 v203, v29, v61
	v_fmac_f32_e32 v200, v30, v62
	v_fmac_f32_e32 v201, v31, v63
	v_fmac_f32_e32 v202, v32, v64
	v_fmac_f32_e32 v203, v33, v65
	v_add_f32_e32 v200, v201, v200
	v_add_f32_e32 v202, v203, v202
	v_cvt_scalef32_pk32_f32_fp6 v[2:33], v[188:193], 1.0
	v_add_f32_e32 v200, v202, v200
	s_add_i32 s38, s24, 7
	v_readlane_b32 s26, v199, s38
	s_mov_b32 s39, 7
	v_readlane_b32 s25, v216, s39
	v_add_f32_dpp v200, v200, v200 quad_perm:[1,0,3,2] row_mask:0xf bank_mask:0xf bound_ctrl:1
	s_nop 1
	v_add_f32_dpp v200, v200, v200 quad_perm:[2,3,0,1] row_mask:0xf bank_mask:0xf bound_ctrl:1
	s_nop 1
	v_add_f32_dpp v200, v200, v200 row_half_mirror row_mask:0xf bank_mask:0xf bound_ctrl:1
	s_nop 1
	v_add_f32_dpp v200, v200, v200 row_mirror row_mask:0xf bank_mask:0xf bound_ctrl:1
	s_nop 1
	v_add_f32_dpp v200, v200, v200 row_bcast:15 row_mask:0xa bank_mask:0xf
	s_nop 1
	v_add_f32_dpp v200, v200, v200 row_bcast:31 row_mask:0xc bank_mask:0xf
	s_nop 0
	v_readlane_b32 s27, v200, 63
	s_mul_i32 s40, s25, 0xc00
	s_add_u32 s28, s62, s40
	s_addc_u32 s29, s63, 0
	global_load_dwordx4 v[182:185], v1, s[28:29]
	global_load_dwordx4 v[186:189], v1, s[28:29] offset:2048
	global_load_dwordx4 v[190:193], v1, s[28:29] offset:1024
	v_mul_f32_e32 v204, s27, v212
	v_mul_f32_e32 v205, 0x3f3504f3, v204
	v_cmp_lt_f32_e64 s[32:33], |v205|, 1.0
	s_and_b64 vcc, exec, s[32:33]
	s_cbranch_vccnz .Lsm_47
	v_fma_f32 v208, |v205|, s9, v214
	v_fma_f32 v208, |v205|, v208, s10
	v_fma_f32 v208, |v205|, v208, s11
	v_fma_f32 v208, |v205|, v208, s12
	v_fma_f32 v208, |v205|, v208, s13
	v_fma_f32 v208, |v205|, v208, s14
	v_fma_f32 v208, |v205|, v208, |v205|
	v_mul_f32_e32 v209, 0xbfb8aa3b, v208
	v_fma_f32 v210, v208, s15, -v209
	v_rndne_f32_e32 v211, v209
	v_fmac_f32_e32 v210, 0xb2a5705f, v208
	v_sub_f32_e32 v209, v209, v211
	v_add_f32_e32 v209, v209, v210
	v_cvt_i32_f32_e32 v210, v211
	v_exp_f32_e32 v209, v209
	v_cmp_nlt_f32_e32 vcc, s16, v208
	v_ldexp_f32 v209, v209, v210
	s_nop 0
	v_cndmask_b32_e32 v209, 0, v209, vcc
	v_cmp_ngt_f32_e32 vcc, s17, v208
	s_nop 1
	v_cndmask_b32_e32 v208, v215, v209, vcc
	v_sub_f32_e32 v210, 1.0, v208
	s_branch .Ljn_47

; DEV void peer_gather_token(const Params& p, int tok) {
;     ...
;       for (int i = 0; i < 32; ++i) acc[i] += act * uv[i];
;     }
;   }
;   const float* gt2 = p.mod + (size_t)b * 12288 + 10240;
;   float* orow = p.out + (size_t)tok * 2048;
; #pragma unroll
;   for (int q = 0; q < 8; ++q) {
;     const int col = lane * 32 + q * 4;
;     float4 x0 = *(const float4*)(orow + col);
;     float4 ga = *(const float4*)(gt2 + col);
;     x0.x += ga.x * acc[q * 4 + 0]; x0.y += ga.y * acc[q * 4 + 1]; x0.z += ga.z * acc[q * 4 + 2]; x0.w += ga.w * acc[q * 4 + 3];
;     *(float4*)(orow + col) = x0;
;   }
.Ljn_47:
	v_bfi_b32 v209, s18, v210, v205
	v_mul_f32_e32 v208, 0.5, v204
	v_add_f32_e32 v209, 1.0, v209
	v_mul_f32_e32 v208, v208, v209
	v_mul_f32_e32 v208, s26, v208
	v_mul_f32_e32 v206, 0x3e800000, v208
	v_pk_fma_f32 v[66:67], v[2:3], v[206:207], v[66:67] op_sel_hi:[1,0,1]
	v_pk_fma_f32 v[68:69], v[4:5], v[206:207], v[68:69] op_sel_hi:[1,0,1]
	v_pk_fma_f32 v[70:71], v[6:7], v[206:207], v[70:71] op_sel_hi:[1,0,1]
	v_pk_fma_f32 v[72:73], v[8:9], v[206:207], v[72:73] op_sel_hi:[1,0,1]
	v_pk_fma_f32 v[74:75], v[10:11], v[206:207], v[74:75] op_sel_hi:[1,0,1]
	v_pk_fma_f32 v[76:77], v[12:13], v[206:207], v[76:77] op_sel_hi:[1,0,1]
	v_pk_fma_f32 v[78:79], v[14:15], v[206:207], v[78:79] op_sel_hi:[1,0,1]
	v_pk_fma_f32 v[80:81], v[16:17], v[206:207], v[80:81] op_sel_hi:[1,0,1]
	v_pk_fma_f32 v[82:83], v[18:19], v[206:207], v[82:83] op_sel_hi:[1,0,1]
	v_pk_fma_f32 v[84:85], v[20:21], v[206:207], v[84:85] op_sel_hi:[1,0,1]
	v_pk_fma_f32 v[86:87], v[22:23], v[206:207], v[86:87] op_sel_hi:[1,0,1]
	v_pk_fma_f32 v[88:89], v[24:25], v[206:207], v[88:89] op_sel_hi:[1,0,1]
	v_pk_fma_f32 v[90:91], v[26:27], v[206:207], v[90:91] op_sel_hi:[1,0,1]
	v_pk_fma_f32 v[92:93], v[28:29], v[206:207], v[92:93] op_sel_hi:[1,0,1]
	v_pk_fma_f32 v[94:95], v[30:31], v[206:207], v[94:95] op_sel_hi:[1,0,1]
	v_pk_fma_f32 v[96:97], v[32:33], v[206:207], v[96:97] op_sel_hi:[1,0,1]
	s_lshr_b32 s38, s20, 11
	s_mul_i32 s38, s38, 0xc000
	s_add_u32 s38, s38, 0xa000
	s_add_u32 s58, s78, s38
	s_addc_u32 s59, s79, 0
	global_load_dwordx4 v[34:37], v244, s[58:59]
	global_load_dwordx4 v[38:41], v244, s[58:59] offset:1024
	global_load_dwordx4 v[42:45], v244, s[58:59] offset:2048
	global_load_dwordx4 v[46:49], v244, s[58:59] offset:3072
	global_load_dwordx4 v[50:53], v245, s[58:59]
	global_load_dwordx4 v[54:57], v245, s[58:59] offset:1024
	global_load_dwordx4 v[58:61], v245, s[58:59] offset:2048
	global_load_dwordx4 v[62:65], v245, s[58:59] offset:3072
	s_lshl_b32 s38, s20, 13
	s_add_u32 s58, s44, s38
	s_addc_u32 s59, s45, 0
	global_load_dwordx4 v[2:5], v244, s[58:59]
	global_load_dwordx4 v[6:9], v244, s[58:59] offset:1024
	global_load_dwordx4 v[10:13], v244, s[58:59] offset:2048
	global_load_dwordx4 v[14:17], v244, s[58:59] offset:3072
	global_load_dwordx4 v[18:21], v245, s[58:59]
	global_load_dwordx4 v[22:25], v245, s[58:59] offset:1024
	global_load_dwordx4 v[26:29], v245, s[58:59] offset:2048
	global_load_dwordx4 v[30:33], v245, s[58:59] offset:3072
	s_waitcnt vmcnt(0)
	v_fmac_f32_e32 v2, v34, v66
	v_fmac_f32_e32 v3, v35, v67
	v_fmac_f32_e32 v4, v36, v68
	v_fmac_f32_e32 v5, v37, v69
	v_fmac_f32_e32 v6, v38, v70
	v_fmac_f32_e32 v7, v39, v71
	v_fmac_f32_e32 v8, v40, v72
	v_fmac_f32_e32 v9, v41, v73
	v_fmac_f32_e32 v10, v42, v74
	v_fmac_f32_e32 v11, v43, v75
	v_fmac_f32_e32 v12, v44, v76
	v_fmac_f32_e32 v13, v45, v77
	v_fmac_f32_e32 v14, v46, v78
	v_fmac_f32_e32 v15, v47, v79
	v_fmac_f32_e32 v16, v48, v80
	v_fmac_f32_e32 v17, v49, v81
	v_fmac_f32_e32 v18, v50, v82
	v_fmac_f32_e32 v19, v51, v83
	v_fmac_f32_e32 v20, v52, v84
	v_fmac_f32_e32 v21, v53, v85
	v_fmac_f32_e32 v22, v54, v86
	v_fmac_f32_e32 v23, v55, v87
	v_fmac_f32_e32 v24, v56, v88
	v_fmac_f32_e32 v25, v57, v89
	v_fmac_f32_e32 v26, v58, v90
	v_fmac_f32_e32 v27, v59, v91
	v_fmac_f32_e32 v28, v60, v92
	v_fmac_f32_e32 v29, v61, v93
	v_fmac_f32_e32 v30, v62, v94
	v_fmac_f32_e32 v31, v63, v95
	v_fmac_f32_e32 v32, v64, v96
	v_fmac_f32_e32 v33, v65, v97
	global_store_dwordx4 v244, v[2:5], s[58:59]
	global_store_dwordx4 v244, v[6:9], s[58:59] offset:1024
	global_store_dwordx4 v244, v[10:13], s[58:59] offset:2048
	global_store_dwordx4 v244, v[14:17], s[58:59] offset:3072
	global_store_dwordx4 v245, v[18:21], s[58:59]
	global_store_dwordx4 v245, v[22:25], s[58:59] offset:1024
	global_store_dwordx4 v245, v[26:29], s[58:59] offset:2048
	global_store_dwordx4 v245, v[30:33], s[58:59] offset:3072
	s_add_i32 s20, s20, s21
	s_cmpk_lt_u32 s20, 0x4000
	s_cbranch_scc0 .Lp12_end
; DEV float bflo(unsigned u) { return __uint_as_float(u << 16); }
; DEV float bfhi(unsigned u) { return __uint_as_float(u & 0xffff0000u); }
; DEV void peer_gather_token(const Params& p, int tok) {
;     ...
;   {
;     const u16* hr = p.h + (size_t)tok * 2048 + lane * 32;
; #pragma unroll
;     for (int q = 0; q < 4; ++q) {
;       u32x4 v = *(const u32x4*)(hr + q * 8);
; #pragma unroll
;       for (int e = 0; e < 4; ++e) { hx[q * 8 + 2 * e] = bflo(v[e]); hx[q * 8 + 2 * e + 1] = bfhi(v[e]); }
;     }
;   }
; #pragma unroll
;   for (int e = 0; e < 32; ++e) acc[e] = 0.f;
;   const int e0 = p.eidx[(size_t)tok * 128 + lane], e1 = p.eidx[(size_t)tok * 128 + 64 + lane];
;   const int g0 = __builtin_bit_cast(int, p.gw[(size_t)tok * 128 + lane]), g1 = __builtin_bit_cast(int, p.gw[(size_t)tok * 128 + 64 + lane]);
;   u32x2 dn[4][3], up[4][3];
;   auto issue = [&](int k, int slot) {
;     const int e = (k < 64) ? __builtin_amdgcn_readlane(e0, k) : __builtin_amdgcn_readlane(e1, k - 64);
;     const unsigned char* dr = p.down8 + (size_t)e * ROW6 + lane * 24;
;     const unsigned char* ur = p.up8 + (size_t)e * ROW6 + lane * 24;
; #pragma unroll
;     for (int i = 0; i < 3; ++i) { dn[slot][i] = *(const u32x2*)(dr + i * 8); up[slot][i] = *(const u32x2*)(ur + i * 8); }
;   };
;   issue(0, 0); issue(1, 1); issue(2, 2);
.Lp12_switch:
	v_mov_b32_e32 v194, v216
	v_mov_b32_e32 v195, v217
	v_mov_b32_e32 v196, v218
	v_mov_b32_e32 v197, v219
	v_mov_b32_e32 v198, v216
	v_mov_b32_e32 v199, v218
	v_lshlrev_b32_e32 v34, 16, v220
	v_and_b32_e32 v35, 0xffff0000, v220
	v_lshlrev_b32_e32 v36, 16, v221
	v_and_b32_e32 v37, 0xffff0000, v221
	v_lshlrev_b32_e32 v38, 16, v222
	v_and_b32_e32 v39, 0xffff0000, v222
	v_lshlrev_b32_e32 v40, 16, v223
	v_and_b32_e32 v41, 0xffff0000, v223
	v_lshlrev_b32_e32 v42, 16, v224
	v_and_b32_e32 v43, 0xffff0000, v224
	v_lshlrev_b32_e32 v44, 16, v225
	v_and_b32_e32 v45, 0xffff0000, v225
	v_lshlrev_b32_e32 v46, 16, v226
	v_and_b32_e32 v47, 0xffff0000, v226
	v_lshlrev_b32_e32 v48, 16, v227
	v_and_b32_e32 v49, 0xffff0000, v227
	v_lshlrev_b32_e32 v50, 16, v228
	v_and_b32_e32 v51, 0xffff0000, v228
	v_lshlrev_b32_e32 v52, 16, v229
	v_and_b32_e32 v53, 0xffff0000, v229
	v_lshlrev_b32_e32 v54, 16, v230
	v_and_b32_e32 v55, 0xffff0000, v230
	v_lshlrev_b32_e32 v56, 16, v231
	v_and_b32_e32 v57, 0xffff0000, v231
	v_lshlrev_b32_e32 v58, 16, v232
	v_and_b32_e32 v59, 0xffff0000, v232
	v_lshlrev_b32_e32 v60, 16, v233
	v_and_b32_e32 v61, 0xffff0000, v233
	v_lshlrev_b32_e32 v62, 16, v234
	v_and_b32_e32 v63, 0xffff0000, v234
	v_lshlrev_b32_e32 v64, 16, v235
	v_and_b32_e32 v65, 0xffff0000, v235
	v_mov_b32_e32 v66, 0
	v_mov_b32_e32 v67, 0
	v_mov_b32_e32 v68, 0
	v_mov_b32_e32 v69, 0
	v_mov_b32_e32 v70, 0
	v_mov_b32_e32 v71, 0
	v_mov_b32_e32 v72, 0
	v_mov_b32_e32 v73, 0
	v_mov_b32_e32 v74, 0
	v_mov_b32_e32 v75, 0
	v_mov_b32_e32 v76, 0
	v_mov_b32_e32 v77, 0
	v_mov_b32_e32 v78, 0
	v_mov_b32_e32 v79, 0
	v_mov_b32_e32 v80, 0
	v_mov_b32_e32 v81, 0
	v_mov_b32_e32 v82, 0
	v_mov_b32_e32 v83, 0
	v_mov_b32_e32 v84, 0
	v_mov_b32_e32 v85, 0
	v_mov_b32_e32 v86, 0
	v_mov_b32_e32 v87, 0
	v_mov_b32_e32 v88, 0
	v_mov_b32_e32 v89, 0
	v_mov_b32_e32 v90, 0
	v_mov_b32_e32 v91, 0
	v_mov_b32_e32 v92, 0
	v_mov_b32_e32 v93, 0
	v_mov_b32_e32 v94, 0
	v_mov_b32_e32 v95, 0
	v_mov_b32_e32 v96, 0
	v_mov_b32_e32 v97, 0
	s_mov_b32 s22, 0
	s_mov_b32 s23, 8
	s_mov_b32 s24, 0
	s_cmp_eq_u32 s43, 0
	s_cbranch_scc1 .Lp12_token
	s_mov_b32 s43, 0
	v_readlane_b32 s25, v194, 0
	s_mul_i32 s40, s25, 0xc00
	s_add_u32 s28, s62, s40
	s_addc_u32 s29, s63, 0
	global_load_dwordx4 v[98:101], v1, s[28:29]
	global_load_dwordx4 v[102:105], v1, s[28:29] offset:2048
	global_load_dwordx4 v[106:109], v1, s[28:29] offset:1024
	v_readlane_b32 s25, v194, 1
	s_mul_i32 s40, s25, 0xc00
	s_add_u32 s28, s62, s40
	s_addc_u32 s29, s63, 0
	global_load_dwordx4 v[110:113], v1, s[28:29]
	global_load_dwordx4 v[114:117], v1, s[28:29] offset:2048
	global_load_dwordx4 v[118:121], v1, s[28:29] offset:1024
	v_readlane_b32 s25, v194, 2
	s_mul_i32 s40, s25, 0xc00
	s_add_u32 s28, s62, s40
	s_addc_u32 s29, s63, 0
	global_load_dwordx4 v[122:125], v1, s[28:29]
	global_load_dwordx4 v[126:129], v1, s[28:29] offset:2048
	global_load_dwordx4 v[130:133], v1, s[28:29] offset:1024
	v_readlane_b32 s25, v194, 3
	s_mul_i32 s40, s25, 0xc00
	s_add_u32 s28, s62, s40
	s_addc_u32 s29, s63, 0
	global_load_dwordx4 v[134:137], v1, s[28:29]
	global_load_dwordx4 v[138:141], v1, s[28:29] offset:2048
	global_load_dwordx4 v[142:145], v1, s[28:29] offset:1024
	v_readlane_b32 s25, v194, 4
	s_mul_i32 s40, s25, 0xc00
	s_add_u32 s28, s62, s40
	s_addc_u32 s29, s63, 0
	global_load_dwordx4 v[146:149], v1, s[28:29]
	global_load_dwordx4 v[150:153], v1, s[28:29] offset:2048
	global_load_dwordx4 v[154:157], v1, s[28:29] offset:1024
	v_readlane_b32 s25, v194, 5
	s_mul_i32 s40, s25, 0xc00
	s_add_u32 s28, s62, s40
	s_addc_u32 s29, s63, 0
	global_load_dwordx4 v[158:161], v1, s[28:29]
	global_load_dwordx4 v[162:165], v1, s[28:29] offset:2048
	global_load_dwordx4 v[166:169], v1, s[28:29] offset:1024
	v_readlane_b32 s25, v194, 6
	s_mul_i32 s40, s25, 0xc00
	s_add_u32 s28, s62, s40
	s_addc_u32 s29, s63, 0
	global_load_dwordx4 v[170:173], v1, s[28:29]
	global_load_dwordx4 v[174:177], v1, s[28:29] offset:2048
	global_load_dwordx4 v[178:181], v1, s[28:29] offset:1024
	v_readlane_b32 s25, v194, 7
	s_mul_i32 s40, s25, 0xc00
	s_add_u32 s28, s62, s40
	s_addc_u32 s29, s63, 0
	global_load_dwordx4 v[182:185], v1, s[28:29]
	global_load_dwordx4 v[186:189], v1, s[28:29] offset:2048
	global_load_dwordx4 v[190:193], v1, s[28:29] offset:1024
	s_branch .Lp12_token
.Lp12_end:
.LBB0_1626:
	s_endpgm
